# wave halves run in phase outside K-loops: offset barrier moved to K-loop entry/exit so both halves epilogues overlap
# speedup vs baseline: 1.0192x; 1.0192x over previous
; #define LAS __attribute__((address_space(3)))
; template <class Epi, class Sched>
; __device__ __forceinline__ void gemm_phase(PG8_LAS unsigned char* lds, const Gemm g, const Sched& S, const Epi& E) {
;     ...
;     const int tid = tix_, wid = __builtin_amdgcn_readfirstlane(tid >> 6), lane = tid & 63, wr = wid >> 2, wc = wid & 3, fr = lane & 15, fq = lane >> 4;
; __global__ void __launch_bounds__(512, 2) mega_fwd(Params p, int ph_lo, int ph_hi) {
;     ...
;     if (threadIdx.x == 0) { ((unsigned*)(shm + 131072))[0] = 0u; ((unsigned*)(shm + 131072))[1] = 0u; ((unsigned*)(shm + 131072))[2] = 0u; ((unsigned*)(shm + 131072))[3] = 0u; }
;     __syncthreads();
;     XcdBarrier xbar = xcd_barrier_post((unsigned*)(p.ws + WS_BAR), (volatile LAS unsigned*)(shm + 131072));
.LBB0_2:
	s_or_b64 exec, exec, s[4:5]
	v_readfirstlane_b32 s78, v228
	s_lshr_b32 s78, s78, 8
	s_waitcnt lgkmcnt(0)
	s_barrier
	s_add_u32 s44, s42, 0x2dd20000
	s_getreg_b32 s3, hwreg(HW_REG_XCC_ID, 0, 4)
	s_addc_u32 s45, s43, 0
	s_and_b32 s3, s3, 15
	s_and_saveexec_b64 s[4:5], s[34:35]
	s_cbranch_execz .LBB0_5
	s_mov_b64 s[6:7], exec
	v_mbcnt_lo_u32_b32 v1, s6, 0
	v_mbcnt_hi_u32_b32 v1, s7, v1
	v_cmp_eq_u32_e32 vcc, 0, v1
	s_and_b64 s[8:9], exec, vcc
	s_mov_b64 exec, s[8:9]
	s_cbranch_execz .LBB0_5
	s_lshl_b32 s8, s3, 8
	s_bcnt1_i32_b64 s6, s[6:7]
	v_mov_b32_e32 v1, s8
	v_mov_b32_e32 v2, s6
	global_atomic_add v1, v2, s[44:45] offset:1024

;     __host__ __device__ bool next(int i, Unit& u) const { const int j = i / 3; if (!StaticOrder::next(j, u)) return false; u.br = i - 3 * j; return true; }
; #define PG8_STAGE(bufoff, gbase, voff) do { _Pragma("unroll") for (int _i = 0; _i < 2; ++_i) \
;         __builtin_amdgcn_global_load_lds((const unsigned*)((const char*)(gbase) + (voff)[_i]), (PG8_LAS unsigned*)(lds + (bufoff) + ldsw + _i * 8192), 16, 0, 0); } while (0)
; template <class Epi, class Sched>
; __device__ __forceinline__ void gemm_phase(PG8_LAS unsigned char* lds, const Gemm g, const Sched& S, const Epi& E) {
;     ...
;     const int tid = tix_, wid = __builtin_amdgcn_readfirstlane(tid >> 6), lane = tid & 63, wr = wid >> 2, wc = wid & 3, fr = lane & 15, fq = lane >> 4;
;     const int K = g.K, nt = K / BK;
;     unsigned voffA[2], voffB[2];
; #pragma unroll
;     for (int i = 0; i < 2; ++i) { int R, C; stage_rc(tid * 16 + i * 8192, R, C);
;         voffA[i] = (unsigned)(R * K + C) * 2u; voffB[i] = (unsigned)(tid * 16 + i * 8192); }
;     const size_t kstep = (size_t)(BK * 2);
;     const size_t hstep = (size_t)HALF * K * 2;
;     const size_t tstep = 2 * hstep;
;     const size_t kstepB = 32768, hstepB = 16384, tstepB = (size_t)nt * 32768;
;     const unsigned ldsw = (unsigned)wid * 1024u;
;     const int aoff = lds_byte(wr * 64 + fr, fq * 8), boff = lds_byte(wc * 32 + fr, fq * 8);
;     ...
;     Unit cur, nxt; int ui = 0;
;     if (!S.next(0, cur)) return;
;     f32x4 acc[2][2][4][2];
; #pragma unroll
;     for (int a = 0; a < 2; ++a)
; #pragma unroll
;         for (int b = 0; b < 2; ++b)
; #pragma unroll
;             for (int m = 0; m < 4; ++m)
; #pragma unroll
;                 for (int n = 0; n < 2; ++n) acc[a][b][m][n] = (f32x4){0.f, 0.f, 0.f, 0.f};
;     bf16x8 At[4][2], B0[2][2], B1[2][2];
;     const char* cA = (const char*)g.A + (size_t)cur.pm * tstep + (size_t)cur.br * g.strideA; const char* cB = (const char*)g.Bt + (size_t)cur.pn * tstepB + (size_t)cur.br * g.strideB;
;     S.a_ready(cur);
;     PG8_STAGE(PG8_SB(0, 0), cB, voffB); PG8_STAGE(PG8_SA(0, 0), cA, voffA); PG8_STAGE(PG8_SB(0, 1), cB + hstepB, voffB); PG8_STAGE(PG8_SA(0, 1), cA + hstep, voffA);
;     if (wr == 1) PG8_BAR;
;     PG8_WAIT_V(4); PG8_BAR;
;     PG8_STAGE(PG8_SB(1, 0), cB + kstepB, voffB); PG8_STAGE(PG8_SA(1, 0), cA + kstep, voffA); PG8_STAGE(PG8_SB(1, 1), cB + hstepB + kstepB, voffB);
;     PG8_WAIT_V(6); PG8_BAR;
.LBB0_72:
	s_or_b64 exec, exec, s[4:5]
	s_mov_b64 s[4:5], s[0:1]
	s_mov_b32 s28, s40
	s_mov_b32 s29, s2
	v_mov_b32_e32 v4, v228
	s_barrier
	s_cmpk_gt_i32 s29, 0xabf
	v_readfirstlane_b32 s30, v4
	s_cbranch_scc1 .LBB0_84
	s_load_dwordx2 s[6:7], s[4:5], 0xa8
	v_lshlrev_b32_e32 v128, 4, v4
	s_mul_hi_i32 s4, s29, 0x2fa0be83
	v_add_u32_e32 v130, 0x2000, v128
	v_ashrrev_i32_e32 v0, 31, v130
	s_waitcnt lgkmcnt(0)
	s_add_u32 s31, s6, 0xc700000
	s_addc_u32 s36, s7, 0
	s_lshr_b32 s8, s4, 31
	s_lshr_b32 s4, s4, 9
	s_add_i32 s4, s4, s8
	v_lshrrev_b32_e32 v0, 22, v0
	s_mulk_i32 s4, 0xac0
	v_add_u32_e32 v0, v130, v0
	s_sub_i32 s4, s29, s4
	v_ashrrev_i32_e32 v5, 10, v0
	s_sext_i32_i16 s8, s4
	v_mul_i32_i24_e32 v1, 0x400, v5
	s_bfe_u32 s8, s8, 0x3001c
	v_sub_u32_e32 v1, v130, v1
	s_add_i32 s8, s4, s8
	v_lshrrev_b32_e32 v2, 4, v1
	s_sext_i32_i16 s9, s8
	s_and_b32 s8, s8, 0xfff8
	s_ashr_i32 s10, s30, 6
	v_bitop3_b32 v1, v2, v1, 32 bitop3:0x6c
	s_sub_i32 s4, s4, s8
	s_ashr_i32 s5, s30, 8
	s_ashr_i32 s37, s29, 31
	s_lshl_b32 s38, s10, 10
	v_ashrrev_i32_e32 v2, 31, v1
	s_ashr_i32 s9, s9, 3
	s_sext_i32_i16 s8, s4
	v_lshrrev_b32_e32 v2, 26, v2
	s_cmp_lt_i32 s8, 0
	s_movk_i32 s39, 0x159
	v_add_u32_e32 v2, v1, v2
	s_cselect_b32 s8, s39, 0x158
	s_waitcnt vmcnt(10)
	v_ashrrev_i32_e32 v6, 6, v2
	v_and_b32_e32 v2, 0xc0, v2
	s_mul_i32 s4, s8, s4
	v_sub_u32_e32 v1, v1, v2
	v_mov_b32_e32 v2, 1
	s_add_i32 s4, s4, s9
	v_ashrrev_i16_sdwa v1, v2, sext(v1) dst_sel:DWORD dst_unused:UNUSED_PAD src0_sel:DWORD src1_sel:BYTE_0
	s_sext_i32_i16 s8, s4
	v_lshlrev_b32_e32 v0, 5, v5
	v_bfe_i32 v7, v1, 0, 16
	v_lshlrev_b32_e32 v1, 3, v5
	s_mulk_i32 s8, 0x2fa1
	v_and_b32_e32 v0, 32, v0
	v_and_b32_e32 v1, 0xffff0, v1
	s_lshr_b32 s9, s8, 31
	s_ashr_i32 s8, s8, 22
	v_add_u32_e32 v0, v0, v7
	v_add_lshl_u32 v1, v6, v1, 12
	s_add_i32 s8, s8, s9
	v_lshl_add_u32 v132, v0, 1, v1
	v_bfe_i32 v1, v4, 27, 1
	s_lshl_b32 s9, s8, 3
	s_mulk_i32 s8, 0x158
	v_lshrrev_b32_e32 v1, 22, v1
	s_sub_i32 s8, s4, s8
	v_add_u32_e32 v1, v128, v1
	s_sext_i32_i16 s4, s8
	v_and_b32_e32 v1, 0xfffffc00, v1
	s_bfe_u32 s4, s4, 0x3001c
	v_sub_u32_e32 v1, v128, v1
	s_add_i32 s11, s8, s4
	v_lshrrev_b32_e32 v3, 4, v1
	s_sext_i32_i16 s4, s11
	s_and_b32 s11, s11, 0xfff8
	v_bitop3_b32 v1, v3, v1, 32 bitop3:0x6c
	s_sub_i32 s8, s8, s11
	v_ashrrev_i32_e32 v3, 31, v1
	s_sext_i32_i16 s8, s8
	v_lshrrev_b32_e32 v3, 26, v3
	s_lshr_b32 s4, s4, 3
	s_add_i32 s20, s9, s8
	v_ashrrev_i32_e32 v0, 31, v4
	v_add_u32_e32 v3, v1, v3
	s_ashr_i32 s21, s20, 31
	s_bfe_i64 s[12:13], s[4:5], 0x100000
	v_lshrrev_b32_e32 v0, 26, v0
	v_ashrrev_i32_e32 v9, 6, v3
	v_and_b32_e32 v3, 0xc0, v3
	s_lshl_b64 s[8:9], s[20:21], 20
	s_lshl_b64 s[12:13], s[12:13], 20
	v_add_u32_e32 v0, v4, v0
	v_sub_u32_e32 v1, v1, v3
	s_add_u32 s22, s6, s12
	v_ashrrev_i32_e32 v8, 6, v0
	v_ashrrev_i16_sdwa v1, v2, sext(v1) dst_sel:DWORD dst_unused:UNUSED_PAD src0_sel:DWORD src1_sel:BYTE_0
	s_addc_u32 s23, s7, s13
	s_add_i32 s21, s38, 0
	v_lshlrev_b32_e32 v0, 5, v8
	s_waitcnt vmcnt(9)
	v_bfe_i32 v10, v1, 0, 16
	v_lshlrev_b32_e32 v1, 3, v8
	s_add_i32 m0, s21, 0x10000
	v_and_b32_e32 v0, 32, v0
	v_and_b32_e32 v1, 0xffff0, v1
	global_load_lds_dwordx4 v128, s[22:23]
	s_add_i32 m0, s21, 0x12000
	v_add_u32_e32 v0, v0, v10
	v_add_lshl_u32 v1, v9, v1, 12
	s_add_u32 s24, s31, s8
	v_lshl_add_u32 v134, v0, 1, v1
	global_load_lds_dwordx4 v130, s[22:23]
	s_addc_u32 s25, s36, s9
	s_mov_b32 m0, s21
	s_add_i32 s46, s21, 0x2000
	global_load_lds_dwordx4 v134, s[24:25]
	s_mov_b32 m0, s46
	s_add_u32 s8, s22, 0x4000
	global_load_lds_dwordx4 v132, s[24:25]
	s_addc_u32 s9, s23, 0
	s_add_i32 m0, s21, 0x14000
	v_mov_b32_e32 v129, 0
	global_load_lds_dwordx4 v128, s[8:9]
	s_add_i32 m0, s21, 0x16000
	v_mov_b32_e32 v135, v129
	global_load_lds_dwordx4 v130, s[8:9]
	s_add_u32 s8, s24, 0x80000
	s_addc_u32 s9, s25, 0
	s_add_i32 s47, s21, 0x4000
	s_mov_b32 m0, s47
	s_add_i32 s48, s21, 0x6000
	global_load_lds_dwordx4 v134, s[8:9]
	s_mov_b32 m0, s48
	v_mov_b32_e32 v133, v129
	global_load_lds_dwordx4 v132, s[8:9]
	s_mov_b32 s49, 0
	v_mov_b32_e32 v131, v129
	v_lshl_add_u64 v[2:3], s[24:25], 0, v[134:135]
	s_cmp_lg_u32 s5, 1
	v_lshl_add_u64 v[0:1], s[24:25], 0, v[132:133]
	s_cbranch_scc1 .LBB0_75
.LBB0_75:
	s_add_u32 s8, s6, 0x10700000
	s_addc_u32 s9, s7, 0
	s_lshl_b32 s10, s10, 5
	s_and_b32 s15, s10, 0x60
	s_lshl_b32 s14, s5, 13
	s_lshl_b32 s16, s15, 7
	s_add_u32 s10, s22, 0x8000
	s_addc_u32 s11, s23, 0
	s_add_i32 m0, s21, 0x18000
	v_lshl_add_u64 v[12:13], s[10:11], 0, v[128:129]
	s_waitcnt vmcnt(4)
	s_barrier
	global_load_lds_dwordx4 v[12:13], off
	v_lshl_add_u64 v[12:13], s[10:11], 0, v[130:131]
	s_add_i32 m0, s21, 0x1a000
	s_mov_b64 s[10:11], 0x80
	s_add_i32 s50, s21, 0x8000
	s_add_i32 s51, s21, 0xa000
	global_load_lds_dwordx4 v[12:13], off
	v_lshl_add_u64 v[2:3], v[2:3], 0, s[10:11]
	s_mov_b32 m0, s50
	s_add_u32 s12, s22, 0xc000
	global_load_lds_dwordx4 v[2:3], off
	v_lshl_add_u64 v[0:1], v[0:1], 0, s[10:11]
	s_mov_b32 m0, s51
	s_addc_u32 s13, s23, 0
	global_load_lds_dwordx4 v[0:1], off
	s_add_i32 m0, s21, 0x1c000
	v_lshl_add_u64 v[0:1], s[12:13], 0, v[128:129]
	global_load_lds_dwordx4 v[0:1], off
	v_lshl_add_u64 v[0:1], s[12:13], 0, v[130:131]
	s_add_i32 m0, s21, 0x1e000
	s_add_i32 s53, 0, 0x10000
	global_load_lds_dwordx4 v[0:1], off
	v_lshrrev_b32_e32 v1, 1, v4
	v_and_b32_e32 v1, 24, v1
	v_and_b32_e32 v0, 15, v4
	v_lshlrev_b32_e32 v2, 1, v1
	v_lshl_or_b32 v146, s5, 6, v0
	v_lshl_or_b32 v0, v0, 6, v2
	v_lshlrev_b32_e32 v2, 2, v4
	v_and_b32_e32 v2, 32, v2
	v_bitop3_b32 v3, v0, s14, v2 bitop3:0xde
	v_bitop3_b32 v147, v0, s16, v2 bitop3:0xde
	v_lshlrev_b32_e32 v0, 15, v8
	v_and_b32_e32 v0, 0xffff0000, v0
	v_or_b32_e32 v148, s15, v1
	v_lshl_add_u32 v0, v9, 12, v0
	v_and_b32_e32 v1, 1, v8
	v_lshl_or_b32 v0, v1, 6, v0
	v_lshl_add_u32 v136, v10, 1, v0
	v_lshlrev_b32_e32 v0, 15, v5
	v_and_b32_e32 v0, 0xffff0000, v0
	s_waitcnt vmcnt(6)
	v_lshl_add_u32 v0, v6, 12, v0
	v_and_b32_e32 v1, 1, v5
	v_lshl_or_b32 v0, v1, 6, v0
	s_add_i32 s54, 0, 0x14000
	s_sext_i32_i16 s56, s4
	s_ashr_i32 s52, s28, 31
	v_mov_b32_e32 v137, v129
	v_lshl_add_u32 v138, v7, 1, v0
	v_mov_b32_e32 v139, v129
	v_mov_b64_e32 v[140:141], 0xac0
	v_mov_b64_e32 v[142:143], 0xabf
	v_add_u32_e32 v149, s53, v147
	v_add_u32_e32 v150, 0, v3
	v_add_u32_e32 v151, s54, v147
	s_movk_i32 s55, 0x2b00
	s_barrier
	s_waitcnt vmcnt(0)

;     __host__ __device__ bool next(int i, Unit& u) const { const int j = i / 3; if (!StaticOrder::next(j, u)) return false; u.br = i - 3 * j; return true; }
; #define PG8_STAGE(bufoff, gbase, voff) do { _Pragma("unroll") for (int _i = 0; _i < 2; ++_i) \
;         __builtin_amdgcn_global_load_lds((const unsigned*)((const char*)(gbase) + (voff)[_i]), (PG8_LAS unsigned*)(lds + (bufoff) + ldsw + _i * 8192), 16, 0, 0); } while (0)
; #define PG8_LDA(dst, b, h) do { _Pragma("unroll") for (int m = 0; m < 4; ++m) _Pragma("unroll") for (int k = 0; k < 2; ++k) dst[m][k] = *(const PG8_LAS bf16x8*)(lds + PG8_SA(b, h) + aoff + m * 2048 + k * 1024); } while (0)
; #define PG8_LDB(dst, b, h) do { _Pragma("unroll") for (int n = 0; n < 2; ++n) _Pragma("unroll") for (int k = 0; k < 2; ++k) dst[n][k] = *(const PG8_LAS bf16x8*)(lds + PG8_SB(b, h) + boff + n * 2048 + k * 1024); } while (0)
; #define PG8_WAIT_L(n) asm volatile("s_waitcnt lgkmcnt(" #n ")" ::: "memory")
; #define PG8_BAR __builtin_amdgcn_s_barrier()
; #define PG8_SCHED __builtin_amdgcn_sched_barrier(0)
; template <class Epi, class Sched>
; __device__ __forceinline__ void gemm_phase(PG8_LAS unsigned char* lds, const Gemm g, const Sched& S, const Epi& E) {
;     ...
;         const bool has_next = S.next(ui + 1, nxt);
;         const char* nA = has_next ? (const char*)g.A + (size_t)nxt.pm * tstep + (size_t)nxt.br * g.strideA : cA; const char* nB = has_next ? (const char*)g.Bt + (size_t)nxt.pn * tstepB + (size_t)nxt.br * g.strideB : cB;
;         for (int t = 0; t < nt; t += 2) {
;             const bool last = (t == nt - 2);
;             const char* a1 = cA + (size_t)(t + 1) * kstep;
;             const char* a2 = last ? nA : cA + (size_t)(t + 2) * kstep; const char* b2 = last ? nB : cB + (size_t)(t + 2) * kstepB;
;             const char* a3 = a2 + kstep; const char* b3 = b2 + kstepB;
;             if (last && has_next) S.a_ready(nxt);
;             PG8_LDB(B0, 0, 0); PG8_SCHED; PG8_LDA(At, 0, 0); PG8_STAGE(PG8_SA(1, 1), a1 + hstep, voffA);
;             PG8_WAIT_L(8); PG8_BAR; PG8_WAIT_L(0); PG8_MMA(0, 0, At, B0); PG8_BAR; PG8_SCHED;
;     ...
;         for (int a = 0; a < 2; ++a)
; #pragma unroll
;             for (int b = 0; b < 2; ++b)
; #pragma unroll
;                 for (int m = 0; m < 4; ++m)
; #pragma unroll
;                     for (int n = 0; n < 2; ++n) acc[a][b][m][n] = (f32x4){0.f, 0.f, 0.f, 0.f};
.LBB0_78:
	s_ashr_i32 s13, s12, 31
	v_cmp_lt_i64_e32 vcc, s[16:17], v[140:141]
	s_lshl_b64 s[16:17], s[12:13], 20
	s_add_u32 s16, s31, s16
	s_addc_u32 s17, s36, s17
	s_and_b64 s[18:19], vcc, exec
	s_cselect_b32 s13, s17, s25
	s_cselect_b32 s57, s16, s24
	s_ashr_i32 s15, s14, 31
	s_lshl_b64 s[18:19], s[14:15], 20
	s_add_u32 s18, s6, s18
	s_addc_u32 s19, s7, s19
	s_and_b64 s[26:27], vcc, exec
	s_cselect_b32 s15, s19, s23
	s_cselect_b32 s58, s18, s22
	s_add_u32 s59, s22, 0x10000
	s_addc_u32 s60, s23, 0
	s_add_u32 s22, s24, 0x80080
	v_mov_b32_e32 v0, 0
	s_addc_u32 s23, s25, 0
	s_mov_b32 s61, -2
	v_mov_b32_e32 v1, v0
	v_mov_b32_e32 v2, v0
	v_mov_b32_e32 v3, v0
	v_mov_b32_e32 v4, v0
	v_mov_b32_e32 v5, v0
	v_mov_b32_e32 v6, v0
	v_mov_b32_e32 v7, v0
	v_mov_b32_e32 v16, v0
	v_mov_b32_e32 v17, v0
	v_mov_b32_e32 v18, v0
	v_mov_b32_e32 v19, v0
	v_mov_b32_e32 v20, v0
	v_mov_b32_e32 v21, v0
	v_mov_b32_e32 v22, v0
	v_mov_b32_e32 v23, v0
	v_mov_b32_e32 v32, v0
	v_mov_b32_e32 v33, v0
	v_mov_b32_e32 v34, v0
	v_mov_b32_e32 v35, v0
	v_mov_b32_e32 v36, v0
	v_mov_b32_e32 v37, v0
	v_mov_b32_e32 v38, v0
	v_mov_b32_e32 v39, v0
	v_mov_b32_e32 v48, v0
	v_mov_b32_e32 v49, v0
	v_mov_b32_e32 v50, v0
	v_mov_b32_e32 v51, v0
	v_mov_b32_e32 v52, v0
	v_mov_b32_e32 v53, v0
	v_mov_b32_e32 v54, v0
	v_mov_b32_e32 v55, v0
	v_mov_b32_e32 v8, v0
	v_mov_b32_e32 v9, v0
	v_mov_b32_e32 v10, v0
	v_mov_b32_e32 v11, v0
	v_mov_b32_e32 v12, v0
	v_mov_b32_e32 v13, v0
	v_mov_b32_e32 v14, v0
	v_mov_b32_e32 v15, v0
	v_mov_b32_e32 v24, v0
	v_mov_b32_e32 v25, v0
	v_mov_b32_e32 v26, v0
	v_mov_b32_e32 v27, v0
	v_mov_b32_e32 v28, v0
	v_mov_b32_e32 v29, v0
	v_mov_b32_e32 v30, v0
	v_mov_b32_e32 v31, v0
	v_mov_b32_e32 v40, v0
	v_mov_b32_e32 v41, v0
	v_mov_b32_e32 v42, v0
	v_mov_b32_e32 v43, v0
	v_mov_b32_e32 v44, v0
	v_mov_b32_e32 v45, v0
	v_mov_b32_e32 v46, v0
	v_mov_b32_e32 v47, v0
	v_mov_b32_e32 v56, v0
	v_mov_b32_e32 v57, v0
	v_mov_b32_e32 v58, v0
	v_mov_b32_e32 v59, v0
	v_mov_b32_e32 v60, v0
	v_mov_b32_e32 v61, v0
	v_mov_b32_e32 v62, v0
	v_mov_b32_e32 v63, v0
	v_mov_b32_e32 v64, v0
	v_mov_b32_e32 v65, v0
	v_mov_b32_e32 v66, v0
	v_mov_b32_e32 v67, v0
	v_mov_b32_e32 v68, v0
	v_mov_b32_e32 v69, v0
	v_mov_b32_e32 v70, v0
	v_mov_b32_e32 v71, v0
	v_mov_b32_e32 v80, v0
	v_mov_b32_e32 v81, v0
	v_mov_b32_e32 v82, v0
	v_mov_b32_e32 v83, v0
	v_mov_b32_e32 v84, v0
	v_mov_b32_e32 v85, v0
	v_mov_b32_e32 v86, v0
	v_mov_b32_e32 v87, v0
	v_mov_b32_e32 v96, v0
	v_mov_b32_e32 v97, v0
	v_mov_b32_e32 v98, v0
	v_mov_b32_e32 v99, v0
	v_mov_b32_e32 v100, v0
	v_mov_b32_e32 v101, v0
	v_mov_b32_e32 v102, v0
	v_mov_b32_e32 v103, v0
	v_mov_b32_e32 v112, v0
	v_mov_b32_e32 v113, v0
	v_mov_b32_e32 v114, v0
	v_mov_b32_e32 v115, v0
	v_mov_b32_e32 v116, v0
	v_mov_b32_e32 v117, v0
	v_mov_b32_e32 v118, v0
	v_mov_b32_e32 v119, v0
	v_mov_b32_e32 v72, v0
	v_mov_b32_e32 v73, v0
	v_mov_b32_e32 v74, v0
	v_mov_b32_e32 v75, v0
	v_mov_b32_e32 v76, v0
	v_mov_b32_e32 v77, v0
	v_mov_b32_e32 v78, v0
	v_mov_b32_e32 v79, v0
	v_mov_b32_e32 v88, v0
	v_mov_b32_e32 v89, v0
	v_mov_b32_e32 v90, v0
	v_mov_b32_e32 v91, v0
	v_mov_b32_e32 v92, v0
	v_mov_b32_e32 v93, v0
	v_mov_b32_e32 v94, v0
	v_mov_b32_e32 v95, v0
	v_mov_b32_e32 v104, v0
	v_mov_b32_e32 v105, v0
	v_mov_b32_e32 v106, v0
	v_mov_b32_e32 v107, v0
	v_mov_b32_e32 v108, v0
	v_mov_b32_e32 v109, v0
	v_mov_b32_e32 v110, v0
	v_mov_b32_e32 v111, v0
	v_mov_b32_e32 v120, v0
	v_mov_b32_e32 v121, v0
	v_mov_b32_e32 v122, v0
	v_mov_b32_e32 v123, v0
	v_mov_b32_e32 v124, v0
	v_mov_b32_e32 v125, v0
	v_mov_b32_e32 v126, v0
	v_mov_b32_e32 v127, v0
	s_cmp_eq_u32 s78, 1
	s_cbranch_scc0 .Lhalf_skip_y_0
	s_barrier
.Lhalf_skip_y_0:
.LBB0_79:
	ds_read_b128 v[152:155], v149
	ds_read_b128 v[156:159], v149 offset:1024
	ds_read_b128 v[160:163], v149 offset:2048
	ds_read_b128 v[164:167], v149 offset:3072
	s_add_u32 s24, s22, 0xfff80080
	s_addc_u32 s25, s23, -1
	s_cmp_eq_u32 s61, 28
	s_cselect_b32 s27, s13, s25
	s_cselect_b32 s26, s57, s24
	s_cselect_b32 s25, s15, s60
	s_cselect_b32 s24, s58, s59
	v_lshl_add_u64 v[144:145], s[22:23], 0, v[136:137]
	s_add_i32 m0, s21, 0xc000
	ds_read_b128 v[168:171], v150
	ds_read_b128 v[172:175], v150 offset:1024
	ds_read_b128 v[176:179], v150 offset:2048
	ds_read_b128 v[180:183], v150 offset:3072
	ds_read_b128 v[184:187], v150 offset:4096
	ds_read_b128 v[188:191], v150 offset:5120
	ds_read_b128 v[192:195], v150 offset:6144
	ds_read_b128 v[196:199], v150 offset:7168
	global_load_lds_dwordx4 v[144:145], off
	v_lshl_add_u64 v[144:145], s[22:23], 0, v[138:139]
	s_add_i32 m0, s21, 0xe000
	s_nop 0
	global_load_lds_dwordx4 v[144:145], off
	s_waitcnt lgkmcnt(8)
	s_barrier
	s_waitcnt lgkmcnt(0)
	s_setprio 1
	s_waitcnt lgkmcnt(0)
	v_mfma_f32_16x16x32_bf16 v[124:127], v[152:155], v[168:171], v[124:127]
	v_mfma_f32_16x16x32_bf16 v[120:123], v[160:163], v[168:171], v[120:123]
	v_mfma_f32_16x16x32_bf16 v[108:111], v[152:155], v[176:179], v[108:111]
	v_mfma_f32_16x16x32_bf16 v[104:107], v[160:163], v[176:179], v[104:107]
	v_mfma_f32_16x16x32_bf16 v[92:95], v[152:155], v[184:187], v[92:95]
	v_mfma_f32_16x16x32_bf16 v[88:91], v[160:163], v[184:187], v[88:91]
	v_mfma_f32_16x16x32_bf16 v[76:79], v[152:155], v[192:195], v[76:79]
	v_mfma_f32_16x16x32_bf16 v[72:75], v[160:163], v[192:195], v[72:75]
	v_mfma_f32_16x16x32_bf16 v[124:127], v[156:159], v[172:175], v[124:127]
	v_mfma_f32_16x16x32_bf16 v[120:123], v[164:167], v[172:175], v[120:123]
	v_mfma_f32_16x16x32_bf16 v[108:111], v[156:159], v[180:183], v[108:111]
	v_mfma_f32_16x16x32_bf16 v[104:107], v[164:167], v[180:183], v[104:107]
	v_mfma_f32_16x16x32_bf16 v[92:95], v[156:159], v[188:191], v[92:95]
	v_mfma_f32_16x16x32_bf16 v[88:91], v[164:167], v[188:191], v[88:91]
	v_mfma_f32_16x16x32_bf16 v[76:79], v[156:159], v[196:199], v[76:79]
	v_mfma_f32_16x16x32_bf16 v[72:75], v[164:167], v[196:199], v[72:75]
	s_setprio 0
	s_barrier
; #define PG8_STAGE(bufoff, gbase, voff) do { _Pragma("unroll") for (int _i = 0; _i < 2; ++_i) \
;         __builtin_amdgcn_global_load_lds((const unsigned*)((const char*)(gbase) + (voff)[_i]), (PG8_LAS unsigned*)(lds + (bufoff) + ldsw + _i * 8192), 16, 0, 0); } while (0)
; #define PG8_LDA(dst, b, h) do { _Pragma("unroll") for (int m = 0; m < 4; ++m) _Pragma("unroll") for (int k = 0; k < 2; ++k) dst[m][k] = *(const PG8_LAS bf16x8*)(lds + PG8_SA(b, h) + aoff + m * 2048 + k * 1024); } while (0)
; #define PG8_LDB(dst, b, h) do { _Pragma("unroll") for (int n = 0; n < 2; ++n) _Pragma("unroll") for (int k = 0; k < 2; ++k) dst[n][k] = *(const PG8_LAS bf16x8*)(lds + PG8_SB(b, h) + boff + n * 2048 + k * 1024); } while (0)
; #define PG8_MMA(ai, bj, At, Bt) do { __builtin_amdgcn_s_setprio(1); _Pragma("unroll") for (int m = 0; m < 4; ++m) _Pragma("unroll") for (int n = 0; n < 2; ++n) _Pragma("unroll") for (int k = 0; k < 2; ++k) \
;         acc[ai][bj][m][n] = __builtin_amdgcn_mfma_f32_16x16x32_bf16(Bt[n][k], At[m][k], acc[ai][bj][m][n], 0, 0, 0); __builtin_amdgcn_s_setprio(0); } while (0)
; #define PG8_WAIT_V(n) asm volatile("s_waitcnt vmcnt(" #n ")" ::: "memory")
; #define PG8_WAIT_L(n) asm volatile("s_waitcnt lgkmcnt(" #n ")" ::: "memory")
; #define PG8_BAR __builtin_amdgcn_s_barrier()
; #define PG8_SCHED __builtin_amdgcn_sched_barrier(0)
; template <class Epi, class Sched>
; __device__ __forceinline__ void gemm_phase(PG8_LAS unsigned char* lds, const Gemm g, const Sched& S, const Epi& E) {
;     ...
;             PG8_LDB(B1, 0, 1); PG8_STAGE(PG8_SB(0, 0), b2, voffB);
;             PG8_BAR; PG8_WAIT_L(0); PG8_MMA(0, 1, At, B1); PG8_BAR;
;             PG8_LDA(At, 0, 1); PG8_STAGE(PG8_SA(0, 0), a2, voffA);
;             PG8_BAR; PG8_WAIT_L(0); PG8_MMA(1, 0, At, B0); PG8_BAR; PG8_SCHED;
;             PG8_STAGE(PG8_SB(0, 1), b2 + hstepB, voffB);
;             PG8_WAIT_V(6); PG8_BAR; PG8_MMA(1, 1, At, B1); PG8_BAR;
;             PG8_LDB(B0, 1, 0); PG8_SCHED; PG8_LDA(At, 1, 0); PG8_STAGE(PG8_SA(0, 1), a2 + hstep, voffA);
;             PG8_WAIT_L(8); PG8_BAR; PG8_WAIT_L(0); PG8_MMA(0, 0, At, B0); PG8_BAR; PG8_SCHED;
	s_add_i32 s62, s53, s38
	v_lshl_add_u64 v[144:145], s[24:25], 0, v[128:129]
	s_mov_b32 m0, s62
	ds_read_b128 v[200:203], v151
	ds_read_b128 v[204:207], v151 offset:1024
	ds_read_b128 v[208:211], v151 offset:2048
	ds_read_b128 v[212:215], v151 offset:3072
	global_load_lds_dwordx4 v[144:145], off
	v_lshl_add_u64 v[144:145], s[24:25], 0, v[130:131]
	s_add_i32 m0, s62, 0x2000
	s_nop 0
	global_load_lds_dwordx4 v[144:145], off
	s_barrier
	s_waitcnt lgkmcnt(0)
	s_setprio 1
	s_waitcnt lgkmcnt(0)
	v_mfma_f32_16x16x32_bf16 v[116:119], v[200:203], v[168:171], v[116:119]
	v_mfma_f32_16x16x32_bf16 v[112:115], v[208:211], v[168:171], v[112:115]
	v_mfma_f32_16x16x32_bf16 v[100:103], v[200:203], v[176:179], v[100:103]
	v_mfma_f32_16x16x32_bf16 v[96:99], v[208:211], v[176:179], v[96:99]
	v_mfma_f32_16x16x32_bf16 v[84:87], v[200:203], v[184:187], v[84:87]
	v_mfma_f32_16x16x32_bf16 v[80:83], v[208:211], v[184:187], v[80:83]
	v_mfma_f32_16x16x32_bf16 v[68:71], v[200:203], v[192:195], v[68:71]
	v_mfma_f32_16x16x32_bf16 v[64:67], v[208:211], v[192:195], v[64:67]
	v_mfma_f32_16x16x32_bf16 v[116:119], v[204:207], v[172:175], v[116:119]
	v_mfma_f32_16x16x32_bf16 v[112:115], v[212:215], v[172:175], v[112:115]
	v_mfma_f32_16x16x32_bf16 v[100:103], v[204:207], v[180:183], v[100:103]
	v_mfma_f32_16x16x32_bf16 v[96:99], v[212:215], v[180:183], v[96:99]
	v_mfma_f32_16x16x32_bf16 v[84:87], v[204:207], v[188:191], v[84:87]
	v_mfma_f32_16x16x32_bf16 v[80:83], v[212:215], v[188:191], v[80:83]
	v_mfma_f32_16x16x32_bf16 v[68:71], v[204:207], v[196:199], v[68:71]
	v_mfma_f32_16x16x32_bf16 v[64:67], v[212:215], v[196:199], v[64:67]
	s_setprio 0
	s_mov_b32 m0, s21
	v_lshl_add_u64 v[144:145], s[26:27], 0, v[134:135]
	s_barrier
	ds_read_b128 v[168:171], v150 offset:16384
	ds_read_b128 v[172:175], v150 offset:17408
	ds_read_b128 v[176:179], v150 offset:18432
	ds_read_b128 v[180:183], v150 offset:19456
	ds_read_b128 v[184:187], v150 offset:20480
	ds_read_b128 v[188:191], v150 offset:21504
	ds_read_b128 v[192:195], v150 offset:22528
	ds_read_b128 v[196:199], v150 offset:23552
	global_load_lds_dwordx4 v[144:145], off
	v_lshl_add_u64 v[216:217], s[26:27], 0, v[132:133]
	s_mov_b32 m0, s46
	s_nop 0
	global_load_lds_dwordx4 v[216:217], off
	s_barrier
	s_waitcnt lgkmcnt(0)
	s_setprio 1
	s_waitcnt lgkmcnt(0)
	v_mfma_f32_16x16x32_bf16 v[60:63], v[152:155], v[168:171], v[60:63]
	v_mfma_f32_16x16x32_bf16 v[56:59], v[160:163], v[168:171], v[56:59]
	v_mfma_f32_16x16x32_bf16 v[44:47], v[152:155], v[176:179], v[44:47]
	v_mfma_f32_16x16x32_bf16 v[40:43], v[160:163], v[176:179], v[40:43]
	v_mfma_f32_16x16x32_bf16 v[28:31], v[152:155], v[184:187], v[28:31]
	v_mfma_f32_16x16x32_bf16 v[24:27], v[160:163], v[184:187], v[24:27]
	v_mfma_f32_16x16x32_bf16 v[12:15], v[152:155], v[192:195], v[12:15]
	v_mfma_f32_16x16x32_bf16 v[8:11], v[160:163], v[192:195], v[8:11]
	v_mfma_f32_16x16x32_bf16 v[60:63], v[156:159], v[172:175], v[60:63]
	v_mfma_f32_16x16x32_bf16 v[56:59], v[164:167], v[172:175], v[56:59]
	v_mfma_f32_16x16x32_bf16 v[44:47], v[156:159], v[180:183], v[44:47]
	v_mfma_f32_16x16x32_bf16 v[40:43], v[164:167], v[180:183], v[40:43]
	v_mfma_f32_16x16x32_bf16 v[28:31], v[156:159], v[188:191], v[28:31]
	v_mfma_f32_16x16x32_bf16 v[24:27], v[164:167], v[188:191], v[24:27]
	v_mfma_f32_16x16x32_bf16 v[12:15], v[156:159], v[196:199], v[12:15]
	v_mfma_f32_16x16x32_bf16 v[8:11], v[164:167], v[196:199], v[8:11]
	s_setprio 0
	s_barrier
	s_add_u32 s62, s24, 0x4000
	s_addc_u32 s63, s25, 0
	s_add_i32 s64, s54, s38
	v_lshl_add_u64 v[152:153], s[62:63], 0, v[128:129]
	s_mov_b32 m0, s64
	s_nop 0
	global_load_lds_dwordx4 v[152:153], off
	v_lshl_add_u64 v[152:153], s[62:63], 0, v[130:131]
	s_add_i32 m0, s64, 0x2000
	s_nop 0
	global_load_lds_dwordx4 v[152:153], off
	s_waitcnt vmcnt(6)
	s_barrier
	s_setprio 1
	v_mfma_f32_16x16x32_bf16 v[52:55], v[200:203], v[168:171], v[52:55]
	v_mfma_f32_16x16x32_bf16 v[48:51], v[208:211], v[168:171], v[48:51]
	v_mfma_f32_16x16x32_bf16 v[36:39], v[200:203], v[176:179], v[36:39]
	v_mfma_f32_16x16x32_bf16 v[32:35], v[208:211], v[176:179], v[32:35]
	v_mfma_f32_16x16x32_bf16 v[20:23], v[200:203], v[184:187], v[20:23]
	v_mfma_f32_16x16x32_bf16 v[16:19], v[208:211], v[184:187], v[16:19]
	v_mfma_f32_16x16x32_bf16 v[4:7], v[200:203], v[192:195], v[4:7]
	v_mfma_f32_16x16x32_bf16 v[0:3], v[208:211], v[192:195], v[0:3]
	v_mfma_f32_16x16x32_bf16 v[52:55], v[204:207], v[172:175], v[52:55]
	v_mfma_f32_16x16x32_bf16 v[48:51], v[212:215], v[172:175], v[48:51]
	v_mfma_f32_16x16x32_bf16 v[36:39], v[204:207], v[180:183], v[36:39]
	v_mfma_f32_16x16x32_bf16 v[32:35], v[212:215], v[180:183], v[32:35]
	v_mfma_f32_16x16x32_bf16 v[20:23], v[204:207], v[188:191], v[20:23]
	v_mfma_f32_16x16x32_bf16 v[16:19], v[212:215], v[188:191], v[16:19]
	v_mfma_f32_16x16x32_bf16 v[4:7], v[204:207], v[196:199], v[4:7]
	v_mfma_f32_16x16x32_bf16 v[0:3], v[212:215], v[196:199], v[0:3]
	s_setprio 0
	s_add_i32 s62, 0, 0x18000
	v_add_u32_e32 v164, s62, v147
	s_barrier
	ds_read_b128 v[152:155], v164
	ds_read_b128 v[156:159], v164 offset:1024
	ds_read_b128 v[160:163], v164 offset:2048
	ds_read_b128 v[164:167], v164 offset:3072
	s_add_u32 s26, s26, 0x80000
	s_addc_u32 s27, s27, 0
	s_mov_b32 m0, s47
	v_lshl_add_u64 v[200:201], s[26:27], 0, v[134:135]
	ds_read_b128 v[168:171], v150 offset:32768
	ds_read_b128 v[172:175], v150 offset:33792
	ds_read_b128 v[176:179], v150 offset:34816
	ds_read_b128 v[180:183], v150 offset:35840
	ds_read_b128 v[184:187], v150 offset:36864
	ds_read_b128 v[188:191], v150 offset:37888
	ds_read_b128 v[192:195], v150 offset:38912
	ds_read_b128 v[196:199], v150 offset:39936
	global_load_lds_dwordx4 v[200:201], off
	v_lshl_add_u64 v[200:201], s[26:27], 0, v[132:133]
	s_mov_b32 m0, s48
	s_nop 0
	global_load_lds_dwordx4 v[200:201], off
	s_waitcnt lgkmcnt(8)
	s_barrier
; #define PG8_STAGE(bufoff, gbase, voff) do { _Pragma("unroll") for (int _i = 0; _i < 2; ++_i) \
;         __builtin_amdgcn_global_load_lds((const unsigned*)((const char*)(gbase) + (voff)[_i]), (PG8_LAS unsigned*)(lds + (bufoff) + ldsw + _i * 8192), 16, 0, 0); } while (0)
; #define PG8_LDA(dst, b, h) do { _Pragma("unroll") for (int m = 0; m < 4; ++m) _Pragma("unroll") for (int k = 0; k < 2; ++k) dst[m][k] = *(const PG8_LAS bf16x8*)(lds + PG8_SA(b, h) + aoff + m * 2048 + k * 1024); } while (0)
; #define PG8_LDB(dst, b, h) do { _Pragma("unroll") for (int n = 0; n < 2; ++n) _Pragma("unroll") for (int k = 0; k < 2; ++k) dst[n][k] = *(const PG8_LAS bf16x8*)(lds + PG8_SB(b, h) + boff + n * 2048 + k * 1024); } while (0)
; #define PG8_MMA(ai, bj, At, Bt) do { __builtin_amdgcn_s_setprio(1); _Pragma("unroll") for (int m = 0; m < 4; ++m) _Pragma("unroll") for (int n = 0; n < 2; ++n) _Pragma("unroll") for (int k = 0; k < 2; ++k) \
;         acc[ai][bj][m][n] = __builtin_amdgcn_mfma_f32_16x16x32_bf16(Bt[n][k], At[m][k], acc[ai][bj][m][n], 0, 0, 0); __builtin_amdgcn_s_setprio(0); } while (0)
; #define PG8_WAIT_V(n) asm volatile("s_waitcnt vmcnt(" #n ")" ::: "memory")
; #define PG8_WAIT_L(n) asm volatile("s_waitcnt lgkmcnt(" #n ")" ::: "memory")
; #define PG8_BAR __builtin_amdgcn_s_barrier()
; #define PG8_SCHED __builtin_amdgcn_sched_barrier(0)
; template <class Epi, class Sched>
; __device__ __forceinline__ void gemm_phase(PG8_LAS unsigned char* lds, const Gemm g, const Sched& S, const Epi& E) {
;     ...
;             PG8_WAIT_L(8); PG8_BAR; PG8_WAIT_L(0); PG8_MMA(0, 0, At, B0); PG8_BAR; PG8_SCHED;
;             PG8_LDB(B1, 1, 1); PG8_STAGE(PG8_SB(1, 0), b3, voffB);
;             PG8_BAR; PG8_WAIT_L(0); PG8_MMA(0, 1, At, B1); PG8_BAR;
;             PG8_LDA(At, 1, 1); PG8_STAGE(PG8_SA(1, 0), a3, voffA);
;             PG8_BAR; PG8_WAIT_L(0); PG8_MMA(1, 0, At, B0); PG8_BAR; PG8_SCHED;
;             PG8_STAGE(PG8_SB(1, 1), b3 + hstepB, voffB);
;             PG8_WAIT_V(6); PG8_BAR; PG8_MMA(1, 1, At, B1); PG8_BAR;
;         }
;         if constexpr (!Epi::AFTER_DRAIN) { E(acc, cur, wr, wc, fr, fq); if constexpr (Epi::IDEMP && EPI_REP > 1) { asm volatile("" ::: "memory"); E(acc, cur, wr, wc, fr, fq); } S.done(cur); }
	s_waitcnt lgkmcnt(0)
	s_setprio 1
	s_waitcnt lgkmcnt(0)
	v_mfma_f32_16x16x32_bf16 v[124:127], v[152:155], v[168:171], v[124:127]
	v_mfma_f32_16x16x32_bf16 v[120:123], v[160:163], v[168:171], v[120:123]
	v_mfma_f32_16x16x32_bf16 v[108:111], v[152:155], v[176:179], v[108:111]
	v_mfma_f32_16x16x32_bf16 v[104:107], v[160:163], v[176:179], v[104:107]
	v_mfma_f32_16x16x32_bf16 v[92:95], v[152:155], v[184:187], v[92:95]
	v_mfma_f32_16x16x32_bf16 v[88:91], v[160:163], v[184:187], v[88:91]
	v_mfma_f32_16x16x32_bf16 v[76:79], v[152:155], v[192:195], v[76:79]
	v_mfma_f32_16x16x32_bf16 v[72:75], v[160:163], v[192:195], v[72:75]
	v_mfma_f32_16x16x32_bf16 v[124:127], v[156:159], v[172:175], v[124:127]
	v_mfma_f32_16x16x32_bf16 v[120:123], v[164:167], v[172:175], v[120:123]
	v_mfma_f32_16x16x32_bf16 v[108:111], v[156:159], v[180:183], v[108:111]
	v_mfma_f32_16x16x32_bf16 v[104:107], v[164:167], v[180:183], v[104:107]
	v_mfma_f32_16x16x32_bf16 v[92:95], v[156:159], v[188:191], v[92:95]
	v_mfma_f32_16x16x32_bf16 v[88:91], v[164:167], v[188:191], v[88:91]
	v_mfma_f32_16x16x32_bf16 v[76:79], v[156:159], v[196:199], v[76:79]
	v_mfma_f32_16x16x32_bf16 v[72:75], v[164:167], v[196:199], v[72:75]
	s_setprio 0
	s_barrier
	s_add_i32 s63, 0, 0x1c000
	s_add_u32 s26, s24, 0x8000
	s_addc_u32 s27, s25, 0
	s_add_i32 s62, s62, s38
	v_add_u32_e32 v212, s63, v147
	v_lshl_add_u64 v[218:219], s[26:27], 0, v[128:129]
	s_mov_b32 m0, s62
	ds_read_b128 v[200:203], v212
	ds_read_b128 v[204:207], v212 offset:1024
	ds_read_b128 v[208:211], v212 offset:2048
	ds_read_b128 v[212:215], v212 offset:3072
	global_load_lds_dwordx4 v[218:219], off
	v_lshl_add_u64 v[218:219], s[26:27], 0, v[130:131]
	s_add_i32 m0, s62, 0x2000
	s_nop 0
	global_load_lds_dwordx4 v[218:219], off
	s_barrier
	s_waitcnt lgkmcnt(0)
	s_setprio 1
	s_waitcnt lgkmcnt(0)
	v_mfma_f32_16x16x32_bf16 v[116:119], v[200:203], v[168:171], v[116:119]
	v_mfma_f32_16x16x32_bf16 v[112:115], v[208:211], v[168:171], v[112:115]
	v_mfma_f32_16x16x32_bf16 v[100:103], v[200:203], v[176:179], v[100:103]
	v_mfma_f32_16x16x32_bf16 v[96:99], v[208:211], v[176:179], v[96:99]
	v_mfma_f32_16x16x32_bf16 v[84:87], v[200:203], v[184:187], v[84:87]
	v_mfma_f32_16x16x32_bf16 v[80:83], v[208:211], v[184:187], v[80:83]
	v_mfma_f32_16x16x32_bf16 v[68:71], v[200:203], v[192:195], v[68:71]
	v_mfma_f32_16x16x32_bf16 v[64:67], v[208:211], v[192:195], v[64:67]
	v_mfma_f32_16x16x32_bf16 v[116:119], v[204:207], v[172:175], v[116:119]
	v_mfma_f32_16x16x32_bf16 v[112:115], v[212:215], v[172:175], v[112:115]
	v_mfma_f32_16x16x32_bf16 v[100:103], v[204:207], v[180:183], v[100:103]
	v_mfma_f32_16x16x32_bf16 v[96:99], v[212:215], v[180:183], v[96:99]
	v_mfma_f32_16x16x32_bf16 v[84:87], v[204:207], v[188:191], v[84:87]
	v_mfma_f32_16x16x32_bf16 v[80:83], v[212:215], v[188:191], v[80:83]
	v_mfma_f32_16x16x32_bf16 v[68:71], v[204:207], v[196:199], v[68:71]
	v_mfma_f32_16x16x32_bf16 v[64:67], v[212:215], v[196:199], v[64:67]
	s_setprio 0
	s_mov_b32 m0, s50
	v_lshl_add_u64 v[144:145], v[144:145], 0, s[10:11]
	s_barrier
	ds_read_b128 v[168:171], v150 offset:49152
	ds_read_b128 v[172:175], v150 offset:50176
	ds_read_b128 v[176:179], v150 offset:51200
	ds_read_b128 v[180:183], v150 offset:52224
	ds_read_b128 v[184:187], v150 offset:53248
	ds_read_b128 v[188:191], v150 offset:54272
	ds_read_b128 v[192:195], v150 offset:55296
	ds_read_b128 v[196:199], v150 offset:56320
	global_load_lds_dwordx4 v[144:145], off
	v_lshl_add_u64 v[144:145], v[216:217], 0, s[10:11]
	s_mov_b32 m0, s51
	s_nop 0
	global_load_lds_dwordx4 v[144:145], off
	s_barrier
	s_waitcnt lgkmcnt(0)
	s_setprio 1
	s_waitcnt lgkmcnt(0)
	v_mfma_f32_16x16x32_bf16 v[60:63], v[152:155], v[168:171], v[60:63]
	v_mfma_f32_16x16x32_bf16 v[56:59], v[160:163], v[168:171], v[56:59]
	v_mfma_f32_16x16x32_bf16 v[44:47], v[152:155], v[176:179], v[44:47]
	v_mfma_f32_16x16x32_bf16 v[40:43], v[160:163], v[176:179], v[40:43]
	v_mfma_f32_16x16x32_bf16 v[28:31], v[152:155], v[184:187], v[28:31]
	v_mfma_f32_16x16x32_bf16 v[24:27], v[160:163], v[184:187], v[24:27]
	v_mfma_f32_16x16x32_bf16 v[12:15], v[152:155], v[192:195], v[12:15]
	v_mfma_f32_16x16x32_bf16 v[8:11], v[160:163], v[192:195], v[8:11]
	v_mfma_f32_16x16x32_bf16 v[60:63], v[156:159], v[172:175], v[60:63]
	v_mfma_f32_16x16x32_bf16 v[56:59], v[164:167], v[172:175], v[56:59]
	v_mfma_f32_16x16x32_bf16 v[44:47], v[156:159], v[180:183], v[44:47]
	v_mfma_f32_16x16x32_bf16 v[40:43], v[164:167], v[180:183], v[40:43]
	v_mfma_f32_16x16x32_bf16 v[28:31], v[156:159], v[188:191], v[28:31]
	v_mfma_f32_16x16x32_bf16 v[24:27], v[164:167], v[188:191], v[24:27]
	v_mfma_f32_16x16x32_bf16 v[12:15], v[156:159], v[196:199], v[12:15]
	v_mfma_f32_16x16x32_bf16 v[8:11], v[164:167], v[196:199], v[8:11]
	s_setprio 0
	s_barrier
	s_add_u32 s24, s24, 0xc000
	s_addc_u32 s25, s25, 0
	s_add_i32 s26, s63, s38
	v_lshl_add_u64 v[144:145], s[24:25], 0, v[128:129]
	s_mov_b32 m0, s26
	s_nop 0
	global_load_lds_dwordx4 v[144:145], off
	v_lshl_add_u64 v[144:145], s[24:25], 0, v[130:131]
	s_add_i32 m0, s26, 0x2000
	s_nop 0
	global_load_lds_dwordx4 v[144:145], off
	s_waitcnt vmcnt(6)
	s_barrier
	s_setprio 1
	v_mfma_f32_16x16x32_bf16 v[52:55], v[200:203], v[168:171], v[52:55]
	v_mfma_f32_16x16x32_bf16 v[48:51], v[208:211], v[168:171], v[48:51]
	v_mfma_f32_16x16x32_bf16 v[36:39], v[200:203], v[176:179], v[36:39]
	v_mfma_f32_16x16x32_bf16 v[32:35], v[208:211], v[176:179], v[32:35]
	v_mfma_f32_16x16x32_bf16 v[20:23], v[200:203], v[184:187], v[20:23]
	v_mfma_f32_16x16x32_bf16 v[16:19], v[208:211], v[184:187], v[16:19]
	v_mfma_f32_16x16x32_bf16 v[4:7], v[200:203], v[192:195], v[4:7]
	v_mfma_f32_16x16x32_bf16 v[0:3], v[208:211], v[192:195], v[0:3]
	v_mfma_f32_16x16x32_bf16 v[52:55], v[204:207], v[172:175], v[52:55]
	v_mfma_f32_16x16x32_bf16 v[48:51], v[212:215], v[172:175], v[48:51]
	v_mfma_f32_16x16x32_bf16 v[36:39], v[204:207], v[180:183], v[36:39]
	v_mfma_f32_16x16x32_bf16 v[32:35], v[212:215], v[180:183], v[32:35]
	v_mfma_f32_16x16x32_bf16 v[20:23], v[204:207], v[188:191], v[20:23]
	v_mfma_f32_16x16x32_bf16 v[16:19], v[212:215], v[188:191], v[16:19]
	v_mfma_f32_16x16x32_bf16 v[4:7], v[204:207], v[196:199], v[4:7]
	v_mfma_f32_16x16x32_bf16 v[0:3], v[212:215], v[196:199], v[0:3]
	s_setprio 0
	s_add_i32 s61, s61, 2
	s_add_u32 s59, s59, 0x10000
	s_addc_u32 s60, s60, 0
	s_add_u32 s22, s22, 0x100
	s_addc_u32 s23, s23, 0
	s_cmp_gt_u32 s61, 29
	s_barrier
	s_cbranch_scc0 .LBB0_79
	s_cmp_eq_u32 s78, 0
	s_cbranch_scc0 .Lhalf_skip_x_0
	s_barrier
; __device__ __forceinline__ unsigned cvt_pk_bf16(float lo, float hi) { unsigned r; asm volatile("v_cvt_pk_bf16_f32 %0, %1, %2" : "=v"(r) : "v"(lo), "v"(hi)); return r; }
; __device__ __forceinline__ float fast_sigmoid(float x) { return __builtin_amdgcn_rcpf(1.0f + __expf(-x)); }
;     __device__ __forceinline__ void operator()(const f32x4 (&acc)[2][2][4][2], const Unit& u, int wr, int wc, int fr, int fq) const {
;         const int row0 = u.pm * BM + wr * 64 + fr; const int col0 = u.pn * HALF + wc * 32 + 8 * fq;
; #pragma unroll
;         for (int ai = 0; ai < 2; ++ai)
; #pragma unroll
;             for (int m = 0; m < 4; ++m) { bf16_t* rowp = O + (size_t)(row0 + ai * HALF + m * 16) * ldc + col0;
;                 f32x4 a0 = acc[ai][0][m][0], a1 = acc[ai][0][m][1], b0 = acc[ai][1][m][0], b1 = acc[ai][1][m][1]; f32x4 v0, v1;
; #pragma unroll
;                 for (int j = 0; j < 4; ++j) { v0[j] = a0[j] * fast_sigmoid(a0[j]) * b0[j]; v1[j] = a1[j] * fast_sigmoid(a1[j]) * b1[j]; }
;                 u32x4 w; w.x = cvt_pk_bf16(v0[0], v0[1]); w.y = cvt_pk_bf16(v0[2], v0[3]); w.z = cvt_pk_bf16(v1[0], v1[1]); w.w = cvt_pk_bf16(v1[2], v1[3]);
;                 __builtin_nontemporal_store(w, (u32x4*)rowp); }
.Lhalf_skip_x_0:
	v_mul_f32_e32 v144, 0xbfb8aa3b, v124
	v_exp_f32_e32 v153, v144
	v_mul_f32_e32 v144, 0xbfb8aa3b, v120
	v_exp_f32_e32 v156, v144
	v_lshl_or_b32 v154, s56, 7, v148
	v_add_f32_e32 v153, 1.0, v153
	v_rcp_f32_e32 v153, v153
	v_add_f32_e32 v156, 1.0, v156
	v_rcp_f32_e32 v158, v156
	v_lshl_add_u32 v152, s20, 8, v146
	v_mul_f32_e32 v124, v124, v153
	v_mul_f32_e32 v116, v124, v116
	v_mul_f32_e32 v124, 0xbfb8aa3b, v125
	v_exp_f32_e32 v124, v124
	v_mul_f32_e32 v153, 0xbfb8aa3b, v121
	v_exp_f32_e32 v153, v153
	v_mul_f32_e32 v120, v120, v158
	v_mul_f32_e32 v120, v120, v112
	v_add_f32_e32 v112, 1.0, v124
	v_rcp_f32_e32 v112, v112
	v_add_f32_e32 v124, 1.0, v153
	v_mul_f32_e32 v153, 0xbfb8aa3b, v126
	v_rcp_f32_e32 v124, v124
	v_exp_f32_e32 v153, v153
	v_mul_f32_e32 v112, v125, v112
	v_mul_f32_e32 v117, v112, v117
	v_mul_f32_e32 v112, v121, v124
	v_add_f32_e32 v121, 1.0, v153
	v_rcp_f32_e32 v121, v121
	v_mul_f32_e32 v124, 0xbfb8aa3b, v122
	v_exp_f32_e32 v124, v124
	v_mul_f32_e32 v125, v112, v113
	v_mul_f32_e32 v112, v126, v121
	v_mul_f32_e32 v113, 0xbfb8aa3b, v127
	v_mul_f32_e32 v121, v112, v118
	v_exp_f32_e32 v113, v113
	v_mul_f32_e32 v118, 0xbfb8aa3b, v123
	v_exp_f32_e32 v118, v118
	v_add_f32_e32 v112, 1.0, v124
	v_rcp_f32_e32 v112, v112
	v_add_f32_e32 v113, 1.0, v113
	v_rcp_f32_e32 v113, v113
	v_add_f32_e32 v118, 1.0, v118
	v_rcp_f32_e32 v118, v118
	v_mul_f32_e32 v112, v122, v112
	v_mul_f32_e32 v122, v112, v114
	v_mul_f32_e32 v112, v127, v113
	v_ashrrev_i32_e32 v155, 31, v154
	v_mov_b64_e32 v[144:145], s[8:9]
	v_mul_f32_e32 v124, v112, v119
	v_mul_f32_e32 v112, v123, v118
	v_mad_i64_i32 v[156:157], s[22:23], v152, s55, v[144:145]
	v_mul_f32_e32 v123, v112, v115
	v_lshlrev_b64 v[112:113], 1, v[154:155]
	v_lshl_add_u64 v[118:119], v[156:157], 0, v[112:113]
	v_cvt_pk_bf16_f32 v114, v116, v117
	v_cvt_pk_bf16_f32 v115, v121, v124
	v_cvt_pk_bf16_f32 v116, v120, v125
	v_cvt_pk_bf16_f32 v117, v122, v123
	global_store_dwordx4 v[118:119], v[114:117], off nt
	s_and_b64 vcc, exec, s[4:5]
	s_mov_b32 s56, s14
	v_mul_f32_e32 v114, 0xbfb8aa3b, v108
	v_exp_f32_e32 v114, v114
	v_mul_f32_e32 v115, 0xbfb8aa3b, v104
	v_exp_f32_e32 v115, v115
	v_or_b32_e32 v116, 16, v152
	v_add_f32_e32 v114, 1.0, v114
	v_rcp_f32_e32 v117, v114
	v_add_f32_e32 v114, 1.0, v115
	v_rcp_f32_e32 v118, v114
	v_mad_i64_i32 v[114:115], s[22:23], v116, s55, v[144:145]
	v_mul_f32_e32 v108, v108, v117
	v_mul_f32_e32 v108, v108, v100
	v_mul_f32_e32 v100, v104, v118
	v_mul_f32_e32 v104, 0xbfb8aa3b, v109
	v_exp_f32_e32 v104, v104
	v_mul_f32_e32 v116, 0xbfb8aa3b, v105
	v_mul_f32_e32 v117, v100, v96
	v_exp_f32_e32 v116, v116
	v_add_f32_e32 v96, 1.0, v104
	v_rcp_f32_e32 v96, v96
	v_mul_f32_e32 v104, 0xbfb8aa3b, v110
	v_exp_f32_e32 v104, v104
	v_add_f32_e32 v100, 1.0, v116
	v_mul_f32_e32 v96, v109, v96
	v_rcp_f32_e32 v100, v100
	v_mul_f32_e32 v96, v96, v101
	v_add_f32_e32 v101, 1.0, v104
	v_rcp_f32_e32 v101, v101
	v_mul_f32_e32 v100, v105, v100
	v_mul_f32_e32 v104, 0xbfb8aa3b, v106
	v_mul_f32_e32 v105, v100, v97
	v_mul_f32_e32 v97, v110, v101
	v_exp_f32_e32 v104, v104
	v_mul_f32_e32 v97, v97, v102
	v_mul_f32_e32 v101, 0xbfb8aa3b, v111
	v_mul_f32_e32 v102, 0xbfb8aa3b, v107
	v_exp_f32_e32 v101, v101
	v_exp_f32_e32 v102, v102
	v_add_f32_e32 v100, 1.0, v104
	v_rcp_f32_e32 v100, v100
	v_add_f32_e32 v101, 1.0, v101
	v_add_f32_e32 v102, 1.0, v102
	v_rcp_f32_e32 v101, v101
	v_rcp_f32_e32 v102, v102
	v_mul_f32_e32 v100, v106, v100
	v_mul_f32_e32 v104, v100, v98
	v_mul_f32_e32 v98, v111, v101
	v_mul_f32_e32 v100, v107, v102
	v_mul_f32_e32 v98, v98, v103
	v_mul_f32_e32 v99, v100, v99
	v_lshl_add_u64 v[100:101], v[114:115], 0, v[112:113]
	v_cvt_pk_bf16_f32 v96, v108, v96
	v_cvt_pk_bf16_f32 v97, v97, v98
	v_cvt_pk_bf16_f32 v98, v117, v105
	v_cvt_pk_bf16_f32 v99, v104, v99
	global_store_dwordx4 v[100:101], v[96:99], off nt
	s_mov_b32 s20, s12
	s_mov_b64 s[24:25], s[16:17]
	v_mul_f32_e32 v96, 0xbfb8aa3b, v92
	v_exp_f32_e32 v96, v96
	v_mul_f32_e32 v97, 0xbfb8aa3b, v88
	v_exp_f32_e32 v97, v97
	v_or_b32_e32 v98, 32, v152
	v_add_f32_e32 v96, 1.0, v96
	v_rcp_f32_e32 v99, v96
	v_add_f32_e32 v96, 1.0, v97
	v_rcp_f32_e32 v100, v96
	v_mad_i64_i32 v[96:97], s[22:23], v98, s55, v[144:145]
	v_mul_f32_e32 v92, v92, v99
	v_mul_f32_e32 v92, v92, v84
	v_mul_f32_e32 v84, v88, v100
	v_mul_f32_e32 v88, 0xbfb8aa3b, v93
	v_exp_f32_e32 v88, v88
	v_mul_f32_e32 v98, 0xbfb8aa3b, v89
	v_mul_f32_e32 v99, v84, v80
	v_exp_f32_e32 v98, v98
	v_add_f32_e32 v80, 1.0, v88
	v_rcp_f32_e32 v80, v80
	v_mul_f32_e32 v88, 0xbfb8aa3b, v94
	v_exp_f32_e32 v88, v88
	v_add_f32_e32 v84, 1.0, v98
	v_mul_f32_e32 v80, v93, v80
	v_rcp_f32_e32 v84, v84
	v_mul_f32_e32 v80, v80, v85
	v_add_f32_e32 v85, 1.0, v88
	v_rcp_f32_e32 v85, v85
	v_mul_f32_e32 v84, v89, v84
	v_mul_f32_e32 v88, 0xbfb8aa3b, v90
	v_mul_f32_e32 v89, v84, v81
	v_mul_f32_e32 v81, v94, v85
	v_exp_f32_e32 v88, v88
	v_mul_f32_e32 v81, v81, v86
	v_mul_f32_e32 v85, 0xbfb8aa3b, v95
	v_mul_f32_e32 v86, 0xbfb8aa3b, v91
	v_exp_f32_e32 v85, v85
	v_exp_f32_e32 v86, v86
	v_add_f32_e32 v84, 1.0, v88
	v_rcp_f32_e32 v84, v84
	v_add_f32_e32 v85, 1.0, v85
	v_add_f32_e32 v86, 1.0, v86
	v_rcp_f32_e32 v85, v85
	v_rcp_f32_e32 v86, v86
	v_mul_f32_e32 v84, v90, v84
	v_mul_f32_e32 v88, v84, v82
	v_mul_f32_e32 v82, v95, v85
	v_mul_f32_e32 v84, v91, v86
	v_mul_f32_e32 v82, v82, v87
	v_mul_f32_e32 v83, v84, v83
	v_lshl_add_u64 v[84:85], v[96:97], 0, v[112:113]
	v_cvt_pk_bf16_f32 v80, v92, v80
	v_cvt_pk_bf16_f32 v81, v81, v82
	v_cvt_pk_bf16_f32 v82, v99, v89
	v_cvt_pk_bf16_f32 v83, v88, v83
	global_store_dwordx4 v[84:85], v[80:83], off nt
	s_nop 1
	v_mul_f32_e32 v80, 0xbfb8aa3b, v76
	v_exp_f32_e32 v80, v80
; __device__ __forceinline__ unsigned cvt_pk_bf16(float lo, float hi) { unsigned r; asm volatile("v_cvt_pk_bf16_f32 %0, %1, %2" : "=v"(r) : "v"(lo), "v"(hi)); return r; }
; __device__ __forceinline__ float fast_sigmoid(float x) { return __builtin_amdgcn_rcpf(1.0f + __expf(-x)); }
;     __device__ __forceinline__ void operator()(const f32x4 (&acc)[2][2][4][2], const Unit& u, int wr, int wc, int fr, int fq) const {
;     ...
;             for (int m = 0; m < 4; ++m) { bf16_t* rowp = O + (size_t)(row0 + ai * HALF + m * 16) * ldc + col0;
;                 f32x4 a0 = acc[ai][0][m][0], a1 = acc[ai][0][m][1], b0 = acc[ai][1][m][0], b1 = acc[ai][1][m][1]; f32x4 v0, v1;
; #pragma unroll
;                 for (int j = 0; j < 4; ++j) { v0[j] = a0[j] * fast_sigmoid(a0[j]) * b0[j]; v1[j] = a1[j] * fast_sigmoid(a1[j]) * b1[j]; }
;                 u32x4 w; w.x = cvt_pk_bf16(v0[0], v0[1]); w.y = cvt_pk_bf16(v0[2], v0[3]); w.z = cvt_pk_bf16(v1[0], v1[1]); w.w = cvt_pk_bf16(v1[2], v1[3]);
;                 __builtin_nontemporal_store(w, (u32x4*)rowp); }
	v_mul_f32_e32 v81, 0xbfb8aa3b, v72
	v_exp_f32_e32 v81, v81
	v_or_b32_e32 v82, 48, v152
	v_add_f32_e32 v80, 1.0, v80
	v_rcp_f32_e32 v83, v80
	v_add_f32_e32 v80, 1.0, v81
	v_rcp_f32_e32 v84, v80
	v_mad_i64_i32 v[80:81], s[22:23], v82, s55, v[144:145]
	v_mul_f32_e32 v76, v76, v83
	v_mul_f32_e32 v76, v76, v68
	v_mul_f32_e32 v68, v72, v84
	v_mul_f32_e32 v72, 0xbfb8aa3b, v77
	v_exp_f32_e32 v72, v72
	v_mul_f32_e32 v82, 0xbfb8aa3b, v73
	v_mul_f32_e32 v83, v68, v64
	v_exp_f32_e32 v82, v82
	v_add_f32_e32 v64, 1.0, v72
	v_rcp_f32_e32 v64, v64
	v_mul_f32_e32 v72, 0xbfb8aa3b, v78
	v_exp_f32_e32 v72, v72
	v_add_f32_e32 v68, 1.0, v82
	v_mul_f32_e32 v64, v77, v64
	v_rcp_f32_e32 v68, v68
	v_mul_f32_e32 v64, v64, v69
	v_add_f32_e32 v69, 1.0, v72
	v_rcp_f32_e32 v69, v69
	v_mul_f32_e32 v68, v73, v68
	v_mul_f32_e32 v72, 0xbfb8aa3b, v74
	v_mul_f32_e32 v73, v68, v65
	v_mul_f32_e32 v65, v78, v69
	v_exp_f32_e32 v72, v72
	v_mul_f32_e32 v65, v65, v70
	v_mul_f32_e32 v69, 0xbfb8aa3b, v79
	v_mul_f32_e32 v70, 0xbfb8aa3b, v75
	v_exp_f32_e32 v69, v69
	v_exp_f32_e32 v70, v70
	v_add_f32_e32 v68, 1.0, v72
	v_rcp_f32_e32 v68, v68
	v_add_f32_e32 v69, 1.0, v69
	v_add_f32_e32 v70, 1.0, v70
	v_rcp_f32_e32 v69, v69
	v_rcp_f32_e32 v70, v70
	v_mul_f32_e32 v68, v74, v68
	v_mul_f32_e32 v72, v68, v66
	v_mul_f32_e32 v66, v79, v69
	v_mul_f32_e32 v68, v75, v70
	v_mul_f32_e32 v66, v66, v71
	v_mul_f32_e32 v67, v68, v67
	v_lshl_add_u64 v[68:69], v[80:81], 0, v[112:113]
	v_cvt_pk_bf16_f32 v64, v76, v64
	v_cvt_pk_bf16_f32 v65, v65, v66
	v_cvt_pk_bf16_f32 v66, v83, v73
	v_cvt_pk_bf16_f32 v67, v72, v67
	global_store_dwordx4 v[68:69], v[64:67], off nt
	s_nop 1
	v_mul_f32_e32 v64, 0xbfb8aa3b, v60
	v_exp_f32_e32 v64, v64
	v_mul_f32_e32 v65, 0xbfb8aa3b, v56
	v_exp_f32_e32 v65, v65
	v_add_u32_e32 v66, 0x80, v152
	v_add_f32_e32 v64, 1.0, v64
	v_rcp_f32_e32 v67, v64
	v_add_f32_e32 v64, 1.0, v65
	v_rcp_f32_e32 v68, v64
	v_mad_i64_i32 v[64:65], s[22:23], v66, s55, v[144:145]
	v_mul_f32_e32 v60, v60, v67
	v_mul_f32_e32 v60, v60, v52
	v_mul_f32_e32 v52, v56, v68
	v_mul_f32_e32 v56, 0xbfb8aa3b, v61
	v_exp_f32_e32 v56, v56
	v_mul_f32_e32 v66, 0xbfb8aa3b, v57
	v_mul_f32_e32 v67, v52, v48
	v_exp_f32_e32 v66, v66
	v_add_f32_e32 v48, 1.0, v56
	v_rcp_f32_e32 v48, v48
	v_mul_f32_e32 v56, 0xbfb8aa3b, v62
	v_exp_f32_e32 v56, v56
	v_add_f32_e32 v52, 1.0, v66
	v_mul_f32_e32 v48, v61, v48
	v_rcp_f32_e32 v52, v52
	v_mul_f32_e32 v48, v48, v53
	v_add_f32_e32 v53, 1.0, v56
	v_rcp_f32_e32 v53, v53
	v_mul_f32_e32 v52, v57, v52
	v_mul_f32_e32 v56, 0xbfb8aa3b, v58
	v_mul_f32_e32 v57, v52, v49
	v_mul_f32_e32 v49, v62, v53
	v_exp_f32_e32 v56, v56
	v_mul_f32_e32 v49, v49, v54
	v_mul_f32_e32 v53, 0xbfb8aa3b, v63
	v_mul_f32_e32 v54, 0xbfb8aa3b, v59
	v_exp_f32_e32 v53, v53
	v_exp_f32_e32 v54, v54
	v_add_f32_e32 v52, 1.0, v56
	v_rcp_f32_e32 v52, v52
	v_add_f32_e32 v53, 1.0, v53
	v_add_f32_e32 v54, 1.0, v54
	v_rcp_f32_e32 v53, v53
	v_rcp_f32_e32 v54, v54
	v_mul_f32_e32 v52, v58, v52
	v_mul_f32_e32 v56, v52, v50
	v_mul_f32_e32 v50, v63, v53
	v_mul_f32_e32 v52, v59, v54
	v_mul_f32_e32 v50, v50, v55
	v_mul_f32_e32 v51, v52, v51
	v_lshl_add_u64 v[52:53], v[64:65], 0, v[112:113]
	v_cvt_pk_bf16_f32 v48, v60, v48
	v_cvt_pk_bf16_f32 v49, v49, v50
	v_cvt_pk_bf16_f32 v50, v67, v57
	v_cvt_pk_bf16_f32 v51, v56, v51
	global_store_dwordx4 v[52:53], v[48:51], off nt
	s_nop 1
	v_mul_f32_e32 v48, 0xbfb8aa3b, v44
	v_exp_f32_e32 v48, v48
	v_mul_f32_e32 v49, 0xbfb8aa3b, v40
	v_exp_f32_e32 v49, v49
	v_add_u32_e32 v50, 0x90, v152
	v_add_f32_e32 v48, 1.0, v48
	v_rcp_f32_e32 v51, v48
	v_add_f32_e32 v48, 1.0, v49
	v_rcp_f32_e32 v52, v48
	v_mad_i64_i32 v[48:49], s[22:23], v50, s55, v[144:145]
	v_mul_f32_e32 v44, v44, v51
	v_mul_f32_e32 v44, v44, v36
	v_mul_f32_e32 v36, v40, v52
	v_mul_f32_e32 v40, 0xbfb8aa3b, v45
	v_exp_f32_e32 v40, v40
	v_mul_f32_e32 v50, 0xbfb8aa3b, v41
	v_mul_f32_e32 v51, v36, v32
	v_exp_f32_e32 v50, v50
	v_add_f32_e32 v32, 1.0, v40
	v_rcp_f32_e32 v32, v32
	v_mul_f32_e32 v40, 0xbfb8aa3b, v46
	v_exp_f32_e32 v40, v40
	v_add_f32_e32 v36, 1.0, v50
	v_mul_f32_e32 v32, v45, v32
	v_rcp_f32_e32 v36, v36
	v_mul_f32_e32 v32, v32, v37
	v_add_f32_e32 v37, 1.0, v40
	v_rcp_f32_e32 v37, v37
	v_mul_f32_e32 v36, v41, v36
	v_mul_f32_e32 v40, 0xbfb8aa3b, v42
; __device__ __forceinline__ unsigned cvt_pk_bf16(float lo, float hi) { unsigned r; asm volatile("v_cvt_pk_bf16_f32 %0, %1, %2" : "=v"(r) : "v"(lo), "v"(hi)); return r; }
; __device__ __forceinline__ float fast_sigmoid(float x) { return __builtin_amdgcn_rcpf(1.0f + __expf(-x)); }
; #define PG8_WAIT_V(n) asm volatile("s_waitcnt vmcnt(" #n ")" ::: "memory")
; #define PG8_BAR __builtin_amdgcn_s_barrier()
;     __device__ __forceinline__ void operator()(const f32x4 (&acc)[2][2][4][2], const Unit& u, int wr, int wc, int fr, int fq) const {
;     ...
;             for (int m = 0; m < 4; ++m) { bf16_t* rowp = O + (size_t)(row0 + ai * HALF + m * 16) * ldc + col0;
;                 f32x4 a0 = acc[ai][0][m][0], a1 = acc[ai][0][m][1], b0 = acc[ai][1][m][0], b1 = acc[ai][1][m][1]; f32x4 v0, v1;
; #pragma unroll
;                 for (int j = 0; j < 4; ++j) { v0[j] = a0[j] * fast_sigmoid(a0[j]) * b0[j]; v1[j] = a1[j] * fast_sigmoid(a1[j]) * b1[j]; }
;                 u32x4 w; w.x = cvt_pk_bf16(v0[0], v0[1]); w.y = cvt_pk_bf16(v0[2], v0[3]); w.z = cvt_pk_bf16(v1[0], v1[1]); w.w = cvt_pk_bf16(v1[2], v1[3]);
;                 __builtin_nontemporal_store(w, (u32x4*)rowp); }
; template <class Epi, class Sched>
; __device__ __forceinline__ void gemm_phase(PG8_LAS unsigned char* lds, const Gemm g, const Sched& S, const Epi& E) {
;     ...
;         if (!has_next) break;
;         if (!(Epi::CHAIN && cur.br < 2))
; #pragma unroll
;         for (int a = 0; a < 2; ++a)
; #pragma unroll
;             for (int b = 0; b < 2; ++b)
; #pragma unroll
;                 for (int m = 0; m < 4; ++m)
; #pragma unroll
;                     for (int n = 0; n < 2; ++n) acc[a][b][m][n] = (f32x4){0.f, 0.f, 0.f, 0.f};
;         cur = nxt; cA = nA; cB = nB; ++ui;
;     }
;     PG8_WAIT_V(0);
;     if (wr == 0) PG8_BAR;
;     PG8_BAR;
	v_mul_f32_e32 v41, v36, v33
	v_mul_f32_e32 v33, v46, v37
	v_exp_f32_e32 v40, v40
	v_mul_f32_e32 v33, v33, v38
	v_mul_f32_e32 v37, 0xbfb8aa3b, v47
	v_mul_f32_e32 v38, 0xbfb8aa3b, v43
	v_exp_f32_e32 v37, v37
	v_exp_f32_e32 v38, v38
	v_add_f32_e32 v36, 1.0, v40
	v_rcp_f32_e32 v36, v36
	v_add_f32_e32 v37, 1.0, v37
	v_add_f32_e32 v38, 1.0, v38
	v_rcp_f32_e32 v37, v37
	v_rcp_f32_e32 v38, v38
	v_mul_f32_e32 v36, v42, v36
	v_mul_f32_e32 v40, v36, v34
	v_mul_f32_e32 v34, v47, v37
	v_mul_f32_e32 v36, v43, v38
	v_mul_f32_e32 v34, v34, v39
	v_mul_f32_e32 v35, v36, v35
	v_lshl_add_u64 v[36:37], v[48:49], 0, v[112:113]
	v_cvt_pk_bf16_f32 v32, v44, v32
	v_cvt_pk_bf16_f32 v33, v33, v34
	v_cvt_pk_bf16_f32 v34, v51, v41
	v_cvt_pk_bf16_f32 v35, v40, v35
	global_store_dwordx4 v[36:37], v[32:35], off nt
	s_nop 1
	v_mul_f32_e32 v32, 0xbfb8aa3b, v28
	v_exp_f32_e32 v32, v32
	v_mul_f32_e32 v33, 0xbfb8aa3b, v24
	v_exp_f32_e32 v33, v33
	v_add_u32_e32 v34, 0xa0, v152
	v_add_f32_e32 v32, 1.0, v32
	v_rcp_f32_e32 v35, v32
	v_add_f32_e32 v32, 1.0, v33
	v_rcp_f32_e32 v36, v32
	v_mad_i64_i32 v[32:33], s[22:23], v34, s55, v[144:145]
	v_mul_f32_e32 v28, v28, v35
	v_mul_f32_e32 v28, v28, v20
	v_mul_f32_e32 v20, v24, v36
	v_mul_f32_e32 v24, 0xbfb8aa3b, v29
	v_exp_f32_e32 v24, v24
	v_mul_f32_e32 v34, 0xbfb8aa3b, v25
	v_mul_f32_e32 v35, v20, v16
	v_exp_f32_e32 v34, v34
	v_add_f32_e32 v16, 1.0, v24
	v_rcp_f32_e32 v16, v16
	v_mul_f32_e32 v24, 0xbfb8aa3b, v30
	v_exp_f32_e32 v24, v24
	v_add_f32_e32 v20, 1.0, v34
	v_mul_f32_e32 v16, v29, v16
	v_rcp_f32_e32 v20, v20
	v_mul_f32_e32 v16, v16, v21
	v_add_f32_e32 v21, 1.0, v24
	v_rcp_f32_e32 v21, v21
	v_mul_f32_e32 v20, v25, v20
	v_mul_f32_e32 v24, 0xbfb8aa3b, v26
	v_mul_f32_e32 v25, v20, v17
	v_mul_f32_e32 v17, v30, v21
	v_exp_f32_e32 v24, v24
	v_mul_f32_e32 v17, v17, v22
	v_mul_f32_e32 v21, 0xbfb8aa3b, v31
	v_mul_f32_e32 v22, 0xbfb8aa3b, v27
	v_exp_f32_e32 v21, v21
	v_exp_f32_e32 v22, v22
	v_add_f32_e32 v20, 1.0, v24
	v_rcp_f32_e32 v20, v20
	v_add_f32_e32 v21, 1.0, v21
	v_add_f32_e32 v22, 1.0, v22
	v_rcp_f32_e32 v21, v21
	v_rcp_f32_e32 v22, v22
	v_mul_f32_e32 v20, v26, v20
	v_mul_f32_e32 v24, v20, v18
	v_mul_f32_e32 v18, v31, v21
	v_mul_f32_e32 v20, v27, v22
	v_mul_f32_e32 v18, v18, v23
	v_mul_f32_e32 v19, v20, v19
	v_lshl_add_u64 v[20:21], v[32:33], 0, v[112:113]
	v_cvt_pk_bf16_f32 v16, v28, v16
	v_cvt_pk_bf16_f32 v17, v17, v18
	v_cvt_pk_bf16_f32 v18, v35, v25
	v_cvt_pk_bf16_f32 v19, v24, v19
	global_store_dwordx4 v[20:21], v[16:19], off nt
	s_nop 1
	v_mul_f32_e32 v16, 0xbfb8aa3b, v12
	v_exp_f32_e32 v16, v16
	v_mul_f32_e32 v17, 0xbfb8aa3b, v8
	v_exp_f32_e32 v17, v17
	v_add_u32_e32 v18, 0xb0, v152
	v_add_f32_e32 v16, 1.0, v16
	v_rcp_f32_e32 v19, v16
	v_add_f32_e32 v16, 1.0, v17
	v_rcp_f32_e32 v20, v16
	v_mad_i64_i32 v[16:17], s[22:23], v18, s55, v[144:145]
	v_mul_f32_e32 v12, v12, v19
	v_mul_f32_e32 v12, v12, v4
	v_mul_f32_e32 v4, v8, v20
	v_mul_f32_e32 v8, 0xbfb8aa3b, v13
	v_exp_f32_e32 v8, v8
	v_mul_f32_e32 v18, 0xbfb8aa3b, v9
	v_mul_f32_e32 v19, v4, v0
	v_exp_f32_e32 v18, v18
	v_add_f32_e32 v0, 1.0, v8
	v_rcp_f32_e32 v0, v0
	v_mul_f32_e32 v8, 0xbfb8aa3b, v14
	v_exp_f32_e32 v8, v8
	v_add_f32_e32 v4, 1.0, v18
	v_mul_f32_e32 v0, v13, v0
	v_rcp_f32_e32 v4, v4
	v_mul_f32_e32 v0, v0, v5
	v_add_f32_e32 v5, 1.0, v8
	v_rcp_f32_e32 v5, v5
	v_mul_f32_e32 v4, v9, v4
	v_mul_f32_e32 v8, 0xbfb8aa3b, v10
	v_mul_f32_e32 v9, v4, v1
	v_mul_f32_e32 v1, v14, v5
	v_exp_f32_e32 v8, v8
	v_mul_f32_e32 v1, v1, v6
	v_mul_f32_e32 v5, 0xbfb8aa3b, v15
	v_mul_f32_e32 v6, 0xbfb8aa3b, v11
	v_exp_f32_e32 v5, v5
	v_exp_f32_e32 v6, v6
	v_add_f32_e32 v4, 1.0, v8
	v_rcp_f32_e32 v4, v4
	v_add_f32_e32 v5, 1.0, v5
	v_add_f32_e32 v6, 1.0, v6
	v_rcp_f32_e32 v5, v5
	v_rcp_f32_e32 v6, v6
	v_mul_f32_e32 v4, v10, v4
	v_mul_f32_e32 v8, v4, v2
	v_mul_f32_e32 v2, v15, v5
	v_mul_f32_e32 v4, v11, v6
	v_mul_f32_e32 v2, v2, v7
	v_mul_f32_e32 v3, v4, v3
	v_lshl_add_u64 v[4:5], v[16:17], 0, v[112:113]
	s_mov_b64 s[22:23], s[18:19]
	v_cvt_pk_bf16_f32 v0, v12, v0
	v_cvt_pk_bf16_f32 v1, v1, v2
	v_cvt_pk_bf16_f32 v2, v19, v9
	v_cvt_pk_bf16_f32 v3, v8, v3
	global_store_dwordx4 v[4:5], v[0:3], off nt
	s_cbranch_vccz .LBB0_76
	s_waitcnt vmcnt(0)
	s_cmpk_gt_u32 s30, 0xff
	s_cbranch_scc1 .LBB0_83

;     __host__ __device__ bool next(int i, Unit& u) const { const int j = i / 3; if (!StaticOrder::next(j, u)) return false; u.br = i - 3 * j; return true; }
; #define PG8_STAGE(bufoff, gbase, voff) do { _Pragma("unroll") for (int _i = 0; _i < 2; ++_i) \
;         __builtin_amdgcn_global_load_lds((const unsigned*)((const char*)(gbase) + (voff)[_i]), (PG8_LAS unsigned*)(lds + (bufoff) + ldsw + _i * 8192), 16, 0, 0); } while (0)
; template <class Epi, class Sched>
; __device__ __forceinline__ void gemm_phase(PG8_LAS unsigned char* lds, const Gemm g, const Sched& S, const Epi& E) {
;     ...
;     const int tid = tix_, wid = __builtin_amdgcn_readfirstlane(tid >> 6), lane = tid & 63, wr = wid >> 2, wc = wid & 3, fr = lane & 15, fq = lane >> 4;
;     const int K = g.K, nt = K / BK;
;     unsigned voffA[2], voffB[2];
; #pragma unroll
;     for (int i = 0; i < 2; ++i) { int R, C; stage_rc(tid * 16 + i * 8192, R, C);
;         voffA[i] = (unsigned)(R * K + C) * 2u; voffB[i] = (unsigned)(tid * 16 + i * 8192); }
;     const size_t kstep = (size_t)(BK * 2);
;     const size_t hstep = (size_t)HALF * K * 2;
;     const size_t tstep = 2 * hstep;
;     const size_t kstepB = 32768, hstepB = 16384, tstepB = (size_t)nt * 32768;
;     const unsigned ldsw = (unsigned)wid * 1024u;
;     const int aoff = lds_byte(wr * 64 + fr, fq * 8), boff = lds_byte(wc * 32 + fr, fq * 8);
;     ...
;     Unit cur, nxt; int ui = 0;
;     if (!S.next(0, cur)) return;
;     f32x4 acc[2][2][4][2];
; #pragma unroll
;     for (int a = 0; a < 2; ++a)
; #pragma unroll
;         for (int b = 0; b < 2; ++b)
; #pragma unroll
;             for (int m = 0; m < 4; ++m)
; #pragma unroll
;                 for (int n = 0; n < 2; ++n) acc[a][b][m][n] = (f32x4){0.f, 0.f, 0.f, 0.f};
;     bf16x8 At[4][2], B0[2][2], B1[2][2];
;     const char* cA = (const char*)g.A + (size_t)cur.pm * tstep + (size_t)cur.br * g.strideA; const char* cB = (const char*)g.Bt + (size_t)cur.pn * tstepB + (size_t)cur.br * g.strideB;
;     S.a_ready(cur);
;     PG8_STAGE(PG8_SB(0, 0), cB, voffB); PG8_STAGE(PG8_SA(0, 0), cA, voffA); PG8_STAGE(PG8_SB(0, 1), cB + hstepB, voffB); PG8_STAGE(PG8_SA(0, 1), cA + hstep, voffA);
;     if (wr == 1) PG8_BAR;
;     PG8_WAIT_V(4); PG8_BAR;
;     PG8_STAGE(PG8_SB(1, 0), cB + kstepB, voffB); PG8_STAGE(PG8_SA(1, 0), cA + kstep, voffA); PG8_STAGE(PG8_SB(1, 1), cB + hstepB + kstepB, voffB);
;     PG8_WAIT_V(6); PG8_BAR;
.LBB0_141:
	v_ashrrev_i32_e32 v0, 31, v4
	v_lshrrev_b32_e32 v0, 26, v0
	v_add_u32_e32 v0, v4, v0
	v_ashrrev_i32_e32 v5, 6, v0
	v_bfe_i32 v0, v4, 27, 1
	v_lshlrev_b32_e32 v128, 4, v4
	v_lshrrev_b32_e32 v0, 22, v0
	v_add_u32_e32 v0, v128, v0
	v_and_b32_e32 v0, 0xfffffc00, v0
	v_sub_u32_e32 v0, v128, v0
	v_lshrrev_b32_e32 v1, 4, v0
	v_bitop3_b32 v0, v1, v0, 32 bitop3:0x6c
	v_ashrrev_i32_e32 v2, 31, v0
	s_waitcnt lgkmcnt(0)
	s_add_u32 s46, s4, 0x10700000
	v_lshrrev_b32_e32 v2, 26, v2
	s_addc_u32 s47, s5, 0
	v_add_u32_e32 v2, v0, v2
	s_add_u32 s48, s4, 0x2b00000
	v_lshlrev_b32_e32 v1, 3, v5
	v_ashrrev_i32_e32 v7, 6, v2
	v_and_b32_e32 v2, 0xc0, v2
	s_addc_u32 s49, s5, 0
	v_and_b32_e32 v1, 0x1fffff0, v1
	v_sub_u32_e32 v0, v0, v2
	v_mov_b32_e32 v2, 1
	s_add_i32 s10, s10, s11
	v_add_u32_e32 v1, v7, v1
	v_lshlrev_b32_e32 v3, 5, v5
	v_ashrrev_i16_sdwa v0, v2, sext(v0) dst_sel:DWORD dst_unused:UNUSED_PAD src0_sel:DWORD src1_sel:BYTE_0
	s_movk_i32 s9, 0x1580
	s_sext_i32_i16 s11, s10
	v_and_b32_e32 v6, 32, v3
	v_bfe_i32 v8, v0, 0, 16
	v_mul_lo_u32 v0, v1, s9
	s_bfe_u32 s11, s11, 0x5001a
	v_or_b32_e32 v0, v0, v6
	v_add_u32_e32 v132, 0x2000, v128
	s_add_i32 s11, s10, s11
	v_add_lshl_u32 v130, v0, v8, 1
	v_ashrrev_i32_e32 v0, 31, v132
	s_sext_i32_i16 s12, s11
	s_and_b32 s11, s11, 0xffe0
	v_lshrrev_b32_e32 v0, 22, v0
	s_sub_i32 s10, s10, s11
	v_add_u32_e32 v0, v132, v0
	s_bfe_i32 s11, s10, 0x80000
	v_ashrrev_i32_e32 v9, 10, v0
	s_bfe_u32 s11, s11, 0x2000d
	v_mul_i32_i24_e32 v0, 0x400, v9
	s_add_i32 s11, s10, s11
	v_sub_u32_e32 v0, v132, v0
	s_bfe_i32 s13, s11, 0x80000
	s_and_b32 s11, s11, 0xfc
	v_lshrrev_b32_e32 v1, 4, v0
	s_ashr_i32 s12, s12, 5
	s_sub_i32 s10, s10, s11
	v_bitop3_b32 v0, v1, v0, 32 bitop3:0x6c
	s_lshl_b32 s12, s12, 2
	s_sext_i32_i16 s13, s13
	s_sext_i32_i8 s10, s10
	v_ashrrev_i32_e32 v3, 31, v0
	s_ashr_i32 s14, s38, 6
	s_add_i32 s63, s12, s10
	s_ashr_i32 s12, s13, 2
	s_ashr_i32 s8, s38, 8
	v_lshrrev_b32_e32 v3, 26, v3
	s_lshl_b32 s50, s14, 10
	s_lshr_b32 s16, s13, 2
	s_mul_hi_i32 s13, s12, 0x2b0000
	s_mul_i32 s12, s12, 0x2b0000
	v_add_u32_e32 v3, v0, v3
	s_add_u32 s26, s48, s12
	v_lshlrev_b32_e32 v1, 3, v9
	v_ashrrev_i32_e32 v10, 6, v3
	v_and_b32_e32 v3, 0xc0, v3
	s_addc_u32 s27, s49, s13
	s_add_i32 s51, s50, 0
	v_and_b32_e32 v1, 0x1fffff0, v1
	v_sub_u32_e32 v0, v0, v3
	s_add_i32 m0, s51, 0x10000
	v_add_u32_e32 v1, v10, v1
	v_lshlrev_b32_e32 v11, 5, v9
	v_ashrrev_i16_sdwa v0, v2, sext(v0) dst_sel:DWORD dst_unused:UNUSED_PAD src0_sel:DWORD src1_sel:BYTE_0
	s_mul_i32 s11, s63, 0x2b0000
	global_load_lds_dwordx4 v128, s[26:27]
	s_add_i32 m0, s51, 0x12000
	v_and_b32_e32 v11, 32, v11
	v_bfe_i32 v12, v0, 0, 16
	v_mul_lo_u32 v0, v1, s9
	s_mul_hi_i32 s10, s63, 0x2b0000
	s_add_u32 s24, s46, s11
	v_or_b32_e32 v0, v0, v11
	global_load_lds_dwordx4 v132, s[26:27]
	s_addc_u32 s25, s47, s10
	s_mov_b32 m0, s51
	s_add_i32 s52, s51, 0x2000
	v_add_lshl_u32 v134, v0, v12, 1
	global_load_lds_dwordx4 v130, s[24:25]
	s_mov_b32 m0, s52
	s_add_u32 s10, s26, 0x4000
	global_load_lds_dwordx4 v134, s[24:25]
	s_addc_u32 s11, s27, 0
	s_add_i32 m0, s51, 0x14000
	v_mov_b32_e32 v129, 0
	global_load_lds_dwordx4 v128, s[10:11]
	s_add_i32 m0, s51, 0x16000
	v_mov_b32_e32 v131, v129
	global_load_lds_dwordx4 v132, s[10:11]
	s_add_u32 s10, s24, 0x158000
	s_addc_u32 s11, s25, 0
	s_add_i32 s53, s51, 0x4000
	s_mov_b32 m0, s53
	s_add_i32 s54, s51, 0x6000
	global_load_lds_dwordx4 v130, s[10:11]
	s_mov_b32 m0, s54
	v_mov_b32_e32 v135, v129
	global_load_lds_dwordx4 v134, s[10:11]
	s_load_dwordx2 s[10:11], s[6:7], 0x0
	s_mov_b32 s55, 0
	v_mov_b32_e32 v133, v129
	v_lshl_add_u64 v[2:3], s[24:25], 0, v[130:131]
	s_cmp_lg_u32 s8, 1
	v_lshl_add_u64 v[0:1], s[24:25], 0, v[134:135]
	s_cbranch_scc1 .LBB0_143
.LBB0_143:
	s_add_u32 s12, s4, 0x2dd24000
	s_addc_u32 s13, s5, 0
	s_lshl_b32 s4, s14, 5
	s_and_b32 s7, s4, 0x60
	s_lshl_b32 s6, s8, 13
	s_lshl_b32 s17, s7, 7
	s_add_u32 s4, s26, 0x8000
	s_addc_u32 s5, s27, 0
	s_add_i32 m0, s51, 0x18000
	v_lshl_add_u64 v[14:15], s[4:5], 0, v[128:129]
	s_waitcnt vmcnt(4)
	s_barrier
	global_load_lds_dwordx4 v[14:15], off
	v_lshl_add_u64 v[14:15], s[4:5], 0, v[132:133]
	s_add_i32 m0, s51, 0x1a000
	s_mov_b64 s[14:15], 0x80
	s_add_i32 s56, s51, 0x8000
	s_add_i32 s57, s51, 0xa000
	global_load_lds_dwordx4 v[14:15], off
	v_lshl_add_u64 v[2:3], v[2:3], 0, s[14:15]
	s_mov_b32 m0, s56
	s_add_u32 s4, s26, 0xc000
	global_load_lds_dwordx4 v[2:3], off
	v_lshl_add_u64 v[0:1], v[0:1], 0, s[14:15]
	s_mov_b32 m0, s57
	s_addc_u32 s5, s27, 0
	global_load_lds_dwordx4 v[0:1], off
	s_add_i32 m0, s51, 0x1c000
	v_lshl_add_u64 v[0:1], s[4:5], 0, v[128:129]
	global_load_lds_dwordx4 v[0:1], off
	v_lshl_add_u64 v[0:1], s[4:5], 0, v[132:133]
	s_add_i32 m0, s51, 0x1e000
	s_add_i32 s59, 0, 0x10000
	global_load_lds_dwordx4 v[0:1], off
	v_lshrrev_b32_e32 v1, 1, v4
	v_and_b32_e32 v1, 24, v1
	v_and_b32_e32 v0, 15, v4
	v_lshlrev_b32_e32 v2, 1, v1
	v_lshl_or_b32 v150, s8, 6, v0
	v_lshl_or_b32 v0, v0, 6, v2
	v_lshlrev_b32_e32 v2, 2, v4
	v_and_b32_e32 v2, 32, v2
	v_bitop3_b32 v3, v0, s6, v2 bitop3:0xde
	v_bitop3_b32 v151, v0, s17, v2 bitop3:0xde
	v_or_b32_e32 v152, s7, v1
	v_lshrrev_b32_e32 v1, 1, v5
	v_mul_lo_u32 v0, v7, s9
	s_mov_b32 s6, 0x15800
	v_mad_u64_u32 v[0:1], s[4:5], v1, s6, v[0:1]
	v_or_b32_e32 v0, v0, v6
	v_add_lshl_u32 v0, v0, v8, 1
	v_mov_b32_e32 v1, v129
	s_mov_b64 s[4:5], 0x158080
	v_lshl_add_u64 v[136:137], v[0:1], 0, s[4:5]
	v_lshrrev_b32_e32 v1, 1, v9
	v_mul_lo_u32 v0, v10, s9
	v_mad_u64_u32 v[0:1], s[6:7], v1, s6, v[0:1]
	s_waitcnt vmcnt(6)
	v_or_b32_e32 v0, v0, v11
	v_add_lshl_u32 v0, v0, v12, 1
	v_mov_b32_e32 v1, v129
	s_add_i32 s60, 0, 0x14000
	s_sext_i32_i8 s64, s16
	s_ashr_i32 s58, s36, 31
	v_lshl_add_u64 v[138:139], v[0:1], 0, s[4:5]
	v_mov_b64_e32 v[140:141], 0x200
	v_mov_b64_e32 v[142:143], 0x1ff
	v_add_u32_e32 v153, s59, v151
	v_add_u32_e32 v154, 0, v3
	v_add_u32_e32 v155, s60, v151
	s_mov_b64 s[16:17], 0x40000
	s_mov_b64 s[18:19], 0x48000
	s_mov_b64 s[20:21], 0x50000
	s_mov_b64 s[22:23], 0x58000
	s_barrier

;     __host__ __device__ bool next(int i, Unit& u) const { const int j = i / 3; if (!StaticOrder::next(j, u)) return false; u.br = i - 3 * j; return true; }
; #define PG8_STAGE(bufoff, gbase, voff) do { _Pragma("unroll") for (int _i = 0; _i < 2; ++_i) \
;         __builtin_amdgcn_global_load_lds((const unsigned*)((const char*)(gbase) + (voff)[_i]), (PG8_LAS unsigned*)(lds + (bufoff) + ldsw + _i * 8192), 16, 0, 0); } while (0)
; #define PG8_LDA(dst, b, h) do { _Pragma("unroll") for (int m = 0; m < 4; ++m) _Pragma("unroll") for (int k = 0; k < 2; ++k) dst[m][k] = *(const PG8_LAS bf16x8*)(lds + PG8_SA(b, h) + aoff + m * 2048 + k * 1024); } while (0)
; #define PG8_LDB(dst, b, h) do { _Pragma("unroll") for (int n = 0; n < 2; ++n) _Pragma("unroll") for (int k = 0; k < 2; ++k) dst[n][k] = *(const PG8_LAS bf16x8*)(lds + PG8_SB(b, h) + boff + n * 2048 + k * 1024); } while (0)
; #define PG8_WAIT_L(n) asm volatile("s_waitcnt lgkmcnt(" #n ")" ::: "memory")
; #define PG8_BAR __builtin_amdgcn_s_barrier()
; #define PG8_SCHED __builtin_amdgcn_sched_barrier(0)
; template <class Epi, class Sched>
; __device__ __forceinline__ void gemm_phase(PG8_LAS unsigned char* lds, const Gemm g, const Sched& S, const Epi& E) {
;     ...
;         const bool has_next = S.next(ui + 1, nxt);
;         const char* nA = has_next ? (const char*)g.A + (size_t)nxt.pm * tstep + (size_t)nxt.br * g.strideA : cA; const char* nB = has_next ? (const char*)g.Bt + (size_t)nxt.pn * tstepB + (size_t)nxt.br * g.strideB : cB;
;         for (int t = 0; t < nt; t += 2) {
;             const bool last = (t == nt - 2);
;             const char* a1 = cA + (size_t)(t + 1) * kstep;
;             const char* a2 = last ? nA : cA + (size_t)(t + 2) * kstep; const char* b2 = last ? nB : cB + (size_t)(t + 2) * kstepB;
;             const char* a3 = a2 + kstep; const char* b3 = b2 + kstepB;
;             if (last && has_next) S.a_ready(nxt);
;             PG8_LDB(B0, 0, 0); PG8_SCHED; PG8_LDA(At, 0, 0); PG8_STAGE(PG8_SA(1, 1), a1 + hstep, voffA);
;             PG8_WAIT_L(8); PG8_BAR; PG8_WAIT_L(0); PG8_MMA(0, 0, At, B0); PG8_BAR; PG8_SCHED;
;     ...
;         for (int a = 0; a < 2; ++a)
; #pragma unroll
;             for (int b = 0; b < 2; ++b)
; #pragma unroll
;                 for (int m = 0; m < 4; ++m)
; #pragma unroll
;                     for (int n = 0; n < 2; ++n) acc[a][b][m][n] = (f32x4){0.f, 0.f, 0.f, 0.f};
.LBB0_154:
	s_add_u32 s65, s26, 0x10000
	v_mov_b32_e32 v0, 0
	s_addc_u32 s66, s27, 0
	s_mov_b32 s67, -2
	v_mov_b32_e32 v1, v0
	v_mov_b32_e32 v2, v0
	v_mov_b32_e32 v3, v0
	v_mov_b32_e32 v4, v0
	v_mov_b32_e32 v5, v0
	v_mov_b32_e32 v6, v0
	v_mov_b32_e32 v7, v0
	v_mov_b32_e32 v16, v0
	v_mov_b32_e32 v17, v0
	v_mov_b32_e32 v18, v0
	v_mov_b32_e32 v19, v0
	v_mov_b32_e32 v20, v0
	v_mov_b32_e32 v21, v0
	v_mov_b32_e32 v22, v0
	v_mov_b32_e32 v23, v0
	v_mov_b32_e32 v32, v0
	v_mov_b32_e32 v33, v0
	v_mov_b32_e32 v34, v0
	v_mov_b32_e32 v35, v0
	v_mov_b32_e32 v36, v0
	v_mov_b32_e32 v37, v0
	v_mov_b32_e32 v38, v0
	v_mov_b32_e32 v39, v0
	v_mov_b32_e32 v48, v0
	v_mov_b32_e32 v49, v0
	v_mov_b32_e32 v50, v0
	v_mov_b32_e32 v51, v0
	v_mov_b32_e32 v52, v0
	v_mov_b32_e32 v53, v0
	v_mov_b32_e32 v54, v0
	v_mov_b32_e32 v55, v0
	v_mov_b32_e32 v8, v0
	v_mov_b32_e32 v9, v0
	v_mov_b32_e32 v10, v0
	v_mov_b32_e32 v11, v0
	v_mov_b32_e32 v12, v0
	v_mov_b32_e32 v13, v0
	v_mov_b32_e32 v14, v0
	v_mov_b32_e32 v15, v0
	v_mov_b32_e32 v24, v0
	v_mov_b32_e32 v25, v0
	v_mov_b32_e32 v26, v0
	v_mov_b32_e32 v27, v0
	v_mov_b32_e32 v28, v0
	v_mov_b32_e32 v29, v0
	v_mov_b32_e32 v30, v0
	v_mov_b32_e32 v31, v0
	v_mov_b32_e32 v40, v0
	v_mov_b32_e32 v41, v0
	v_mov_b32_e32 v42, v0
	v_mov_b32_e32 v43, v0
	v_mov_b32_e32 v44, v0
	v_mov_b32_e32 v45, v0
	v_mov_b32_e32 v46, v0
	v_mov_b32_e32 v47, v0
	v_mov_b32_e32 v56, v0
	v_mov_b32_e32 v57, v0
	v_mov_b32_e32 v58, v0
	v_mov_b32_e32 v59, v0
	v_mov_b32_e32 v60, v0
	v_mov_b32_e32 v61, v0
	v_mov_b32_e32 v62, v0
	v_mov_b32_e32 v63, v0
	v_mov_b32_e32 v64, v0
	v_mov_b32_e32 v65, v0
	v_mov_b32_e32 v66, v0
	v_mov_b32_e32 v67, v0
	v_mov_b32_e32 v68, v0
	v_mov_b32_e32 v69, v0
	v_mov_b32_e32 v70, v0
	v_mov_b32_e32 v71, v0
	v_mov_b32_e32 v80, v0
	v_mov_b32_e32 v81, v0
	v_mov_b32_e32 v82, v0
	v_mov_b32_e32 v83, v0
	v_mov_b32_e32 v84, v0
	v_mov_b32_e32 v85, v0
	v_mov_b32_e32 v86, v0
	v_mov_b32_e32 v87, v0
	v_mov_b32_e32 v96, v0
	v_mov_b32_e32 v97, v0
	v_mov_b32_e32 v98, v0
	v_mov_b32_e32 v99, v0
	v_mov_b32_e32 v100, v0
	v_mov_b32_e32 v101, v0
	v_mov_b32_e32 v102, v0
	v_mov_b32_e32 v103, v0
	v_mov_b32_e32 v112, v0
	v_mov_b32_e32 v113, v0
	v_mov_b32_e32 v114, v0
	v_mov_b32_e32 v115, v0
	v_mov_b32_e32 v116, v0
	v_mov_b32_e32 v117, v0
	v_mov_b32_e32 v118, v0
	v_mov_b32_e32 v119, v0
	v_mov_b32_e32 v72, v0
	v_mov_b32_e32 v73, v0
	v_mov_b32_e32 v74, v0
	v_mov_b32_e32 v75, v0
	v_mov_b32_e32 v76, v0
	v_mov_b32_e32 v77, v0
	v_mov_b32_e32 v78, v0
	v_mov_b32_e32 v79, v0
	v_mov_b32_e32 v88, v0
	v_mov_b32_e32 v89, v0
	v_mov_b32_e32 v90, v0
	v_mov_b32_e32 v91, v0
	v_mov_b32_e32 v92, v0
	v_mov_b32_e32 v93, v0
	v_mov_b32_e32 v94, v0
	v_mov_b32_e32 v95, v0
	v_mov_b32_e32 v104, v0
	v_mov_b32_e32 v105, v0
	v_mov_b32_e32 v106, v0
	v_mov_b32_e32 v107, v0
	v_mov_b32_e32 v108, v0
	v_mov_b32_e32 v109, v0
	v_mov_b32_e32 v110, v0
	v_mov_b32_e32 v111, v0
	v_mov_b32_e32 v120, v0
	v_mov_b32_e32 v121, v0
	v_mov_b32_e32 v122, v0
	v_mov_b32_e32 v123, v0
	v_mov_b32_e32 v124, v0
	v_mov_b32_e32 v125, v0
	v_mov_b32_e32 v126, v0
	v_mov_b32_e32 v127, v0
	s_cmp_eq_u32 s78, 1
	s_cbranch_scc0 .Lhalf_skip_y_1
	s_barrier
.Lhalf_skip_y_1:
.LBB0_155:
	ds_read_b128 v[144:147], v153
	ds_read_b128 v[156:159], v153 offset:1024
	ds_read_b128 v[160:163], v153 offset:2048
	ds_read_b128 v[164:167], v153 offset:3072
	s_add_u32 s26, s24, 0x100
	s_addc_u32 s27, s25, 0
	s_cmpk_eq_i32 s67, 0x52
	s_cselect_b32 s31, s7, s27
	s_cselect_b32 s30, s6, s26
	s_cselect_b32 s29, s9, s66
	s_cselect_b32 s28, s8, s65
	v_lshl_add_u64 v[148:149], s[24:25], 0, v[136:137]
	s_add_i32 m0, s51, 0xc000
	ds_read_b128 v[168:171], v154
	ds_read_b128 v[172:175], v154 offset:1024
	ds_read_b128 v[176:179], v154 offset:2048
	ds_read_b128 v[180:183], v154 offset:3072
	ds_read_b128 v[184:187], v154 offset:4096
	ds_read_b128 v[188:191], v154 offset:5120
	ds_read_b128 v[192:195], v154 offset:6144
	ds_read_b128 v[196:199], v154 offset:7168
	global_load_lds_dwordx4 v[148:149], off
	v_lshl_add_u64 v[148:149], s[24:25], 0, v[138:139]
	s_add_i32 m0, s51, 0xe000
	s_nop 0
	global_load_lds_dwordx4 v[148:149], off
	s_waitcnt lgkmcnt(8)
	s_barrier
	s_waitcnt lgkmcnt(0)
	s_setprio 1
	s_waitcnt lgkmcnt(0)
	v_mfma_f32_16x16x32_bf16 v[124:127], v[144:147], v[168:171], v[124:127]
	v_mfma_f32_16x16x32_bf16 v[120:123], v[160:163], v[168:171], v[120:123]
	v_mfma_f32_16x16x32_bf16 v[108:111], v[144:147], v[176:179], v[108:111]
	v_mfma_f32_16x16x32_bf16 v[104:107], v[160:163], v[176:179], v[104:107]
	v_mfma_f32_16x16x32_bf16 v[92:95], v[144:147], v[184:187], v[92:95]
	v_mfma_f32_16x16x32_bf16 v[88:91], v[160:163], v[184:187], v[88:91]
	v_mfma_f32_16x16x32_bf16 v[76:79], v[144:147], v[192:195], v[76:79]
	v_mfma_f32_16x16x32_bf16 v[72:75], v[160:163], v[192:195], v[72:75]
	v_mfma_f32_16x16x32_bf16 v[124:127], v[156:159], v[172:175], v[124:127]
	v_mfma_f32_16x16x32_bf16 v[120:123], v[164:167], v[172:175], v[120:123]
	v_mfma_f32_16x16x32_bf16 v[108:111], v[156:159], v[180:183], v[108:111]
	v_mfma_f32_16x16x32_bf16 v[104:107], v[164:167], v[180:183], v[104:107]
	v_mfma_f32_16x16x32_bf16 v[92:95], v[156:159], v[188:191], v[92:95]
	v_mfma_f32_16x16x32_bf16 v[88:91], v[164:167], v[188:191], v[88:91]
	v_mfma_f32_16x16x32_bf16 v[76:79], v[156:159], v[196:199], v[76:79]
	v_mfma_f32_16x16x32_bf16 v[72:75], v[164:167], v[196:199], v[72:75]
	s_setprio 0
	s_barrier
	s_add_i32 s24, s59, s50
	v_lshl_add_u64 v[148:149], s[28:29], 0, v[128:129]
	s_mov_b32 m0, s24
	ds_read_b128 v[200:203], v155
	ds_read_b128 v[204:207], v155 offset:1024
	ds_read_b128 v[208:211], v155 offset:2048
	ds_read_b128 v[212:215], v155 offset:3072
	global_load_lds_dwordx4 v[148:149], off
	v_lshl_add_u64 v[148:149], s[28:29], 0, v[132:133]
	s_add_i32 m0, s24, 0x2000
	s_nop 0
	global_load_lds_dwordx4 v[148:149], off
	s_barrier
; #define PG8_STAGE(bufoff, gbase, voff) do { _Pragma("unroll") for (int _i = 0; _i < 2; ++_i) \
;         __builtin_amdgcn_global_load_lds((const unsigned*)((const char*)(gbase) + (voff)[_i]), (PG8_LAS unsigned*)(lds + (bufoff) + ldsw + _i * 8192), 16, 0, 0); } while (0)
; #define PG8_LDA(dst, b, h) do { _Pragma("unroll") for (int m = 0; m < 4; ++m) _Pragma("unroll") for (int k = 0; k < 2; ++k) dst[m][k] = *(const PG8_LAS bf16x8*)(lds + PG8_SA(b, h) + aoff + m * 2048 + k * 1024); } while (0)
; #define PG8_LDB(dst, b, h) do { _Pragma("unroll") for (int n = 0; n < 2; ++n) _Pragma("unroll") for (int k = 0; k < 2; ++k) dst[n][k] = *(const PG8_LAS bf16x8*)(lds + PG8_SB(b, h) + boff + n * 2048 + k * 1024); } while (0)
; #define PG8_MMA(ai, bj, At, Bt) do { __builtin_amdgcn_s_setprio(1); _Pragma("unroll") for (int m = 0; m < 4; ++m) _Pragma("unroll") for (int n = 0; n < 2; ++n) _Pragma("unroll") for (int k = 0; k < 2; ++k) \
;         acc[ai][bj][m][n] = __builtin_amdgcn_mfma_f32_16x16x32_bf16(Bt[n][k], At[m][k], acc[ai][bj][m][n], 0, 0, 0); __builtin_amdgcn_s_setprio(0); } while (0)
; #define PG8_WAIT_V(n) asm volatile("s_waitcnt vmcnt(" #n ")" ::: "memory")
; #define PG8_WAIT_L(n) asm volatile("s_waitcnt lgkmcnt(" #n ")" ::: "memory")
; #define PG8_BAR __builtin_amdgcn_s_barrier()
; #define PG8_SCHED __builtin_amdgcn_sched_barrier(0)
; template <class Epi, class Sched>
; __device__ __forceinline__ void gemm_phase(PG8_LAS unsigned char* lds, const Gemm g, const Sched& S, const Epi& E) {
;     ...
;             PG8_LDB(B1, 0, 1); PG8_STAGE(PG8_SB(0, 0), b2, voffB);
;             PG8_BAR; PG8_WAIT_L(0); PG8_MMA(0, 1, At, B1); PG8_BAR;
;             PG8_LDA(At, 0, 1); PG8_STAGE(PG8_SA(0, 0), a2, voffA);
;             PG8_BAR; PG8_WAIT_L(0); PG8_MMA(1, 0, At, B0); PG8_BAR; PG8_SCHED;
;             PG8_STAGE(PG8_SB(0, 1), b2 + hstepB, voffB);
;             PG8_WAIT_V(6); PG8_BAR; PG8_MMA(1, 1, At, B1); PG8_BAR;
;             PG8_LDB(B0, 1, 0); PG8_SCHED; PG8_LDA(At, 1, 0); PG8_STAGE(PG8_SA(0, 1), a2 + hstep, voffA);
;             PG8_WAIT_L(8); PG8_BAR; PG8_WAIT_L(0); PG8_MMA(0, 0, At, B0); PG8_BAR; PG8_SCHED;
	s_waitcnt lgkmcnt(0)
	s_setprio 1
	s_waitcnt lgkmcnt(0)
	v_mfma_f32_16x16x32_bf16 v[116:119], v[200:203], v[168:171], v[116:119]
	v_mfma_f32_16x16x32_bf16 v[112:115], v[208:211], v[168:171], v[112:115]
	v_mfma_f32_16x16x32_bf16 v[100:103], v[200:203], v[176:179], v[100:103]
	v_mfma_f32_16x16x32_bf16 v[96:99], v[208:211], v[176:179], v[96:99]
	v_mfma_f32_16x16x32_bf16 v[84:87], v[200:203], v[184:187], v[84:87]
	v_mfma_f32_16x16x32_bf16 v[80:83], v[208:211], v[184:187], v[80:83]
	v_mfma_f32_16x16x32_bf16 v[68:71], v[200:203], v[192:195], v[68:71]
	v_mfma_f32_16x16x32_bf16 v[64:67], v[208:211], v[192:195], v[64:67]
	v_mfma_f32_16x16x32_bf16 v[116:119], v[204:207], v[172:175], v[116:119]
	v_mfma_f32_16x16x32_bf16 v[112:115], v[212:215], v[172:175], v[112:115]
	v_mfma_f32_16x16x32_bf16 v[100:103], v[204:207], v[180:183], v[100:103]
	v_mfma_f32_16x16x32_bf16 v[96:99], v[212:215], v[180:183], v[96:99]
	v_mfma_f32_16x16x32_bf16 v[84:87], v[204:207], v[188:191], v[84:87]
	v_mfma_f32_16x16x32_bf16 v[80:83], v[212:215], v[188:191], v[80:83]
	v_mfma_f32_16x16x32_bf16 v[68:71], v[204:207], v[196:199], v[68:71]
	v_mfma_f32_16x16x32_bf16 v[64:67], v[212:215], v[196:199], v[64:67]
	s_setprio 0
	s_mov_b32 m0, s51
	v_lshl_add_u64 v[148:149], s[30:31], 0, v[130:131]
	s_barrier
	ds_read_b128 v[168:171], v154 offset:16384
	ds_read_b128 v[172:175], v154 offset:17408
	ds_read_b128 v[176:179], v154 offset:18432
	ds_read_b128 v[180:183], v154 offset:19456
	ds_read_b128 v[184:187], v154 offset:20480
	ds_read_b128 v[188:191], v154 offset:21504
	ds_read_b128 v[192:195], v154 offset:22528
	ds_read_b128 v[196:199], v154 offset:23552
	global_load_lds_dwordx4 v[148:149], off
	v_lshl_add_u64 v[216:217], s[30:31], 0, v[134:135]
	s_mov_b32 m0, s52
	s_nop 0
	global_load_lds_dwordx4 v[216:217], off
	s_barrier
	s_waitcnt lgkmcnt(0)
	s_setprio 1
	s_waitcnt lgkmcnt(0)
	v_mfma_f32_16x16x32_bf16 v[60:63], v[144:147], v[168:171], v[60:63]
	v_mfma_f32_16x16x32_bf16 v[56:59], v[160:163], v[168:171], v[56:59]
	v_mfma_f32_16x16x32_bf16 v[44:47], v[144:147], v[176:179], v[44:47]
	v_mfma_f32_16x16x32_bf16 v[40:43], v[160:163], v[176:179], v[40:43]
	v_mfma_f32_16x16x32_bf16 v[28:31], v[144:147], v[184:187], v[28:31]
	v_mfma_f32_16x16x32_bf16 v[24:27], v[160:163], v[184:187], v[24:27]
	v_mfma_f32_16x16x32_bf16 v[12:15], v[144:147], v[192:195], v[12:15]
	v_mfma_f32_16x16x32_bf16 v[8:11], v[160:163], v[192:195], v[8:11]
	v_mfma_f32_16x16x32_bf16 v[60:63], v[156:159], v[172:175], v[60:63]
	v_mfma_f32_16x16x32_bf16 v[56:59], v[164:167], v[172:175], v[56:59]
	v_mfma_f32_16x16x32_bf16 v[44:47], v[156:159], v[180:183], v[44:47]
	v_mfma_f32_16x16x32_bf16 v[40:43], v[164:167], v[180:183], v[40:43]
	v_mfma_f32_16x16x32_bf16 v[28:31], v[156:159], v[188:191], v[28:31]
	v_mfma_f32_16x16x32_bf16 v[24:27], v[164:167], v[188:191], v[24:27]
	v_mfma_f32_16x16x32_bf16 v[12:15], v[156:159], v[196:199], v[12:15]
	v_mfma_f32_16x16x32_bf16 v[8:11], v[164:167], v[196:199], v[8:11]
	s_setprio 0
	s_barrier
	s_add_u32 s24, s28, 0x4000
	s_addc_u32 s25, s29, 0
	s_add_i32 s68, s60, s50
	v_lshl_add_u64 v[144:145], s[24:25], 0, v[128:129]
	s_mov_b32 m0, s68
	s_nop 0
	global_load_lds_dwordx4 v[144:145], off
	v_lshl_add_u64 v[144:145], s[24:25], 0, v[132:133]
	s_add_i32 m0, s68, 0x2000
	s_nop 0
	global_load_lds_dwordx4 v[144:145], off
	s_waitcnt vmcnt(6)
	s_barrier
	s_setprio 1
	v_mfma_f32_16x16x32_bf16 v[52:55], v[200:203], v[168:171], v[52:55]
	v_mfma_f32_16x16x32_bf16 v[48:51], v[208:211], v[168:171], v[48:51]
	v_mfma_f32_16x16x32_bf16 v[36:39], v[200:203], v[176:179], v[36:39]
	v_mfma_f32_16x16x32_bf16 v[32:35], v[208:211], v[176:179], v[32:35]
	v_mfma_f32_16x16x32_bf16 v[20:23], v[200:203], v[184:187], v[20:23]
	v_mfma_f32_16x16x32_bf16 v[16:19], v[208:211], v[184:187], v[16:19]
	v_mfma_f32_16x16x32_bf16 v[4:7], v[200:203], v[192:195], v[4:7]
	v_mfma_f32_16x16x32_bf16 v[0:3], v[208:211], v[192:195], v[0:3]
	v_mfma_f32_16x16x32_bf16 v[52:55], v[204:207], v[172:175], v[52:55]
	v_mfma_f32_16x16x32_bf16 v[48:51], v[212:215], v[172:175], v[48:51]
	v_mfma_f32_16x16x32_bf16 v[36:39], v[204:207], v[180:183], v[36:39]
	v_mfma_f32_16x16x32_bf16 v[32:35], v[212:215], v[180:183], v[32:35]
	v_mfma_f32_16x16x32_bf16 v[20:23], v[204:207], v[188:191], v[20:23]
	v_mfma_f32_16x16x32_bf16 v[16:19], v[212:215], v[188:191], v[16:19]
	v_mfma_f32_16x16x32_bf16 v[4:7], v[204:207], v[196:199], v[4:7]
	v_mfma_f32_16x16x32_bf16 v[0:3], v[212:215], v[196:199], v[0:3]
	s_setprio 0
	s_add_i32 s68, 0, 0x18000
	v_add_u32_e32 v164, s68, v151
	s_barrier
	ds_read_b128 v[144:147], v164
	ds_read_b128 v[156:159], v164 offset:1024
	ds_read_b128 v[160:163], v164 offset:2048
	ds_read_b128 v[164:167], v164 offset:3072
	s_add_u32 s24, s30, 0x158000
	s_addc_u32 s25, s31, 0
	s_mov_b32 m0, s53
	v_lshl_add_u64 v[200:201], s[24:25], 0, v[130:131]
	ds_read_b128 v[168:171], v154 offset:32768
	ds_read_b128 v[172:175], v154 offset:33792
	ds_read_b128 v[176:179], v154 offset:34816
	ds_read_b128 v[180:183], v154 offset:35840
	ds_read_b128 v[184:187], v154 offset:36864
	ds_read_b128 v[188:191], v154 offset:37888
	ds_read_b128 v[192:195], v154 offset:38912
	ds_read_b128 v[196:199], v154 offset:39936
	global_load_lds_dwordx4 v[200:201], off
	v_lshl_add_u64 v[200:201], s[24:25], 0, v[134:135]
	s_mov_b32 m0, s54
	s_nop 0
	global_load_lds_dwordx4 v[200:201], off
	s_waitcnt lgkmcnt(8)
	s_barrier
; #define PG8_STAGE(bufoff, gbase, voff) do { _Pragma("unroll") for (int _i = 0; _i < 2; ++_i) \
;         __builtin_amdgcn_global_load_lds((const unsigned*)((const char*)(gbase) + (voff)[_i]), (PG8_LAS unsigned*)(lds + (bufoff) + ldsw + _i * 8192), 16, 0, 0); } while (0)
; #define PG8_LDA(dst, b, h) do { _Pragma("unroll") for (int m = 0; m < 4; ++m) _Pragma("unroll") for (int k = 0; k < 2; ++k) dst[m][k] = *(const PG8_LAS bf16x8*)(lds + PG8_SA(b, h) + aoff + m * 2048 + k * 1024); } while (0)
; #define PG8_LDB(dst, b, h) do { _Pragma("unroll") for (int n = 0; n < 2; ++n) _Pragma("unroll") for (int k = 0; k < 2; ++k) dst[n][k] = *(const PG8_LAS bf16x8*)(lds + PG8_SB(b, h) + boff + n * 2048 + k * 1024); } while (0)
; #define PG8_MMA(ai, bj, At, Bt) do { __builtin_amdgcn_s_setprio(1); _Pragma("unroll") for (int m = 0; m < 4; ++m) _Pragma("unroll") for (int n = 0; n < 2; ++n) _Pragma("unroll") for (int k = 0; k < 2; ++k) \
;         acc[ai][bj][m][n] = __builtin_amdgcn_mfma_f32_16x16x32_bf16(Bt[n][k], At[m][k], acc[ai][bj][m][n], 0, 0, 0); __builtin_amdgcn_s_setprio(0); } while (0)
; #define PG8_WAIT_V(n) asm volatile("s_waitcnt vmcnt(" #n ")" ::: "memory")
; #define PG8_WAIT_L(n) asm volatile("s_waitcnt lgkmcnt(" #n ")" ::: "memory")
; #define PG8_BAR __builtin_amdgcn_s_barrier()
; #define PG8_SCHED __builtin_amdgcn_sched_barrier(0)
; template <class Epi, class Sched>
; __device__ __forceinline__ void gemm_phase(PG8_LAS unsigned char* lds, const Gemm g, const Sched& S, const Epi& E) {
;     ...
;             PG8_WAIT_L(8); PG8_BAR; PG8_WAIT_L(0); PG8_MMA(0, 0, At, B0); PG8_BAR; PG8_SCHED;
;             PG8_LDB(B1, 1, 1); PG8_STAGE(PG8_SB(1, 0), b3, voffB);
;             PG8_BAR; PG8_WAIT_L(0); PG8_MMA(0, 1, At, B1); PG8_BAR;
;             PG8_LDA(At, 1, 1); PG8_STAGE(PG8_SA(1, 0), a3, voffA);
;             PG8_BAR; PG8_WAIT_L(0); PG8_MMA(1, 0, At, B0); PG8_BAR; PG8_SCHED;
;             PG8_STAGE(PG8_SB(1, 1), b3 + hstepB, voffB);
;             PG8_WAIT_V(6); PG8_BAR; PG8_MMA(1, 1, At, B1); PG8_BAR;
;         }
;         if constexpr (!Epi::AFTER_DRAIN) { E(acc, cur, wr, wc, fr, fq); if constexpr (Epi::IDEMP && EPI_REP > 1) { asm volatile("" ::: "memory"); E(acc, cur, wr, wc, fr, fq); } S.done(cur); }
	s_waitcnt lgkmcnt(0)
	s_setprio 1
	s_waitcnt lgkmcnt(0)
	v_mfma_f32_16x16x32_bf16 v[124:127], v[144:147], v[168:171], v[124:127]
	v_mfma_f32_16x16x32_bf16 v[120:123], v[160:163], v[168:171], v[120:123]
	v_mfma_f32_16x16x32_bf16 v[108:111], v[144:147], v[176:179], v[108:111]
	v_mfma_f32_16x16x32_bf16 v[104:107], v[160:163], v[176:179], v[104:107]
	v_mfma_f32_16x16x32_bf16 v[92:95], v[144:147], v[184:187], v[92:95]
	v_mfma_f32_16x16x32_bf16 v[88:91], v[160:163], v[184:187], v[88:91]
	v_mfma_f32_16x16x32_bf16 v[76:79], v[144:147], v[192:195], v[76:79]
	v_mfma_f32_16x16x32_bf16 v[72:75], v[160:163], v[192:195], v[72:75]
	v_mfma_f32_16x16x32_bf16 v[124:127], v[156:159], v[172:175], v[124:127]
	v_mfma_f32_16x16x32_bf16 v[120:123], v[164:167], v[172:175], v[120:123]
	v_mfma_f32_16x16x32_bf16 v[108:111], v[156:159], v[180:183], v[108:111]
	v_mfma_f32_16x16x32_bf16 v[104:107], v[164:167], v[180:183], v[104:107]
	v_mfma_f32_16x16x32_bf16 v[92:95], v[156:159], v[188:191], v[92:95]
	v_mfma_f32_16x16x32_bf16 v[88:91], v[164:167], v[188:191], v[88:91]
	v_mfma_f32_16x16x32_bf16 v[76:79], v[156:159], v[196:199], v[76:79]
	v_mfma_f32_16x16x32_bf16 v[72:75], v[164:167], v[196:199], v[72:75]
	s_setprio 0
	s_barrier
	s_add_i32 s30, 0, 0x1c000
	s_add_u32 s24, s28, 0x8000
	s_addc_u32 s25, s29, 0
	s_add_i32 s31, s68, s50
	v_add_u32_e32 v212, s30, v151
	v_lshl_add_u64 v[218:219], s[24:25], 0, v[128:129]
	s_mov_b32 m0, s31
	ds_read_b128 v[200:203], v212
	ds_read_b128 v[204:207], v212 offset:1024
	ds_read_b128 v[208:211], v212 offset:2048
	ds_read_b128 v[212:215], v212 offset:3072
	global_load_lds_dwordx4 v[218:219], off
	v_lshl_add_u64 v[218:219], s[24:25], 0, v[132:133]
	s_add_i32 m0, s31, 0x2000
	s_nop 0
	global_load_lds_dwordx4 v[218:219], off
	s_barrier
	s_waitcnt lgkmcnt(0)
	s_setprio 1
	s_waitcnt lgkmcnt(0)
	v_mfma_f32_16x16x32_bf16 v[116:119], v[200:203], v[168:171], v[116:119]
	v_mfma_f32_16x16x32_bf16 v[112:115], v[208:211], v[168:171], v[112:115]
	v_mfma_f32_16x16x32_bf16 v[100:103], v[200:203], v[176:179], v[100:103]
	v_mfma_f32_16x16x32_bf16 v[96:99], v[208:211], v[176:179], v[96:99]
	v_mfma_f32_16x16x32_bf16 v[84:87], v[200:203], v[184:187], v[84:87]
	v_mfma_f32_16x16x32_bf16 v[80:83], v[208:211], v[184:187], v[80:83]
	v_mfma_f32_16x16x32_bf16 v[68:71], v[200:203], v[192:195], v[68:71]
	v_mfma_f32_16x16x32_bf16 v[64:67], v[208:211], v[192:195], v[64:67]
	v_mfma_f32_16x16x32_bf16 v[116:119], v[204:207], v[172:175], v[116:119]
	v_mfma_f32_16x16x32_bf16 v[112:115], v[212:215], v[172:175], v[112:115]
	v_mfma_f32_16x16x32_bf16 v[100:103], v[204:207], v[180:183], v[100:103]
	v_mfma_f32_16x16x32_bf16 v[96:99], v[212:215], v[180:183], v[96:99]
	v_mfma_f32_16x16x32_bf16 v[84:87], v[204:207], v[188:191], v[84:87]
	v_mfma_f32_16x16x32_bf16 v[80:83], v[212:215], v[188:191], v[80:83]
	v_mfma_f32_16x16x32_bf16 v[68:71], v[204:207], v[196:199], v[68:71]
	v_mfma_f32_16x16x32_bf16 v[64:67], v[212:215], v[196:199], v[64:67]
	s_setprio 0
	s_mov_b32 m0, s56
	v_lshl_add_u64 v[148:149], v[148:149], 0, s[14:15]
	s_barrier
	ds_read_b128 v[168:171], v154 offset:49152
	ds_read_b128 v[172:175], v154 offset:50176
	ds_read_b128 v[176:179], v154 offset:51200
	ds_read_b128 v[180:183], v154 offset:52224
	ds_read_b128 v[184:187], v154 offset:53248
	ds_read_b128 v[188:191], v154 offset:54272
	ds_read_b128 v[192:195], v154 offset:55296
	ds_read_b128 v[196:199], v154 offset:56320
	global_load_lds_dwordx4 v[148:149], off
	v_lshl_add_u64 v[148:149], v[216:217], 0, s[14:15]
	s_mov_b32 m0, s57
	s_nop 0
	global_load_lds_dwordx4 v[148:149], off
	s_barrier
	s_waitcnt lgkmcnt(0)
	s_setprio 1
	s_waitcnt lgkmcnt(0)
	v_mfma_f32_16x16x32_bf16 v[60:63], v[144:147], v[168:171], v[60:63]
	v_mfma_f32_16x16x32_bf16 v[56:59], v[160:163], v[168:171], v[56:59]
	v_mfma_f32_16x16x32_bf16 v[44:47], v[144:147], v[176:179], v[44:47]
	v_mfma_f32_16x16x32_bf16 v[40:43], v[160:163], v[176:179], v[40:43]
	v_mfma_f32_16x16x32_bf16 v[28:31], v[144:147], v[184:187], v[28:31]
	v_mfma_f32_16x16x32_bf16 v[24:27], v[160:163], v[184:187], v[24:27]
	v_mfma_f32_16x16x32_bf16 v[12:15], v[144:147], v[192:195], v[12:15]
	v_mfma_f32_16x16x32_bf16 v[8:11], v[160:163], v[192:195], v[8:11]
	v_mfma_f32_16x16x32_bf16 v[60:63], v[156:159], v[172:175], v[60:63]
	v_mfma_f32_16x16x32_bf16 v[56:59], v[164:167], v[172:175], v[56:59]
	v_mfma_f32_16x16x32_bf16 v[44:47], v[156:159], v[180:183], v[44:47]
	v_mfma_f32_16x16x32_bf16 v[40:43], v[164:167], v[180:183], v[40:43]
	v_mfma_f32_16x16x32_bf16 v[28:31], v[156:159], v[188:191], v[28:31]
	v_mfma_f32_16x16x32_bf16 v[24:27], v[164:167], v[188:191], v[24:27]
	v_mfma_f32_16x16x32_bf16 v[12:15], v[156:159], v[196:199], v[12:15]
	v_mfma_f32_16x16x32_bf16 v[8:11], v[164:167], v[196:199], v[8:11]
	s_setprio 0
	s_barrier
	s_add_u32 s24, s28, 0xc000
	s_addc_u32 s25, s29, 0
	s_add_i32 s28, s30, s50
	v_lshl_add_u64 v[144:145], s[24:25], 0, v[128:129]
	s_mov_b32 m0, s28
	s_nop 0
	global_load_lds_dwordx4 v[144:145], off
	v_lshl_add_u64 v[144:145], s[24:25], 0, v[132:133]
	s_add_i32 m0, s28, 0x2000
	s_nop 0
	global_load_lds_dwordx4 v[144:145], off
	s_waitcnt vmcnt(6)
	s_barrier
	s_setprio 1
	v_mfma_f32_16x16x32_bf16 v[52:55], v[200:203], v[168:171], v[52:55]
	v_mfma_f32_16x16x32_bf16 v[48:51], v[208:211], v[168:171], v[48:51]
	v_mfma_f32_16x16x32_bf16 v[36:39], v[200:203], v[176:179], v[36:39]
	v_mfma_f32_16x16x32_bf16 v[32:35], v[208:211], v[176:179], v[32:35]
	v_mfma_f32_16x16x32_bf16 v[20:23], v[200:203], v[184:187], v[20:23]
	v_mfma_f32_16x16x32_bf16 v[16:19], v[208:211], v[184:187], v[16:19]
	v_mfma_f32_16x16x32_bf16 v[4:7], v[200:203], v[192:195], v[4:7]
	v_mfma_f32_16x16x32_bf16 v[0:3], v[208:211], v[192:195], v[0:3]
	v_mfma_f32_16x16x32_bf16 v[52:55], v[204:207], v[172:175], v[52:55]
	v_mfma_f32_16x16x32_bf16 v[48:51], v[212:215], v[172:175], v[48:51]
	v_mfma_f32_16x16x32_bf16 v[36:39], v[204:207], v[180:183], v[36:39]
	v_mfma_f32_16x16x32_bf16 v[32:35], v[212:215], v[180:183], v[32:35]
	v_mfma_f32_16x16x32_bf16 v[20:23], v[204:207], v[188:191], v[20:23]
	v_mfma_f32_16x16x32_bf16 v[16:19], v[212:215], v[188:191], v[16:19]
	v_mfma_f32_16x16x32_bf16 v[4:7], v[204:207], v[196:199], v[4:7]
	v_mfma_f32_16x16x32_bf16 v[0:3], v[212:215], v[196:199], v[0:3]
	s_setprio 0
	s_add_i32 s67, s67, 2
	s_add_u32 s65, s65, 0x10000
	s_addc_u32 s66, s66, 0
	s_cmpk_gt_u32 s67, 0x53
	s_mov_b64 s[24:25], s[26:27]
	s_barrier
	s_cbranch_scc0 .LBB0_155
	s_cmp_eq_u32 s78, 0
	s_cbranch_scc0 .Lhalf_skip_x_1
	s_barrier
; __device__ __forceinline__ unsigned cvt_pk_bf16(float lo, float hi) { unsigned r; asm volatile("v_cvt_pk_bf16_f32 %0, %1, %2" : "=v"(r) : "v"(lo), "v"(hi)); return r; }
;     __device__ __forceinline__ void operator()(const f32x4 (&acc)[2][2][4][2], const Unit& u, int wr, int wc, int fr, int fq) const {
;         const int row0 = u.pm * BM + wr * 64 + fr, col0 = u.pn * BM + wc * 32 + 8 * fq;
;         if (FIRST) {
; #pragma unroll
;             for (int ai = 0; ai < 2; ++ai)
; #pragma unroll
;                 for (int m = 0; m < 4; ++m) { const size_t off = (size_t)(row0 + ai * HALF + m * 16) * 2048 + col0;
; #pragma unroll
;                     for (int bj = 0; bj < 2; ++bj) { const size_t o = off + bj * HALF; const f32x4 r0 = *(const f32x4*)(X + o), r1 = *(const f32x4*)(X + o + 4);
;                         const f32x4 v0 = r0 + acc[ai][bj][m][0] * scale, v1 = r1 + acc[ai][bj][m][1] * scale;
;                         u32x4 w; w.x = cvt_pk_bf16(v0[0], v0[1]); w.y = cvt_pk_bf16(v0[2], v0[3]); w.z = cvt_pk_bf16(v1[0], v1[1]); w.w = cvt_pk_bf16(v1[2], v1[3]);
;                         *(u32x4*)(H + o) = w; } }
.Lhalf_skip_x_1:
	v_lshl_add_u32 v148, s63, 8, v150
	v_lshl_or_b32 v146, s64, 8, v152
	v_ashrrev_i32_e32 v149, 31, v148
	v_ashrrev_i32_e32 v147, 31, v146
	v_lshlrev_b64 v[144:145], 11, v[148:149]
	v_lshl_add_u64 v[144:145], v[144:145], 0, v[146:147]
	v_lshl_add_u64 v[164:165], v[144:145], 2, s[10:11]
	global_load_dwordx4 v[156:159], v[164:165], off
	global_load_dwordx4 v[160:163], v[164:165], off offset:16
	v_lshlrev_b64 v[166:167], 1, v[144:145]
	v_lshl_add_u64 v[168:169], s[12:13], 0, v[166:167]
	v_or_b32_e32 v166, 0x100, v166
	s_and_b64 vcc, exec, s[4:5]
	s_mov_b32 s64, s62
	s_mov_b32 s63, s61
	s_mov_b64 s[26:27], s[8:9]
	s_mov_b64 s[24:25], s[6:7]
	s_waitcnt vmcnt(0)
	v_pk_fma_f32 v[124:125], v[124:125], 0.5, v[156:157] op_sel_hi:[1,0,1]
	v_pk_fma_f32 v[156:157], v[122:123], 0.5, v[162:163] op_sel_hi:[1,0,1]
	v_pk_fma_f32 v[122:123], v[120:121], 0.5, v[160:161] op_sel_hi:[1,0,1]
	v_pk_fma_f32 v[126:127], v[126:127], 0.5, v[158:159] op_sel_hi:[1,0,1]
	v_cvt_pk_bf16_f32 v120, v124, v125
	v_lshl_add_u64 v[160:161], s[12:13], 0, v[166:167]
	v_cvt_pk_bf16_f32 v121, v126, v127
	v_cvt_pk_bf16_f32 v122, v122, v123
	v_cvt_pk_bf16_f32 v123, v156, v157
	global_store_dwordx4 v[168:169], v[120:123], off
	global_load_dwordx4 v[120:123], v[164:165], off offset:512
	s_nop 0
	global_load_dwordx4 v[124:127], v[164:165], off offset:528
	v_or_b32_e32 v156, 16, v148
	v_ashrrev_i32_e32 v157, 31, v156
	v_lshlrev_b64 v[156:157], 11, v[156:157]
	v_lshl_add_u64 v[156:157], v[156:157], 0, v[146:147]
	v_lshl_add_u64 v[158:159], v[156:157], 2, s[10:11]
	s_waitcnt vmcnt(0)
	v_pk_fma_f32 v[116:117], v[116:117], 0.5, v[120:121] op_sel_hi:[1,0,1]
	v_pk_fma_f32 v[120:121], v[114:115], 0.5, v[126:127] op_sel_hi:[1,0,1]
	v_pk_fma_f32 v[114:115], v[112:113], 0.5, v[124:125] op_sel_hi:[1,0,1]
	v_pk_fma_f32 v[118:119], v[118:119], 0.5, v[122:123] op_sel_hi:[1,0,1]
	v_cvt_pk_bf16_f32 v112, v116, v117
	s_nop 0
	v_cvt_pk_bf16_f32 v113, v118, v119
	v_cvt_pk_bf16_f32 v114, v114, v115
	v_cvt_pk_bf16_f32 v115, v120, v121
	global_store_dwordx4 v[160:161], v[112:115], off
	global_load_dwordx4 v[112:115], v[158:159], off
	s_nop 0
	global_load_dwordx4 v[116:119], v[158:159], off offset:16
	v_lshlrev_b64 v[120:121], 1, v[156:157]
	v_lshl_add_u64 v[122:123], s[12:13], 0, v[120:121]
	v_or_b32_e32 v120, 0x100, v120
	s_waitcnt vmcnt(0)
	v_pk_fma_f32 v[108:109], v[108:109], 0.5, v[112:113] op_sel_hi:[1,0,1]
	v_pk_fma_f32 v[112:113], v[106:107], 0.5, v[118:119] op_sel_hi:[1,0,1]
	v_pk_fma_f32 v[106:107], v[104:105], 0.5, v[116:117] op_sel_hi:[1,0,1]
	v_pk_fma_f32 v[110:111], v[110:111], 0.5, v[114:115] op_sel_hi:[1,0,1]
	v_cvt_pk_bf16_f32 v104, v108, v109
	v_lshl_add_u64 v[116:117], s[12:13], 0, v[120:121]
	v_cvt_pk_bf16_f32 v105, v110, v111
	v_cvt_pk_bf16_f32 v106, v106, v107
	v_cvt_pk_bf16_f32 v107, v112, v113
	global_store_dwordx4 v[122:123], v[104:107], off
	global_load_dwordx4 v[104:107], v[158:159], off offset:512
	s_nop 0
	global_load_dwordx4 v[108:111], v[158:159], off offset:528
	v_or_b32_e32 v112, 32, v148
	v_ashrrev_i32_e32 v113, 31, v112
	v_lshlrev_b64 v[112:113], 11, v[112:113]
	v_lshl_add_u64 v[112:113], v[112:113], 0, v[146:147]
	v_lshl_add_u64 v[114:115], v[112:113], 2, s[10:11]
	s_waitcnt vmcnt(0)
	v_pk_fma_f32 v[100:101], v[100:101], 0.5, v[104:105] op_sel_hi:[1,0,1]
	v_pk_fma_f32 v[104:105], v[98:99], 0.5, v[110:111] op_sel_hi:[1,0,1]
	v_pk_fma_f32 v[98:99], v[96:97], 0.5, v[108:109] op_sel_hi:[1,0,1]
	v_pk_fma_f32 v[102:103], v[102:103], 0.5, v[106:107] op_sel_hi:[1,0,1]
	v_cvt_pk_bf16_f32 v96, v100, v101
	s_nop 0
	v_cvt_pk_bf16_f32 v97, v102, v103
	v_cvt_pk_bf16_f32 v98, v98, v99
	v_cvt_pk_bf16_f32 v99, v104, v105
	global_store_dwordx4 v[116:117], v[96:99], off
	global_load_dwordx4 v[96:99], v[114:115], off
	s_nop 0
	global_load_dwordx4 v[100:103], v[114:115], off offset:16
	v_lshlrev_b64 v[104:105], 1, v[112:113]
	v_lshl_add_u64 v[106:107], s[12:13], 0, v[104:105]
	v_or_b32_e32 v104, 0x100, v104
	s_waitcnt vmcnt(0)
	v_pk_fma_f32 v[92:93], v[92:93], 0.5, v[96:97] op_sel_hi:[1,0,1]
	v_pk_fma_f32 v[96:97], v[90:91], 0.5, v[102:103] op_sel_hi:[1,0,1]
	v_pk_fma_f32 v[90:91], v[88:89], 0.5, v[100:101] op_sel_hi:[1,0,1]
	v_pk_fma_f32 v[94:95], v[94:95], 0.5, v[98:99] op_sel_hi:[1,0,1]
	v_cvt_pk_bf16_f32 v88, v92, v93
	v_lshl_add_u64 v[100:101], s[12:13], 0, v[104:105]
	v_cvt_pk_bf16_f32 v89, v94, v95
	v_cvt_pk_bf16_f32 v90, v90, v91
	v_cvt_pk_bf16_f32 v91, v96, v97
	global_store_dwordx4 v[106:107], v[88:91], off
	global_load_dwordx4 v[88:91], v[114:115], off offset:512
	s_nop 0
	global_load_dwordx4 v[92:95], v[114:115], off offset:528
	v_or_b32_e32 v96, 48, v148
	v_ashrrev_i32_e32 v97, 31, v96
	v_lshlrev_b64 v[96:97], 11, v[96:97]
	v_lshl_add_u64 v[96:97], v[96:97], 0, v[146:147]
	v_lshl_add_u64 v[98:99], v[96:97], 2, s[10:11]
	s_waitcnt vmcnt(0)
	v_pk_fma_f32 v[84:85], v[84:85], 0.5, v[88:89] op_sel_hi:[1,0,1]
	v_pk_fma_f32 v[88:89], v[82:83], 0.5, v[94:95] op_sel_hi:[1,0,1]
	v_pk_fma_f32 v[82:83], v[80:81], 0.5, v[92:93] op_sel_hi:[1,0,1]
	v_pk_fma_f32 v[86:87], v[86:87], 0.5, v[90:91] op_sel_hi:[1,0,1]
	v_cvt_pk_bf16_f32 v80, v84, v85
	s_nop 0
	v_cvt_pk_bf16_f32 v81, v86, v87
	v_cvt_pk_bf16_f32 v82, v82, v83
	v_cvt_pk_bf16_f32 v83, v88, v89
	global_store_dwordx4 v[100:101], v[80:83], off
	global_load_dwordx4 v[80:83], v[98:99], off
	s_nop 0
	global_load_dwordx4 v[84:87], v[98:99], off offset:16
	v_lshlrev_b64 v[88:89], 1, v[96:97]
	v_lshl_add_u64 v[90:91], s[12:13], 0, v[88:89]
	v_or_b32_e32 v88, 0x100, v88
	s_waitcnt vmcnt(0)
; __device__ __forceinline__ unsigned cvt_pk_bf16(float lo, float hi) { unsigned r; asm volatile("v_cvt_pk_bf16_f32 %0, %1, %2" : "=v"(r) : "v"(lo), "v"(hi)); return r; }
; #define PG8_WAIT_V(n) asm volatile("s_waitcnt vmcnt(" #n ")" ::: "memory")
; #define PG8_BAR __builtin_amdgcn_s_barrier()
;     __device__ __forceinline__ void operator()(const f32x4 (&acc)[2][2][4][2], const Unit& u, int wr, int wc, int fr, int fq) const {
;     ...
;             for (int ai = 0; ai < 2; ++ai)
; #pragma unroll
;                 for (int m = 0; m < 4; ++m) { const size_t off = (size_t)(row0 + ai * HALF + m * 16) * 2048 + col0;
; #pragma unroll
;                     for (int bj = 0; bj < 2; ++bj) { const size_t o = off + bj * HALF; const f32x4 r0 = *(const f32x4*)(X + o), r1 = *(const f32x4*)(X + o + 4);
;                         const f32x4 v0 = r0 + acc[ai][bj][m][0] * scale, v1 = r1 + acc[ai][bj][m][1] * scale;
;                         u32x4 w; w.x = cvt_pk_bf16(v0[0], v0[1]); w.y = cvt_pk_bf16(v0[2], v0[3]); w.z = cvt_pk_bf16(v1[0], v1[1]); w.w = cvt_pk_bf16(v1[2], v1[3]);
;                         *(u32x4*)(H + o) = w; } }
; template <class Epi, class Sched>
; __device__ __forceinline__ void gemm_phase(PG8_LAS unsigned char* lds, const Gemm g, const Sched& S, const Epi& E) {
;     ...
;         if (!has_next) break;
;         if (!(Epi::CHAIN && cur.br < 2))
; #pragma unroll
;         for (int a = 0; a < 2; ++a)
; #pragma unroll
;             for (int b = 0; b < 2; ++b)
; #pragma unroll
;                 for (int m = 0; m < 4; ++m)
; #pragma unroll
;                     for (int n = 0; n < 2; ++n) acc[a][b][m][n] = (f32x4){0.f, 0.f, 0.f, 0.f};
;         cur = nxt; cA = nA; cB = nB; ++ui;
;     }
;     PG8_WAIT_V(0);
;     if (wr == 0) PG8_BAR;
;     PG8_BAR;
	v_pk_fma_f32 v[76:77], v[76:77], 0.5, v[80:81] op_sel_hi:[1,0,1]
	v_pk_fma_f32 v[80:81], v[74:75], 0.5, v[86:87] op_sel_hi:[1,0,1]
	v_pk_fma_f32 v[74:75], v[72:73], 0.5, v[84:85] op_sel_hi:[1,0,1]
	v_pk_fma_f32 v[78:79], v[78:79], 0.5, v[82:83] op_sel_hi:[1,0,1]
	v_cvt_pk_bf16_f32 v72, v76, v77
	v_lshl_add_u64 v[84:85], s[12:13], 0, v[88:89]
	v_cvt_pk_bf16_f32 v73, v78, v79
	v_cvt_pk_bf16_f32 v74, v74, v75
	v_cvt_pk_bf16_f32 v75, v80, v81
	global_store_dwordx4 v[90:91], v[72:75], off
	global_load_dwordx4 v[72:75], v[98:99], off offset:512
	s_nop 0
	global_load_dwordx4 v[76:79], v[98:99], off offset:528
	v_lshl_add_u64 v[80:81], v[144:145], 0, s[16:17]
	v_lshl_add_u64 v[82:83], v[80:81], 2, s[10:11]
	s_waitcnt vmcnt(0)
	v_pk_fma_f32 v[68:69], v[68:69], 0.5, v[72:73] op_sel_hi:[1,0,1]
	v_pk_fma_f32 v[72:73], v[66:67], 0.5, v[78:79] op_sel_hi:[1,0,1]
	v_pk_fma_f32 v[66:67], v[64:65], 0.5, v[76:77] op_sel_hi:[1,0,1]
	v_pk_fma_f32 v[70:71], v[70:71], 0.5, v[74:75] op_sel_hi:[1,0,1]
	v_cvt_pk_bf16_f32 v64, v68, v69
	s_nop 0
	v_cvt_pk_bf16_f32 v65, v70, v71
	v_cvt_pk_bf16_f32 v66, v66, v67
	v_cvt_pk_bf16_f32 v67, v72, v73
	global_store_dwordx4 v[84:85], v[64:67], off
	global_load_dwordx4 v[64:67], v[82:83], off
	s_nop 0
	global_load_dwordx4 v[68:71], v[82:83], off offset:16
	v_lshlrev_b64 v[72:73], 1, v[80:81]
	v_lshl_add_u64 v[74:75], s[12:13], 0, v[72:73]
	v_or_b32_e32 v72, 0x100, v72
	s_waitcnt vmcnt(0)
	v_pk_fma_f32 v[60:61], v[60:61], 0.5, v[64:65] op_sel_hi:[1,0,1]
	v_pk_fma_f32 v[64:65], v[58:59], 0.5, v[70:71] op_sel_hi:[1,0,1]
	v_pk_fma_f32 v[58:59], v[56:57], 0.5, v[68:69] op_sel_hi:[1,0,1]
	v_pk_fma_f32 v[62:63], v[62:63], 0.5, v[66:67] op_sel_hi:[1,0,1]
	v_cvt_pk_bf16_f32 v56, v60, v61
	v_lshl_add_u64 v[68:69], s[12:13], 0, v[72:73]
	v_cvt_pk_bf16_f32 v57, v62, v63
	v_cvt_pk_bf16_f32 v58, v58, v59
	v_cvt_pk_bf16_f32 v59, v64, v65
	global_store_dwordx4 v[74:75], v[56:59], off
	global_load_dwordx4 v[56:59], v[82:83], off offset:512
	s_nop 0
	global_load_dwordx4 v[60:63], v[82:83], off offset:528
	v_lshl_add_u64 v[64:65], v[144:145], 0, s[18:19]
	v_lshl_add_u64 v[66:67], v[64:65], 2, s[10:11]
	s_waitcnt vmcnt(0)
	v_pk_fma_f32 v[52:53], v[52:53], 0.5, v[56:57] op_sel_hi:[1,0,1]
	v_pk_fma_f32 v[56:57], v[50:51], 0.5, v[62:63] op_sel_hi:[1,0,1]
	v_pk_fma_f32 v[50:51], v[48:49], 0.5, v[60:61] op_sel_hi:[1,0,1]
	v_pk_fma_f32 v[54:55], v[54:55], 0.5, v[58:59] op_sel_hi:[1,0,1]
	v_cvt_pk_bf16_f32 v48, v52, v53
	s_nop 0
	v_cvt_pk_bf16_f32 v49, v54, v55
	v_cvt_pk_bf16_f32 v50, v50, v51
	v_cvt_pk_bf16_f32 v51, v56, v57
	global_store_dwordx4 v[68:69], v[48:51], off
	global_load_dwordx4 v[48:51], v[66:67], off
	s_nop 0
	global_load_dwordx4 v[52:55], v[66:67], off offset:16
	v_lshlrev_b64 v[56:57], 1, v[64:65]
	v_lshl_add_u64 v[58:59], s[12:13], 0, v[56:57]
	v_or_b32_e32 v56, 0x100, v56
	s_waitcnt vmcnt(0)
	v_pk_fma_f32 v[44:45], v[44:45], 0.5, v[48:49] op_sel_hi:[1,0,1]
	v_pk_fma_f32 v[48:49], v[42:43], 0.5, v[54:55] op_sel_hi:[1,0,1]
	v_pk_fma_f32 v[42:43], v[40:41], 0.5, v[52:53] op_sel_hi:[1,0,1]
	v_pk_fma_f32 v[46:47], v[46:47], 0.5, v[50:51] op_sel_hi:[1,0,1]
	v_cvt_pk_bf16_f32 v40, v44, v45
	v_lshl_add_u64 v[52:53], s[12:13], 0, v[56:57]
	v_cvt_pk_bf16_f32 v41, v46, v47
	v_cvt_pk_bf16_f32 v42, v42, v43
	v_cvt_pk_bf16_f32 v43, v48, v49
	global_store_dwordx4 v[58:59], v[40:43], off
	global_load_dwordx4 v[40:43], v[66:67], off offset:512
	s_nop 0
	global_load_dwordx4 v[44:47], v[66:67], off offset:528
	v_lshl_add_u64 v[48:49], v[144:145], 0, s[20:21]
	v_lshl_add_u64 v[50:51], v[48:49], 2, s[10:11]
	s_waitcnt vmcnt(0)
	v_pk_fma_f32 v[36:37], v[36:37], 0.5, v[40:41] op_sel_hi:[1,0,1]
	v_pk_fma_f32 v[40:41], v[34:35], 0.5, v[46:47] op_sel_hi:[1,0,1]
	v_pk_fma_f32 v[34:35], v[32:33], 0.5, v[44:45] op_sel_hi:[1,0,1]
	v_pk_fma_f32 v[38:39], v[38:39], 0.5, v[42:43] op_sel_hi:[1,0,1]
	v_cvt_pk_bf16_f32 v32, v36, v37
	s_nop 0
	v_cvt_pk_bf16_f32 v33, v38, v39
	v_cvt_pk_bf16_f32 v34, v34, v35
	v_cvt_pk_bf16_f32 v35, v40, v41
	global_store_dwordx4 v[52:53], v[32:35], off
	global_load_dwordx4 v[32:35], v[50:51], off
	s_nop 0
	global_load_dwordx4 v[36:39], v[50:51], off offset:16
	v_lshlrev_b64 v[40:41], 1, v[48:49]
	v_lshl_add_u64 v[42:43], s[12:13], 0, v[40:41]
	v_or_b32_e32 v40, 0x100, v40
	s_waitcnt vmcnt(0)
	v_pk_fma_f32 v[28:29], v[28:29], 0.5, v[32:33] op_sel_hi:[1,0,1]
	v_pk_fma_f32 v[32:33], v[26:27], 0.5, v[38:39] op_sel_hi:[1,0,1]
	v_pk_fma_f32 v[26:27], v[24:25], 0.5, v[36:37] op_sel_hi:[1,0,1]
	v_pk_fma_f32 v[30:31], v[30:31], 0.5, v[34:35] op_sel_hi:[1,0,1]
	v_cvt_pk_bf16_f32 v24, v28, v29
	v_lshl_add_u64 v[36:37], s[12:13], 0, v[40:41]
	v_cvt_pk_bf16_f32 v25, v30, v31
	v_cvt_pk_bf16_f32 v26, v26, v27
	v_cvt_pk_bf16_f32 v27, v32, v33
	global_store_dwordx4 v[42:43], v[24:27], off
	global_load_dwordx4 v[24:27], v[50:51], off offset:512
	s_nop 0
	global_load_dwordx4 v[28:31], v[50:51], off offset:528
	v_lshl_add_u64 v[32:33], v[144:145], 0, s[22:23]
	v_lshl_add_u64 v[34:35], v[32:33], 2, s[10:11]
	s_waitcnt vmcnt(0)
	v_pk_fma_f32 v[20:21], v[20:21], 0.5, v[24:25] op_sel_hi:[1,0,1]
	v_pk_fma_f32 v[24:25], v[18:19], 0.5, v[30:31] op_sel_hi:[1,0,1]
	v_pk_fma_f32 v[18:19], v[16:17], 0.5, v[28:29] op_sel_hi:[1,0,1]
	v_pk_fma_f32 v[22:23], v[22:23], 0.5, v[26:27] op_sel_hi:[1,0,1]
	v_cvt_pk_bf16_f32 v16, v20, v21
	s_nop 0
	v_cvt_pk_bf16_f32 v17, v22, v23
	v_cvt_pk_bf16_f32 v18, v18, v19
	v_cvt_pk_bf16_f32 v19, v24, v25
	global_store_dwordx4 v[36:37], v[16:19], off
	global_load_dwordx4 v[16:19], v[34:35], off
	s_nop 0
	global_load_dwordx4 v[20:23], v[34:35], off offset:16
	v_lshlrev_b64 v[24:25], 1, v[32:33]
	v_lshl_add_u64 v[26:27], s[12:13], 0, v[24:25]
	v_or_b32_e32 v24, 0x100, v24
	s_waitcnt vmcnt(0)
	v_pk_fma_f32 v[12:13], v[12:13], 0.5, v[16:17] op_sel_hi:[1,0,1]
	v_pk_fma_f32 v[16:17], v[10:11], 0.5, v[22:23] op_sel_hi:[1,0,1]
	v_pk_fma_f32 v[10:11], v[8:9], 0.5, v[20:21] op_sel_hi:[1,0,1]
	v_pk_fma_f32 v[14:15], v[14:15], 0.5, v[18:19] op_sel_hi:[1,0,1]
	v_cvt_pk_bf16_f32 v8, v12, v13
	s_nop 0
	v_cvt_pk_bf16_f32 v9, v14, v15
	v_cvt_pk_bf16_f32 v10, v10, v11
	v_cvt_pk_bf16_f32 v11, v16, v17
	global_store_dwordx4 v[26:27], v[8:11], off
	global_load_dwordx4 v[8:11], v[34:35], off offset:512
	s_nop 0
	global_load_dwordx4 v[12:15], v[34:35], off offset:528
	v_lshl_add_u64 v[16:17], s[12:13], 0, v[24:25]
	s_waitcnt vmcnt(0)
	v_pk_fma_f32 v[4:5], v[4:5], 0.5, v[8:9] op_sel_hi:[1,0,1]
	v_pk_fma_f32 v[8:9], v[2:3], 0.5, v[14:15] op_sel_hi:[1,0,1]
	v_pk_fma_f32 v[2:3], v[0:1], 0.5, v[12:13] op_sel_hi:[1,0,1]
	v_pk_fma_f32 v[6:7], v[6:7], 0.5, v[10:11] op_sel_hi:[1,0,1]
	v_cvt_pk_bf16_f32 v0, v4, v5
	s_nop 0
	v_cvt_pk_bf16_f32 v1, v6, v7
	v_cvt_pk_bf16_f32 v2, v2, v3
	v_cvt_pk_bf16_f32 v3, v8, v9
	global_store_dwordx4 v[16:17], v[0:3], off
	s_cbranch_vccz .LBB0_144
	s_waitcnt vmcnt(0)
	s_cmpk_gt_u32 s38, 0xff
	s_cbranch_scc1 .LBB0_159

;     __host__ __device__ bool next(int i, Unit& u) const { const int j = i / 3; if (!StaticOrder::next(j, u)) return false; u.br = i - 3 * j; return true; }
; #define PG8_STAGE(bufoff, gbase, voff) do { _Pragma("unroll") for (int _i = 0; _i < 2; ++_i) \
;         __builtin_amdgcn_global_load_lds((const unsigned*)((const char*)(gbase) + (voff)[_i]), (PG8_LAS unsigned*)(lds + (bufoff) + ldsw + _i * 8192), 16, 0, 0); } while (0)
; template <class Epi, class Sched>
; __device__ __forceinline__ void gemm_phase(PG8_LAS unsigned char* lds, const Gemm g, const Sched& S, const Epi& E) {
;     ...
;     const int tid = tix_, wid = __builtin_amdgcn_readfirstlane(tid >> 6), lane = tid & 63, wr = wid >> 2, wc = wid & 3, fr = lane & 15, fq = lane >> 4;
;     const int K = g.K, nt = K / BK;
;     unsigned voffA[2], voffB[2];
; #pragma unroll
;     for (int i = 0; i < 2; ++i) { int R, C; stage_rc(tid * 16 + i * 8192, R, C);
;         voffA[i] = (unsigned)(R * K + C) * 2u; voffB[i] = (unsigned)(tid * 16 + i * 8192); }
;     const size_t kstep = (size_t)(BK * 2);
;     const size_t hstep = (size_t)HALF * K * 2;
;     const size_t tstep = 2 * hstep;
;     const size_t kstepB = 32768, hstepB = 16384, tstepB = (size_t)nt * 32768;
;     const unsigned ldsw = (unsigned)wid * 1024u;
;     const int aoff = lds_byte(wr * 64 + fr, fq * 8), boff = lds_byte(wc * 32 + fr, fq * 8);
;     ...
;     Unit cur, nxt; int ui = 0;
;     if (!S.next(0, cur)) return;
;     f32x4 acc[2][2][4][2];
; #pragma unroll
;     for (int a = 0; a < 2; ++a)
; #pragma unroll
;         for (int b = 0; b < 2; ++b)
; #pragma unroll
;             for (int m = 0; m < 4; ++m)
; #pragma unroll
;                 for (int n = 0; n < 2; ++n) acc[a][b][m][n] = (f32x4){0.f, 0.f, 0.f, 0.f};
;     bf16x8 At[4][2], B0[2][2], B1[2][2];
;     const char* cA = (const char*)g.A + (size_t)cur.pm * tstep + (size_t)cur.br * g.strideA; const char* cB = (const char*)g.Bt + (size_t)cur.pn * tstepB + (size_t)cur.br * g.strideB;
;     S.a_ready(cur);
;     PG8_STAGE(PG8_SB(0, 0), cB, voffB); PG8_STAGE(PG8_SA(0, 0), cA, voffA); PG8_STAGE(PG8_SB(0, 1), cB + hstepB, voffB); PG8_STAGE(PG8_SA(0, 1), cA + hstep, voffA);
;     if (wr == 1) PG8_BAR;
;     PG8_WAIT_V(4); PG8_BAR;
;     PG8_STAGE(PG8_SB(1, 0), cB + kstepB, voffB); PG8_STAGE(PG8_SA(1, 0), cA + kstep, voffA); PG8_STAGE(PG8_SB(1, 1), cB + hstepB + kstepB, voffB);
;     PG8_WAIT_V(6); PG8_BAR;
.LBB0_271:
	s_andn2_b64 vcc, exec, s[4:5]
	s_cbranch_vccnz .LBB0_379
	v_ashrrev_i32_e32 v0, 31, v4
	v_lshrrev_b32_e32 v0, 26, v0
	v_add_u32_e32 v0, v4, v0
	v_ashrrev_i32_e32 v5, 6, v0
	v_bfe_i32 v0, v4, 27, 1
	v_lshlrev_b32_e32 v128, 4, v4
	v_lshrrev_b32_e32 v0, 22, v0
	v_add_u32_e32 v0, v128, v0
	v_and_b32_e32 v0, 0xfffffc00, v0
	v_sub_u32_e32 v0, v128, v0
	v_lshrrev_b32_e32 v1, 4, v0
	v_bitop3_b32 v0, v1, v0, 32 bitop3:0x6c
	v_ashrrev_i32_e32 v2, 31, v0
	v_lshrrev_b32_e32 v2, 26, v2
	v_add_u32_e32 v2, v0, v2
	v_ashrrev_i32_e32 v6, 6, v2
	v_and_b32_e32 v2, 0xc0, v2
	v_sub_u32_e32 v0, v0, v2
	v_mov_b32_e32 v2, 1
	v_lshlrev_b32_e32 v1, 3, v5
	v_lshlrev_b32_e32 v3, 5, v5
	v_ashrrev_i16_sdwa v0, v2, sext(v0) dst_sel:DWORD dst_unused:UNUSED_PAD src0_sel:DWORD src1_sel:BYTE_0
	v_and_b32_e32 v1, 0xffff0, v1
	v_and_b32_e32 v3, 32, v3
	v_bfe_i32 v7, v0, 0, 16
	v_add_u32_e32 v0, v3, v7
	v_add_lshl_u32 v1, v6, v1, 12
	v_add_u32_e32 v132, 0x2000, v128
	v_lshl_add_u32 v130, v0, 1, v1
	v_ashrrev_i32_e32 v0, 31, v132
	v_lshrrev_b32_e32 v0, 22, v0
	v_add_u32_e32 v0, v132, v0
	v_ashrrev_i32_e32 v8, 10, v0
	v_mul_i32_i24_e32 v0, 0x400, v8
	s_waitcnt lgkmcnt(0)
	s_add_u32 s21, s10, 0xc700000
	v_sub_u32_e32 v0, v132, v0
	s_addc_u32 s23, s11, 0
	v_lshrrev_b32_e32 v1, 4, v0
	s_add_u32 s25, s10, 0x4080000
	v_bitop3_b32 v0, v1, v0, 32 bitop3:0x6c
	s_addc_u32 s27, s11, 0
	v_ashrrev_i32_e32 v3, 31, v0
	s_ashr_i32 s5, s19, 6
	s_ashr_i32 s47, s46, 31
	s_ashr_i32 s9, s8, 31
	s_ashr_i32 s4, s19, 8
	v_lshrrev_b32_e32 v3, 26, v3
	s_lshl_b32 s53, s5, 10
	s_lshl_b64 s[12:13], s[46:47], 20
	s_lshl_b64 s[6:7], s[8:9], 20
	v_add_u32_e32 v3, v0, v3
	s_add_u32 s6, s25, s6
	v_ashrrev_i32_e32 v9, 6, v3
	v_and_b32_e32 v3, 0xc0, v3
	s_addc_u32 s7, s27, s7
	s_add_i32 s54, s53, 0
	v_sub_u32_e32 v0, v0, v3
	s_add_i32 m0, s54, 0x10000
	v_lshlrev_b32_e32 v1, 3, v8
	v_lshlrev_b32_e32 v10, 5, v8
	v_ashrrev_i16_sdwa v0, v2, sext(v0) dst_sel:DWORD dst_unused:UNUSED_PAD src0_sel:DWORD src1_sel:BYTE_0
	global_load_lds_dwordx4 v128, s[6:7]
	s_add_i32 m0, s54, 0x12000
	v_and_b32_e32 v1, 0xffff0, v1
	v_and_b32_e32 v11, 32, v10
	v_bfe_i32 v10, v0, 0, 16
	s_add_u32 s48, s21, s12
	v_add_u32_e32 v0, v11, v10
	v_add_lshl_u32 v1, v9, v1, 12
	global_load_lds_dwordx4 v132, s[6:7]
	s_addc_u32 s49, s23, s13
	s_mov_b32 m0, s54
	s_add_i32 s55, s54, 0x2000
	v_lshl_add_u32 v134, v0, 1, v1
	global_load_lds_dwordx4 v130, s[48:49]
	s_mov_b32 m0, s55
	s_add_u32 s12, s6, 0x4000
	global_load_lds_dwordx4 v134, s[48:49]
	s_addc_u32 s13, s7, 0
	s_add_i32 m0, s54, 0x14000
	v_mov_b32_e32 v129, 0
	global_load_lds_dwordx4 v128, s[12:13]
	s_add_i32 m0, s54, 0x16000
	v_mov_b32_e32 v131, v129
	global_load_lds_dwordx4 v132, s[12:13]
	s_add_u32 s12, s48, 0x80000
	s_addc_u32 s13, s49, 0
	s_add_i32 s56, s54, 0x4000
	s_mov_b32 m0, s56
	s_add_i32 s57, s54, 0x6000
	global_load_lds_dwordx4 v130, s[12:13]
	s_mov_b32 m0, s57
	v_mov_b32_e32 v135, v129
	global_load_lds_dwordx4 v134, s[12:13]
	s_mov_b32 s58, 0
	v_mov_b32_e32 v133, v129
	v_lshl_add_u64 v[2:3], s[48:49], 0, v[130:131]
	s_cmp_lg_u32 s4, 1
	v_lshl_add_u64 v[0:1], s[48:49], 0, v[134:135]
	s_cbranch_scc1 .LBB0_274
.LBB0_274:
	s_lshl_b32 s5, s5, 5
	s_and_b32 s5, s5, 0x60
	s_lshl_b32 s9, s4, 13
	s_lshl_b32 s14, s5, 7
	s_add_u32 s12, s6, 0x8000
	s_addc_u32 s13, s7, 0
	s_add_i32 m0, s54, 0x18000
	v_lshl_add_u64 v[12:13], s[12:13], 0, v[128:129]
	s_waitcnt vmcnt(4)
	s_barrier
	global_load_lds_dwordx4 v[12:13], off
	v_lshl_add_u64 v[12:13], s[12:13], 0, v[132:133]
	s_add_i32 m0, s54, 0x1a000
	s_mov_b64 s[12:13], 0x80
	s_add_i32 s59, s54, 0x8000
	s_add_i32 s60, s54, 0xa000
	global_load_lds_dwordx4 v[12:13], off
	v_lshl_add_u64 v[2:3], v[2:3], 0, s[12:13]
	s_mov_b32 m0, s59
	s_add_u32 s28, s6, 0xc000
	global_load_lds_dwordx4 v[2:3], off
	v_lshl_add_u64 v[0:1], v[0:1], 0, s[12:13]
	s_mov_b32 m0, s60
	s_addc_u32 s29, s7, 0
	global_load_lds_dwordx4 v[0:1], off
	s_add_i32 m0, s54, 0x1c000
	v_lshl_add_u64 v[0:1], s[28:29], 0, v[128:129]
	global_load_lds_dwordx4 v[0:1], off
	v_lshl_add_u64 v[0:1], s[28:29], 0, v[132:133]
	s_add_i32 m0, s54, 0x1e000
	s_add_i32 s63, 0, 0x10000
	global_load_lds_dwordx4 v[0:1], off
	v_lshrrev_b32_e32 v1, 1, v4
	v_and_b32_e32 v1, 24, v1
	v_and_b32_e32 v0, 15, v4
	v_lshlrev_b32_e32 v2, 1, v1
	v_lshl_or_b32 v144, s4, 6, v0
	v_lshl_or_b32 v0, v0, 6, v2
	v_lshlrev_b32_e32 v2, 2, v4
	v_and_b32_e32 v2, 32, v2
	v_bitop3_b32 v3, v0, s9, v2 bitop3:0xde
	v_bitop3_b32 v145, v0, s14, v2 bitop3:0xde
	v_lshlrev_b32_e32 v0, 15, v5
	v_and_b32_e32 v0, 0xffff0000, v0
	v_or_b32_e32 v146, s5, v1
	v_lshl_add_u32 v0, v6, 12, v0
	v_and_b32_e32 v1, 1, v5
	v_lshl_or_b32 v0, v1, 6, v0
	v_lshl_add_u32 v136, v7, 1, v0
	v_lshlrev_b32_e32 v0, 15, v8
	v_and_b32_e32 v0, 0xffff0000, v0
	s_waitcnt vmcnt(6)
	v_lshl_add_u32 v0, v9, 12, v0
	v_and_b32_e32 v1, 1, v8
	v_lshl_or_b32 v0, v1, 6, v0
	s_add_i32 s64, 0, 0x14000
	s_ashr_i32 s61, s52, 31
	v_mov_b32_e32 v137, v129
	v_lshl_add_u32 v138, v10, 1, v0
	v_mov_b32_e32 v139, v129
	v_mov_b64_e32 v[140:141], 0xa80
	v_mov_b64_e32 v[142:143], 0xa7f
	s_movk_i32 s62, 0x151
	v_add_u32_e32 v147, s63, v145
	v_add_u32_e32 v148, 0, v3
	v_add_u32_e32 v149, s64, v145
	s_mov_b32 s14, 0x3e6d3388
	s_mov_b32 s16, 0x3f07dc22
	s_mov_b32 s18, 0xbf3a00e3
	s_mov_b32 s20, 0x3f35f0e3
	s_mov_b32 s22, 0xbe11a98e
	s_mov_b32 s24, 0x3e027906
	s_mov_b32 s26, 0xbf38aa3b
	s_movk_i32 s65, 0x1800
	s_mov_b32 s66, 0x1b300000
	s_barrier
	s_branch .LBB0_277

;     __host__ __device__ bool next(int i, Unit& u) const { const int j = i / 3; if (!StaticOrder::next(j, u)) return false; u.br = i - 3 * j; return true; }
; #define PG8_STAGE(bufoff, gbase, voff) do { _Pragma("unroll") for (int _i = 0; _i < 2; ++_i) \
;         __builtin_amdgcn_global_load_lds((const unsigned*)((const char*)(gbase) + (voff)[_i]), (PG8_LAS unsigned*)(lds + (bufoff) + ldsw + _i * 8192), 16, 0, 0); } while (0)
; #define PG8_LDA(dst, b, h) do { _Pragma("unroll") for (int m = 0; m < 4; ++m) _Pragma("unroll") for (int k = 0; k < 2; ++k) dst[m][k] = *(const PG8_LAS bf16x8*)(lds + PG8_SA(b, h) + aoff + m * 2048 + k * 1024); } while (0)
; #define PG8_LDB(dst, b, h) do { _Pragma("unroll") for (int n = 0; n < 2; ++n) _Pragma("unroll") for (int k = 0; k < 2; ++k) dst[n][k] = *(const PG8_LAS bf16x8*)(lds + PG8_SB(b, h) + boff + n * 2048 + k * 1024); } while (0)
; #define PG8_WAIT_L(n) asm volatile("s_waitcnt lgkmcnt(" #n ")" ::: "memory")
; #define PG8_BAR __builtin_amdgcn_s_barrier()
; #define PG8_SCHED __builtin_amdgcn_sched_barrier(0)
; template <class Epi, class Sched>
; __device__ __forceinline__ void gemm_phase(PG8_LAS unsigned char* lds, const Gemm g, const Sched& S, const Epi& E) {
;     ...
;         const bool has_next = S.next(ui + 1, nxt);
;         const char* nA = has_next ? (const char*)g.A + (size_t)nxt.pm * tstep + (size_t)nxt.br * g.strideA : cA; const char* nB = has_next ? (const char*)g.Bt + (size_t)nxt.pn * tstepB + (size_t)nxt.br * g.strideB : cB;
;         for (int t = 0; t < nt; t += 2) {
;             const bool last = (t == nt - 2);
;             const char* a1 = cA + (size_t)(t + 1) * kstep;
;             const char* a2 = last ? nA : cA + (size_t)(t + 2) * kstep; const char* b2 = last ? nB : cB + (size_t)(t + 2) * kstepB;
;             const char* a3 = a2 + kstep; const char* b3 = b2 + kstepB;
;             if (last && has_next) S.a_ready(nxt);
;             PG8_LDB(B0, 0, 0); PG8_SCHED; PG8_LDA(At, 0, 0); PG8_STAGE(PG8_SA(1, 1), a1 + hstep, voffA);
;             PG8_WAIT_L(8); PG8_BAR; PG8_WAIT_L(0); PG8_MMA(0, 0, At, B0); PG8_BAR; PG8_SCHED;
;     ...
;         for (int a = 0; a < 2; ++a)
; #pragma unroll
;             for (int b = 0; b < 2; ++b)
; #pragma unroll
;                 for (int m = 0; m < 4; ++m)
; #pragma unroll
;                     for (int n = 0; n < 2; ++n) acc[a][b][m][n] = (f32x4){0.f, 0.f, 0.f, 0.f};
.LBB0_279:
	s_ashr_i32 s29, s28, 31
	v_cmp_lt_i64_e32 vcc, s[36:37], v[140:141]
	s_lshl_b64 s[36:37], s[28:29], 20
	s_add_u32 s36, s21, s36
	s_addc_u32 s37, s23, s37
	s_and_b64 s[38:39], vcc, exec
	s_cselect_b32 s9, s37, s49
	s_cselect_b32 s29, s36, s48
	s_ashr_i32 s31, s30, 31
	s_lshl_b64 s[38:39], s[30:31], 20
	s_add_u32 s38, s25, s38
	s_addc_u32 s39, s27, s39
	s_and_b64 s[50:51], vcc, exec
	s_cselect_b32 s31, s39, s7
	s_cselect_b32 s47, s38, s6
	s_add_u32 s67, s6, 0x10000
	s_addc_u32 s68, s7, 0
	s_add_u32 s6, s48, 0x80080
	v_mov_b32_e32 v0, 0
	s_addc_u32 s7, s49, 0
	s_mov_b32 s69, -2
	v_mov_b32_e32 v1, v0
	v_mov_b32_e32 v2, v0
	v_mov_b32_e32 v3, v0
	v_mov_b32_e32 v4, v0
	v_mov_b32_e32 v5, v0
	v_mov_b32_e32 v6, v0
	v_mov_b32_e32 v7, v0
	v_mov_b32_e32 v16, v0
	v_mov_b32_e32 v17, v0
	v_mov_b32_e32 v18, v0
	v_mov_b32_e32 v19, v0
	v_mov_b32_e32 v20, v0
	v_mov_b32_e32 v21, v0
	v_mov_b32_e32 v22, v0
	v_mov_b32_e32 v23, v0
	v_mov_b32_e32 v32, v0
	v_mov_b32_e32 v33, v0
	v_mov_b32_e32 v34, v0
	v_mov_b32_e32 v35, v0
	v_mov_b32_e32 v36, v0
	v_mov_b32_e32 v37, v0
	v_mov_b32_e32 v38, v0
	v_mov_b32_e32 v39, v0
	v_mov_b32_e32 v48, v0
	v_mov_b32_e32 v49, v0
	v_mov_b32_e32 v50, v0
	v_mov_b32_e32 v51, v0
	v_mov_b32_e32 v52, v0
	v_mov_b32_e32 v53, v0
	v_mov_b32_e32 v54, v0
	v_mov_b32_e32 v55, v0
	v_mov_b32_e32 v8, v0
	v_mov_b32_e32 v9, v0
	v_mov_b32_e32 v10, v0
	v_mov_b32_e32 v11, v0
	v_mov_b32_e32 v12, v0
	v_mov_b32_e32 v13, v0
	v_mov_b32_e32 v14, v0
	v_mov_b32_e32 v15, v0
	v_mov_b32_e32 v24, v0
	v_mov_b32_e32 v25, v0
	v_mov_b32_e32 v26, v0
	v_mov_b32_e32 v27, v0
	v_mov_b32_e32 v28, v0
	v_mov_b32_e32 v29, v0
	v_mov_b32_e32 v30, v0
	v_mov_b32_e32 v31, v0
	v_mov_b32_e32 v40, v0
	v_mov_b32_e32 v41, v0
	v_mov_b32_e32 v42, v0
	v_mov_b32_e32 v43, v0
	v_mov_b32_e32 v44, v0
	v_mov_b32_e32 v45, v0
	v_mov_b32_e32 v46, v0
	v_mov_b32_e32 v47, v0
	v_mov_b32_e32 v56, v0
	v_mov_b32_e32 v57, v0
	v_mov_b32_e32 v58, v0
	v_mov_b32_e32 v59, v0
	v_mov_b32_e32 v60, v0
	v_mov_b32_e32 v61, v0
	v_mov_b32_e32 v62, v0
	v_mov_b32_e32 v63, v0
	v_mov_b32_e32 v64, v0
	v_mov_b32_e32 v65, v0
	v_mov_b32_e32 v66, v0
	v_mov_b32_e32 v67, v0
	v_mov_b32_e32 v68, v0
	v_mov_b32_e32 v69, v0
	v_mov_b32_e32 v70, v0
	v_mov_b32_e32 v71, v0
	v_mov_b32_e32 v80, v0
	v_mov_b32_e32 v81, v0
	v_mov_b32_e32 v82, v0
	v_mov_b32_e32 v83, v0
	v_mov_b32_e32 v84, v0
	v_mov_b32_e32 v85, v0
	v_mov_b32_e32 v86, v0
	v_mov_b32_e32 v87, v0
	v_mov_b32_e32 v96, v0
	v_mov_b32_e32 v97, v0
	v_mov_b32_e32 v98, v0
	v_mov_b32_e32 v99, v0
	v_mov_b32_e32 v100, v0
	v_mov_b32_e32 v101, v0
	v_mov_b32_e32 v102, v0
	v_mov_b32_e32 v103, v0
	v_mov_b32_e32 v112, v0
	v_mov_b32_e32 v113, v0
	v_mov_b32_e32 v114, v0
	v_mov_b32_e32 v115, v0
	v_mov_b32_e32 v116, v0
	v_mov_b32_e32 v117, v0
	v_mov_b32_e32 v118, v0
	v_mov_b32_e32 v119, v0
	v_mov_b32_e32 v72, v0
	v_mov_b32_e32 v73, v0
	v_mov_b32_e32 v74, v0
	v_mov_b32_e32 v75, v0
	v_mov_b32_e32 v76, v0
	v_mov_b32_e32 v77, v0
	v_mov_b32_e32 v78, v0
	v_mov_b32_e32 v79, v0
	v_mov_b32_e32 v88, v0
	v_mov_b32_e32 v89, v0
	v_mov_b32_e32 v90, v0
	v_mov_b32_e32 v91, v0
	v_mov_b32_e32 v92, v0
	v_mov_b32_e32 v93, v0
	v_mov_b32_e32 v94, v0
	v_mov_b32_e32 v95, v0
	v_mov_b32_e32 v104, v0
	v_mov_b32_e32 v105, v0
	v_mov_b32_e32 v106, v0
	v_mov_b32_e32 v107, v0
	v_mov_b32_e32 v108, v0
	v_mov_b32_e32 v109, v0
	v_mov_b32_e32 v110, v0
	v_mov_b32_e32 v111, v0
	v_mov_b32_e32 v120, v0
	v_mov_b32_e32 v121, v0
	v_mov_b32_e32 v122, v0
	v_mov_b32_e32 v123, v0
	v_mov_b32_e32 v124, v0
	v_mov_b32_e32 v125, v0
	v_mov_b32_e32 v126, v0
	v_mov_b32_e32 v127, v0
	s_cmp_eq_u32 s78, 1
	s_cbranch_scc0 .Lhalf_skip_y_2
	s_barrier
.Lhalf_skip_y_2:
.LBB0_280:
	ds_read_b128 v[150:153], v147
	ds_read_b128 v[154:157], v147 offset:1024
	ds_read_b128 v[158:161], v147 offset:2048
	ds_read_b128 v[162:165], v147 offset:3072
	s_add_u32 s48, s6, 0xfff80080
	s_addc_u32 s49, s7, -1
	s_cmp_eq_u32 s69, 28
	s_cselect_b32 s51, s9, s49
	s_cselect_b32 s50, s29, s48
	s_cselect_b32 s49, s31, s68
	s_cselect_b32 s48, s47, s67
	v_lshl_add_u64 v[198:199], s[6:7], 0, v[136:137]
	s_add_i32 m0, s54, 0xc000
	ds_read_b128 v[166:169], v148
	ds_read_b128 v[170:173], v148 offset:1024
	ds_read_b128 v[174:177], v148 offset:2048
	ds_read_b128 v[178:181], v148 offset:3072
	ds_read_b128 v[182:185], v148 offset:4096
	ds_read_b128 v[186:189], v148 offset:5120
	ds_read_b128 v[190:193], v148 offset:6144
	ds_read_b128 v[194:197], v148 offset:7168
	global_load_lds_dwordx4 v[198:199], off
	v_lshl_add_u64 v[198:199], s[6:7], 0, v[138:139]
	s_add_i32 m0, s54, 0xe000
	s_nop 0
	global_load_lds_dwordx4 v[198:199], off
	s_waitcnt lgkmcnt(8)
	s_barrier
	s_waitcnt lgkmcnt(0)
	s_setprio 1
	s_waitcnt lgkmcnt(0)
	v_mfma_f32_16x16x32_bf16 v[124:127], v[150:153], v[166:169], v[124:127]
	v_mfma_f32_16x16x32_bf16 v[120:123], v[158:161], v[166:169], v[120:123]
	v_mfma_f32_16x16x32_bf16 v[108:111], v[150:153], v[174:177], v[108:111]
	v_mfma_f32_16x16x32_bf16 v[104:107], v[158:161], v[174:177], v[104:107]
	v_mfma_f32_16x16x32_bf16 v[92:95], v[150:153], v[182:185], v[92:95]
	v_mfma_f32_16x16x32_bf16 v[88:91], v[158:161], v[182:185], v[88:91]
	v_mfma_f32_16x16x32_bf16 v[76:79], v[150:153], v[190:193], v[76:79]
	v_mfma_f32_16x16x32_bf16 v[72:75], v[158:161], v[190:193], v[72:75]
	v_mfma_f32_16x16x32_bf16 v[124:127], v[154:157], v[170:173], v[124:127]
	v_mfma_f32_16x16x32_bf16 v[120:123], v[162:165], v[170:173], v[120:123]
	v_mfma_f32_16x16x32_bf16 v[108:111], v[154:157], v[178:181], v[108:111]
	v_mfma_f32_16x16x32_bf16 v[104:107], v[162:165], v[178:181], v[104:107]
	v_mfma_f32_16x16x32_bf16 v[92:95], v[154:157], v[186:189], v[92:95]
	v_mfma_f32_16x16x32_bf16 v[88:91], v[162:165], v[186:189], v[88:91]
	v_mfma_f32_16x16x32_bf16 v[76:79], v[154:157], v[194:197], v[76:79]
	v_mfma_f32_16x16x32_bf16 v[72:75], v[162:165], v[194:197], v[72:75]
	s_setprio 0
	s_barrier
; #define PG8_STAGE(bufoff, gbase, voff) do { _Pragma("unroll") for (int _i = 0; _i < 2; ++_i) \
;         __builtin_amdgcn_global_load_lds((const unsigned*)((const char*)(gbase) + (voff)[_i]), (PG8_LAS unsigned*)(lds + (bufoff) + ldsw + _i * 8192), 16, 0, 0); } while (0)
; #define PG8_LDA(dst, b, h) do { _Pragma("unroll") for (int m = 0; m < 4; ++m) _Pragma("unroll") for (int k = 0; k < 2; ++k) dst[m][k] = *(const PG8_LAS bf16x8*)(lds + PG8_SA(b, h) + aoff + m * 2048 + k * 1024); } while (0)
; #define PG8_LDB(dst, b, h) do { _Pragma("unroll") for (int n = 0; n < 2; ++n) _Pragma("unroll") for (int k = 0; k < 2; ++k) dst[n][k] = *(const PG8_LAS bf16x8*)(lds + PG8_SB(b, h) + boff + n * 2048 + k * 1024); } while (0)
; #define PG8_MMA(ai, bj, At, Bt) do { __builtin_amdgcn_s_setprio(1); _Pragma("unroll") for (int m = 0; m < 4; ++m) _Pragma("unroll") for (int n = 0; n < 2; ++n) _Pragma("unroll") for (int k = 0; k < 2; ++k) \
;         acc[ai][bj][m][n] = __builtin_amdgcn_mfma_f32_16x16x32_bf16(Bt[n][k], At[m][k], acc[ai][bj][m][n], 0, 0, 0); __builtin_amdgcn_s_setprio(0); } while (0)
; #define PG8_WAIT_V(n) asm volatile("s_waitcnt vmcnt(" #n ")" ::: "memory")
; #define PG8_WAIT_L(n) asm volatile("s_waitcnt lgkmcnt(" #n ")" ::: "memory")
; #define PG8_BAR __builtin_amdgcn_s_barrier()
; #define PG8_SCHED __builtin_amdgcn_sched_barrier(0)
; template <class Epi, class Sched>
; __device__ __forceinline__ void gemm_phase(PG8_LAS unsigned char* lds, const Gemm g, const Sched& S, const Epi& E) {
;     ...
;             PG8_LDB(B1, 0, 1); PG8_STAGE(PG8_SB(0, 0), b2, voffB);
;             PG8_BAR; PG8_WAIT_L(0); PG8_MMA(0, 1, At, B1); PG8_BAR;
;             PG8_LDA(At, 0, 1); PG8_STAGE(PG8_SA(0, 0), a2, voffA);
;             PG8_BAR; PG8_WAIT_L(0); PG8_MMA(1, 0, At, B0); PG8_BAR; PG8_SCHED;
;             PG8_STAGE(PG8_SB(0, 1), b2 + hstepB, voffB);
;             PG8_WAIT_V(6); PG8_BAR; PG8_MMA(1, 1, At, B1); PG8_BAR;
;             PG8_LDB(B0, 1, 0); PG8_SCHED; PG8_LDA(At, 1, 0); PG8_STAGE(PG8_SA(0, 1), a2 + hstep, voffA);
;             PG8_WAIT_L(8); PG8_BAR; PG8_WAIT_L(0); PG8_MMA(0, 0, At, B0); PG8_BAR; PG8_SCHED;
	s_add_i32 s70, s63, s53
	v_lshl_add_u64 v[214:215], s[48:49], 0, v[128:129]
	s_mov_b32 m0, s70
	ds_read_b128 v[198:201], v149
	ds_read_b128 v[202:205], v149 offset:1024
	ds_read_b128 v[206:209], v149 offset:2048
	ds_read_b128 v[210:213], v149 offset:3072
	global_load_lds_dwordx4 v[214:215], off
	v_lshl_add_u64 v[214:215], s[48:49], 0, v[132:133]
	s_add_i32 m0, s70, 0x2000
	s_nop 0
	global_load_lds_dwordx4 v[214:215], off
	s_barrier
	s_waitcnt lgkmcnt(0)
	s_setprio 1
	s_waitcnt lgkmcnt(0)
	v_mfma_f32_16x16x32_bf16 v[116:119], v[198:201], v[166:169], v[116:119]
	v_mfma_f32_16x16x32_bf16 v[112:115], v[206:209], v[166:169], v[112:115]
	v_mfma_f32_16x16x32_bf16 v[100:103], v[198:201], v[174:177], v[100:103]
	v_mfma_f32_16x16x32_bf16 v[96:99], v[206:209], v[174:177], v[96:99]
	v_mfma_f32_16x16x32_bf16 v[84:87], v[198:201], v[182:185], v[84:87]
	v_mfma_f32_16x16x32_bf16 v[80:83], v[206:209], v[182:185], v[80:83]
	v_mfma_f32_16x16x32_bf16 v[68:71], v[198:201], v[190:193], v[68:71]
	v_mfma_f32_16x16x32_bf16 v[64:67], v[206:209], v[190:193], v[64:67]
	v_mfma_f32_16x16x32_bf16 v[116:119], v[202:205], v[170:173], v[116:119]
	v_mfma_f32_16x16x32_bf16 v[112:115], v[210:213], v[170:173], v[112:115]
	v_mfma_f32_16x16x32_bf16 v[100:103], v[202:205], v[178:181], v[100:103]
	v_mfma_f32_16x16x32_bf16 v[96:99], v[210:213], v[178:181], v[96:99]
	v_mfma_f32_16x16x32_bf16 v[84:87], v[202:205], v[186:189], v[84:87]
	v_mfma_f32_16x16x32_bf16 v[80:83], v[210:213], v[186:189], v[80:83]
	v_mfma_f32_16x16x32_bf16 v[68:71], v[202:205], v[194:197], v[68:71]
	v_mfma_f32_16x16x32_bf16 v[64:67], v[210:213], v[194:197], v[64:67]
	s_setprio 0
	s_mov_b32 m0, s54
	v_lshl_add_u64 v[214:215], s[50:51], 0, v[130:131]
	s_barrier
	ds_read_b128 v[166:169], v148 offset:16384
	ds_read_b128 v[170:173], v148 offset:17408
	ds_read_b128 v[174:177], v148 offset:18432
	ds_read_b128 v[178:181], v148 offset:19456
	ds_read_b128 v[182:185], v148 offset:20480
	ds_read_b128 v[186:189], v148 offset:21504
	ds_read_b128 v[190:193], v148 offset:22528
	ds_read_b128 v[194:197], v148 offset:23552
	global_load_lds_dwordx4 v[214:215], off
	v_lshl_add_u64 v[216:217], s[50:51], 0, v[134:135]
	s_mov_b32 m0, s55
	s_nop 0
	global_load_lds_dwordx4 v[216:217], off
	s_barrier
	s_waitcnt lgkmcnt(0)
	s_setprio 1
	s_waitcnt lgkmcnt(0)
	v_mfma_f32_16x16x32_bf16 v[60:63], v[150:153], v[166:169], v[60:63]
	v_mfma_f32_16x16x32_bf16 v[56:59], v[158:161], v[166:169], v[56:59]
	v_mfma_f32_16x16x32_bf16 v[44:47], v[150:153], v[174:177], v[44:47]
	v_mfma_f32_16x16x32_bf16 v[40:43], v[158:161], v[174:177], v[40:43]
	v_mfma_f32_16x16x32_bf16 v[28:31], v[150:153], v[182:185], v[28:31]
	v_mfma_f32_16x16x32_bf16 v[24:27], v[158:161], v[182:185], v[24:27]
	v_mfma_f32_16x16x32_bf16 v[12:15], v[150:153], v[190:193], v[12:15]
	v_mfma_f32_16x16x32_bf16 v[8:11], v[158:161], v[190:193], v[8:11]
	v_mfma_f32_16x16x32_bf16 v[60:63], v[154:157], v[170:173], v[60:63]
	v_mfma_f32_16x16x32_bf16 v[56:59], v[162:165], v[170:173], v[56:59]
	v_mfma_f32_16x16x32_bf16 v[44:47], v[154:157], v[178:181], v[44:47]
	v_mfma_f32_16x16x32_bf16 v[40:43], v[162:165], v[178:181], v[40:43]
	v_mfma_f32_16x16x32_bf16 v[28:31], v[154:157], v[186:189], v[28:31]
	v_mfma_f32_16x16x32_bf16 v[24:27], v[162:165], v[186:189], v[24:27]
	v_mfma_f32_16x16x32_bf16 v[12:15], v[154:157], v[194:197], v[12:15]
	v_mfma_f32_16x16x32_bf16 v[8:11], v[162:165], v[194:197], v[8:11]
	s_setprio 0
	s_barrier
	s_add_u32 s70, s48, 0x4000
	s_addc_u32 s71, s49, 0
	s_add_i32 s72, s64, s53
	v_lshl_add_u64 v[150:151], s[70:71], 0, v[128:129]
	s_mov_b32 m0, s72
	s_nop 0
	global_load_lds_dwordx4 v[150:151], off
	v_lshl_add_u64 v[150:151], s[70:71], 0, v[132:133]
	s_add_i32 m0, s72, 0x2000
	s_nop 0
	global_load_lds_dwordx4 v[150:151], off
	s_waitcnt vmcnt(6)
	s_barrier
	s_setprio 1
	v_mfma_f32_16x16x32_bf16 v[52:55], v[198:201], v[166:169], v[52:55]
	v_mfma_f32_16x16x32_bf16 v[48:51], v[206:209], v[166:169], v[48:51]
	v_mfma_f32_16x16x32_bf16 v[36:39], v[198:201], v[174:177], v[36:39]
	v_mfma_f32_16x16x32_bf16 v[32:35], v[206:209], v[174:177], v[32:35]
	v_mfma_f32_16x16x32_bf16 v[20:23], v[198:201], v[182:185], v[20:23]
	v_mfma_f32_16x16x32_bf16 v[16:19], v[206:209], v[182:185], v[16:19]
	v_mfma_f32_16x16x32_bf16 v[4:7], v[198:201], v[190:193], v[4:7]
	v_mfma_f32_16x16x32_bf16 v[0:3], v[206:209], v[190:193], v[0:3]
	v_mfma_f32_16x16x32_bf16 v[52:55], v[202:205], v[170:173], v[52:55]
	v_mfma_f32_16x16x32_bf16 v[48:51], v[210:213], v[170:173], v[48:51]
	v_mfma_f32_16x16x32_bf16 v[36:39], v[202:205], v[178:181], v[36:39]
	v_mfma_f32_16x16x32_bf16 v[32:35], v[210:213], v[178:181], v[32:35]
	v_mfma_f32_16x16x32_bf16 v[20:23], v[202:205], v[186:189], v[20:23]
	v_mfma_f32_16x16x32_bf16 v[16:19], v[210:213], v[186:189], v[16:19]
	v_mfma_f32_16x16x32_bf16 v[4:7], v[202:205], v[194:197], v[4:7]
	v_mfma_f32_16x16x32_bf16 v[0:3], v[210:213], v[194:197], v[0:3]
	s_setprio 0
	s_add_i32 s70, 0, 0x18000
	v_add_u32_e32 v162, s70, v145
	s_barrier
	ds_read_b128 v[150:153], v162
	ds_read_b128 v[154:157], v162 offset:1024
	ds_read_b128 v[158:161], v162 offset:2048
	ds_read_b128 v[162:165], v162 offset:3072
	s_add_u32 s50, s50, 0x80000
	s_addc_u32 s51, s51, 0
	s_mov_b32 m0, s56
	v_lshl_add_u64 v[198:199], s[50:51], 0, v[130:131]
	ds_read_b128 v[166:169], v148 offset:32768
	ds_read_b128 v[170:173], v148 offset:33792
	ds_read_b128 v[174:177], v148 offset:34816
	ds_read_b128 v[178:181], v148 offset:35840
	ds_read_b128 v[182:185], v148 offset:36864
	ds_read_b128 v[186:189], v148 offset:37888
	ds_read_b128 v[190:193], v148 offset:38912
	ds_read_b128 v[194:197], v148 offset:39936
	global_load_lds_dwordx4 v[198:199], off
	v_lshl_add_u64 v[198:199], s[50:51], 0, v[134:135]
	s_mov_b32 m0, s57
	s_nop 0
	global_load_lds_dwordx4 v[198:199], off
	s_waitcnt lgkmcnt(8)
	s_barrier
; #define PG8_STAGE(bufoff, gbase, voff) do { _Pragma("unroll") for (int _i = 0; _i < 2; ++_i) \
;         __builtin_amdgcn_global_load_lds((const unsigned*)((const char*)(gbase) + (voff)[_i]), (PG8_LAS unsigned*)(lds + (bufoff) + ldsw + _i * 8192), 16, 0, 0); } while (0)
; #define PG8_LDA(dst, b, h) do { _Pragma("unroll") for (int m = 0; m < 4; ++m) _Pragma("unroll") for (int k = 0; k < 2; ++k) dst[m][k] = *(const PG8_LAS bf16x8*)(lds + PG8_SA(b, h) + aoff + m * 2048 + k * 1024); } while (0)
; #define PG8_LDB(dst, b, h) do { _Pragma("unroll") for (int n = 0; n < 2; ++n) _Pragma("unroll") for (int k = 0; k < 2; ++k) dst[n][k] = *(const PG8_LAS bf16x8*)(lds + PG8_SB(b, h) + boff + n * 2048 + k * 1024); } while (0)
; #define PG8_MMA(ai, bj, At, Bt) do { __builtin_amdgcn_s_setprio(1); _Pragma("unroll") for (int m = 0; m < 4; ++m) _Pragma("unroll") for (int n = 0; n < 2; ++n) _Pragma("unroll") for (int k = 0; k < 2; ++k) \
;         acc[ai][bj][m][n] = __builtin_amdgcn_mfma_f32_16x16x32_bf16(Bt[n][k], At[m][k], acc[ai][bj][m][n], 0, 0, 0); __builtin_amdgcn_s_setprio(0); } while (0)
; #define PG8_WAIT_V(n) asm volatile("s_waitcnt vmcnt(" #n ")" ::: "memory")
; #define PG8_WAIT_L(n) asm volatile("s_waitcnt lgkmcnt(" #n ")" ::: "memory")
; #define PG8_BAR __builtin_amdgcn_s_barrier()
; #define PG8_SCHED __builtin_amdgcn_sched_barrier(0)
; template <class Epi, class Sched>
; __device__ __forceinline__ void gemm_phase(PG8_LAS unsigned char* lds, const Gemm g, const Sched& S, const Epi& E) {
;     ...
;             PG8_WAIT_L(8); PG8_BAR; PG8_WAIT_L(0); PG8_MMA(0, 0, At, B0); PG8_BAR; PG8_SCHED;
;             PG8_LDB(B1, 1, 1); PG8_STAGE(PG8_SB(1, 0), b3, voffB);
;             PG8_BAR; PG8_WAIT_L(0); PG8_MMA(0, 1, At, B1); PG8_BAR;
;             PG8_LDA(At, 1, 1); PG8_STAGE(PG8_SA(1, 0), a3, voffA);
;             PG8_BAR; PG8_WAIT_L(0); PG8_MMA(1, 0, At, B0); PG8_BAR; PG8_SCHED;
;             PG8_STAGE(PG8_SB(1, 1), b3 + hstepB, voffB);
;             PG8_WAIT_V(6); PG8_BAR; PG8_MMA(1, 1, At, B1); PG8_BAR;
;         }
;         if constexpr (!Epi::AFTER_DRAIN) { E(acc, cur, wr, wc, fr, fq); if constexpr (Epi::IDEMP && EPI_REP > 1) { asm volatile("" ::: "memory"); E(acc, cur, wr, wc, fr, fq); } S.done(cur); }
	s_waitcnt lgkmcnt(0)
	s_setprio 1
	s_waitcnt lgkmcnt(0)
	v_mfma_f32_16x16x32_bf16 v[124:127], v[150:153], v[166:169], v[124:127]
	v_mfma_f32_16x16x32_bf16 v[120:123], v[158:161], v[166:169], v[120:123]
	v_mfma_f32_16x16x32_bf16 v[108:111], v[150:153], v[174:177], v[108:111]
	v_mfma_f32_16x16x32_bf16 v[104:107], v[158:161], v[174:177], v[104:107]
	v_mfma_f32_16x16x32_bf16 v[92:95], v[150:153], v[182:185], v[92:95]
	v_mfma_f32_16x16x32_bf16 v[88:91], v[158:161], v[182:185], v[88:91]
	v_mfma_f32_16x16x32_bf16 v[76:79], v[150:153], v[190:193], v[76:79]
	v_mfma_f32_16x16x32_bf16 v[72:75], v[158:161], v[190:193], v[72:75]
	v_mfma_f32_16x16x32_bf16 v[124:127], v[154:157], v[170:173], v[124:127]
	v_mfma_f32_16x16x32_bf16 v[120:123], v[162:165], v[170:173], v[120:123]
	v_mfma_f32_16x16x32_bf16 v[108:111], v[154:157], v[178:181], v[108:111]
	v_mfma_f32_16x16x32_bf16 v[104:107], v[162:165], v[178:181], v[104:107]
	v_mfma_f32_16x16x32_bf16 v[92:95], v[154:157], v[186:189], v[92:95]
	v_mfma_f32_16x16x32_bf16 v[88:91], v[162:165], v[186:189], v[88:91]
	v_mfma_f32_16x16x32_bf16 v[76:79], v[154:157], v[194:197], v[76:79]
	v_mfma_f32_16x16x32_bf16 v[72:75], v[162:165], v[194:197], v[72:75]
	s_setprio 0
	s_barrier
	s_add_i32 s71, 0, 0x1c000
	s_add_u32 s50, s48, 0x8000
	s_addc_u32 s51, s49, 0
	s_add_i32 s70, s70, s53
	v_add_u32_e32 v210, s71, v145
	v_lshl_add_u64 v[218:219], s[50:51], 0, v[128:129]
	s_mov_b32 m0, s70
	ds_read_b128 v[198:201], v210
	ds_read_b128 v[202:205], v210 offset:1024
	ds_read_b128 v[206:209], v210 offset:2048
	ds_read_b128 v[210:213], v210 offset:3072
	global_load_lds_dwordx4 v[218:219], off
	v_lshl_add_u64 v[218:219], s[50:51], 0, v[132:133]
	s_add_i32 m0, s70, 0x2000
	s_nop 0
	global_load_lds_dwordx4 v[218:219], off
	s_barrier
	s_waitcnt lgkmcnt(0)
	s_setprio 1
	s_waitcnt lgkmcnt(0)
	v_mfma_f32_16x16x32_bf16 v[116:119], v[198:201], v[166:169], v[116:119]
	v_mfma_f32_16x16x32_bf16 v[112:115], v[206:209], v[166:169], v[112:115]
	v_mfma_f32_16x16x32_bf16 v[100:103], v[198:201], v[174:177], v[100:103]
	v_mfma_f32_16x16x32_bf16 v[96:99], v[206:209], v[174:177], v[96:99]
	v_mfma_f32_16x16x32_bf16 v[84:87], v[198:201], v[182:185], v[84:87]
	v_mfma_f32_16x16x32_bf16 v[80:83], v[206:209], v[182:185], v[80:83]
	v_mfma_f32_16x16x32_bf16 v[68:71], v[198:201], v[190:193], v[68:71]
	v_mfma_f32_16x16x32_bf16 v[64:67], v[206:209], v[190:193], v[64:67]
	v_mfma_f32_16x16x32_bf16 v[116:119], v[202:205], v[170:173], v[116:119]
	v_mfma_f32_16x16x32_bf16 v[112:115], v[210:213], v[170:173], v[112:115]
	v_mfma_f32_16x16x32_bf16 v[100:103], v[202:205], v[178:181], v[100:103]
	v_mfma_f32_16x16x32_bf16 v[96:99], v[210:213], v[178:181], v[96:99]
	v_mfma_f32_16x16x32_bf16 v[84:87], v[202:205], v[186:189], v[84:87]
	v_mfma_f32_16x16x32_bf16 v[80:83], v[210:213], v[186:189], v[80:83]
	v_mfma_f32_16x16x32_bf16 v[68:71], v[202:205], v[194:197], v[68:71]
	v_mfma_f32_16x16x32_bf16 v[64:67], v[210:213], v[194:197], v[64:67]
	s_setprio 0
	s_mov_b32 m0, s59
	v_lshl_add_u64 v[214:215], v[214:215], 0, s[12:13]
	s_barrier
	ds_read_b128 v[166:169], v148 offset:49152
	ds_read_b128 v[170:173], v148 offset:50176
	ds_read_b128 v[174:177], v148 offset:51200
	ds_read_b128 v[178:181], v148 offset:52224
	ds_read_b128 v[182:185], v148 offset:53248
	ds_read_b128 v[186:189], v148 offset:54272
	ds_read_b128 v[190:193], v148 offset:55296
	ds_read_b128 v[194:197], v148 offset:56320
	global_load_lds_dwordx4 v[214:215], off
	v_lshl_add_u64 v[214:215], v[216:217], 0, s[12:13]
	s_mov_b32 m0, s60
	s_nop 0
	global_load_lds_dwordx4 v[214:215], off
	s_barrier
	s_waitcnt lgkmcnt(0)
	s_setprio 1
	s_waitcnt lgkmcnt(0)
	v_mfma_f32_16x16x32_bf16 v[60:63], v[150:153], v[166:169], v[60:63]
	v_mfma_f32_16x16x32_bf16 v[56:59], v[158:161], v[166:169], v[56:59]
	v_mfma_f32_16x16x32_bf16 v[44:47], v[150:153], v[174:177], v[44:47]
	v_mfma_f32_16x16x32_bf16 v[40:43], v[158:161], v[174:177], v[40:43]
	v_mfma_f32_16x16x32_bf16 v[28:31], v[150:153], v[182:185], v[28:31]
	v_mfma_f32_16x16x32_bf16 v[24:27], v[158:161], v[182:185], v[24:27]
	v_mfma_f32_16x16x32_bf16 v[12:15], v[150:153], v[190:193], v[12:15]
	v_mfma_f32_16x16x32_bf16 v[8:11], v[158:161], v[190:193], v[8:11]
	v_mfma_f32_16x16x32_bf16 v[60:63], v[154:157], v[170:173], v[60:63]
	v_mfma_f32_16x16x32_bf16 v[56:59], v[162:165], v[170:173], v[56:59]
	v_mfma_f32_16x16x32_bf16 v[44:47], v[154:157], v[178:181], v[44:47]
	v_mfma_f32_16x16x32_bf16 v[40:43], v[162:165], v[178:181], v[40:43]
	v_mfma_f32_16x16x32_bf16 v[28:31], v[154:157], v[186:189], v[28:31]
	v_mfma_f32_16x16x32_bf16 v[24:27], v[162:165], v[186:189], v[24:27]
	v_mfma_f32_16x16x32_bf16 v[12:15], v[154:157], v[194:197], v[12:15]
	v_mfma_f32_16x16x32_bf16 v[8:11], v[162:165], v[194:197], v[8:11]
	s_setprio 0
	s_barrier
	s_add_u32 s48, s48, 0xc000
	s_addc_u32 s49, s49, 0
	s_add_i32 s50, s71, s53
	v_lshl_add_u64 v[150:151], s[48:49], 0, v[128:129]
	s_mov_b32 m0, s50
	s_nop 0
	global_load_lds_dwordx4 v[150:151], off
	v_lshl_add_u64 v[150:151], s[48:49], 0, v[132:133]
	s_add_i32 m0, s50, 0x2000
	s_nop 0
	global_load_lds_dwordx4 v[150:151], off
	s_waitcnt vmcnt(6)
	s_barrier
	s_setprio 1
	v_mfma_f32_16x16x32_bf16 v[52:55], v[198:201], v[166:169], v[52:55]
	v_mfma_f32_16x16x32_bf16 v[48:51], v[206:209], v[166:169], v[48:51]
	v_mfma_f32_16x16x32_bf16 v[36:39], v[198:201], v[174:177], v[36:39]
	v_mfma_f32_16x16x32_bf16 v[32:35], v[206:209], v[174:177], v[32:35]
	v_mfma_f32_16x16x32_bf16 v[20:23], v[198:201], v[182:185], v[20:23]
	v_mfma_f32_16x16x32_bf16 v[16:19], v[206:209], v[182:185], v[16:19]
	v_mfma_f32_16x16x32_bf16 v[4:7], v[198:201], v[190:193], v[4:7]
	v_mfma_f32_16x16x32_bf16 v[0:3], v[206:209], v[190:193], v[0:3]
	v_mfma_f32_16x16x32_bf16 v[52:55], v[202:205], v[170:173], v[52:55]
	v_mfma_f32_16x16x32_bf16 v[48:51], v[210:213], v[170:173], v[48:51]
	v_mfma_f32_16x16x32_bf16 v[36:39], v[202:205], v[178:181], v[36:39]
	v_mfma_f32_16x16x32_bf16 v[32:35], v[210:213], v[178:181], v[32:35]
	v_mfma_f32_16x16x32_bf16 v[20:23], v[202:205], v[186:189], v[20:23]
	v_mfma_f32_16x16x32_bf16 v[16:19], v[210:213], v[186:189], v[16:19]
	v_mfma_f32_16x16x32_bf16 v[4:7], v[202:205], v[194:197], v[4:7]
	v_mfma_f32_16x16x32_bf16 v[0:3], v[210:213], v[194:197], v[0:3]
	s_setprio 0
	s_add_i32 s69, s69, 2
	s_add_u32 s67, s67, 0x10000
	s_addc_u32 s68, s68, 0
	s_add_u32 s6, s6, 0x100
	s_addc_u32 s7, s7, 0
	s_cmp_gt_u32 s69, 29
	s_barrier
	s_cbranch_scc0 .LBB0_280
	s_cmp_eq_u32 s78, 0
	s_cbranch_scc0 .Lhalf_skip_x_2
	s_barrier
; __device__ __forceinline__ f32x2 gelu_pk(f32x2 v) {
;     const f32x2 av = __builtin_elementwise_abs(v), d = av * 0.2316418882f + 1.0f;
;     f32x2 t; t.x = __builtin_amdgcn_rcpf(d.x); t.y = __builtin_amdgcn_rcpf(d.y);
;     f32x2 q = t * 0.5307027145f + (-0.7265760135f); q = q * t + 0.7107068705f; q = q * t + (-0.142248368f); q = q * t + 0.127414796f; q = q * t;
;     const f32x2 s = (v * v) * (-0.72134752044f);
;     f32x2 e; e.x = __builtin_amdgcn_exp2f(s.x); e.y = __builtin_amdgcn_exp2f(s.y);
;     const f32x2 m = v * (q * e), r = v - m;
;     f32x2 o; o.x = v.x < 0.f ? m.x : r.x; o.y = v.y < 0.f ? m.y : r.y; return o;
; }
;     __device__ __forceinline__ void operator()(const f32x4 (&acc)[2][2][4][2], const Unit& u, int wr, int wc, int fr, int fq) const {
;         const int row0 = u.pm * BM + wr * 64 + fr; const int pn = u.pn;
;         const int mode = pn < 8 ? 1 : (pn < 18 ? 0 : 2);
;         bf16_t* base = mode == 2 ? ZG : ZA; const int ldc = mode == 2 ? ZGW : ZAW; const int col0 = (mode == 2 ? (pn - 18) : pn) * BM + wc * 32 + 8 * fq;
; #pragma unroll
;         for (int ai = 0; ai < 2; ++ai)
; #pragma unroll
;             for (int m = 0; m < 4; ++m) { bf16_t* rowp = base + (size_t)(row0 + ai * HALF + m * 16) * ldc + col0;
; #pragma unroll
;                 for (int bj = 0; bj < 2; ++bj) { f32x4 v0 = acc[ai][bj][m][0], v1 = acc[ai][bj][m][1];
;                     if (mode == 1) { f32x2 a = gelu_pk((f32x2){v0[0], v0[1]}), b = gelu_pk((f32x2){v0[2], v0[3]}), c = gelu_pk((f32x2){v1[0], v1[1]}), d = gelu_pk((f32x2){v1[2], v1[3]});
;                         v0 = (f32x4){a.x, a.y, b.x, b.y}; v1 = (f32x4){c.x, c.y, d.x, d.y}; }
.Lhalf_skip_x_2:
	s_cmp_lt_i32 s8, 8
	s_cselect_b64 s[48:49], -1, 0
	s_cmp_gt_i32 s8, 17
	s_cselect_b64 s[50:51], -1, 0
	s_cmp_gt_i32 s8, 7
	s_mov_b64 s[6:7], -1
	s_cbranch_scc1 .LBB0_283
	v_and_b32_e32 v151, 0x7fffffff, v125
	v_and_b32_e32 v150, 0x7fffffff, v124
	v_pk_fma_f32 v[150:151], v[150:151], s[14:15], 1.0 op_sel_hi:[1,0,0]
	v_mov_b64_e32 v[156:157], s[18:19]
	v_rcp_f32_e32 v150, v150
	v_rcp_f32_e32 v151, v151
	v_pk_mul_f32 v[154:155], v[124:125], v[124:125]
	v_and_b32_e32 v159, 0x7fffffff, v127
	v_pk_mul_f32 v[154:155], v[154:155], s[26:27] op_sel_hi:[1,0]
	v_pk_fma_f32 v[152:153], v[150:151], s[16:17], v[156:157] op_sel_hi:[1,0,0]
	v_exp_f32_e32 v154, v154
	v_pk_fma_f32 v[152:153], v[150:151], v[152:153], s[20:21] op_sel_hi:[1,1,0]
	v_exp_f32_e32 v155, v155
	v_pk_fma_f32 v[152:153], v[150:151], v[152:153], s[22:23] op_sel_hi:[1,1,0]
	v_and_b32_e32 v158, 0x7fffffff, v126
	v_pk_fma_f32 v[152:153], v[150:151], v[152:153], s[24:25] op_sel_hi:[1,1,0]
	v_pk_fma_f32 v[158:159], v[158:159], s[14:15], 1.0 op_sel_hi:[1,0,0]
	v_pk_mul_f32 v[150:151], v[150:151], v[152:153]
	v_rcp_f32_e32 v158, v158
	v_rcp_f32_e32 v159, v159
	v_pk_mul_f32 v[150:151], v[154:155], v[150:151]
	v_cmp_gt_f32_e32 vcc, 0, v124
	v_pk_mul_f32 v[154:155], v[124:125], v[150:151]
	v_pk_fma_f32 v[150:151], v[124:125], v[150:151], v[124:125] neg_lo:[1,0,0] neg_hi:[1,0,0]
	v_pk_mul_f32 v[152:153], v[126:127], v[126:127]
	v_cndmask_b32_e32 v150, v150, v154, vcc
	v_cmp_gt_f32_e32 vcc, 0, v125
	v_pk_mul_f32 v[152:153], v[152:153], s[26:27] op_sel_hi:[1,0]
	v_and_b32_e32 v163, 0x7fffffff, v123
	v_cndmask_b32_e32 v151, v151, v155, vcc
	v_pk_fma_f32 v[154:155], v[158:159], s[16:17], v[156:157] op_sel_hi:[1,0,0]
	v_exp_f32_e32 v152, v152
	v_pk_fma_f32 v[154:155], v[158:159], v[154:155], s[20:21] op_sel_hi:[1,1,0]
	v_exp_f32_e32 v153, v153
	v_pk_fma_f32 v[154:155], v[158:159], v[154:155], s[22:23] op_sel_hi:[1,1,0]
	v_cmp_gt_f32_e32 vcc, 0, v126
	v_pk_fma_f32 v[154:155], v[158:159], v[154:155], s[24:25] op_sel_hi:[1,1,0]
	v_and_b32_e32 v162, 0x7fffffff, v122
	v_pk_mul_f32 v[154:155], v[158:159], v[154:155]
	v_and_b32_e32 v159, 0x7fffffff, v121
	v_and_b32_e32 v158, 0x7fffffff, v120
	v_pk_fma_f32 v[158:159], v[158:159], s[14:15], 1.0 op_sel_hi:[1,0,0]
	v_pk_mul_f32 v[152:153], v[152:153], v[154:155]
	v_rcp_f32_e32 v158, v158
	v_rcp_f32_e32 v159, v159
	v_pk_mul_f32 v[154:155], v[126:127], v[152:153]
	v_pk_fma_f32 v[152:153], v[126:127], v[152:153], v[126:127] neg_lo:[1,0,0] neg_hi:[1,0,0]
	v_pk_fma_f32 v[162:163], v[162:163], s[14:15], 1.0 op_sel_hi:[1,0,0]
	v_cndmask_b32_e32 v152, v152, v154, vcc
	v_cmp_gt_f32_e32 vcc, 0, v127
	v_rcp_f32_e32 v162, v162
	v_rcp_f32_e32 v163, v163
	v_cndmask_b32_e32 v153, v153, v155, vcc
	v_pk_fma_f32 v[154:155], v[158:159], s[16:17], v[156:157] op_sel_hi:[1,0,0]
	v_pk_mul_f32 v[160:161], v[120:121], v[120:121]
	v_pk_fma_f32 v[154:155], v[158:159], v[154:155], s[20:21] op_sel_hi:[1,1,0]
	v_pk_mul_f32 v[160:161], v[160:161], s[26:27] op_sel_hi:[1,0]
	v_pk_fma_f32 v[154:155], v[158:159], v[154:155], s[22:23] op_sel_hi:[1,1,0]
	v_exp_f32_e32 v160, v160
	v_pk_fma_f32 v[154:155], v[158:159], v[154:155], s[24:25] op_sel_hi:[1,1,0]
	v_exp_f32_e32 v161, v161
	v_pk_mul_f32 v[154:155], v[158:159], v[154:155]
	v_pk_mul_f32 v[158:159], v[122:123], v[122:123]
	v_pk_fma_f32 v[156:157], v[162:163], s[16:17], v[156:157] op_sel_hi:[1,0,0]
	v_pk_mul_f32 v[158:159], v[158:159], s[26:27] op_sel_hi:[1,0]
	v_pk_fma_f32 v[156:157], v[162:163], v[156:157], s[20:21] op_sel_hi:[1,1,0]
	v_exp_f32_e32 v158, v158
	v_exp_f32_e32 v159, v159
	v_pk_fma_f32 v[156:157], v[162:163], v[156:157], s[22:23] op_sel_hi:[1,1,0]
	v_pk_mul_f32 v[154:155], v[160:161], v[154:155]
	v_pk_fma_f32 v[156:157], v[162:163], v[156:157], s[24:25] op_sel_hi:[1,1,0]
	v_pk_mul_f32 v[160:161], v[120:121], v[154:155]
	v_pk_fma_f32 v[154:155], v[120:121], v[154:155], v[120:121] neg_lo:[1,0,0] neg_hi:[1,0,0]
	v_cmp_gt_f32_e32 vcc, 0, v120
	v_pk_mul_f32 v[156:157], v[162:163], v[156:157]
	s_mov_b64 s[6:7], 0
	v_cndmask_b32_e32 v154, v154, v160, vcc
	v_cmp_gt_f32_e32 vcc, 0, v121
	v_pk_mul_f32 v[156:157], v[158:159], v[156:157]
	s_nop 0
	v_cndmask_b32_e32 v155, v155, v161, vcc
	v_pk_mul_f32 v[158:159], v[122:123], v[156:157]
	v_pk_fma_f32 v[156:157], v[122:123], v[156:157], v[122:123] neg_lo:[1,0,0] neg_hi:[1,0,0]
	v_cmp_gt_f32_e32 vcc, 0, v122
	s_nop 1
	v_cndmask_b32_e32 v156, v156, v158, vcc
	v_cmp_gt_f32_e32 vcc, 0, v123
	s_nop 1
	v_cndmask_b32_e32 v157, v157, v159, vcc

; #define PG8_WAIT_V(n) asm volatile("s_waitcnt vmcnt(" #n ")" ::: "memory")
; #define PG8_BAR __builtin_amdgcn_s_barrier()
; template <class Epi, class Sched>
; __device__ __forceinline__ void gemm_phase(PG8_LAS unsigned char* lds, const Gemm g, const Sched& S, const Epi& E) {
;     ...
;     PG8_WAIT_V(0);
;     if (wr == 0) PG8_BAR;
;     PG8_BAR;
.LBB0_376:
	s_waitcnt vmcnt(0)
	s_cmpk_gt_u32 s19, 0xff
	s_cbranch_scc1 .LBB0_378
.LBB0_378:
	s_barrier

;     __host__ __device__ bool next(int i, Unit& u) const { const int j = i / 3; if (!StaticOrder::next(j, u)) return false; u.br = i - 3 * j; return true; }
; #define PG8_STAGE(bufoff, gbase, voff) do { _Pragma("unroll") for (int _i = 0; _i < 2; ++_i) \
;         __builtin_amdgcn_global_load_lds((const unsigned*)((const char*)(gbase) + (voff)[_i]), (PG8_LAS unsigned*)(lds + (bufoff) + ldsw + _i * 8192), 16, 0, 0); } while (0)
; template <class Epi, class Sched>
; __device__ __forceinline__ void gemm_phase(PG8_LAS unsigned char* lds, const Gemm g, const Sched& S, const Epi& E) {
;     ...
;     const int tid = tix_, wid = __builtin_amdgcn_readfirstlane(tid >> 6), lane = tid & 63, wr = wid >> 2, wc = wid & 3, fr = lane & 15, fq = lane >> 4;
;     const int K = g.K, nt = K / BK;
;     unsigned voffA[2], voffB[2];
; #pragma unroll
;     for (int i = 0; i < 2; ++i) { int R, C; stage_rc(tid * 16 + i * 8192, R, C);
;         voffA[i] = (unsigned)(R * K + C) * 2u; voffB[i] = (unsigned)(tid * 16 + i * 8192); }
;     const size_t kstep = (size_t)(BK * 2);
;     const size_t hstep = (size_t)HALF * K * 2;
;     const size_t tstep = 2 * hstep;
;     const size_t kstepB = 32768, hstepB = 16384, tstepB = (size_t)nt * 32768;
;     const unsigned ldsw = (unsigned)wid * 1024u;
;     const int aoff = lds_byte(wr * 64 + fr, fq * 8), boff = lds_byte(wc * 32 + fr, fq * 8);
;     ...
;     Unit cur, nxt; int ui = 0;
;     if (!S.next(0, cur)) return;
;     f32x4 acc[2][2][4][2];
; #pragma unroll
;     for (int a = 0; a < 2; ++a)
; #pragma unroll
;         for (int b = 0; b < 2; ++b)
; #pragma unroll
;             for (int m = 0; m < 4; ++m)
; #pragma unroll
;                 for (int n = 0; n < 2; ++n) acc[a][b][m][n] = (f32x4){0.f, 0.f, 0.f, 0.f};
;     bf16x8 At[4][2], B0[2][2], B1[2][2];
;     const char* cA = (const char*)g.A + (size_t)cur.pm * tstep + (size_t)cur.br * g.strideA; const char* cB = (const char*)g.Bt + (size_t)cur.pn * tstepB + (size_t)cur.br * g.strideB;
;     S.a_ready(cur);
;     PG8_STAGE(PG8_SB(0, 0), cB, voffB); PG8_STAGE(PG8_SA(0, 0), cA, voffA); PG8_STAGE(PG8_SB(0, 1), cB + hstepB, voffB); PG8_STAGE(PG8_SA(0, 1), cA + hstep, voffA);
;     if (wr == 1) PG8_BAR;
;     PG8_WAIT_V(4); PG8_BAR;
;     PG8_STAGE(PG8_SB(1, 0), cB + kstepB, voffB); PG8_STAGE(PG8_SA(1, 0), cA + kstep, voffA); PG8_STAGE(PG8_SB(1, 1), cB + hstepB + kstepB, voffB);
;     PG8_WAIT_V(6); PG8_BAR;
.LBB0_385:
	s_andn2_b64 vcc, exec, s[6:7]
	s_cbranch_vccnz .LBB0_465
	v_ashrrev_i32_e32 v0, 31, v4
	v_lshrrev_b32_e32 v0, 26, v0
	v_add_u32_e32 v0, v4, v0
	v_ashrrev_i32_e32 v5, 6, v0
	v_bfe_i32 v0, v4, 27, 1
	v_lshlrev_b32_e32 v128, 4, v4
	v_lshrrev_b32_e32 v0, 22, v0
	v_add_u32_e32 v0, v128, v0
	v_and_b32_e32 v0, 0xfffffc00, v0
	v_sub_u32_e32 v0, v128, v0
	v_lshrrev_b32_e32 v1, 4, v0
	v_bitop3_b32 v0, v1, v0, 32 bitop3:0x6c
	v_ashrrev_i32_e32 v2, 31, v0
	v_lshrrev_b32_e32 v2, 26, v2
	v_add_u32_e32 v2, v0, v2
	v_ashrrev_i32_e32 v6, 6, v2
	v_and_b32_e32 v2, 0xc0, v2
	v_sub_u32_e32 v0, v0, v2
	v_mov_b32_e32 v146, 1
	v_lshlrev_b32_e32 v1, 3, v5
	v_lshlrev_b32_e32 v3, 5, v5
	v_ashrrev_i16_sdwa v0, v146, sext(v0) dst_sel:DWORD dst_unused:UNUSED_PAD src0_sel:DWORD src1_sel:BYTE_0
	v_and_b32_e32 v1, 0xffff0, v1
	v_and_b32_e32 v3, 32, v3
	v_bfe_i32 v7, v0, 0, 16
	v_add_u32_e32 v0, v3, v7
	v_add_lshl_u32 v1, v6, v1, 12
	v_add_u32_e32 v132, 0x2000, v128
	v_lshl_add_u32 v130, v0, 1, v1
	v_ashrrev_i32_e32 v0, 31, v132
	v_lshrrev_b32_e32 v0, 22, v0
	v_add_u32_e32 v0, v132, v0
	v_ashrrev_i32_e32 v8, 10, v0
	s_waitcnt lgkmcnt(0)
	s_add_u32 s37, s10, 0x6a80000
	v_mul_i32_i24_e32 v0, 0x400, v8
	s_addc_u32 s38, s11, 0
	v_sub_u32_e32 v0, v132, v0
	s_ashr_i32 s7, s36, 6
	s_ashr_i32 s6, s36, 8
	v_lshrrev_b32_e32 v1, 4, v0
	s_lshl_b32 s39, s7, 10
	v_bitop3_b32 v0, v1, v0, 32 bitop3:0x6c
	s_add_u32 s46, s10, 0x2d300000
	v_ashrrev_i32_e32 v2, 31, v0
	s_addc_u32 s47, s11, 0
	s_ashr_i32 s23, s22, 31
	s_ashr_i32 s5, s4, 31
	v_lshrrev_b32_e32 v2, 26, v2
	s_lshl_b64 s[8:9], s[22:23], 20
	s_lshl_b64 s[12:13], s[4:5], 20
	v_add_u32_e32 v2, v0, v2
	s_add_u32 s24, s37, s12
	v_ashrrev_i32_e32 v9, 6, v2
	v_and_b32_e32 v2, 0xc0, v2
	s_addc_u32 s25, s38, s13
	s_add_i32 s48, s39, 0
	v_sub_u32_e32 v0, v0, v2
	s_add_i32 m0, s48, 0x10000
	v_lshlrev_b32_e32 v1, 3, v8
	v_lshlrev_b32_e32 v3, 5, v8
	v_ashrrev_i16_sdwa v0, v146, sext(v0) dst_sel:DWORD dst_unused:UNUSED_PAD src0_sel:DWORD src1_sel:BYTE_0
	global_load_lds_dwordx4 v128, s[24:25]
	s_add_i32 m0, s48, 0x12000
	v_and_b32_e32 v1, 0xffff0, v1
	v_and_b32_e32 v3, 32, v3
	v_bfe_i32 v10, v0, 0, 16
	s_add_u32 s26, s46, s8
	v_add_u32_e32 v0, v3, v10
	v_add_lshl_u32 v1, v9, v1, 12
	global_load_lds_dwordx4 v132, s[24:25]
	s_addc_u32 s27, s47, s9
	s_mov_b32 m0, s48
	s_add_i32 s49, s48, 0x2000
	v_lshl_add_u32 v134, v0, 1, v1
	global_load_lds_dwordx4 v130, s[26:27]
	s_mov_b32 m0, s49
	s_add_u32 s8, s24, 0x4000
	global_load_lds_dwordx4 v134, s[26:27]
	s_addc_u32 s9, s25, 0
	s_add_i32 m0, s48, 0x14000
	v_mov_b32_e32 v137, 0
	global_load_lds_dwordx4 v128, s[8:9]
	s_add_i32 m0, s48, 0x16000
	v_mov_b32_e32 v131, v137
	global_load_lds_dwordx4 v132, s[8:9]
	s_add_u32 s8, s26, 0x80000
	s_addc_u32 s9, s27, 0
	s_add_i32 s50, s48, 0x4000
	s_mov_b32 m0, s50
	s_add_i32 s51, s48, 0x6000
	global_load_lds_dwordx4 v130, s[8:9]
	s_mov_b32 m0, s51
	v_mov_b32_e32 v135, v137
	global_load_lds_dwordx4 v134, s[8:9]
	s_mov_b32 s53, 0
	v_mov_b32_e32 v129, v137
	v_mov_b32_e32 v133, v137
	v_lshl_add_u64 v[2:3], s[26:27], 0, v[130:131]
	s_cmp_lg_u32 s6, 1
	v_lshl_add_u64 v[0:1], s[26:27], 0, v[134:135]
	s_cbranch_scc1 .LBB0_388
.LBB0_388:
	s_lshl_b32 s54, s6, 6
	s_lshl_b32 s5, s6, 13
	s_lshl_b32 s6, s7, 5
	s_and_b32 s14, s6, 0x60
	s_lshl_b32 s15, s14, 7
	s_add_u32 s6, s10, 0x2d700000
	s_addc_u32 s7, s11, 0
	s_add_u32 s8, s10, 0x2db00000
	s_addc_u32 s9, s11, 0
	s_add_u32 s10, s24, 0x8000
	s_addc_u32 s11, s25, 0
	s_add_i32 m0, s48, 0x18000
	v_lshl_add_u64 v[12:13], s[10:11], 0, v[128:129]
	s_waitcnt vmcnt(4)
	s_barrier
	global_load_lds_dwordx4 v[12:13], off
	v_lshl_add_u64 v[12:13], s[10:11], 0, v[132:133]
	s_add_i32 m0, s48, 0x1a000
	s_mov_b64 s[10:11], 0x80
	s_add_i32 s55, s48, 0x8000
	s_add_i32 s56, s48, 0xa000
	global_load_lds_dwordx4 v[12:13], off
	v_lshl_add_u64 v[2:3], v[2:3], 0, s[10:11]
	s_mov_b32 m0, s55
	s_add_u32 s12, s24, 0xc000
	global_load_lds_dwordx4 v[2:3], off
	v_lshl_add_u64 v[0:1], v[0:1], 0, s[10:11]
	s_mov_b32 m0, s56
	s_addc_u32 s13, s25, 0
	global_load_lds_dwordx4 v[0:1], off
	s_add_i32 m0, s48, 0x1c000
	v_lshl_add_u64 v[0:1], s[12:13], 0, v[128:129]
	global_load_lds_dwordx4 v[0:1], off
	v_lshl_add_u64 v[0:1], s[12:13], 0, v[132:133]
	s_add_i32 m0, s48, 0x1e000
	v_and_b32_e32 v147, 15, v4
	global_load_lds_dwordx4 v[0:1], off
	v_lshrrev_b32_e32 v0, 1, v4
	v_and_b32_e32 v0, 24, v0
	v_lshlrev_b32_e32 v1, 1, v0
	v_lshlrev_b32_e32 v2, 2, v4
	v_or_b32_e32 v149, s14, v0
	v_lshlrev_b32_e32 v0, 15, v5
	v_lshl_or_b32 v1, v147, 6, v1
	v_and_b32_e32 v2, 32, v2
	v_and_b32_e32 v0, 0xffff0000, v0
	v_bitop3_b32 v3, v1, s5, v2 bitop3:0xde
	v_bitop3_b32 v148, v1, s15, v2 bitop3:0xde
	v_lshl_add_u32 v0, v6, 12, v0
	v_and_b32_e32 v1, 1, v5
	v_lshl_or_b32 v0, v1, 6, v0
	v_lshl_add_u32 v138, v7, 1, v0
	v_lshlrev_b32_e32 v0, 15, v8
	v_and_b32_e32 v0, 0xffff0000, v0
	s_waitcnt vmcnt(6)
	v_lshl_add_u32 v0, v9, 12, v0
	v_and_b32_e32 v1, 1, v8
	v_lshl_or_b32 v0, v1, 6, v0
	s_add_i32 s59, 0, 0x10000
	s_add_i32 s60, 0, 0x14000
	s_ashr_i32 s57, s52, 31
	v_mov_b32_e32 v139, v137
	v_lshl_add_u32 v140, v10, 1, v0
	v_mov_b32_e32 v141, v137
	s_movk_i32 s58, 0xf8
	v_add_u32_e32 v150, s59, v148
	v_add_u32_e32 v151, 0, v3
	v_add_u32_e32 v152, s60, v148
	s_movk_i32 s61, 0xdf
	s_movk_i32 s62, 0xef
	s_movk_i32 s63, 0xff
	v_mov_b32_e32 v153, 0xcf
	s_barrier
	s_branch .LBB0_390

;     __host__ __device__ bool next(int i, Unit& u) const { const int j = i / 3; if (!StaticOrder::next(j, u)) return false; u.br = i - 3 * j; return true; }
; #define PG8_STAGE(bufoff, gbase, voff) do { _Pragma("unroll") for (int _i = 0; _i < 2; ++_i) \
;         __builtin_amdgcn_global_load_lds((const unsigned*)((const char*)(gbase) + (voff)[_i]), (PG8_LAS unsigned*)(lds + (bufoff) + ldsw + _i * 8192), 16, 0, 0); } while (0)
; #define PG8_LDA(dst, b, h) do { _Pragma("unroll") for (int m = 0; m < 4; ++m) _Pragma("unroll") for (int k = 0; k < 2; ++k) dst[m][k] = *(const PG8_LAS bf16x8*)(lds + PG8_SA(b, h) + aoff + m * 2048 + k * 1024); } while (0)
; #define PG8_LDB(dst, b, h) do { _Pragma("unroll") for (int n = 0; n < 2; ++n) _Pragma("unroll") for (int k = 0; k < 2; ++k) dst[n][k] = *(const PG8_LAS bf16x8*)(lds + PG8_SB(b, h) + boff + n * 2048 + k * 1024); } while (0)
; #define PG8_WAIT_L(n) asm volatile("s_waitcnt lgkmcnt(" #n ")" ::: "memory")
; #define PG8_BAR __builtin_amdgcn_s_barrier()
; #define PG8_SCHED __builtin_amdgcn_sched_barrier(0)
; template <class Epi, class Sched>
; __device__ __forceinline__ void gemm_phase(PG8_LAS unsigned char* lds, const Gemm g, const Sched& S, const Epi& E) {
;     ...
;         const bool has_next = S.next(ui + 1, nxt);
;         const char* nA = has_next ? (const char*)g.A + (size_t)nxt.pm * tstep + (size_t)nxt.br * g.strideA : cA; const char* nB = has_next ? (const char*)g.Bt + (size_t)nxt.pn * tstepB + (size_t)nxt.br * g.strideB : cB;
;         for (int t = 0; t < nt; t += 2) {
;             const bool last = (t == nt - 2);
;             const char* a1 = cA + (size_t)(t + 1) * kstep;
;             const char* a2 = last ? nA : cA + (size_t)(t + 2) * kstep; const char* b2 = last ? nB : cB + (size_t)(t + 2) * kstepB;
;             const char* a3 = a2 + kstep; const char* b3 = b2 + kstepB;
;             if (last && has_next) S.a_ready(nxt);
;             PG8_LDB(B0, 0, 0); PG8_SCHED; PG8_LDA(At, 0, 0); PG8_STAGE(PG8_SA(1, 1), a1 + hstep, voffA);
;             PG8_WAIT_L(8); PG8_BAR; PG8_WAIT_L(0); PG8_MMA(0, 0, At, B0); PG8_BAR; PG8_SCHED;
;     ...
;         for (int a = 0; a < 2; ++a)
; #pragma unroll
;             for (int b = 0; b < 2; ++b)
; #pragma unroll
;                 for (int m = 0; m < 4; ++m)
; #pragma unroll
;                     for (int n = 0; n < 2; ++n) acc[a][b][m][n] = (f32x4){0.f, 0.f, 0.f, 0.f};
.LBB0_396:
	s_ashr_i32 s15, s14, 31
	v_cmp_lt_i64_e64 s[28:29], s[18:19], 32
	s_lshl_b64 s[18:19], s[14:15], 20
	s_add_u32 s18, s46, s18
	s_addc_u32 s19, s47, s19
	s_and_b64 s[20:21], s[28:29], exec
	s_cselect_b32 s5, s19, s27
	s_cselect_b32 s15, s18, s26
	s_ashr_i32 s17, s16, 31
	s_lshl_b64 s[20:21], s[16:17], 20
	s_add_u32 s20, s37, s20
	s_addc_u32 s21, s38, s21
	s_and_b64 s[28:29], s[28:29], exec
	s_cselect_b32 s17, s21, s25
	s_cselect_b32 s23, s20, s24
	s_add_u32 s64, s24, 0x10000
	s_addc_u32 s65, s25, 0
	s_add_u32 s24, s26, 0x80080
	v_mov_b32_e32 v0, 0
	s_addc_u32 s25, s27, 0
	s_mov_b32 s66, -2
	v_mov_b32_e32 v1, v0
	v_mov_b32_e32 v2, v0
	v_mov_b32_e32 v3, v0
	v_mov_b32_e32 v4, v0
	v_mov_b32_e32 v5, v0
	v_mov_b32_e32 v6, v0
	v_mov_b32_e32 v7, v0
	v_mov_b32_e32 v16, v0
	v_mov_b32_e32 v17, v0
	v_mov_b32_e32 v18, v0
	v_mov_b32_e32 v19, v0
	v_mov_b32_e32 v20, v0
	v_mov_b32_e32 v21, v0
	v_mov_b32_e32 v22, v0
	v_mov_b32_e32 v23, v0
	v_mov_b32_e32 v32, v0
	v_mov_b32_e32 v33, v0
	v_mov_b32_e32 v34, v0
	v_mov_b32_e32 v35, v0
	v_mov_b32_e32 v36, v0
	v_mov_b32_e32 v37, v0
	v_mov_b32_e32 v38, v0
	v_mov_b32_e32 v39, v0
	v_mov_b32_e32 v48, v0
	v_mov_b32_e32 v49, v0
	v_mov_b32_e32 v50, v0
	v_mov_b32_e32 v51, v0
	v_mov_b32_e32 v52, v0
	v_mov_b32_e32 v53, v0
	v_mov_b32_e32 v54, v0
	v_mov_b32_e32 v55, v0
	v_mov_b32_e32 v8, v0
	v_mov_b32_e32 v9, v0
	v_mov_b32_e32 v10, v0
	v_mov_b32_e32 v11, v0
	v_mov_b32_e32 v12, v0
	v_mov_b32_e32 v13, v0
	v_mov_b32_e32 v14, v0
	v_mov_b32_e32 v15, v0
	v_mov_b32_e32 v24, v0
	v_mov_b32_e32 v25, v0
	v_mov_b32_e32 v26, v0
	v_mov_b32_e32 v27, v0
	v_mov_b32_e32 v28, v0
	v_mov_b32_e32 v29, v0
	v_mov_b32_e32 v30, v0
	v_mov_b32_e32 v31, v0
	v_mov_b32_e32 v40, v0
	v_mov_b32_e32 v41, v0
	v_mov_b32_e32 v42, v0
	v_mov_b32_e32 v43, v0
	v_mov_b32_e32 v44, v0
	v_mov_b32_e32 v45, v0
	v_mov_b32_e32 v46, v0
	v_mov_b32_e32 v47, v0
	v_mov_b32_e32 v56, v0
	v_mov_b32_e32 v57, v0
	v_mov_b32_e32 v58, v0
	v_mov_b32_e32 v59, v0
	v_mov_b32_e32 v60, v0
	v_mov_b32_e32 v61, v0
	v_mov_b32_e32 v62, v0
	v_mov_b32_e32 v63, v0
	v_mov_b32_e32 v64, v0
	v_mov_b32_e32 v65, v0
	v_mov_b32_e32 v66, v0
	v_mov_b32_e32 v67, v0
	v_mov_b32_e32 v68, v0
	v_mov_b32_e32 v69, v0
	v_mov_b32_e32 v70, v0
	v_mov_b32_e32 v71, v0
	v_mov_b32_e32 v80, v0
	v_mov_b32_e32 v81, v0
	v_mov_b32_e32 v82, v0
	v_mov_b32_e32 v83, v0
	v_mov_b32_e32 v84, v0
	v_mov_b32_e32 v85, v0
	v_mov_b32_e32 v86, v0
	v_mov_b32_e32 v87, v0
	v_mov_b32_e32 v96, v0
	v_mov_b32_e32 v97, v0
	v_mov_b32_e32 v98, v0
	v_mov_b32_e32 v99, v0
	v_mov_b32_e32 v100, v0
	v_mov_b32_e32 v101, v0
	v_mov_b32_e32 v102, v0
	v_mov_b32_e32 v103, v0
	v_mov_b32_e32 v112, v0
	v_mov_b32_e32 v113, v0
	v_mov_b32_e32 v114, v0
	v_mov_b32_e32 v115, v0
	v_mov_b32_e32 v116, v0
	v_mov_b32_e32 v117, v0
	v_mov_b32_e32 v118, v0
	v_mov_b32_e32 v119, v0
	v_mov_b32_e32 v72, v0
	v_mov_b32_e32 v73, v0
	v_mov_b32_e32 v74, v0
	v_mov_b32_e32 v75, v0
	v_mov_b32_e32 v76, v0
	v_mov_b32_e32 v77, v0
	v_mov_b32_e32 v78, v0
	v_mov_b32_e32 v79, v0
	v_mov_b32_e32 v88, v0
	v_mov_b32_e32 v89, v0
	v_mov_b32_e32 v90, v0
	v_mov_b32_e32 v91, v0
	v_mov_b32_e32 v92, v0
	v_mov_b32_e32 v93, v0
	v_mov_b32_e32 v94, v0
	v_mov_b32_e32 v95, v0
	v_mov_b32_e32 v104, v0
	v_mov_b32_e32 v105, v0
	v_mov_b32_e32 v106, v0
	v_mov_b32_e32 v107, v0
	v_mov_b32_e32 v108, v0
	v_mov_b32_e32 v109, v0
	v_mov_b32_e32 v110, v0
	v_mov_b32_e32 v111, v0
	v_mov_b32_e32 v120, v0
	v_mov_b32_e32 v121, v0
	v_mov_b32_e32 v122, v0
	v_mov_b32_e32 v123, v0
	v_mov_b32_e32 v124, v0
	v_mov_b32_e32 v125, v0
	v_mov_b32_e32 v126, v0
	v_mov_b32_e32 v127, v0
	s_cmp_eq_u32 s78, 1
	s_cbranch_scc0 .Lhalf_skip_y_3
	s_barrier
.Lhalf_skip_y_3:
.LBB0_397:
	ds_read_b128 v[142:145], v150
	ds_read_b128 v[154:157], v150 offset:1024
	ds_read_b128 v[158:161], v150 offset:2048
	ds_read_b128 v[162:165], v150 offset:3072
	s_add_u32 s26, s24, 0xfff80080
	s_addc_u32 s27, s25, -1
	s_cmp_eq_u32 s66, 28
	s_cselect_b32 s29, s5, s27
	s_cselect_b32 s28, s15, s26
	s_cselect_b32 s27, s17, s65
	s_cselect_b32 s26, s23, s64
	v_lshl_add_u64 v[198:199], s[24:25], 0, v[138:139]
	s_add_i32 m0, s48, 0xc000
	ds_read_b128 v[166:169], v151
	ds_read_b128 v[170:173], v151 offset:1024
	ds_read_b128 v[174:177], v151 offset:2048
	ds_read_b128 v[178:181], v151 offset:3072
	ds_read_b128 v[182:185], v151 offset:4096
	ds_read_b128 v[186:189], v151 offset:5120
	ds_read_b128 v[190:193], v151 offset:6144
	ds_read_b128 v[194:197], v151 offset:7168
	global_load_lds_dwordx4 v[198:199], off
	v_lshl_add_u64 v[198:199], s[24:25], 0, v[140:141]
	s_add_i32 m0, s48, 0xe000
	s_nop 0
	global_load_lds_dwordx4 v[198:199], off
	s_waitcnt lgkmcnt(8)
	s_barrier
	s_waitcnt lgkmcnt(0)
	s_setprio 1
	s_waitcnt lgkmcnt(0)
	v_mfma_f32_16x16x32_bf16 v[124:127], v[142:145], v[166:169], v[124:127]
	v_mfma_f32_16x16x32_bf16 v[120:123], v[158:161], v[166:169], v[120:123]
	v_mfma_f32_16x16x32_bf16 v[108:111], v[142:145], v[174:177], v[108:111]
	v_mfma_f32_16x16x32_bf16 v[104:107], v[158:161], v[174:177], v[104:107]
	v_mfma_f32_16x16x32_bf16 v[92:95], v[142:145], v[182:185], v[92:95]
	v_mfma_f32_16x16x32_bf16 v[88:91], v[158:161], v[182:185], v[88:91]
	v_mfma_f32_16x16x32_bf16 v[76:79], v[142:145], v[190:193], v[76:79]
	v_mfma_f32_16x16x32_bf16 v[72:75], v[158:161], v[190:193], v[72:75]
	v_mfma_f32_16x16x32_bf16 v[124:127], v[154:157], v[170:173], v[124:127]
	v_mfma_f32_16x16x32_bf16 v[120:123], v[162:165], v[170:173], v[120:123]
	v_mfma_f32_16x16x32_bf16 v[108:111], v[154:157], v[178:181], v[108:111]
	v_mfma_f32_16x16x32_bf16 v[104:107], v[162:165], v[178:181], v[104:107]
	v_mfma_f32_16x16x32_bf16 v[92:95], v[154:157], v[186:189], v[92:95]
	v_mfma_f32_16x16x32_bf16 v[88:91], v[162:165], v[186:189], v[88:91]
	v_mfma_f32_16x16x32_bf16 v[76:79], v[154:157], v[194:197], v[76:79]
	v_mfma_f32_16x16x32_bf16 v[72:75], v[162:165], v[194:197], v[72:75]
	s_setprio 0
	s_barrier
; #define PG8_STAGE(bufoff, gbase, voff) do { _Pragma("unroll") for (int _i = 0; _i < 2; ++_i) \
;         __builtin_amdgcn_global_load_lds((const unsigned*)((const char*)(gbase) + (voff)[_i]), (PG8_LAS unsigned*)(lds + (bufoff) + ldsw + _i * 8192), 16, 0, 0); } while (0)
; #define PG8_LDA(dst, b, h) do { _Pragma("unroll") for (int m = 0; m < 4; ++m) _Pragma("unroll") for (int k = 0; k < 2; ++k) dst[m][k] = *(const PG8_LAS bf16x8*)(lds + PG8_SA(b, h) + aoff + m * 2048 + k * 1024); } while (0)
; #define PG8_LDB(dst, b, h) do { _Pragma("unroll") for (int n = 0; n < 2; ++n) _Pragma("unroll") for (int k = 0; k < 2; ++k) dst[n][k] = *(const PG8_LAS bf16x8*)(lds + PG8_SB(b, h) + boff + n * 2048 + k * 1024); } while (0)
; #define PG8_MMA(ai, bj, At, Bt) do { __builtin_amdgcn_s_setprio(1); _Pragma("unroll") for (int m = 0; m < 4; ++m) _Pragma("unroll") for (int n = 0; n < 2; ++n) _Pragma("unroll") for (int k = 0; k < 2; ++k) \
;         acc[ai][bj][m][n] = __builtin_amdgcn_mfma_f32_16x16x32_bf16(Bt[n][k], At[m][k], acc[ai][bj][m][n], 0, 0, 0); __builtin_amdgcn_s_setprio(0); } while (0)
; #define PG8_WAIT_V(n) asm volatile("s_waitcnt vmcnt(" #n ")" ::: "memory")
; #define PG8_WAIT_L(n) asm volatile("s_waitcnt lgkmcnt(" #n ")" ::: "memory")
; #define PG8_BAR __builtin_amdgcn_s_barrier()
; #define PG8_SCHED __builtin_amdgcn_sched_barrier(0)
; template <class Epi, class Sched>
; __device__ __forceinline__ void gemm_phase(PG8_LAS unsigned char* lds, const Gemm g, const Sched& S, const Epi& E) {
;     ...
;             PG8_LDB(B1, 0, 1); PG8_STAGE(PG8_SB(0, 0), b2, voffB);
;             PG8_BAR; PG8_WAIT_L(0); PG8_MMA(0, 1, At, B1); PG8_BAR;
;             PG8_LDA(At, 0, 1); PG8_STAGE(PG8_SA(0, 0), a2, voffA);
;             PG8_BAR; PG8_WAIT_L(0); PG8_MMA(1, 0, At, B0); PG8_BAR; PG8_SCHED;
;             PG8_STAGE(PG8_SB(0, 1), b2 + hstepB, voffB);
;             PG8_WAIT_V(6); PG8_BAR; PG8_MMA(1, 1, At, B1); PG8_BAR;
;             PG8_LDB(B0, 1, 0); PG8_SCHED; PG8_LDA(At, 1, 0); PG8_STAGE(PG8_SA(0, 1), a2 + hstep, voffA);
;             PG8_WAIT_L(8); PG8_BAR; PG8_WAIT_L(0); PG8_MMA(0, 0, At, B0); PG8_BAR; PG8_SCHED;
	s_add_i32 s67, s59, s39
	v_lshl_add_u64 v[214:215], s[26:27], 0, v[128:129]
	s_mov_b32 m0, s67
	ds_read_b128 v[198:201], v152
	ds_read_b128 v[202:205], v152 offset:1024
	ds_read_b128 v[206:209], v152 offset:2048
	ds_read_b128 v[210:213], v152 offset:3072
	global_load_lds_dwordx4 v[214:215], off
	v_lshl_add_u64 v[214:215], s[26:27], 0, v[132:133]
	s_add_i32 m0, s67, 0x2000
	s_nop 0
	global_load_lds_dwordx4 v[214:215], off
	s_barrier
	s_waitcnt lgkmcnt(0)
	s_setprio 1
	s_waitcnt lgkmcnt(0)
	v_mfma_f32_16x16x32_bf16 v[116:119], v[198:201], v[166:169], v[116:119]
	v_mfma_f32_16x16x32_bf16 v[112:115], v[206:209], v[166:169], v[112:115]
	v_mfma_f32_16x16x32_bf16 v[100:103], v[198:201], v[174:177], v[100:103]
	v_mfma_f32_16x16x32_bf16 v[96:99], v[206:209], v[174:177], v[96:99]
	v_mfma_f32_16x16x32_bf16 v[84:87], v[198:201], v[182:185], v[84:87]
	v_mfma_f32_16x16x32_bf16 v[80:83], v[206:209], v[182:185], v[80:83]
	v_mfma_f32_16x16x32_bf16 v[68:71], v[198:201], v[190:193], v[68:71]
	v_mfma_f32_16x16x32_bf16 v[64:67], v[206:209], v[190:193], v[64:67]
	v_mfma_f32_16x16x32_bf16 v[116:119], v[202:205], v[170:173], v[116:119]
	v_mfma_f32_16x16x32_bf16 v[112:115], v[210:213], v[170:173], v[112:115]
	v_mfma_f32_16x16x32_bf16 v[100:103], v[202:205], v[178:181], v[100:103]
	v_mfma_f32_16x16x32_bf16 v[96:99], v[210:213], v[178:181], v[96:99]
	v_mfma_f32_16x16x32_bf16 v[84:87], v[202:205], v[186:189], v[84:87]
	v_mfma_f32_16x16x32_bf16 v[80:83], v[210:213], v[186:189], v[80:83]
	v_mfma_f32_16x16x32_bf16 v[68:71], v[202:205], v[194:197], v[68:71]
	v_mfma_f32_16x16x32_bf16 v[64:67], v[210:213], v[194:197], v[64:67]
	s_setprio 0
	s_mov_b32 m0, s48
	v_lshl_add_u64 v[214:215], s[28:29], 0, v[130:131]
	s_barrier
	ds_read_b128 v[166:169], v151 offset:16384
	ds_read_b128 v[170:173], v151 offset:17408
	ds_read_b128 v[174:177], v151 offset:18432
	ds_read_b128 v[178:181], v151 offset:19456
	ds_read_b128 v[182:185], v151 offset:20480
	ds_read_b128 v[186:189], v151 offset:21504
	ds_read_b128 v[190:193], v151 offset:22528
	ds_read_b128 v[194:197], v151 offset:23552
	global_load_lds_dwordx4 v[214:215], off
	v_lshl_add_u64 v[216:217], s[28:29], 0, v[134:135]
	s_mov_b32 m0, s49
	s_nop 0
	global_load_lds_dwordx4 v[216:217], off
	s_barrier
	s_waitcnt lgkmcnt(0)
	s_setprio 1
	s_waitcnt lgkmcnt(0)
	v_mfma_f32_16x16x32_bf16 v[60:63], v[142:145], v[166:169], v[60:63]
	v_mfma_f32_16x16x32_bf16 v[56:59], v[158:161], v[166:169], v[56:59]
	v_mfma_f32_16x16x32_bf16 v[44:47], v[142:145], v[174:177], v[44:47]
	v_mfma_f32_16x16x32_bf16 v[40:43], v[158:161], v[174:177], v[40:43]
	v_mfma_f32_16x16x32_bf16 v[28:31], v[142:145], v[182:185], v[28:31]
	v_mfma_f32_16x16x32_bf16 v[24:27], v[158:161], v[182:185], v[24:27]
	v_mfma_f32_16x16x32_bf16 v[12:15], v[142:145], v[190:193], v[12:15]
	v_mfma_f32_16x16x32_bf16 v[8:11], v[158:161], v[190:193], v[8:11]
	v_mfma_f32_16x16x32_bf16 v[60:63], v[154:157], v[170:173], v[60:63]
	v_mfma_f32_16x16x32_bf16 v[56:59], v[162:165], v[170:173], v[56:59]
	v_mfma_f32_16x16x32_bf16 v[44:47], v[154:157], v[178:181], v[44:47]
	v_mfma_f32_16x16x32_bf16 v[40:43], v[162:165], v[178:181], v[40:43]
	v_mfma_f32_16x16x32_bf16 v[28:31], v[154:157], v[186:189], v[28:31]
	v_mfma_f32_16x16x32_bf16 v[24:27], v[162:165], v[186:189], v[24:27]
	v_mfma_f32_16x16x32_bf16 v[12:15], v[154:157], v[194:197], v[12:15]
	v_mfma_f32_16x16x32_bf16 v[8:11], v[162:165], v[194:197], v[8:11]
	s_setprio 0
	s_barrier
	s_add_u32 s68, s26, 0x4000
	s_addc_u32 s69, s27, 0
	s_add_i32 s67, s60, s39
	v_lshl_add_u64 v[142:143], s[68:69], 0, v[128:129]
	s_mov_b32 m0, s67
	s_nop 0
	global_load_lds_dwordx4 v[142:143], off
	v_lshl_add_u64 v[142:143], s[68:69], 0, v[132:133]
	s_add_i32 m0, s67, 0x2000
	s_nop 0
	global_load_lds_dwordx4 v[142:143], off
	s_waitcnt vmcnt(6)
	s_barrier
	s_setprio 1
	v_mfma_f32_16x16x32_bf16 v[52:55], v[198:201], v[166:169], v[52:55]
	v_mfma_f32_16x16x32_bf16 v[48:51], v[206:209], v[166:169], v[48:51]
	v_mfma_f32_16x16x32_bf16 v[36:39], v[198:201], v[174:177], v[36:39]
	v_mfma_f32_16x16x32_bf16 v[32:35], v[206:209], v[174:177], v[32:35]
	v_mfma_f32_16x16x32_bf16 v[20:23], v[198:201], v[182:185], v[20:23]
	v_mfma_f32_16x16x32_bf16 v[16:19], v[206:209], v[182:185], v[16:19]
	v_mfma_f32_16x16x32_bf16 v[4:7], v[198:201], v[190:193], v[4:7]
	v_mfma_f32_16x16x32_bf16 v[0:3], v[206:209], v[190:193], v[0:3]
	v_mfma_f32_16x16x32_bf16 v[52:55], v[202:205], v[170:173], v[52:55]
	v_mfma_f32_16x16x32_bf16 v[48:51], v[210:213], v[170:173], v[48:51]
	v_mfma_f32_16x16x32_bf16 v[36:39], v[202:205], v[178:181], v[36:39]
	v_mfma_f32_16x16x32_bf16 v[32:35], v[210:213], v[178:181], v[32:35]
	v_mfma_f32_16x16x32_bf16 v[20:23], v[202:205], v[186:189], v[20:23]
	v_mfma_f32_16x16x32_bf16 v[16:19], v[210:213], v[186:189], v[16:19]
	v_mfma_f32_16x16x32_bf16 v[4:7], v[202:205], v[194:197], v[4:7]
	v_mfma_f32_16x16x32_bf16 v[0:3], v[210:213], v[194:197], v[0:3]
	s_setprio 0
	s_add_i32 s67, 0, 0x18000
	v_add_u32_e32 v136, s67, v148
	s_barrier
	ds_read_b128 v[142:145], v136
	ds_read_b128 v[154:157], v136 offset:1024
	ds_read_b128 v[158:161], v136 offset:2048
	ds_read_b128 v[162:165], v136 offset:3072
	s_add_u32 s28, s28, 0x80000
	s_addc_u32 s29, s29, 0
	s_mov_b32 m0, s50
	v_lshl_add_u64 v[198:199], s[28:29], 0, v[130:131]
	ds_read_b128 v[166:169], v151 offset:32768
	ds_read_b128 v[170:173], v151 offset:33792
	ds_read_b128 v[174:177], v151 offset:34816
	ds_read_b128 v[178:181], v151 offset:35840
	ds_read_b128 v[182:185], v151 offset:36864
	ds_read_b128 v[186:189], v151 offset:37888
	ds_read_b128 v[190:193], v151 offset:38912
	ds_read_b128 v[194:197], v151 offset:39936
	global_load_lds_dwordx4 v[198:199], off
	v_lshl_add_u64 v[198:199], s[28:29], 0, v[134:135]
	s_mov_b32 m0, s51
	s_nop 0
	global_load_lds_dwordx4 v[198:199], off
	s_waitcnt lgkmcnt(8)
	s_barrier
; #define PG8_STAGE(bufoff, gbase, voff) do { _Pragma("unroll") for (int _i = 0; _i < 2; ++_i) \
;         __builtin_amdgcn_global_load_lds((const unsigned*)((const char*)(gbase) + (voff)[_i]), (PG8_LAS unsigned*)(lds + (bufoff) + ldsw + _i * 8192), 16, 0, 0); } while (0)
; #define PG8_LDA(dst, b, h) do { _Pragma("unroll") for (int m = 0; m < 4; ++m) _Pragma("unroll") for (int k = 0; k < 2; ++k) dst[m][k] = *(const PG8_LAS bf16x8*)(lds + PG8_SA(b, h) + aoff + m * 2048 + k * 1024); } while (0)
; #define PG8_LDB(dst, b, h) do { _Pragma("unroll") for (int n = 0; n < 2; ++n) _Pragma("unroll") for (int k = 0; k < 2; ++k) dst[n][k] = *(const PG8_LAS bf16x8*)(lds + PG8_SB(b, h) + boff + n * 2048 + k * 1024); } while (0)
; #define PG8_MMA(ai, bj, At, Bt) do { __builtin_amdgcn_s_setprio(1); _Pragma("unroll") for (int m = 0; m < 4; ++m) _Pragma("unroll") for (int n = 0; n < 2; ++n) _Pragma("unroll") for (int k = 0; k < 2; ++k) \
;         acc[ai][bj][m][n] = __builtin_amdgcn_mfma_f32_16x16x32_bf16(Bt[n][k], At[m][k], acc[ai][bj][m][n], 0, 0, 0); __builtin_amdgcn_s_setprio(0); } while (0)
; #define PG8_WAIT_V(n) asm volatile("s_waitcnt vmcnt(" #n ")" ::: "memory")
; #define PG8_WAIT_L(n) asm volatile("s_waitcnt lgkmcnt(" #n ")" ::: "memory")
; #define PG8_BAR __builtin_amdgcn_s_barrier()
; #define PG8_SCHED __builtin_amdgcn_sched_barrier(0)
; template <class Epi, class Sched>
; __device__ __forceinline__ void gemm_phase(PG8_LAS unsigned char* lds, const Gemm g, const Sched& S, const Epi& E) {
;     ...
;             PG8_LDB(B0, 1, 0); PG8_SCHED; PG8_LDA(At, 1, 0); PG8_STAGE(PG8_SA(0, 1), a2 + hstep, voffA);
;             PG8_WAIT_L(8); PG8_BAR; PG8_WAIT_L(0); PG8_MMA(0, 0, At, B0); PG8_BAR; PG8_SCHED;
;             PG8_LDB(B1, 1, 1); PG8_STAGE(PG8_SB(1, 0), b3, voffB);
;             PG8_BAR; PG8_WAIT_L(0); PG8_MMA(0, 1, At, B1); PG8_BAR;
;             PG8_LDA(At, 1, 1); PG8_STAGE(PG8_SA(1, 0), a3, voffA);
;             PG8_BAR; PG8_WAIT_L(0); PG8_MMA(1, 0, At, B0); PG8_BAR; PG8_SCHED;
;             PG8_STAGE(PG8_SB(1, 1), b3 + hstepB, voffB);
;             PG8_WAIT_V(6); PG8_BAR; PG8_MMA(1, 1, At, B1); PG8_BAR;
;         }
	s_waitcnt lgkmcnt(0)
	s_setprio 1
	s_waitcnt lgkmcnt(0)
	v_mfma_f32_16x16x32_bf16 v[124:127], v[142:145], v[166:169], v[124:127]
	v_mfma_f32_16x16x32_bf16 v[120:123], v[158:161], v[166:169], v[120:123]
	v_mfma_f32_16x16x32_bf16 v[108:111], v[142:145], v[174:177], v[108:111]
	v_mfma_f32_16x16x32_bf16 v[104:107], v[158:161], v[174:177], v[104:107]
	v_mfma_f32_16x16x32_bf16 v[92:95], v[142:145], v[182:185], v[92:95]
	v_mfma_f32_16x16x32_bf16 v[88:91], v[158:161], v[182:185], v[88:91]
	v_mfma_f32_16x16x32_bf16 v[76:79], v[142:145], v[190:193], v[76:79]
	v_mfma_f32_16x16x32_bf16 v[72:75], v[158:161], v[190:193], v[72:75]
	v_mfma_f32_16x16x32_bf16 v[124:127], v[154:157], v[170:173], v[124:127]
	v_mfma_f32_16x16x32_bf16 v[120:123], v[162:165], v[170:173], v[120:123]
	v_mfma_f32_16x16x32_bf16 v[108:111], v[154:157], v[178:181], v[108:111]
	v_mfma_f32_16x16x32_bf16 v[104:107], v[162:165], v[178:181], v[104:107]
	v_mfma_f32_16x16x32_bf16 v[92:95], v[154:157], v[186:189], v[92:95]
	v_mfma_f32_16x16x32_bf16 v[88:91], v[162:165], v[186:189], v[88:91]
	v_mfma_f32_16x16x32_bf16 v[76:79], v[154:157], v[194:197], v[76:79]
	v_mfma_f32_16x16x32_bf16 v[72:75], v[162:165], v[194:197], v[72:75]
	s_setprio 0
	s_barrier
	s_add_i32 s68, 0, 0x1c000
	s_add_u32 s28, s26, 0x8000
	s_addc_u32 s29, s27, 0
	s_add_i32 s67, s67, s39
	v_add_u32_e32 v136, s68, v148
	v_lshl_add_u64 v[218:219], s[28:29], 0, v[128:129]
	s_mov_b32 m0, s67
	ds_read_b128 v[198:201], v136
	ds_read_b128 v[202:205], v136 offset:1024
	ds_read_b128 v[206:209], v136 offset:2048
	ds_read_b128 v[210:213], v136 offset:3072
	global_load_lds_dwordx4 v[218:219], off
	v_lshl_add_u64 v[218:219], s[28:29], 0, v[132:133]
	s_add_i32 m0, s67, 0x2000
	s_nop 0
	global_load_lds_dwordx4 v[218:219], off
	s_barrier
	s_waitcnt lgkmcnt(0)
	s_setprio 1
	s_waitcnt lgkmcnt(0)
	v_mfma_f32_16x16x32_bf16 v[116:119], v[198:201], v[166:169], v[116:119]
	v_mfma_f32_16x16x32_bf16 v[112:115], v[206:209], v[166:169], v[112:115]
	v_mfma_f32_16x16x32_bf16 v[100:103], v[198:201], v[174:177], v[100:103]
	v_mfma_f32_16x16x32_bf16 v[96:99], v[206:209], v[174:177], v[96:99]
	v_mfma_f32_16x16x32_bf16 v[84:87], v[198:201], v[182:185], v[84:87]
	v_mfma_f32_16x16x32_bf16 v[80:83], v[206:209], v[182:185], v[80:83]
	v_mfma_f32_16x16x32_bf16 v[68:71], v[198:201], v[190:193], v[68:71]
	v_mfma_f32_16x16x32_bf16 v[64:67], v[206:209], v[190:193], v[64:67]
	v_mfma_f32_16x16x32_bf16 v[116:119], v[202:205], v[170:173], v[116:119]
	v_mfma_f32_16x16x32_bf16 v[112:115], v[210:213], v[170:173], v[112:115]
	v_mfma_f32_16x16x32_bf16 v[100:103], v[202:205], v[178:181], v[100:103]
	v_mfma_f32_16x16x32_bf16 v[96:99], v[210:213], v[178:181], v[96:99]
	v_mfma_f32_16x16x32_bf16 v[84:87], v[202:205], v[186:189], v[84:87]
	v_mfma_f32_16x16x32_bf16 v[80:83], v[210:213], v[186:189], v[80:83]
	v_mfma_f32_16x16x32_bf16 v[68:71], v[202:205], v[194:197], v[68:71]
	v_mfma_f32_16x16x32_bf16 v[64:67], v[210:213], v[194:197], v[64:67]
	s_setprio 0
	s_mov_b32 m0, s55
	v_lshl_add_u64 v[214:215], v[214:215], 0, s[10:11]
	s_barrier
	ds_read_b128 v[166:169], v151 offset:49152
	ds_read_b128 v[170:173], v151 offset:50176
	ds_read_b128 v[174:177], v151 offset:51200
	ds_read_b128 v[178:181], v151 offset:52224
	ds_read_b128 v[182:185], v151 offset:53248
	ds_read_b128 v[186:189], v151 offset:54272
	ds_read_b128 v[190:193], v151 offset:55296
	ds_read_b128 v[194:197], v151 offset:56320
	global_load_lds_dwordx4 v[214:215], off
	v_lshl_add_u64 v[214:215], v[216:217], 0, s[10:11]
	s_mov_b32 m0, s56
	s_nop 0
	global_load_lds_dwordx4 v[214:215], off
	s_barrier
	s_waitcnt lgkmcnt(0)
	s_setprio 1
	s_waitcnt lgkmcnt(0)
	v_mfma_f32_16x16x32_bf16 v[60:63], v[142:145], v[166:169], v[60:63]
	v_mfma_f32_16x16x32_bf16 v[56:59], v[158:161], v[166:169], v[56:59]
	v_mfma_f32_16x16x32_bf16 v[44:47], v[142:145], v[174:177], v[44:47]
	v_mfma_f32_16x16x32_bf16 v[40:43], v[158:161], v[174:177], v[40:43]
	v_mfma_f32_16x16x32_bf16 v[28:31], v[142:145], v[182:185], v[28:31]
	v_mfma_f32_16x16x32_bf16 v[24:27], v[158:161], v[182:185], v[24:27]
	v_mfma_f32_16x16x32_bf16 v[12:15], v[142:145], v[190:193], v[12:15]
	v_mfma_f32_16x16x32_bf16 v[8:11], v[158:161], v[190:193], v[8:11]
	v_mfma_f32_16x16x32_bf16 v[60:63], v[154:157], v[170:173], v[60:63]
	v_mfma_f32_16x16x32_bf16 v[56:59], v[162:165], v[170:173], v[56:59]
	v_mfma_f32_16x16x32_bf16 v[44:47], v[154:157], v[178:181], v[44:47]
	v_mfma_f32_16x16x32_bf16 v[40:43], v[162:165], v[178:181], v[40:43]
	v_mfma_f32_16x16x32_bf16 v[28:31], v[154:157], v[186:189], v[28:31]
	v_mfma_f32_16x16x32_bf16 v[24:27], v[162:165], v[186:189], v[24:27]
	v_mfma_f32_16x16x32_bf16 v[12:15], v[154:157], v[194:197], v[12:15]
	v_mfma_f32_16x16x32_bf16 v[8:11], v[162:165], v[194:197], v[8:11]
	s_setprio 0
	s_barrier
	s_add_u32 s26, s26, 0xc000
	s_addc_u32 s27, s27, 0
	s_add_i32 s28, s68, s39
	v_lshl_add_u64 v[142:143], s[26:27], 0, v[128:129]
	s_mov_b32 m0, s28
	s_nop 0
	global_load_lds_dwordx4 v[142:143], off
	v_lshl_add_u64 v[142:143], s[26:27], 0, v[132:133]
	s_add_i32 m0, s28, 0x2000
	s_nop 0
	global_load_lds_dwordx4 v[142:143], off
	s_waitcnt vmcnt(6)
	s_barrier
	s_setprio 1
	v_mfma_f32_16x16x32_bf16 v[52:55], v[198:201], v[166:169], v[52:55]
	v_mfma_f32_16x16x32_bf16 v[48:51], v[206:209], v[166:169], v[48:51]
	v_mfma_f32_16x16x32_bf16 v[36:39], v[198:201], v[174:177], v[36:39]
	v_mfma_f32_16x16x32_bf16 v[32:35], v[206:209], v[174:177], v[32:35]
	v_mfma_f32_16x16x32_bf16 v[20:23], v[198:201], v[182:185], v[20:23]
	v_mfma_f32_16x16x32_bf16 v[16:19], v[206:209], v[182:185], v[16:19]
	v_mfma_f32_16x16x32_bf16 v[4:7], v[198:201], v[190:193], v[4:7]
	v_mfma_f32_16x16x32_bf16 v[0:3], v[206:209], v[190:193], v[0:3]
	v_mfma_f32_16x16x32_bf16 v[52:55], v[202:205], v[170:173], v[52:55]
	v_mfma_f32_16x16x32_bf16 v[48:51], v[210:213], v[170:173], v[48:51]
	v_mfma_f32_16x16x32_bf16 v[36:39], v[202:205], v[178:181], v[36:39]
	v_mfma_f32_16x16x32_bf16 v[32:35], v[210:213], v[178:181], v[32:35]
	v_mfma_f32_16x16x32_bf16 v[20:23], v[202:205], v[186:189], v[20:23]
	v_mfma_f32_16x16x32_bf16 v[16:19], v[210:213], v[186:189], v[16:19]
	v_mfma_f32_16x16x32_bf16 v[4:7], v[202:205], v[194:197], v[4:7]
	v_mfma_f32_16x16x32_bf16 v[0:3], v[210:213], v[194:197], v[0:3]
	s_setprio 0
	s_add_i32 s66, s66, 2
	s_add_u32 s64, s64, 0x10000
	s_addc_u32 s65, s65, 0
	s_add_u32 s24, s24, 0x100
	s_addc_u32 s25, s25, 0
	s_cmp_gt_u32 s66, 29
	s_barrier
	s_cbranch_scc0 .LBB0_397
	s_cmp_eq_u32 s78, 0
	s_cbranch_scc0 .Lhalf_skip_x_3
	s_barrier
; __device__ __forceinline__ unsigned cvt_pk_bf16(float lo, float hi) { unsigned r; asm volatile("v_cvt_pk_bf16_f32 %0, %1, %2" : "=v"(r) : "v"(lo), "v"(hi)); return r; }
;     __device__ __forceinline__ void operator()(const f32x4 (&acc)[2][2][4][2], const Unit& u, int wr, int wc, int fr, int fq) const {
;     ...
;             for (int m = 0; m < 4; ++m) { const int row = row0 + ai * HALF + m * 16;
; #pragma unroll
;                 for (int bj = 0; bj < 2; ++bj) { const f32x4 v0 = acc[ai][bj][m][0], v1 = acc[ai][bj][m][1]; const int col = col0 + bj * HALF;
;                     u32x4 w; w.x = cvt_pk_bf16(v0[0], v0[1]); w.y = cvt_pk_bf16(v0[2], v0[3]); w.z = cvt_pk_bf16(v1[0], v1[1]); w.w = cvt_pk_bf16(v1[2], v1[3]);
;                     if (u.pn < 4) *(u32x4*)(O + (size_t)row * 2048 + col) = w;
;                     else { const int cc = col - 1024, hh = cc >> 8, d = cc & 255, b = row >> 8, mm = row & 255; bf16_t* vt = VT + ((size_t)((b * 4 + hh) * 256 + d)) * 256 + mm;
;                         vt[0] = (bf16_t)(w.x & 0xffffu); vt[256] = (bf16_t)(w.x >> 16); vt[512] = (bf16_t)(w.y & 0xffffu); vt[768] = (bf16_t)(w.y >> 16);
;                         vt[1024] = (bf16_t)(w.z & 0xffffu); vt[1280] = (bf16_t)(w.z >> 16); vt[1536] = (bf16_t)(w.w & 0xffffu); vt[1792] = (bf16_t)(w.w >> 16); } } }
.Lhalf_skip_x_3:
	s_lshl_b32 s24, s22, 8
	s_add_i32 s24, s24, s54
	s_lshl_b32 s25, s4, 8
	s_cmp_gt_i32 s4, 3
	s_cselect_b64 s[22:23], -1, 0
	s_lshl_b32 s4, s24, 2
	s_add_i32 s15, s25, 0xfffffc00
	s_and_b32 s17, s4, 0xfffffc00
	s_add_i32 s17, s17, s15
	v_bitop3_b32 v136, s24, v153, v147 bitop3:0xc8
	v_or_b32_e32 v142, s17, v149
	s_mov_b64 s[4:5], -1
	s_and_b64 vcc, exec, s[22:23]
	v_ashrrev_i32_e32 v143, 31, v142
	v_lshlrev_b32_e32 v136, 1, v136
	v_cvt_pk_bf16_f32 v124, v124, v125
	v_cvt_pk_bf16_f32 v125, v126, v127
	v_cvt_pk_bf16_f32 v126, v120, v121
	v_cvt_pk_bf16_f32 v127, v122, v123
	s_cbranch_vccz .LBB0_400
	v_lshlrev_b64 v[120:121], 9, v[142:143]
	v_lshl_add_u64 v[120:121], s[8:9], 0, v[120:121]
	v_lshl_add_u64 v[120:121], v[120:121], 0, v[136:137]
	global_store_short v[120:121], v124, off
	global_store_short_d16_hi v[120:121], v124, off offset:512
	global_store_short v[120:121], v125, off offset:1024
	global_store_short_d16_hi v[120:121], v125, off offset:1536
	global_store_short v[120:121], v126, off offset:2048
	global_store_short_d16_hi v[120:121], v126, off offset:2560
	global_store_short v[120:121], v127, off offset:3072
	global_store_short_d16_hi v[120:121], v127, off offset:3584
	s_mov_b64 s[4:5], 0

; #define PG8_WAIT_V(n) asm volatile("s_waitcnt vmcnt(" #n ")" ::: "memory")
; #define PG8_BAR __builtin_amdgcn_s_barrier()
; template <class Epi, class Sched>
; __device__ __forceinline__ void gemm_phase(PG8_LAS unsigned char* lds, const Gemm g, const Sched& S, const Epi& E) {
;     ...
;     PG8_WAIT_V(0);
;     if (wr == 0) PG8_BAR;
;     PG8_BAR;
.LBB0_462:
	s_waitcnt vmcnt(0)
	s_cmpk_gt_u32 s36, 0xff
	s_cbranch_scc1 .LBB0_464
.LBB0_464:
	s_barrier

;     __host__ __device__ bool next(int i, Unit& u) const { const int j = i / 3; if (!StaticOrder::next(j, u)) return false; u.br = i - 3 * j; return true; }
; #define PG8_STAGE(bufoff, gbase, voff) do { _Pragma("unroll") for (int _i = 0; _i < 2; ++_i) \
;         __builtin_amdgcn_global_load_lds((const unsigned*)((const char*)(gbase) + (voff)[_i]), (PG8_LAS unsigned*)(lds + (bufoff) + ldsw + _i * 8192), 16, 0, 0); } while (0)
; template <class Epi, class Sched>
; __device__ __forceinline__ void gemm_phase(PG8_LAS unsigned char* lds, const Gemm g, const Sched& S, const Epi& E) {
;     ...
;     const int tid = tix_, wid = __builtin_amdgcn_readfirstlane(tid >> 6), lane = tid & 63, wr = wid >> 2, wc = wid & 3, fr = lane & 15, fq = lane >> 4;
;     const int K = g.K, nt = K / BK;
;     unsigned voffA[2], voffB[2];
; #pragma unroll
;     for (int i = 0; i < 2; ++i) { int R, C; stage_rc(tid * 16 + i * 8192, R, C);
;         voffA[i] = (unsigned)(R * K + C) * 2u; voffB[i] = (unsigned)(tid * 16 + i * 8192); }
;     const size_t kstep = (size_t)(BK * 2);
;     const size_t hstep = (size_t)HALF * K * 2;
;     const size_t tstep = 2 * hstep;
;     const size_t kstepB = 32768, hstepB = 16384, tstepB = (size_t)nt * 32768;
;     const unsigned ldsw = (unsigned)wid * 1024u;
;     const int aoff = lds_byte(wr * 64 + fr, fq * 8), boff = lds_byte(wc * 32 + fr, fq * 8);
;     ...
;     Unit cur, nxt; int ui = 0;
;     if (!S.next(0, cur)) return;
;     f32x4 acc[2][2][4][2];
; #pragma unroll
;     for (int a = 0; a < 2; ++a)
; #pragma unroll
;         for (int b = 0; b < 2; ++b)
; #pragma unroll
;             for (int m = 0; m < 4; ++m)
; #pragma unroll
;                 for (int n = 0; n < 2; ++n) acc[a][b][m][n] = (f32x4){0.f, 0.f, 0.f, 0.f};
;     bf16x8 At[4][2], B0[2][2], B1[2][2];
;     const char* cA = (const char*)g.A + (size_t)cur.pm * tstep + (size_t)cur.br * g.strideA; const char* cB = (const char*)g.Bt + (size_t)cur.pn * tstepB + (size_t)cur.br * g.strideB;
;     S.a_ready(cur);
;     PG8_STAGE(PG8_SB(0, 0), cB, voffB); PG8_STAGE(PG8_SA(0, 0), cA, voffA); PG8_STAGE(PG8_SB(0, 1), cB + hstepB, voffB); PG8_STAGE(PG8_SA(0, 1), cA + hstep, voffA);
;     if (wr == 1) PG8_BAR;
;     PG8_WAIT_V(4); PG8_BAR;
;     PG8_STAGE(PG8_SB(1, 0), cB + kstepB, voffB); PG8_STAGE(PG8_SA(1, 0), cA + kstep, voffA); PG8_STAGE(PG8_SB(1, 1), cB + hstepB + kstepB, voffB);
.LBB0_600:
	s_andn2_b64 vcc, exec, s[10:11]
	s_cbranch_vccnz .LBB0_716
	v_ashrrev_i32_e32 v0, 31, v1
	v_lshrrev_b32_e32 v0, 26, v0
	v_add_u32_e32 v0, v1, v0
	v_ashrrev_i32_e32 v6, 6, v0
	v_bfe_i32 v0, v1, 27, 1
	v_lshlrev_b32_e32 v196, 4, v1
	v_lshrrev_b32_e32 v0, 22, v0
	v_add_u32_e32 v0, v196, v0
	v_and_b32_e32 v0, 0xfffffc00, v0
	v_sub_u32_e32 v0, v196, v0
	v_lshrrev_b32_e32 v2, 4, v0
	v_bitop3_b32 v0, v2, v0, 32 bitop3:0x6c
	v_ashrrev_i32_e32 v3, 31, v0
	v_lshrrev_b32_e32 v3, 26, v3
	v_add_u32_e32 v3, v0, v3
	v_ashrrev_i32_e32 v7, 6, v3
	v_and_b32_e32 v3, 0xc0, v3
	v_sub_u32_e32 v0, v0, v3
	v_mov_b32_e32 v3, 1
	v_lshlrev_b32_e32 v2, 3, v6
	v_lshlrev_b32_e32 v4, 5, v6
	v_ashrrev_i16_sdwa v0, v3, sext(v0) dst_sel:DWORD dst_unused:UNUSED_PAD src0_sel:DWORD src1_sel:BYTE_0
	v_and_b32_e32 v2, 0x1ffff0, v2
	v_and_b32_e32 v4, 32, v4
	v_bfe_i32 v8, v0, 0, 16
	v_add_u32_e32 v0, v4, v8
	v_add_lshl_u32 v2, v7, v2, 11
	v_add_u32_e32 v200, 0x2000, v196
	v_lshl_add_u32 v198, v0, 1, v2
	v_ashrrev_i32_e32 v0, 31, v200
	v_lshrrev_b32_e32 v0, 22, v0
	v_add_u32_e32 v0, v200, v0
	v_ashrrev_i32_e32 v9, 10, v0
	v_mul_i32_i24_e32 v0, 0x400, v9
	s_waitcnt lgkmcnt(0)
	s_add_u32 s38, s4, 0x27300000
	v_sub_u32_e32 v0, v200, v0
	s_addc_u32 s39, s5, 0
	v_lshrrev_b32_e32 v2, 4, v0
	s_add_u32 s46, s4, 0x7280000
	v_bitop3_b32 v0, v2, v0, 32 bitop3:0x6c
	s_addc_u32 s47, s5, 0
	v_ashrrev_i32_e32 v4, 31, v0
	s_ashr_i32 s12, s37, 6
	s_ashr_i32 s7, s6, 31
	s_ashr_i32 s9, s8, 31
	s_ashr_i32 s14, s37, 8
	v_lshrrev_b32_e32 v4, 26, v4
	s_lshl_b32 s48, s12, 10
	s_lshl_b64 s[10:11], s[6:7], 19
	s_lshl_b64 s[16:17], s[8:9], 19
	v_add_u32_e32 v4, v0, v4
	s_add_u32 s24, s46, s16
	v_ashrrev_i32_e32 v10, 6, v4
	v_and_b32_e32 v4, 0xc0, v4
	s_addc_u32 s25, s47, s17
	s_add_i32 s49, s48, 0
	v_sub_u32_e32 v0, v0, v4
	s_add_i32 m0, s49, 0x10000
	v_lshlrev_b32_e32 v2, 3, v9
	v_lshlrev_b32_e32 v5, 5, v9
	v_ashrrev_i16_sdwa v0, v3, sext(v0) dst_sel:DWORD dst_unused:UNUSED_PAD src0_sel:DWORD src1_sel:BYTE_0
	global_load_lds_dwordx4 v196, s[24:25]
	s_add_i32 m0, s49, 0x12000
	v_and_b32_e32 v2, 0x1ffff0, v2
	v_and_b32_e32 v5, 32, v5
	v_bfe_i32 v11, v0, 0, 16
	s_add_u32 s26, s38, s10
	v_add_u32_e32 v0, v5, v11
	v_add_lshl_u32 v2, v10, v2, 11
	global_load_lds_dwordx4 v200, s[24:25]
	s_addc_u32 s27, s39, s11
	s_mov_b32 m0, s49
	s_add_i32 s50, s49, 0x2000
	v_lshl_add_u32 v202, v0, 1, v2
	global_load_lds_dwordx4 v198, s[26:27]
	s_mov_b32 m0, s50
	s_add_u32 s10, s24, 0x4000
	global_load_lds_dwordx4 v202, s[26:27]
	s_addc_u32 s11, s25, 0
	s_add_i32 m0, s49, 0x14000
	v_mov_b32_e32 v0, 0
	global_load_lds_dwordx4 v196, s[10:11]
	s_add_i32 m0, s49, 0x16000
	v_mov_b32_e32 v199, v0
	global_load_lds_dwordx4 v200, s[10:11]
	s_add_u32 s10, s26, 0x40000
	s_addc_u32 s11, s27, 0
	s_add_i32 s51, s49, 0x4000
	s_mov_b32 m0, s51
	s_add_i32 s52, s49, 0x6000
	global_load_lds_dwordx4 v198, s[10:11]
	s_mov_b32 m0, s52
	v_mov_b32_e32 v203, v0
	global_load_lds_dwordx4 v202, s[10:11]
	v_mov_b32_e32 v197, v0
	v_mov_b32_e32 v201, v0
	v_lshl_add_u64 v[4:5], s[26:27], 0, v[198:199]
	s_cmp_lg_u32 s14, 1
	v_lshl_add_u64 v[2:3], s[26:27], 0, v[202:203]
	s_cbranch_scc1 .LBB0_603
; #define PG8_STAGE(bufoff, gbase, voff) do { _Pragma("unroll") for (int _i = 0; _i < 2; ++_i) \
;         __builtin_amdgcn_global_load_lds((const unsigned*)((const char*)(gbase) + (voff)[_i]), (PG8_LAS unsigned*)(lds + (bufoff) + ldsw + _i * 8192), 16, 0, 0); } while (0)
; #define PG8_WAIT_V(n) asm volatile("s_waitcnt vmcnt(" #n ")" ::: "memory")
; #define PG8_BAR __builtin_amdgcn_s_barrier()
; template <class Epi, class Sched>
; __device__ __forceinline__ void gemm_phase(PG8_LAS unsigned char* lds, const Gemm g, const Sched& S, const Epi& E) {
;     ...
;     f32x4 acc[2][2][4][2];
; #pragma unroll
;     for (int a = 0; a < 2; ++a)
; #pragma unroll
;         for (int b = 0; b < 2; ++b)
; #pragma unroll
;             for (int m = 0; m < 4; ++m)
; #pragma unroll
;                 for (int n = 0; n < 2; ++n) acc[a][b][m][n] = (f32x4){0.f, 0.f, 0.f, 0.f};
;     ...
;     PG8_STAGE(PG8_SB(0, 0), cB, voffB); PG8_STAGE(PG8_SA(0, 0), cA, voffA); PG8_STAGE(PG8_SB(0, 1), cB + hstepB, voffB); PG8_STAGE(PG8_SA(0, 1), cA + hstep, voffA);
;     if (wr == 1) PG8_BAR;
;     PG8_WAIT_V(4); PG8_BAR;
;     PG8_STAGE(PG8_SB(1, 0), cB + kstepB, voffB); PG8_STAGE(PG8_SA(1, 0), cA + kstep, voffA); PG8_STAGE(PG8_SB(1, 1), cB + hstepB + kstepB, voffB);
;     PG8_WAIT_V(6); PG8_BAR;
.LBB0_603:
	s_add_u32 s10, s4, 0xc700000
	s_addc_u32 s11, s5, 0
	s_add_u32 s53, s4, 0x1b300000
	s_addc_u32 s54, s5, 0
	s_lshl_b32 s4, s12, 5
	s_and_b32 s9, s4, 0x60
	s_lshl_b32 s7, s14, 13
	s_lshl_b32 s15, s9, 7
	s_add_u32 s4, s24, 0x8000
	s_addc_u32 s5, s25, 0
	s_add_i32 m0, s49, 0x18000
	v_lshl_add_u64 v[12:13], s[4:5], 0, v[196:197]
	s_waitcnt vmcnt(4)
	s_barrier
	global_load_lds_dwordx4 v[12:13], off
	v_lshl_add_u64 v[12:13], s[4:5], 0, v[200:201]
	s_add_i32 m0, s49, 0x1a000
	s_mov_b64 s[12:13], 0x80
	s_add_i32 s55, s49, 0x8000
	s_add_i32 s56, s49, 0xa000
	global_load_lds_dwordx4 v[12:13], off
	v_lshl_add_u64 v[4:5], v[4:5], 0, s[12:13]
	s_mov_b32 m0, s55
	s_add_u32 s4, s24, 0xc000
	global_load_lds_dwordx4 v[4:5], off
	v_lshl_add_u64 v[2:3], v[2:3], 0, s[12:13]
	s_mov_b32 m0, s56
	s_addc_u32 s5, s25, 0
	global_load_lds_dwordx4 v[2:3], off
	s_add_i32 m0, s49, 0x1c000
	v_lshl_add_u64 v[2:3], s[4:5], 0, v[196:197]
	global_load_lds_dwordx4 v[2:3], off
	v_lshl_add_u64 v[2:3], s[4:5], 0, v[200:201]
	s_add_i32 m0, s49, 0x1e000
	v_mov_b32_e32 v205, v0
	global_load_lds_dwordx4 v[2:3], off
	v_lshrrev_b32_e32 v3, 1, v1
	v_and_b32_e32 v3, 24, v3
	v_and_b32_e32 v2, 15, v1
	v_lshlrev_b32_e32 v4, 1, v3
	v_lshlrev_b32_e32 v1, 2, v1
	v_lshl_or_b32 v230, s14, 6, v2
	v_lshl_or_b32 v2, v2, 6, v4
	v_and_b32_e32 v1, 32, v1
	v_bitop3_b32 v4, v2, s7, v1 bitop3:0xde
	v_bitop3_b32 v231, v2, s15, v1 bitop3:0xde
	v_lshlrev_b32_e32 v1, 14, v6
	v_and_b32_e32 v1, 0xffff8000, v1
	v_lshl_add_u32 v1, v7, 11, v1
	v_and_b32_e32 v2, 1, v6
	v_lshl_or_b32 v1, v2, 6, v1
	v_lshl_add_u32 v204, v8, 1, v1
	v_lshlrev_b32_e32 v1, 14, v9
	v_and_b32_e32 v1, 0xffff8000, v1
	v_lshl_add_u32 v1, v10, 11, v1
	v_and_b32_e32 v2, 1, v9
	s_waitcnt vmcnt(6)
	v_or_b32_e32 v232, s9, v3
	v_lshl_or_b32 v1, v2, 6, v1
	v_mov_b32_e32 v2, v0
	v_mov_b32_e32 v3, v0
	v_lshl_add_u32 v206, v11, 1, v1
	v_mov_b32_e32 v1, v0
	v_add_u32_e32 v233, 0, v4
	v_mov_b64_e32 v[38:39], v[2:3]
	v_mov_b64_e32 v[42:43], v[2:3]
	v_mov_b64_e32 v[46:47], v[2:3]
	v_mov_b64_e32 v[50:51], v[2:3]
	v_mov_b64_e32 v[54:55], v[2:3]
	v_mov_b64_e32 v[58:59], v[2:3]
	v_mov_b64_e32 v[62:63], v[2:3]
	v_mov_b64_e32 v[66:67], v[2:3]
	v_mov_b64_e32 v[70:71], v[2:3]
	v_mov_b64_e32 v[74:75], v[2:3]
	v_mov_b64_e32 v[78:79], v[2:3]
	v_mov_b64_e32 v[82:83], v[2:3]
	v_mov_b64_e32 v[86:87], v[2:3]
	v_mov_b64_e32 v[90:91], v[2:3]
	v_mov_b64_e32 v[94:95], v[2:3]
	v_mov_b64_e32 v[98:99], v[2:3]
	v_mov_b64_e32 v[102:103], v[2:3]
	v_mov_b64_e32 v[106:107], v[2:3]
	v_mov_b64_e32 v[110:111], v[2:3]
	v_mov_b64_e32 v[114:115], v[2:3]
	v_mov_b64_e32 v[118:119], v[2:3]
	v_mov_b64_e32 v[122:123], v[2:3]
	v_mov_b64_e32 v[126:127], v[2:3]
	v_mov_b64_e32 v[130:131], v[2:3]
	v_mov_b64_e32 v[14:15], v[2:3]
	v_mov_b64_e32 v[18:19], v[2:3]
	v_mov_b64_e32 v[22:23], v[2:3]
	v_mov_b64_e32 v[26:27], v[2:3]
	v_mov_b64_e32 v[30:31], v[2:3]
	v_mov_b64_e32 v[34:35], v[2:3]
	v_mov_b64_e32 v[10:11], v[2:3]
	v_mov_b64_e32 v[6:7], v[2:3]
	v_mov_b32_e32 v207, v0
	s_mov_b32 s9, 0
	v_mov_b64_e32 v[208:209], 0x200
	v_mov_b64_e32 v[210:211], 0x1ff
	s_add_i32 s57, 0, 0x10000
	s_add_i32 s58, 0, 0x14000
	s_movk_i32 s59, 0x3000
	v_mov_b64_e32 v[36:37], v[0:1]
	v_mov_b64_e32 v[40:41], v[0:1]
	v_mov_b64_e32 v[44:45], v[0:1]
	v_mov_b64_e32 v[48:49], v[0:1]
	v_mov_b64_e32 v[52:53], v[0:1]
	v_mov_b64_e32 v[56:57], v[0:1]
	v_mov_b64_e32 v[60:61], v[0:1]
	v_mov_b64_e32 v[64:65], v[0:1]
	v_mov_b64_e32 v[68:69], v[0:1]
	v_mov_b64_e32 v[72:73], v[0:1]
	v_mov_b64_e32 v[76:77], v[0:1]
	v_mov_b64_e32 v[80:81], v[0:1]
	v_mov_b64_e32 v[84:85], v[0:1]
	v_mov_b64_e32 v[88:89], v[0:1]
	v_mov_b64_e32 v[92:93], v[0:1]
	v_mov_b64_e32 v[96:97], v[0:1]
	v_mov_b64_e32 v[100:101], v[0:1]
	v_mov_b64_e32 v[104:105], v[0:1]
	v_mov_b64_e32 v[108:109], v[0:1]
	v_mov_b64_e32 v[112:113], v[0:1]
	v_mov_b64_e32 v[116:117], v[0:1]
	v_mov_b64_e32 v[120:121], v[0:1]
	v_mov_b64_e32 v[124:125], v[0:1]
	v_mov_b64_e32 v[128:129], v[0:1]
	v_mov_b64_e32 v[12:13], v[0:1]
	v_mov_b64_e32 v[16:17], v[0:1]
	v_mov_b64_e32 v[20:21], v[0:1]
	v_mov_b64_e32 v[24:25], v[0:1]
	v_mov_b64_e32 v[28:29], v[0:1]
	v_mov_b64_e32 v[32:33], v[0:1]
	v_mov_b64_e32 v[8:9], v[0:1]
	v_mov_b64_e32 v[4:5], v[0:1]
	s_mov_b32 s60, 0
	s_barrier
	s_branch .LBB0_606

;     __host__ __device__ bool next(int i, Unit& u) const { const int j = i / 3; if (!StaticOrder::next(j, u)) return false; u.br = i - 3 * j; return true; }
; #define PG8_STAGE(bufoff, gbase, voff) do { _Pragma("unroll") for (int _i = 0; _i < 2; ++_i) \
;         __builtin_amdgcn_global_load_lds((const unsigned*)((const char*)(gbase) + (voff)[_i]), (PG8_LAS unsigned*)(lds + (bufoff) + ldsw + _i * 8192), 16, 0, 0); } while (0)
; #define PG8_LDA(dst, b, h) do { _Pragma("unroll") for (int m = 0; m < 4; ++m) _Pragma("unroll") for (int k = 0; k < 2; ++k) dst[m][k] = *(const PG8_LAS bf16x8*)(lds + PG8_SA(b, h) + aoff + m * 2048 + k * 1024); } while (0)
; #define PG8_LDB(dst, b, h) do { _Pragma("unroll") for (int n = 0; n < 2; ++n) _Pragma("unroll") for (int k = 0; k < 2; ++k) dst[n][k] = *(const PG8_LAS bf16x8*)(lds + PG8_SB(b, h) + boff + n * 2048 + k * 1024); } while (0)
; #define PG8_WAIT_L(n) asm volatile("s_waitcnt lgkmcnt(" #n ")" ::: "memory")
; #define PG8_BAR __builtin_amdgcn_s_barrier()
; #define PG8_SCHED __builtin_amdgcn_sched_barrier(0)
; template <class Epi, class Sched>
; __device__ __forceinline__ void gemm_phase(PG8_LAS unsigned char* lds, const Gemm g, const Sched& S, const Epi& E) {
;     ...
;         const bool has_next = S.next(ui + 1, nxt);
;         const char* nA = has_next ? (const char*)g.A + (size_t)nxt.pm * tstep + (size_t)nxt.br * g.strideA : cA; const char* nB = has_next ? (const char*)g.Bt + (size_t)nxt.pn * tstepB + (size_t)nxt.br * g.strideB : cB;
;         for (int t = 0; t < nt; t += 2) {
;             const bool last = (t == nt - 2);
;             const char* a1 = cA + (size_t)(t + 1) * kstep;
;             const char* a2 = last ? nA : cA + (size_t)(t + 2) * kstep; const char* b2 = last ? nB : cB + (size_t)(t + 2) * kstepB;
;             const char* a3 = a2 + kstep; const char* b3 = b2 + kstepB;
;             if (last && has_next) S.a_ready(nxt);
;             PG8_LDB(B0, 0, 0); PG8_SCHED; PG8_LDA(At, 0, 0); PG8_STAGE(PG8_SA(1, 1), a1 + hstep, voffA);
;             PG8_WAIT_L(8); PG8_BAR; PG8_WAIT_L(0); PG8_MMA(0, 0, At, B0); PG8_BAR; PG8_SCHED;
;             PG8_LDB(B1, 0, 1); PG8_STAGE(PG8_SB(0, 0), b2, voffB);
;             PG8_BAR; PG8_WAIT_L(0); PG8_MMA(0, 1, At, B1); PG8_BAR;
;             PG8_LDA(At, 0, 1); PG8_STAGE(PG8_SA(0, 0), a2, voffA);
.LBB0_612:
	s_ashr_i32 s15, s14, 31
	s_lshl_b64 s[20:21], s[14:15], 19
	s_add_u32 s7, s38, s20
	s_addc_u32 s15, s39, s21
	s_ashr_i32 s19, s18, 31
	s_lshl_b64 s[20:21], s[18:19], 25
	s_add_u32 s20, s7, s20
	v_cmp_lt_i64_e64 s[4:5], s[4:5], v[208:209]
	s_addc_u32 s21, s15, s21
	s_and_b64 s[22:23], s[4:5], exec
	s_cselect_b32 s7, s21, s27
	s_cselect_b32 s15, s20, s26
	s_ashr_i32 s17, s16, 31
	s_lshl_b64 s[22:23], s[16:17], 19
	s_add_u32 s17, s46, s22
	s_addc_u32 s28, s47, s23
	s_lshl_b64 s[22:23], s[18:19], 22
	s_add_u32 s22, s17, s22
	s_addc_u32 s23, s28, s23
	s_and_b64 s[28:29], s[4:5], exec
	s_cselect_b32 s17, s23, s25
	s_cselect_b32 s19, s22, s24
	s_add_u32 s61, s24, 0x10000
	s_addc_u32 s62, s25, 0
	s_add_u32 s24, s26, 0x40080
	s_addc_u32 s25, s27, 0
	s_mov_b32 s63, -2
	s_cmp_eq_u32 s78, 1
	s_cbranch_scc0 .Lhalf_skip_y_4
	s_barrier
.Lhalf_skip_y_4:
.LBB0_613:
	v_add_u32_e32 v1, s57, v231
	ds_read_b128 v[132:135], v1
	ds_read_b128 v[136:139], v1 offset:1024
	ds_read_b128 v[140:143], v1 offset:2048
	ds_read_b128 v[144:147], v1 offset:3072
	s_add_u32 s26, s24, 0xfffc0080
	s_addc_u32 s27, s25, -1
	s_cmp_eq_u32 s63, 12
	s_cselect_b32 s29, s7, s27
	s_cselect_b32 s28, s15, s26
	s_cselect_b32 s27, s17, s62
	s_cselect_b32 s26, s19, s61
	v_lshl_add_u64 v[2:3], s[24:25], 0, v[204:205]
	s_add_i32 m0, s49, 0xc000
	ds_read_b128 v[148:151], v233
	ds_read_b128 v[152:155], v233 offset:1024
	ds_read_b128 v[156:159], v233 offset:2048
	ds_read_b128 v[160:163], v233 offset:3072
	ds_read_b128 v[164:167], v233 offset:4096
	ds_read_b128 v[168:171], v233 offset:5120
	ds_read_b128 v[172:175], v233 offset:6144
	ds_read_b128 v[176:179], v233 offset:7168
	global_load_lds_dwordx4 v[2:3], off
	v_lshl_add_u64 v[2:3], s[24:25], 0, v[206:207]
	s_add_i32 m0, s49, 0xe000
	s_nop 0
	global_load_lds_dwordx4 v[2:3], off
	s_waitcnt lgkmcnt(8)
	s_barrier
	s_waitcnt lgkmcnt(0)
	s_setprio 1
	s_waitcnt lgkmcnt(0)
	v_mfma_f32_16x16x32_bf16 v[2:5], v[132:135], v[148:151], v[4:7]
	v_mfma_f32_16x16x32_bf16 v[6:9], v[140:143], v[148:151], v[8:11]
	v_mfma_f32_16x16x32_bf16 v[32:35], v[132:135], v[156:159], v[32:35]
	v_mfma_f32_16x16x32_bf16 v[28:31], v[140:143], v[156:159], v[28:31]
	v_mfma_f32_16x16x32_bf16 v[24:27], v[132:135], v[164:167], v[24:27]
	v_mfma_f32_16x16x32_bf16 v[20:23], v[140:143], v[164:167], v[20:23]
	v_mfma_f32_16x16x32_bf16 v[16:19], v[132:135], v[172:175], v[16:19]
	v_mfma_f32_16x16x32_bf16 v[12:15], v[140:143], v[172:175], v[12:15]
	v_mfma_f32_16x16x32_bf16 v[2:5], v[136:139], v[152:155], v[2:5]
	v_mfma_f32_16x16x32_bf16 v[8:11], v[144:147], v[152:155], v[6:9]
	v_mfma_f32_16x16x32_bf16 v[32:35], v[136:139], v[160:163], v[32:35]
	v_mfma_f32_16x16x32_bf16 v[28:31], v[144:147], v[160:163], v[28:31]
	v_mfma_f32_16x16x32_bf16 v[24:27], v[136:139], v[168:171], v[24:27]
	v_mfma_f32_16x16x32_bf16 v[20:23], v[144:147], v[168:171], v[20:23]
	v_mfma_f32_16x16x32_bf16 v[16:19], v[136:139], v[176:179], v[16:19]
	v_mfma_f32_16x16x32_bf16 v[12:15], v[144:147], v[176:179], v[12:15]
	s_setprio 0
	s_barrier
	s_add_i32 s64, s57, s48
	v_add_u32_e32 v1, s58, v231
	v_lshl_add_u64 v[6:7], s[26:27], 0, v[196:197]
	s_mov_b32 m0, s64
	ds_read_b128 v[180:183], v1
	ds_read_b128 v[184:187], v1 offset:1024
	ds_read_b128 v[188:191], v1 offset:2048
	ds_read_b128 v[192:195], v1 offset:3072
	global_load_lds_dwordx4 v[6:7], off
	v_lshl_add_u64 v[6:7], s[26:27], 0, v[200:201]
	s_add_i32 m0, s64, 0x2000
	s_nop 0
	global_load_lds_dwordx4 v[6:7], off
	s_barrier
	s_waitcnt lgkmcnt(0)
	s_setprio 1
	s_waitcnt lgkmcnt(0)
	v_mfma_f32_16x16x32_bf16 v[128:131], v[180:183], v[148:151], v[128:131]
	v_mfma_f32_16x16x32_bf16 v[124:127], v[188:191], v[148:151], v[124:127]
	v_mfma_f32_16x16x32_bf16 v[120:123], v[180:183], v[156:159], v[120:123]
	v_mfma_f32_16x16x32_bf16 v[116:119], v[188:191], v[156:159], v[116:119]
	v_mfma_f32_16x16x32_bf16 v[112:115], v[180:183], v[164:167], v[112:115]
	v_mfma_f32_16x16x32_bf16 v[108:111], v[188:191], v[164:167], v[108:111]
	v_mfma_f32_16x16x32_bf16 v[104:107], v[180:183], v[172:175], v[104:107]
	v_mfma_f32_16x16x32_bf16 v[100:103], v[188:191], v[172:175], v[100:103]
	v_mfma_f32_16x16x32_bf16 v[128:131], v[184:187], v[152:155], v[128:131]
	v_mfma_f32_16x16x32_bf16 v[124:127], v[192:195], v[152:155], v[124:127]
	v_mfma_f32_16x16x32_bf16 v[120:123], v[184:187], v[160:163], v[120:123]
	v_mfma_f32_16x16x32_bf16 v[116:119], v[192:195], v[160:163], v[116:119]
	v_mfma_f32_16x16x32_bf16 v[112:115], v[184:187], v[168:171], v[112:115]
	v_mfma_f32_16x16x32_bf16 v[108:111], v[192:195], v[168:171], v[108:111]
	v_mfma_f32_16x16x32_bf16 v[104:107], v[184:187], v[176:179], v[104:107]
	v_mfma_f32_16x16x32_bf16 v[100:103], v[192:195], v[176:179], v[100:103]
	s_setprio 0
	s_mov_b32 m0, s49
	v_lshl_add_u64 v[212:213], s[28:29], 0, v[198:199]
	s_barrier
	ds_read_b128 v[148:151], v233 offset:16384
	ds_read_b128 v[152:155], v233 offset:17408
	ds_read_b128 v[156:159], v233 offset:18432
	ds_read_b128 v[160:163], v233 offset:19456
	ds_read_b128 v[164:167], v233 offset:20480
	ds_read_b128 v[168:171], v233 offset:21504
	ds_read_b128 v[172:175], v233 offset:22528
	ds_read_b128 v[176:179], v233 offset:23552
	global_load_lds_dwordx4 v[212:213], off
	v_lshl_add_u64 v[214:215], s[28:29], 0, v[202:203]
	s_mov_b32 m0, s50
	s_nop 0
	global_load_lds_dwordx4 v[214:215], off
	s_barrier
; #define PG8_STAGE(bufoff, gbase, voff) do { _Pragma("unroll") for (int _i = 0; _i < 2; ++_i) \
;         __builtin_amdgcn_global_load_lds((const unsigned*)((const char*)(gbase) + (voff)[_i]), (PG8_LAS unsigned*)(lds + (bufoff) + ldsw + _i * 8192), 16, 0, 0); } while (0)
; #define PG8_LDA(dst, b, h) do { _Pragma("unroll") for (int m = 0; m < 4; ++m) _Pragma("unroll") for (int k = 0; k < 2; ++k) dst[m][k] = *(const PG8_LAS bf16x8*)(lds + PG8_SA(b, h) + aoff + m * 2048 + k * 1024); } while (0)
; #define PG8_LDB(dst, b, h) do { _Pragma("unroll") for (int n = 0; n < 2; ++n) _Pragma("unroll") for (int k = 0; k < 2; ++k) dst[n][k] = *(const PG8_LAS bf16x8*)(lds + PG8_SB(b, h) + boff + n * 2048 + k * 1024); } while (0)
; #define PG8_MMA(ai, bj, At, Bt) do { __builtin_amdgcn_s_setprio(1); _Pragma("unroll") for (int m = 0; m < 4; ++m) _Pragma("unroll") for (int n = 0; n < 2; ++n) _Pragma("unroll") for (int k = 0; k < 2; ++k) \
;         acc[ai][bj][m][n] = __builtin_amdgcn_mfma_f32_16x16x32_bf16(Bt[n][k], At[m][k], acc[ai][bj][m][n], 0, 0, 0); __builtin_amdgcn_s_setprio(0); } while (0)
; #define PG8_WAIT_V(n) asm volatile("s_waitcnt vmcnt(" #n ")" ::: "memory")
; #define PG8_WAIT_L(n) asm volatile("s_waitcnt lgkmcnt(" #n ")" ::: "memory")
; #define PG8_BAR __builtin_amdgcn_s_barrier()
; #define PG8_SCHED __builtin_amdgcn_sched_barrier(0)
; template <class Epi, class Sched>
; __device__ __forceinline__ void gemm_phase(PG8_LAS unsigned char* lds, const Gemm g, const Sched& S, const Epi& E) {
;     ...
;             PG8_BAR; PG8_WAIT_L(0); PG8_MMA(1, 0, At, B0); PG8_BAR; PG8_SCHED;
;             PG8_STAGE(PG8_SB(0, 1), b2 + hstepB, voffB);
;             PG8_WAIT_V(6); PG8_BAR; PG8_MMA(1, 1, At, B1); PG8_BAR;
;             PG8_LDB(B0, 1, 0); PG8_SCHED; PG8_LDA(At, 1, 0); PG8_STAGE(PG8_SA(0, 1), a2 + hstep, voffA);
;             PG8_WAIT_L(8); PG8_BAR; PG8_WAIT_L(0); PG8_MMA(0, 0, At, B0); PG8_BAR; PG8_SCHED;
	s_waitcnt lgkmcnt(0)
	s_setprio 1
	s_waitcnt lgkmcnt(0)
	v_mfma_f32_16x16x32_bf16 v[96:99], v[132:135], v[148:151], v[96:99]
	v_mfma_f32_16x16x32_bf16 v[92:95], v[140:143], v[148:151], v[92:95]
	v_mfma_f32_16x16x32_bf16 v[88:91], v[132:135], v[156:159], v[88:91]
	v_mfma_f32_16x16x32_bf16 v[84:87], v[140:143], v[156:159], v[84:87]
	v_mfma_f32_16x16x32_bf16 v[80:83], v[132:135], v[164:167], v[80:83]
	v_mfma_f32_16x16x32_bf16 v[76:79], v[140:143], v[164:167], v[76:79]
	v_mfma_f32_16x16x32_bf16 v[72:75], v[132:135], v[172:175], v[72:75]
	v_mfma_f32_16x16x32_bf16 v[68:71], v[140:143], v[172:175], v[68:71]
	v_mfma_f32_16x16x32_bf16 v[96:99], v[136:139], v[152:155], v[96:99]
	v_mfma_f32_16x16x32_bf16 v[92:95], v[144:147], v[152:155], v[92:95]
	v_mfma_f32_16x16x32_bf16 v[88:91], v[136:139], v[160:163], v[88:91]
	v_mfma_f32_16x16x32_bf16 v[84:87], v[144:147], v[160:163], v[84:87]
	v_mfma_f32_16x16x32_bf16 v[80:83], v[136:139], v[168:171], v[80:83]
	v_mfma_f32_16x16x32_bf16 v[76:79], v[144:147], v[168:171], v[76:79]
	v_mfma_f32_16x16x32_bf16 v[72:75], v[136:139], v[176:179], v[72:75]
	v_mfma_f32_16x16x32_bf16 v[68:71], v[144:147], v[176:179], v[68:71]
	s_setprio 0
	s_barrier
	s_add_u32 s64, s26, 0x4000
	s_addc_u32 s65, s27, 0
	s_add_i32 s66, s58, s48
	v_lshl_add_u64 v[6:7], s[64:65], 0, v[196:197]
	s_mov_b32 m0, s66
	s_nop 0
	global_load_lds_dwordx4 v[6:7], off
	v_lshl_add_u64 v[6:7], s[64:65], 0, v[200:201]
	s_add_i32 m0, s66, 0x2000
	s_nop 0
	global_load_lds_dwordx4 v[6:7], off
	s_waitcnt vmcnt(6)
	s_barrier
	s_setprio 1
	v_mfma_f32_16x16x32_bf16 v[64:67], v[180:183], v[148:151], v[64:67]
	v_mfma_f32_16x16x32_bf16 v[60:63], v[188:191], v[148:151], v[60:63]
	v_mfma_f32_16x16x32_bf16 v[56:59], v[180:183], v[156:159], v[56:59]
	v_mfma_f32_16x16x32_bf16 v[52:55], v[188:191], v[156:159], v[52:55]
	v_mfma_f32_16x16x32_bf16 v[48:51], v[180:183], v[164:167], v[48:51]
	v_mfma_f32_16x16x32_bf16 v[44:47], v[188:191], v[164:167], v[44:47]
	v_mfma_f32_16x16x32_bf16 v[40:43], v[180:183], v[172:175], v[40:43]
	v_mfma_f32_16x16x32_bf16 v[36:39], v[188:191], v[172:175], v[36:39]
	v_mfma_f32_16x16x32_bf16 v[64:67], v[184:187], v[152:155], v[64:67]
	v_mfma_f32_16x16x32_bf16 v[60:63], v[192:195], v[152:155], v[60:63]
	v_mfma_f32_16x16x32_bf16 v[56:59], v[184:187], v[160:163], v[56:59]
	v_mfma_f32_16x16x32_bf16 v[52:55], v[192:195], v[160:163], v[52:55]
	v_mfma_f32_16x16x32_bf16 v[48:51], v[184:187], v[168:171], v[48:51]
	v_mfma_f32_16x16x32_bf16 v[44:47], v[192:195], v[168:171], v[44:47]
	v_mfma_f32_16x16x32_bf16 v[40:43], v[184:187], v[176:179], v[40:43]
	v_mfma_f32_16x16x32_bf16 v[36:39], v[192:195], v[176:179], v[36:39]
	s_setprio 0
	s_add_i32 s64, 0, 0x18000
	v_add_u32_e32 v1, s64, v231
	s_barrier
	ds_read_b128 v[132:135], v1
	ds_read_b128 v[136:139], v1 offset:1024
	ds_read_b128 v[140:143], v1 offset:2048
	ds_read_b128 v[144:147], v1 offset:3072
	s_add_u32 s28, s28, 0x40000
	s_addc_u32 s29, s29, 0
	s_mov_b32 m0, s51
	v_lshl_add_u64 v[6:7], s[28:29], 0, v[198:199]
	ds_read_b128 v[148:151], v233 offset:32768
	ds_read_b128 v[152:155], v233 offset:33792
	ds_read_b128 v[156:159], v233 offset:34816
	ds_read_b128 v[160:163], v233 offset:35840
	ds_read_b128 v[164:167], v233 offset:36864
	ds_read_b128 v[168:171], v233 offset:37888
	ds_read_b128 v[172:175], v233 offset:38912
	ds_read_b128 v[176:179], v233 offset:39936
	global_load_lds_dwordx4 v[6:7], off
	v_lshl_add_u64 v[6:7], s[28:29], 0, v[202:203]
	s_mov_b32 m0, s52
	s_nop 0
	global_load_lds_dwordx4 v[6:7], off
	s_waitcnt lgkmcnt(8)
	s_barrier
	s_waitcnt lgkmcnt(0)
	s_setprio 1
	s_waitcnt lgkmcnt(0)
	v_mfma_f32_16x16x32_bf16 v[2:5], v[132:135], v[148:151], v[2:5]
	v_mfma_f32_16x16x32_bf16 v[8:11], v[140:143], v[148:151], v[8:11]
	v_mfma_f32_16x16x32_bf16 v[32:35], v[132:135], v[156:159], v[32:35]
	v_mfma_f32_16x16x32_bf16 v[28:31], v[140:143], v[156:159], v[28:31]
	v_mfma_f32_16x16x32_bf16 v[24:27], v[132:135], v[164:167], v[24:27]
	v_mfma_f32_16x16x32_bf16 v[20:23], v[140:143], v[164:167], v[20:23]
	v_mfma_f32_16x16x32_bf16 v[16:19], v[132:135], v[172:175], v[16:19]
	v_mfma_f32_16x16x32_bf16 v[12:15], v[140:143], v[172:175], v[12:15]
	v_mfma_f32_16x16x32_bf16 v[4:7], v[136:139], v[152:155], v[2:5]
	v_mfma_f32_16x16x32_bf16 v[8:11], v[144:147], v[152:155], v[8:11]
	v_mfma_f32_16x16x32_bf16 v[32:35], v[136:139], v[160:163], v[32:35]
	v_mfma_f32_16x16x32_bf16 v[28:31], v[144:147], v[160:163], v[28:31]
	v_mfma_f32_16x16x32_bf16 v[24:27], v[136:139], v[168:171], v[24:27]
	v_mfma_f32_16x16x32_bf16 v[20:23], v[144:147], v[168:171], v[20:23]
	v_mfma_f32_16x16x32_bf16 v[16:19], v[136:139], v[176:179], v[16:19]
	v_mfma_f32_16x16x32_bf16 v[12:15], v[144:147], v[176:179], v[12:15]
	s_setprio 0
	s_barrier
	s_add_i32 s65, 0, 0x1c000
	s_add_u32 s28, s26, 0x8000
	s_addc_u32 s29, s27, 0
	s_add_i32 s64, s64, s48
	v_add_u32_e32 v1, s65, v231
	v_lshl_add_u64 v[2:3], s[28:29], 0, v[196:197]
	s_mov_b32 m0, s64
	ds_read_b128 v[180:183], v1
	ds_read_b128 v[184:187], v1 offset:1024
	ds_read_b128 v[188:191], v1 offset:2048
	ds_read_b128 v[192:195], v1 offset:3072
	global_load_lds_dwordx4 v[2:3], off
	v_lshl_add_u64 v[2:3], s[28:29], 0, v[200:201]
	s_add_i32 m0, s64, 0x2000
	s_nop 0
	global_load_lds_dwordx4 v[2:3], off
	s_barrier
; #define PG8_STAGE(bufoff, gbase, voff) do { _Pragma("unroll") for (int _i = 0; _i < 2; ++_i) \
;         __builtin_amdgcn_global_load_lds((const unsigned*)((const char*)(gbase) + (voff)[_i]), (PG8_LAS unsigned*)(lds + (bufoff) + ldsw + _i * 8192), 16, 0, 0); } while (0)
; #define PG8_LDA(dst, b, h) do { _Pragma("unroll") for (int m = 0; m < 4; ++m) _Pragma("unroll") for (int k = 0; k < 2; ++k) dst[m][k] = *(const PG8_LAS bf16x8*)(lds + PG8_SA(b, h) + aoff + m * 2048 + k * 1024); } while (0)
; #define PG8_LDB(dst, b, h) do { _Pragma("unroll") for (int n = 0; n < 2; ++n) _Pragma("unroll") for (int k = 0; k < 2; ++k) dst[n][k] = *(const PG8_LAS bf16x8*)(lds + PG8_SB(b, h) + boff + n * 2048 + k * 1024); } while (0)
; #define PG8_MMA(ai, bj, At, Bt) do { __builtin_amdgcn_s_setprio(1); _Pragma("unroll") for (int m = 0; m < 4; ++m) _Pragma("unroll") for (int n = 0; n < 2; ++n) _Pragma("unroll") for (int k = 0; k < 2; ++k) \
;         acc[ai][bj][m][n] = __builtin_amdgcn_mfma_f32_16x16x32_bf16(Bt[n][k], At[m][k], acc[ai][bj][m][n], 0, 0, 0); __builtin_amdgcn_s_setprio(0); } while (0)
; #define PG8_WAIT_V(n) asm volatile("s_waitcnt vmcnt(" #n ")" ::: "memory")
; #define PG8_WAIT_L(n) asm volatile("s_waitcnt lgkmcnt(" #n ")" ::: "memory")
; #define PG8_BAR __builtin_amdgcn_s_barrier()
;     __device__ __forceinline__ void operator()(f32x4 (&acc)[2][2][4][2], const Unit& u, int wr, int wc, int fr, int fq) const {
;     ...
;                 for (int bj = 0; bj < 2; ++bj) { const bf16_t* gp = G + (size_t)(row0 + ai * HALF + m * 16) * ZGW + br * 2048 + col0 + bj * HALF;
;                     ga[m][bj] = *(const u32x4*)gp; if (br < 2) gb[m][bj] = *(const u32x4*)(gp + 2048); }
; template <class Epi, class Sched>
; __device__ __forceinline__ void gemm_phase(PG8_LAS unsigned char* lds, const Gemm g, const Sched& S, const Epi& E) {
;     ...
;             PG8_WAIT_L(8); PG8_BAR; PG8_WAIT_L(0); PG8_MMA(0, 0, At, B0); PG8_BAR; PG8_SCHED;
;             PG8_LDB(B1, 1, 1); PG8_STAGE(PG8_SB(1, 0), b3, voffB);
;             PG8_BAR; PG8_WAIT_L(0); PG8_MMA(0, 1, At, B1); PG8_BAR;
;             PG8_LDA(At, 1, 1); PG8_STAGE(PG8_SA(1, 0), a3, voffA);
;             PG8_BAR; PG8_WAIT_L(0); PG8_MMA(1, 0, At, B0); PG8_BAR; PG8_SCHED;
;             PG8_STAGE(PG8_SB(1, 1), b3 + hstepB, voffB);
;             PG8_WAIT_V(6); PG8_BAR; PG8_MMA(1, 1, At, B1); PG8_BAR;
;         }
	s_waitcnt lgkmcnt(0)
	s_setprio 1
	s_waitcnt lgkmcnt(0)
	v_mfma_f32_16x16x32_bf16 v[128:131], v[180:183], v[148:151], v[128:131]
	v_mfma_f32_16x16x32_bf16 v[124:127], v[188:191], v[148:151], v[124:127]
	v_mfma_f32_16x16x32_bf16 v[120:123], v[180:183], v[156:159], v[120:123]
	v_mfma_f32_16x16x32_bf16 v[116:119], v[188:191], v[156:159], v[116:119]
	v_mfma_f32_16x16x32_bf16 v[112:115], v[180:183], v[164:167], v[112:115]
	v_mfma_f32_16x16x32_bf16 v[108:111], v[188:191], v[164:167], v[108:111]
	v_mfma_f32_16x16x32_bf16 v[104:107], v[180:183], v[172:175], v[104:107]
	v_mfma_f32_16x16x32_bf16 v[100:103], v[188:191], v[172:175], v[100:103]
	v_mfma_f32_16x16x32_bf16 v[128:131], v[184:187], v[152:155], v[128:131]
	v_mfma_f32_16x16x32_bf16 v[124:127], v[192:195], v[152:155], v[124:127]
	v_mfma_f32_16x16x32_bf16 v[120:123], v[184:187], v[160:163], v[120:123]
	v_mfma_f32_16x16x32_bf16 v[116:119], v[192:195], v[160:163], v[116:119]
	v_mfma_f32_16x16x32_bf16 v[112:115], v[184:187], v[168:171], v[112:115]
	v_mfma_f32_16x16x32_bf16 v[108:111], v[192:195], v[168:171], v[108:111]
	v_mfma_f32_16x16x32_bf16 v[104:107], v[184:187], v[176:179], v[104:107]
	v_mfma_f32_16x16x32_bf16 v[100:103], v[192:195], v[176:179], v[100:103]
	s_setprio 0
	s_mov_b32 m0, s55
	v_lshl_add_u64 v[2:3], v[212:213], 0, s[12:13]
	s_barrier
	ds_read_b128 v[148:151], v233 offset:49152
	ds_read_b128 v[152:155], v233 offset:50176
	ds_read_b128 v[156:159], v233 offset:51200
	ds_read_b128 v[160:163], v233 offset:52224
	ds_read_b128 v[164:167], v233 offset:53248
	ds_read_b128 v[168:171], v233 offset:54272
	ds_read_b128 v[172:175], v233 offset:55296
	ds_read_b128 v[176:179], v233 offset:56320
	global_load_lds_dwordx4 v[2:3], off
	v_lshl_add_u64 v[2:3], v[214:215], 0, s[12:13]
	s_mov_b32 m0, s56
	s_nop 0
	global_load_lds_dwordx4 v[2:3], off
	s_barrier
	s_waitcnt lgkmcnt(0)
	s_setprio 1
	s_waitcnt lgkmcnt(0)
	v_mfma_f32_16x16x32_bf16 v[96:99], v[132:135], v[148:151], v[96:99]
	v_mfma_f32_16x16x32_bf16 v[92:95], v[140:143], v[148:151], v[92:95]
	v_mfma_f32_16x16x32_bf16 v[88:91], v[132:135], v[156:159], v[88:91]
	v_mfma_f32_16x16x32_bf16 v[84:87], v[140:143], v[156:159], v[84:87]
	v_mfma_f32_16x16x32_bf16 v[80:83], v[132:135], v[164:167], v[80:83]
	v_mfma_f32_16x16x32_bf16 v[76:79], v[140:143], v[164:167], v[76:79]
	v_mfma_f32_16x16x32_bf16 v[72:75], v[132:135], v[172:175], v[72:75]
	v_mfma_f32_16x16x32_bf16 v[68:71], v[140:143], v[172:175], v[68:71]
	v_mfma_f32_16x16x32_bf16 v[96:99], v[136:139], v[152:155], v[96:99]
	v_mfma_f32_16x16x32_bf16 v[92:95], v[144:147], v[152:155], v[92:95]
	v_mfma_f32_16x16x32_bf16 v[88:91], v[136:139], v[160:163], v[88:91]
	v_mfma_f32_16x16x32_bf16 v[84:87], v[144:147], v[160:163], v[84:87]
	v_mfma_f32_16x16x32_bf16 v[80:83], v[136:139], v[168:171], v[80:83]
	v_mfma_f32_16x16x32_bf16 v[76:79], v[144:147], v[168:171], v[76:79]
	v_mfma_f32_16x16x32_bf16 v[72:75], v[136:139], v[176:179], v[72:75]
	v_mfma_f32_16x16x32_bf16 v[68:71], v[144:147], v[176:179], v[68:71]
	s_setprio 0
	s_barrier
	s_add_u32 s26, s26, 0xc000
	s_addc_u32 s27, s27, 0
	s_add_i32 s28, s65, s48
	v_lshl_add_u64 v[2:3], s[26:27], 0, v[196:197]
	s_mov_b32 m0, s28
	s_nop 0
	global_load_lds_dwordx4 v[2:3], off
	v_lshl_add_u64 v[2:3], s[26:27], 0, v[200:201]
	s_add_i32 m0, s28, 0x2000
	s_nop 0
	global_load_lds_dwordx4 v[2:3], off
	s_waitcnt vmcnt(6)
	s_barrier
	s_setprio 1
	v_mfma_f32_16x16x32_bf16 v[64:67], v[180:183], v[148:151], v[64:67]
	v_mfma_f32_16x16x32_bf16 v[60:63], v[188:191], v[148:151], v[60:63]
	v_mfma_f32_16x16x32_bf16 v[56:59], v[180:183], v[156:159], v[56:59]
	v_mfma_f32_16x16x32_bf16 v[52:55], v[188:191], v[156:159], v[52:55]
	v_mfma_f32_16x16x32_bf16 v[48:51], v[180:183], v[164:167], v[48:51]
	v_mfma_f32_16x16x32_bf16 v[44:47], v[188:191], v[164:167], v[44:47]
	v_mfma_f32_16x16x32_bf16 v[40:43], v[180:183], v[172:175], v[40:43]
	v_mfma_f32_16x16x32_bf16 v[36:39], v[188:191], v[172:175], v[36:39]
	v_mfma_f32_16x16x32_bf16 v[64:67], v[184:187], v[152:155], v[64:67]
	v_mfma_f32_16x16x32_bf16 v[60:63], v[192:195], v[152:155], v[60:63]
	v_mfma_f32_16x16x32_bf16 v[56:59], v[184:187], v[160:163], v[56:59]
	v_mfma_f32_16x16x32_bf16 v[52:55], v[192:195], v[160:163], v[52:55]
	v_mfma_f32_16x16x32_bf16 v[48:51], v[184:187], v[168:171], v[48:51]
	v_mfma_f32_16x16x32_bf16 v[44:47], v[192:195], v[168:171], v[44:47]
	v_mfma_f32_16x16x32_bf16 v[40:43], v[184:187], v[176:179], v[40:43]
	v_mfma_f32_16x16x32_bf16 v[36:39], v[192:195], v[176:179], v[36:39]
	s_setprio 0
	s_add_i32 s63, s63, 2
	s_add_u32 s61, s61, 0x10000
	s_addc_u32 s62, s62, 0
	s_add_u32 s24, s24, 0x100
	s_addc_u32 s25, s25, 0
	s_cmp_gt_u32 s63, 13
	s_barrier
	s_cbranch_scc0 .LBB0_613
	s_cmp_eq_u32 s78, 0
	s_cbranch_scc0 .Lhalf_skip_x_4
	s_barrier
.Lhalf_skip_x_4:
	s_lshl_b32 s26, s9, 11
	s_ashr_i32 s27, s26, 31
	s_cmp_lt_i32 s9, 2
	v_lshl_add_u32 v212, s6, 8, v230
	s_cselect_b64 s[6:7], -1, 0
	s_cmp_gt_i32 s9, 1
	v_lshl_or_b32 v2, s8, 8, v232
	s_cselect_b64 s[24:25], -1, 0
	s_lshl_b64 s[8:9], s[26:27], 1
	s_add_u32 s8, s53, s8
	v_ashrrev_i32_e32 v3, 31, v2
	s_addc_u32 s9, s54, s9
	v_lshl_add_u64 v[214:215], v[2:3], 1, s[8:9]
	v_mad_i64_i32 v[132:133], s[8:9], v212, s59, v[214:215]
	global_load_dwordx4 v[192:195], v[132:133], off
	s_and_b64 vcc, exec, s[24:25]
	s_cbranch_vccnz .LBB0_616
	v_add_co_u32_e32 v134, vcc, 0x1000, v132
	s_nop 1
	v_addc_co_u32_e32 v135, vcc, 0, v133, vcc
	global_load_dwordx4 v[160:163], v[134:135], off

; #define PG8_WAIT_V(n) asm volatile("s_waitcnt vmcnt(" #n ")" ::: "memory")
; #define PG8_BAR __builtin_amdgcn_s_barrier()
; template <class Epi, class Sched>
; __device__ __forceinline__ void gemm_phase(PG8_LAS unsigned char* lds, const Gemm g, const Sched& S, const Epi& E) {
;     ...
;     PG8_WAIT_V(0);
;     if (wr == 0) PG8_BAR;
;     PG8_BAR;
.LBB0_713:
	s_waitcnt vmcnt(0)
	s_cmpk_gt_u32 s37, 0xff
	s_cbranch_scc1 .LBB0_715
.LBB0_715:
	s_barrier

;     __host__ __device__ bool next(int i, Unit& u) const { const int j = i / 3; if (!StaticOrder::next(j, u)) return false; u.br = i - 3 * j; return true; }
; #define PG8_STAGE(bufoff, gbase, voff) do { _Pragma("unroll") for (int _i = 0; _i < 2; ++_i) \
;         __builtin_amdgcn_global_load_lds((const unsigned*)((const char*)(gbase) + (voff)[_i]), (PG8_LAS unsigned*)(lds + (bufoff) + ldsw + _i * 8192), 16, 0, 0); } while (0)
; template <class Epi, class Sched>
; __device__ __forceinline__ void gemm_phase(PG8_LAS unsigned char* lds, const Gemm g, const Sched& S, const Epi& E) {
;     ...
;     const int tid = tix_, wid = __builtin_amdgcn_readfirstlane(tid >> 6), lane = tid & 63, wr = wid >> 2, wc = wid & 3, fr = lane & 15, fq = lane >> 4;
;     const int K = g.K, nt = K / BK;
;     unsigned voffA[2], voffB[2];
; #pragma unroll
;     for (int i = 0; i < 2; ++i) { int R, C; stage_rc(tid * 16 + i * 8192, R, C);
;         voffA[i] = (unsigned)(R * K + C) * 2u; voffB[i] = (unsigned)(tid * 16 + i * 8192); }
;     const size_t kstep = (size_t)(BK * 2);
;     const size_t hstep = (size_t)HALF * K * 2;
;     const size_t tstep = 2 * hstep;
;     const size_t kstepB = 32768, hstepB = 16384, tstepB = (size_t)nt * 32768;
;     const unsigned ldsw = (unsigned)wid * 1024u;
;     const int aoff = lds_byte(wr * 64 + fr, fq * 8), boff = lds_byte(wc * 32 + fr, fq * 8);
;     ...
;     Unit cur, nxt; int ui = 0;
;     if (!S.next(0, cur)) return;
;     f32x4 acc[2][2][4][2];
; #pragma unroll
;     for (int a = 0; a < 2; ++a)
; #pragma unroll
;         for (int b = 0; b < 2; ++b)
; #pragma unroll
;             for (int m = 0; m < 4; ++m)
; #pragma unroll
;                 for (int n = 0; n < 2; ++n) acc[a][b][m][n] = (f32x4){0.f, 0.f, 0.f, 0.f};
;     bf16x8 At[4][2], B0[2][2], B1[2][2];
;     const char* cA = (const char*)g.A + (size_t)cur.pm * tstep + (size_t)cur.br * g.strideA; const char* cB = (const char*)g.Bt + (size_t)cur.pn * tstepB + (size_t)cur.br * g.strideB;
;     S.a_ready(cur);
;     PG8_STAGE(PG8_SB(0, 0), cB, voffB); PG8_STAGE(PG8_SA(0, 0), cA, voffA); PG8_STAGE(PG8_SB(0, 1), cB + hstepB, voffB); PG8_STAGE(PG8_SA(0, 1), cA + hstep, voffA);
;     if (wr == 1) PG8_BAR;
;     PG8_WAIT_V(4); PG8_BAR;
;     PG8_STAGE(PG8_SB(1, 0), cB + kstepB, voffB); PG8_STAGE(PG8_SA(1, 0), cA + kstep, voffA); PG8_STAGE(PG8_SB(1, 1), cB + hstepB + kstepB, voffB);
;     PG8_WAIT_V(6); PG8_BAR;
.LBB0_773:
	v_ashrrev_i32_e32 v0, 31, v4
	v_lshrrev_b32_e32 v0, 26, v0
	v_add_u32_e32 v0, v4, v0
	v_ashrrev_i32_e32 v5, 6, v0
	v_bfe_i32 v0, v4, 27, 1
	v_lshlrev_b32_e32 v164, 4, v4
	v_lshrrev_b32_e32 v0, 22, v0
	v_add_u32_e32 v0, v164, v0
	v_and_b32_e32 v0, 0xfffffc00, v0
	v_sub_u32_e32 v0, v164, v0
	s_waitcnt lgkmcnt(0)
	s_add_u32 s50, s4, 0xc700000
	v_lshrrev_b32_e32 v1, 4, v0
	s_addc_u32 s51, s5, 0
	v_bitop3_b32 v0, v1, v0, 32 bitop3:0x6c
	s_add_u32 s52, s4, 0x7e80000
	v_ashrrev_i32_e32 v2, 31, v0
	s_addc_u32 s53, s5, 0
	v_lshrrev_b32_e32 v2, 26, v2
	s_add_i32 s6, s8, s6
	v_add_u32_e32 v2, v0, v2
	s_sext_i32_i16 s7, s6
	v_lshlrev_b32_e32 v1, 3, v5
	v_ashrrev_i32_e32 v6, 6, v2
	v_and_b32_e32 v2, 0xc0, v2
	s_bfe_u32 s7, s7, 0x5001a
	v_and_b32_e32 v1, 0xffff0, v1
	v_lshlrev_b32_e32 v3, 5, v5
	v_sub_u32_e32 v0, v0, v2
	v_mov_b32_e32 v2, 1
	s_add_i32 s7, s6, s7
	v_add_u32_e32 v1, v6, v1
	v_and_b32_e32 v7, 32, v3
	v_ashrrev_i16_sdwa v0, v2, sext(v0) dst_sel:DWORD dst_unused:UNUSED_PAD src0_sel:DWORD src1_sel:BYTE_0
	s_sext_i32_i16 s8, s7
	s_and_b32 s7, s7, 0xffe0
	v_bfe_i32 v8, v0, 0, 16
	v_lshl_or_b32 v0, v1, 11, v7
	v_add_u32_e32 v168, 0x2000, v164
	s_sub_i32 s6, s6, s7
	v_add_lshl_u32 v166, v0, v8, 1
	v_ashrrev_i32_e32 v0, 31, v168
	s_bfe_i32 s7, s6, 0x80000
	v_lshrrev_b32_e32 v0, 22, v0
	s_bfe_u32 s7, s7, 0x2000d
	v_add_u32_e32 v0, v168, v0
	s_add_i32 s7, s6, s7
	v_ashrrev_i32_e32 v9, 10, v0
	s_bfe_i32 s9, s7, 0x80000
	s_and_b32 s7, s7, 0xfc
	v_mul_i32_i24_e32 v0, 0x400, v9
	s_ashr_i32 s8, s8, 5
	s_sub_i32 s6, s6, s7
	v_sub_u32_e32 v0, v168, v0
	s_lshl_b32 s8, s8, 2
	s_sext_i32_i16 s9, s9
	s_sext_i32_i8 s6, s6
	v_lshrrev_b32_e32 v1, 4, v0
	s_ashr_i32 s13, s48, 8
	s_lshr_b32 s12, s9, 2
	s_add_i32 s26, s8, s6
	s_ashr_i32 s10, s48, 6
	v_bitop3_b32 v0, v1, v0, 32 bitop3:0x6c
	s_ashr_i32 s27, s26, 31
	s_bfe_i64 s[8:9], s[12:13], 0x100000
	v_ashrrev_i32_e32 v3, 31, v0
	s_lshl_b32 s54, s10, 10
	s_lshl_b64 s[6:7], s[26:27], 20
	s_lshl_b64 s[8:9], s[8:9], 20
	v_lshrrev_b32_e32 v3, 26, v3
	s_add_u32 s30, s52, s8
	v_add_u32_e32 v3, v0, v3
	s_addc_u32 s31, s53, s9
	s_add_i32 s27, s54, 0
	v_lshlrev_b32_e32 v1, 3, v9
	v_ashrrev_i32_e32 v10, 6, v3
	v_and_b32_e32 v3, 0xc0, v3
	s_add_i32 m0, s27, 0x10000
	v_and_b32_e32 v1, 0xffff0, v1
	v_lshlrev_b32_e32 v11, 5, v9
	v_sub_u32_e32 v0, v0, v3
	global_load_lds_dwordx4 v164, s[30:31]
	s_add_i32 m0, s27, 0x12000
	v_add_u32_e32 v1, v10, v1
	v_and_b32_e32 v11, 32, v11
	v_ashrrev_i16_sdwa v0, v2, sext(v0) dst_sel:DWORD dst_unused:UNUSED_PAD src0_sel:DWORD src1_sel:BYTE_0
	s_add_u32 s28, s50, s6
	v_bfe_i32 v12, v0, 0, 16
	v_lshl_or_b32 v0, v1, 11, v11
	global_load_lds_dwordx4 v168, s[30:31]
	s_addc_u32 s29, s51, s7
	s_mov_b32 m0, s27
	s_add_i32 s55, s27, 0x2000
	v_add_lshl_u32 v170, v0, v12, 1
	global_load_lds_dwordx4 v166, s[28:29]
	s_mov_b32 m0, s55
	s_add_u32 s6, s30, 0x4000
	global_load_lds_dwordx4 v170, s[28:29]
	s_addc_u32 s7, s31, 0
	s_add_i32 m0, s27, 0x14000
	v_mov_b32_e32 v165, 0
	global_load_lds_dwordx4 v164, s[6:7]
	s_add_i32 m0, s27, 0x16000
	v_mov_b32_e32 v167, v165
	global_load_lds_dwordx4 v168, s[6:7]
	s_add_u32 s6, s28, 0x80000
	s_addc_u32 s7, s29, 0
	s_add_i32 s56, s27, 0x4000
	s_mov_b32 m0, s56
	s_add_i32 s57, s27, 0x6000
	global_load_lds_dwordx4 v166, s[6:7]
	s_mov_b32 m0, s57
	v_mov_b32_e32 v171, v165
	global_load_lds_dwordx4 v170, s[6:7]
	s_mov_b32 s58, 0
	v_mov_b32_e32 v169, v165
	v_lshl_add_u64 v[2:3], s[28:29], 0, v[166:167]
	v_lshl_add_u64 v[0:1], s[28:29], 0, v[170:171]
	s_cmp_lg_u32 s13, 1
	s_mov_b64 s[6:7], 0x80000
	s_cbranch_scc1 .LBB0_775
.LBB0_775:
	s_add_u32 s8, s4, 0x2dd24000
	s_addc_u32 s9, s5, 0
	s_lshl_b32 s4, s10, 5
	s_and_b32 s15, s4, 0x60
	s_lshl_b32 s14, s13, 13
	s_lshl_b32 s16, s15, 7
	s_add_u32 s4, s30, 0x8000
	s_addc_u32 s5, s31, 0
	s_add_i32 m0, s27, 0x18000
	v_lshl_add_u64 v[14:15], s[4:5], 0, v[164:165]
	s_waitcnt vmcnt(4)
	s_barrier
	global_load_lds_dwordx4 v[14:15], off
	v_lshl_add_u64 v[14:15], s[4:5], 0, v[168:169]
	s_add_i32 m0, s27, 0x1a000
	s_mov_b64 s[10:11], 0x80
	s_add_i32 s59, s27, 0x8000
	s_add_i32 s60, s27, 0xa000
	global_load_lds_dwordx4 v[14:15], off
	v_lshl_add_u64 v[2:3], v[2:3], 0, s[10:11]
	s_mov_b32 m0, s59
	s_add_u32 s4, s30, 0xc000
	global_load_lds_dwordx4 v[2:3], off
	v_lshl_add_u64 v[0:1], v[0:1], 0, s[10:11]
	s_mov_b32 m0, s60
	s_addc_u32 s5, s31, 0
	global_load_lds_dwordx4 v[0:1], off
	s_add_i32 m0, s27, 0x1c000
	v_lshl_add_u64 v[0:1], s[4:5], 0, v[164:165]
	global_load_lds_dwordx4 v[0:1], off
	v_lshl_add_u64 v[0:1], s[4:5], 0, v[168:169]
	s_add_i32 m0, s27, 0x1e000
	s_mov_b64 s[4:5], 0x80080
	global_load_lds_dwordx4 v[0:1], off
	v_lshrrev_b32_e32 v1, 1, v4
	v_and_b32_e32 v1, 24, v1
	v_and_b32_e32 v0, 15, v4
	v_lshlrev_b32_e32 v2, 1, v1
	v_lshl_or_b32 v194, s13, 6, v0
	v_lshl_or_b32 v0, v0, 6, v2
	v_lshlrev_b32_e32 v2, 2, v4
	v_and_b32_e32 v2, 32, v2
	v_bitop3_b32 v3, v0, s14, v2 bitop3:0xde
	v_bitop3_b32 v195, v0, s16, v2 bitop3:0xde
	v_lshlrev_b32_e32 v0, 14, v5
	v_and_b32_e32 v0, 0x7fff8000, v0
	v_lshl_add_u32 v0, v6, 11, v0
	v_or_b32_e32 v0, v0, v7
	v_or_b32_e32 v196, s15, v1
	v_add_lshl_u32 v0, v0, v8, 1
	v_mov_b32_e32 v1, v165
	v_lshl_add_u64 v[172:173], v[0:1], 0, s[4:5]
	v_lshlrev_b32_e32 v0, 14, v9
	v_and_b32_e32 v0, 0x7fff8000, v0
	v_lshl_add_u32 v0, v10, 11, v0
	s_waitcnt vmcnt(6)
	v_or_b32_e32 v0, v0, v11
	v_add_lshl_u32 v0, v0, v12, 1
	s_add_i32 s62, 0, 0x10000
	s_add_i32 s63, 0, 0x14000
	s_sext_i32_i8 s64, s12
	s_ashr_i32 s61, s46, 31
	v_lshl_add_u64 v[174:175], v[0:1], 0, s[4:5]
	v_mov_b64_e32 v[176:177], 0x200
	v_mov_b64_e32 v[178:179], 0x1ff
	v_add_u32_e32 v197, s62, v195
	v_add_u32_e32 v198, 0, v3
	v_add_u32_e32 v199, s63, v195
	s_mov_b64 s[12:13], 0x90000
	s_mov_b64 s[14:15], 0xa0000
	s_mov_b64 s[16:17], 0xb0000
	s_barrier

;     __host__ __device__ bool next(int i, Unit& u) const { const int j = i / 3; if (!StaticOrder::next(j, u)) return false; u.br = i - 3 * j; return true; }
; #define PG8_STAGE(bufoff, gbase, voff) do { _Pragma("unroll") for (int _i = 0; _i < 2; ++_i) \
;         __builtin_amdgcn_global_load_lds((const unsigned*)((const char*)(gbase) + (voff)[_i]), (PG8_LAS unsigned*)(lds + (bufoff) + ldsw + _i * 8192), 16, 0, 0); } while (0)
; #define PG8_LDA(dst, b, h) do { _Pragma("unroll") for (int m = 0; m < 4; ++m) _Pragma("unroll") for (int k = 0; k < 2; ++k) dst[m][k] = *(const PG8_LAS bf16x8*)(lds + PG8_SA(b, h) + aoff + m * 2048 + k * 1024); } while (0)
; #define PG8_LDB(dst, b, h) do { _Pragma("unroll") for (int n = 0; n < 2; ++n) _Pragma("unroll") for (int k = 0; k < 2; ++k) dst[n][k] = *(const PG8_LAS bf16x8*)(lds + PG8_SB(b, h) + boff + n * 2048 + k * 1024); } while (0)
; #define PG8_WAIT_L(n) asm volatile("s_waitcnt lgkmcnt(" #n ")" ::: "memory")
; #define PG8_BAR __builtin_amdgcn_s_barrier()
; template <class Epi, class Sched>
; __device__ __forceinline__ void gemm_phase(PG8_LAS unsigned char* lds, const Gemm g, const Sched& S, const Epi& E) {
;     ...
;         const bool has_next = S.next(ui + 1, nxt);
;         const char* nA = has_next ? (const char*)g.A + (size_t)nxt.pm * tstep + (size_t)nxt.br * g.strideA : cA; const char* nB = has_next ? (const char*)g.Bt + (size_t)nxt.pn * tstepB + (size_t)nxt.br * g.strideB : cB;
;         for (int t = 0; t < nt; t += 2) {
;             const bool last = (t == nt - 2);
;             const char* a1 = cA + (size_t)(t + 1) * kstep;
;             const char* a2 = last ? nA : cA + (size_t)(t + 2) * kstep; const char* b2 = last ? nB : cB + (size_t)(t + 2) * kstepB;
;             const char* a3 = a2 + kstep; const char* b3 = b2 + kstepB;
;             if (last && has_next) S.a_ready(nxt);
;             PG8_LDB(B0, 0, 0); PG8_SCHED; PG8_LDA(At, 0, 0); PG8_STAGE(PG8_SA(1, 1), a1 + hstep, voffA);
;             PG8_WAIT_L(8); PG8_BAR; PG8_WAIT_L(0); PG8_MMA(0, 0, At, B0); PG8_BAR; PG8_SCHED;
;     ...
;         if (!(Epi::CHAIN && cur.br < 2))
; #pragma unroll
;         for (int a = 0; a < 2; ++a)
; #pragma unroll
;             for (int b = 0; b < 2; ++b)
; #pragma unroll
;                 for (int m = 0; m < 4; ++m)
; #pragma unroll
;                     for (int n = 0; n < 2; ++n) acc[a][b][m][n] = (f32x4){0.f, 0.f, 0.f, 0.f};
.LBB0_782:
	s_ashr_i32 s19, s18, 31
	v_cmp_lt_i64_e32 vcc, s[22:23], v[176:177]
	s_lshl_b64 s[22:23], s[18:19], 20
	s_add_u32 s22, s50, s22
	s_addc_u32 s23, s51, s23
	s_and_b64 s[24:25], vcc, exec
	s_cselect_b32 s19, s23, s29
	s_cselect_b32 s65, s22, s28
	s_ashr_i32 s21, s20, 31
	s_lshl_b64 s[24:25], s[20:21], 20
	s_add_u32 s24, s52, s24
	s_addc_u32 s25, s53, s25
	s_and_b64 s[36:37], vcc, exec
	s_cselect_b32 s21, s25, s31
	s_cselect_b32 s66, s24, s30
	s_add_u32 s67, s30, 0x10000
	v_mov_b32_e32 v0, 0
	s_addc_u32 s68, s31, 0
	s_mov_b32 s69, -2
	v_mov_b32_e32 v1, v0
	v_mov_b32_e32 v2, v0
	v_mov_b32_e32 v3, v0
	v_mov_b32_e32 v4, v0
	v_mov_b32_e32 v5, v0
	v_mov_b32_e32 v6, v0
	v_mov_b32_e32 v7, v0
	v_mov_b32_e32 v16, v0
	v_mov_b32_e32 v17, v0
	v_mov_b32_e32 v18, v0
	v_mov_b32_e32 v19, v0
	v_mov_b32_e32 v20, v0
	v_mov_b32_e32 v21, v0
	v_mov_b32_e32 v22, v0
	v_mov_b32_e32 v23, v0
	v_mov_b32_e32 v32, v0
	v_mov_b32_e32 v33, v0
	v_mov_b32_e32 v34, v0
	v_mov_b32_e32 v35, v0
	v_mov_b32_e32 v36, v0
	v_mov_b32_e32 v37, v0
	v_mov_b32_e32 v38, v0
	v_mov_b32_e32 v39, v0
	v_mov_b32_e32 v48, v0
	v_mov_b32_e32 v49, v0
	v_mov_b32_e32 v50, v0
	v_mov_b32_e32 v51, v0
	v_mov_b32_e32 v52, v0
	v_mov_b32_e32 v53, v0
	v_mov_b32_e32 v54, v0
	v_mov_b32_e32 v55, v0
	v_mov_b32_e32 v8, v0
	v_mov_b32_e32 v9, v0
	v_mov_b32_e32 v10, v0
	v_mov_b32_e32 v11, v0
	v_mov_b32_e32 v12, v0
	v_mov_b32_e32 v13, v0
	v_mov_b32_e32 v14, v0
	v_mov_b32_e32 v15, v0
	v_mov_b32_e32 v24, v0
	v_mov_b32_e32 v25, v0
	v_mov_b32_e32 v26, v0
	v_mov_b32_e32 v27, v0
	v_mov_b32_e32 v28, v0
	v_mov_b32_e32 v29, v0
	v_mov_b32_e32 v30, v0
	v_mov_b32_e32 v31, v0
	v_mov_b32_e32 v40, v0
	v_mov_b32_e32 v41, v0
	v_mov_b32_e32 v42, v0
	v_mov_b32_e32 v43, v0
	v_mov_b32_e32 v44, v0
	v_mov_b32_e32 v45, v0
	v_mov_b32_e32 v46, v0
	v_mov_b32_e32 v47, v0
	v_mov_b32_e32 v56, v0
	v_mov_b32_e32 v57, v0
	v_mov_b32_e32 v58, v0
	v_mov_b32_e32 v59, v0
	v_mov_b32_e32 v60, v0
	v_mov_b32_e32 v61, v0
	v_mov_b32_e32 v62, v0
	v_mov_b32_e32 v63, v0
	v_mov_b32_e32 v64, v0
	v_mov_b32_e32 v65, v0
	v_mov_b32_e32 v66, v0
	v_mov_b32_e32 v67, v0
	v_mov_b32_e32 v68, v0
	v_mov_b32_e32 v69, v0
	v_mov_b32_e32 v70, v0
	v_mov_b32_e32 v71, v0
	v_mov_b32_e32 v80, v0
	v_mov_b32_e32 v81, v0
	v_mov_b32_e32 v82, v0
	v_mov_b32_e32 v83, v0
	v_mov_b32_e32 v84, v0
	v_mov_b32_e32 v85, v0
	v_mov_b32_e32 v86, v0
	v_mov_b32_e32 v87, v0
	v_mov_b32_e32 v96, v0
	v_mov_b32_e32 v97, v0
	v_mov_b32_e32 v98, v0
	v_mov_b32_e32 v99, v0
	v_mov_b32_e32 v100, v0
	v_mov_b32_e32 v101, v0
	v_mov_b32_e32 v102, v0
	v_mov_b32_e32 v103, v0
	v_mov_b32_e32 v108, v0
	v_mov_b32_e32 v109, v0
	v_mov_b32_e32 v110, v0
	v_mov_b32_e32 v111, v0
	v_mov_b32_e32 v112, v0
	v_mov_b32_e32 v113, v0
	v_mov_b32_e32 v114, v0
	v_mov_b32_e32 v115, v0
	v_mov_b32_e32 v72, v0
	v_mov_b32_e32 v73, v0
	v_mov_b32_e32 v74, v0
	v_mov_b32_e32 v75, v0
	v_mov_b32_e32 v76, v0
	v_mov_b32_e32 v77, v0
	v_mov_b32_e32 v78, v0
	v_mov_b32_e32 v79, v0
	v_mov_b32_e32 v88, v0
	v_mov_b32_e32 v89, v0
	v_mov_b32_e32 v90, v0
	v_mov_b32_e32 v91, v0
	v_mov_b32_e32 v92, v0
	v_mov_b32_e32 v93, v0
	v_mov_b32_e32 v94, v0
	v_mov_b32_e32 v95, v0
	v_mov_b32_e32 v104, v0
	v_mov_b32_e32 v105, v0
	v_mov_b32_e32 v106, v0
	v_mov_b32_e32 v107, v0
	v_mov_b32_e32 v116, v0
	v_mov_b32_e32 v117, v0
	v_mov_b32_e32 v118, v0
	v_mov_b32_e32 v119, v0
	v_mov_b32_e32 v120, v0
	v_mov_b32_e32 v121, v0
	v_mov_b32_e32 v122, v0
	v_mov_b32_e32 v123, v0
	v_mov_b32_e32 v124, v0
	v_mov_b32_e32 v125, v0
	v_mov_b32_e32 v126, v0
	v_mov_b32_e32 v127, v0
	s_cmp_eq_u32 s78, 1
	s_cbranch_scc0 .Lhalf_skip_y_5
	s_barrier
.Lhalf_skip_y_5:
.LBB0_783:
	ds_read_b128 v[128:131], v197
	ds_read_b128 v[132:135], v197 offset:1024
	ds_read_b128 v[136:139], v197 offset:2048
	ds_read_b128 v[140:143], v197 offset:3072
	s_add_u32 s30, s28, 0x100
	s_addc_u32 s31, s29, 0
	s_cmp_eq_u32 s69, 28
	s_cselect_b32 s39, s19, s31
	s_cselect_b32 s38, s65, s30
	s_cselect_b32 s37, s21, s68
	s_cselect_b32 s36, s66, s67
	v_lshl_add_u64 v[192:193], s[28:29], 0, v[172:173]
	s_add_i32 m0, s27, 0xc000
	ds_read_b128 v[144:147], v198
	ds_read_b128 v[148:151], v198 offset:1024
	ds_read_b128 v[152:155], v198 offset:2048
	ds_read_b128 v[156:159], v198 offset:3072
	ds_read_b128 v[160:163], v198 offset:4096
	ds_read_b128 v[180:183], v198 offset:5120
	ds_read_b128 v[184:187], v198 offset:6144
	ds_read_b128 v[188:191], v198 offset:7168
	global_load_lds_dwordx4 v[192:193], off
	v_lshl_add_u64 v[192:193], s[28:29], 0, v[174:175]
	s_add_i32 m0, s27, 0xe000
	s_nop 0
	global_load_lds_dwordx4 v[192:193], off
	s_waitcnt lgkmcnt(8)
	s_barrier
	s_waitcnt lgkmcnt(0)
	s_setprio 1
	s_waitcnt lgkmcnt(0)
	v_mfma_f32_16x16x32_bf16 v[124:127], v[128:131], v[144:147], v[124:127]
	v_mfma_f32_16x16x32_bf16 v[120:123], v[136:139], v[144:147], v[120:123]
	v_mfma_f32_16x16x32_bf16 v[116:119], v[128:131], v[152:155], v[116:119]
	v_mfma_f32_16x16x32_bf16 v[104:107], v[136:139], v[152:155], v[104:107]
	v_mfma_f32_16x16x32_bf16 v[92:95], v[128:131], v[160:163], v[92:95]
	v_mfma_f32_16x16x32_bf16 v[88:91], v[136:139], v[160:163], v[88:91]
	v_mfma_f32_16x16x32_bf16 v[76:79], v[128:131], v[184:187], v[76:79]
	v_mfma_f32_16x16x32_bf16 v[72:75], v[136:139], v[184:187], v[72:75]
	v_mfma_f32_16x16x32_bf16 v[124:127], v[132:135], v[148:151], v[124:127]
	v_mfma_f32_16x16x32_bf16 v[120:123], v[140:143], v[148:151], v[120:123]
	v_mfma_f32_16x16x32_bf16 v[116:119], v[132:135], v[156:159], v[116:119]
	v_mfma_f32_16x16x32_bf16 v[104:107], v[140:143], v[156:159], v[104:107]
	v_mfma_f32_16x16x32_bf16 v[92:95], v[132:135], v[180:183], v[92:95]
	v_mfma_f32_16x16x32_bf16 v[88:91], v[140:143], v[180:183], v[88:91]
	v_mfma_f32_16x16x32_bf16 v[76:79], v[132:135], v[188:191], v[76:79]
	v_mfma_f32_16x16x32_bf16 v[72:75], v[140:143], v[188:191], v[72:75]
	s_setprio 0
	s_barrier
; #define PG8_STAGE(bufoff, gbase, voff) do { _Pragma("unroll") for (int _i = 0; _i < 2; ++_i) \
;         __builtin_amdgcn_global_load_lds((const unsigned*)((const char*)(gbase) + (voff)[_i]), (PG8_LAS unsigned*)(lds + (bufoff) + ldsw + _i * 8192), 16, 0, 0); } while (0)
; #define PG8_LDA(dst, b, h) do { _Pragma("unroll") for (int m = 0; m < 4; ++m) _Pragma("unroll") for (int k = 0; k < 2; ++k) dst[m][k] = *(const PG8_LAS bf16x8*)(lds + PG8_SA(b, h) + aoff + m * 2048 + k * 1024); } while (0)
; #define PG8_LDB(dst, b, h) do { _Pragma("unroll") for (int n = 0; n < 2; ++n) _Pragma("unroll") for (int k = 0; k < 2; ++k) dst[n][k] = *(const PG8_LAS bf16x8*)(lds + PG8_SB(b, h) + boff + n * 2048 + k * 1024); } while (0)
; #define PG8_MMA(ai, bj, At, Bt) do { __builtin_amdgcn_s_setprio(1); _Pragma("unroll") for (int m = 0; m < 4; ++m) _Pragma("unroll") for (int n = 0; n < 2; ++n) _Pragma("unroll") for (int k = 0; k < 2; ++k) \
;         acc[ai][bj][m][n] = __builtin_amdgcn_mfma_f32_16x16x32_bf16(Bt[n][k], At[m][k], acc[ai][bj][m][n], 0, 0, 0); __builtin_amdgcn_s_setprio(0); } while (0)
; #define PG8_WAIT_V(n) asm volatile("s_waitcnt vmcnt(" #n ")" ::: "memory")
; #define PG8_WAIT_L(n) asm volatile("s_waitcnt lgkmcnt(" #n ")" ::: "memory")
; #define PG8_BAR __builtin_amdgcn_s_barrier()
; #define PG8_SCHED __builtin_amdgcn_sched_barrier(0)
; template <class Epi, class Sched>
; __device__ __forceinline__ void gemm_phase(PG8_LAS unsigned char* lds, const Gemm g, const Sched& S, const Epi& E) {
;     ...
;             PG8_LDB(B1, 0, 1); PG8_STAGE(PG8_SB(0, 0), b2, voffB);
;             PG8_BAR; PG8_WAIT_L(0); PG8_MMA(0, 1, At, B1); PG8_BAR;
;             PG8_LDA(At, 0, 1); PG8_STAGE(PG8_SA(0, 0), a2, voffA);
;             PG8_BAR; PG8_WAIT_L(0); PG8_MMA(1, 0, At, B0); PG8_BAR; PG8_SCHED;
;             PG8_STAGE(PG8_SB(0, 1), b2 + hstepB, voffB);
;             PG8_WAIT_V(6); PG8_BAR; PG8_MMA(1, 1, At, B1); PG8_BAR;
;             PG8_LDB(B0, 1, 0); PG8_SCHED; PG8_LDA(At, 1, 0); PG8_STAGE(PG8_SA(0, 1), a2 + hstep, voffA);
;             PG8_WAIT_L(8); PG8_BAR; PG8_WAIT_L(0); PG8_MMA(0, 0, At, B0); PG8_BAR; PG8_SCHED;
	s_add_i32 s28, s62, s54
	v_lshl_add_u64 v[192:193], s[36:37], 0, v[164:165]
	s_mov_b32 m0, s28
	ds_read_b128 v[200:203], v199
	ds_read_b128 v[204:207], v199 offset:1024
	ds_read_b128 v[208:211], v199 offset:2048
	ds_read_b128 v[212:215], v199 offset:3072
	global_load_lds_dwordx4 v[192:193], off
	v_lshl_add_u64 v[192:193], s[36:37], 0, v[168:169]
	s_add_i32 m0, s28, 0x2000
	s_nop 0
	global_load_lds_dwordx4 v[192:193], off
	s_barrier
	s_waitcnt lgkmcnt(0)
	s_setprio 1
	s_waitcnt lgkmcnt(0)
	v_mfma_f32_16x16x32_bf16 v[112:115], v[200:203], v[144:147], v[112:115]
	v_mfma_f32_16x16x32_bf16 v[108:111], v[208:211], v[144:147], v[108:111]
	v_mfma_f32_16x16x32_bf16 v[100:103], v[200:203], v[152:155], v[100:103]
	v_mfma_f32_16x16x32_bf16 v[96:99], v[208:211], v[152:155], v[96:99]
	v_mfma_f32_16x16x32_bf16 v[84:87], v[200:203], v[160:163], v[84:87]
	v_mfma_f32_16x16x32_bf16 v[80:83], v[208:211], v[160:163], v[80:83]
	v_mfma_f32_16x16x32_bf16 v[68:71], v[200:203], v[184:187], v[68:71]
	v_mfma_f32_16x16x32_bf16 v[64:67], v[208:211], v[184:187], v[64:67]
	v_mfma_f32_16x16x32_bf16 v[112:115], v[204:207], v[148:151], v[112:115]
	v_mfma_f32_16x16x32_bf16 v[108:111], v[212:215], v[148:151], v[108:111]
	v_mfma_f32_16x16x32_bf16 v[100:103], v[204:207], v[156:159], v[100:103]
	v_mfma_f32_16x16x32_bf16 v[96:99], v[212:215], v[156:159], v[96:99]
	v_mfma_f32_16x16x32_bf16 v[84:87], v[204:207], v[180:183], v[84:87]
	v_mfma_f32_16x16x32_bf16 v[80:83], v[212:215], v[180:183], v[80:83]
	v_mfma_f32_16x16x32_bf16 v[68:71], v[204:207], v[188:191], v[68:71]
	v_mfma_f32_16x16x32_bf16 v[64:67], v[212:215], v[188:191], v[64:67]
	s_setprio 0
	s_mov_b32 m0, s27
	v_lshl_add_u64 v[192:193], s[38:39], 0, v[166:167]
	s_barrier
	ds_read_b128 v[144:147], v198 offset:16384
	ds_read_b128 v[148:151], v198 offset:17408
	ds_read_b128 v[152:155], v198 offset:18432
	ds_read_b128 v[156:159], v198 offset:19456
	ds_read_b128 v[160:163], v198 offset:20480
	ds_read_b128 v[180:183], v198 offset:21504
	ds_read_b128 v[184:187], v198 offset:22528
	ds_read_b128 v[188:191], v198 offset:23552
	global_load_lds_dwordx4 v[192:193], off
	v_lshl_add_u64 v[216:217], s[38:39], 0, v[170:171]
	s_mov_b32 m0, s55
	s_nop 0
	global_load_lds_dwordx4 v[216:217], off
	s_barrier
	s_waitcnt lgkmcnt(0)
	s_setprio 1
	s_waitcnt lgkmcnt(0)
	v_mfma_f32_16x16x32_bf16 v[60:63], v[128:131], v[144:147], v[60:63]
	v_mfma_f32_16x16x32_bf16 v[56:59], v[136:139], v[144:147], v[56:59]
	v_mfma_f32_16x16x32_bf16 v[44:47], v[128:131], v[152:155], v[44:47]
	v_mfma_f32_16x16x32_bf16 v[40:43], v[136:139], v[152:155], v[40:43]
	v_mfma_f32_16x16x32_bf16 v[28:31], v[128:131], v[160:163], v[28:31]
	v_mfma_f32_16x16x32_bf16 v[24:27], v[136:139], v[160:163], v[24:27]
	v_mfma_f32_16x16x32_bf16 v[12:15], v[128:131], v[184:187], v[12:15]
	v_mfma_f32_16x16x32_bf16 v[8:11], v[136:139], v[184:187], v[8:11]
	v_mfma_f32_16x16x32_bf16 v[60:63], v[132:135], v[148:151], v[60:63]
	v_mfma_f32_16x16x32_bf16 v[56:59], v[140:143], v[148:151], v[56:59]
	v_mfma_f32_16x16x32_bf16 v[44:47], v[132:135], v[156:159], v[44:47]
	v_mfma_f32_16x16x32_bf16 v[40:43], v[140:143], v[156:159], v[40:43]
	v_mfma_f32_16x16x32_bf16 v[28:31], v[132:135], v[180:183], v[28:31]
	v_mfma_f32_16x16x32_bf16 v[24:27], v[140:143], v[180:183], v[24:27]
	v_mfma_f32_16x16x32_bf16 v[12:15], v[132:135], v[188:191], v[12:15]
	v_mfma_f32_16x16x32_bf16 v[8:11], v[140:143], v[188:191], v[8:11]
	s_setprio 0
	s_barrier
	s_add_u32 s28, s36, 0x4000
	s_addc_u32 s29, s37, 0
	s_add_i32 s70, s63, s54
	v_lshl_add_u64 v[128:129], s[28:29], 0, v[164:165]
	s_mov_b32 m0, s70
	s_nop 0
	global_load_lds_dwordx4 v[128:129], off
	v_lshl_add_u64 v[128:129], s[28:29], 0, v[168:169]
	s_add_i32 m0, s70, 0x2000
	s_nop 0
	global_load_lds_dwordx4 v[128:129], off
	s_waitcnt vmcnt(6)
	s_barrier
	s_setprio 1
	v_mfma_f32_16x16x32_bf16 v[52:55], v[200:203], v[144:147], v[52:55]
	v_mfma_f32_16x16x32_bf16 v[48:51], v[208:211], v[144:147], v[48:51]
	v_mfma_f32_16x16x32_bf16 v[36:39], v[200:203], v[152:155], v[36:39]
	v_mfma_f32_16x16x32_bf16 v[32:35], v[208:211], v[152:155], v[32:35]
	v_mfma_f32_16x16x32_bf16 v[20:23], v[200:203], v[160:163], v[20:23]
	v_mfma_f32_16x16x32_bf16 v[16:19], v[208:211], v[160:163], v[16:19]
	v_mfma_f32_16x16x32_bf16 v[4:7], v[200:203], v[184:187], v[4:7]
	v_mfma_f32_16x16x32_bf16 v[0:3], v[208:211], v[184:187], v[0:3]
	v_mfma_f32_16x16x32_bf16 v[52:55], v[204:207], v[148:151], v[52:55]
	v_mfma_f32_16x16x32_bf16 v[48:51], v[212:215], v[148:151], v[48:51]
	v_mfma_f32_16x16x32_bf16 v[36:39], v[204:207], v[156:159], v[36:39]
	v_mfma_f32_16x16x32_bf16 v[32:35], v[212:215], v[156:159], v[32:35]
	v_mfma_f32_16x16x32_bf16 v[20:23], v[204:207], v[180:183], v[20:23]
	v_mfma_f32_16x16x32_bf16 v[16:19], v[212:215], v[180:183], v[16:19]
	v_mfma_f32_16x16x32_bf16 v[4:7], v[204:207], v[188:191], v[4:7]
	v_mfma_f32_16x16x32_bf16 v[0:3], v[212:215], v[188:191], v[0:3]
	s_setprio 0
	s_add_i32 s70, 0, 0x18000
	v_add_u32_e32 v140, s70, v195
	s_barrier
	ds_read_b128 v[128:131], v140
	ds_read_b128 v[132:135], v140 offset:1024
	ds_read_b128 v[136:139], v140 offset:2048
	ds_read_b128 v[140:143], v140 offset:3072
	s_add_u32 s28, s38, 0x80000
	s_addc_u32 s29, s39, 0
	s_mov_b32 m0, s56
	v_lshl_add_u64 v[200:201], s[28:29], 0, v[166:167]
	ds_read_b128 v[144:147], v198 offset:32768
	ds_read_b128 v[148:151], v198 offset:33792
	ds_read_b128 v[152:155], v198 offset:34816
	ds_read_b128 v[156:159], v198 offset:35840
	ds_read_b128 v[160:163], v198 offset:36864
	ds_read_b128 v[180:183], v198 offset:37888
	ds_read_b128 v[184:187], v198 offset:38912
	ds_read_b128 v[188:191], v198 offset:39936
	global_load_lds_dwordx4 v[200:201], off
	v_lshl_add_u64 v[200:201], s[28:29], 0, v[170:171]
	s_mov_b32 m0, s57
	s_nop 0
	global_load_lds_dwordx4 v[200:201], off
	s_waitcnt lgkmcnt(8)
	s_barrier
; #define PG8_STAGE(bufoff, gbase, voff) do { _Pragma("unroll") for (int _i = 0; _i < 2; ++_i) \
;         __builtin_amdgcn_global_load_lds((const unsigned*)((const char*)(gbase) + (voff)[_i]), (PG8_LAS unsigned*)(lds + (bufoff) + ldsw + _i * 8192), 16, 0, 0); } while (0)
; #define PG8_LDA(dst, b, h) do { _Pragma("unroll") for (int m = 0; m < 4; ++m) _Pragma("unroll") for (int k = 0; k < 2; ++k) dst[m][k] = *(const PG8_LAS bf16x8*)(lds + PG8_SA(b, h) + aoff + m * 2048 + k * 1024); } while (0)
; #define PG8_LDB(dst, b, h) do { _Pragma("unroll") for (int n = 0; n < 2; ++n) _Pragma("unroll") for (int k = 0; k < 2; ++k) dst[n][k] = *(const PG8_LAS bf16x8*)(lds + PG8_SB(b, h) + boff + n * 2048 + k * 1024); } while (0)
; #define PG8_MMA(ai, bj, At, Bt) do { __builtin_amdgcn_s_setprio(1); _Pragma("unroll") for (int m = 0; m < 4; ++m) _Pragma("unroll") for (int n = 0; n < 2; ++n) _Pragma("unroll") for (int k = 0; k < 2; ++k) \
;         acc[ai][bj][m][n] = __builtin_amdgcn_mfma_f32_16x16x32_bf16(Bt[n][k], At[m][k], acc[ai][bj][m][n], 0, 0, 0); __builtin_amdgcn_s_setprio(0); } while (0)
; #define PG8_WAIT_V(n) asm volatile("s_waitcnt vmcnt(" #n ")" ::: "memory")
; #define PG8_WAIT_L(n) asm volatile("s_waitcnt lgkmcnt(" #n ")" ::: "memory")
; #define PG8_BAR __builtin_amdgcn_s_barrier()
; #define PG8_SCHED __builtin_amdgcn_sched_barrier(0)
; template <class Epi, class Sched>
; __device__ __forceinline__ void gemm_phase(PG8_LAS unsigned char* lds, const Gemm g, const Sched& S, const Epi& E) {
;     ...
;             PG8_WAIT_L(8); PG8_BAR; PG8_WAIT_L(0); PG8_MMA(0, 0, At, B0); PG8_BAR; PG8_SCHED;
;             PG8_LDB(B1, 1, 1); PG8_STAGE(PG8_SB(1, 0), b3, voffB);
;             PG8_BAR; PG8_WAIT_L(0); PG8_MMA(0, 1, At, B1); PG8_BAR;
;             PG8_LDA(At, 1, 1); PG8_STAGE(PG8_SA(1, 0), a3, voffA);
;             PG8_BAR; PG8_WAIT_L(0); PG8_MMA(1, 0, At, B0); PG8_BAR; PG8_SCHED;
;             PG8_STAGE(PG8_SB(1, 1), b3 + hstepB, voffB);
;             PG8_WAIT_V(6); PG8_BAR; PG8_MMA(1, 1, At, B1); PG8_BAR;
;         }
	s_waitcnt lgkmcnt(0)
	s_setprio 1
	s_waitcnt lgkmcnt(0)
	v_mfma_f32_16x16x32_bf16 v[124:127], v[128:131], v[144:147], v[124:127]
	v_mfma_f32_16x16x32_bf16 v[120:123], v[136:139], v[144:147], v[120:123]
	v_mfma_f32_16x16x32_bf16 v[116:119], v[128:131], v[152:155], v[116:119]
	v_mfma_f32_16x16x32_bf16 v[104:107], v[136:139], v[152:155], v[104:107]
	v_mfma_f32_16x16x32_bf16 v[92:95], v[128:131], v[160:163], v[92:95]
	v_mfma_f32_16x16x32_bf16 v[88:91], v[136:139], v[160:163], v[88:91]
	v_mfma_f32_16x16x32_bf16 v[76:79], v[128:131], v[184:187], v[76:79]
	v_mfma_f32_16x16x32_bf16 v[72:75], v[136:139], v[184:187], v[72:75]
	v_mfma_f32_16x16x32_bf16 v[124:127], v[132:135], v[148:151], v[124:127]
	v_mfma_f32_16x16x32_bf16 v[120:123], v[140:143], v[148:151], v[120:123]
	v_mfma_f32_16x16x32_bf16 v[116:119], v[132:135], v[156:159], v[116:119]
	v_mfma_f32_16x16x32_bf16 v[104:107], v[140:143], v[156:159], v[104:107]
	v_mfma_f32_16x16x32_bf16 v[92:95], v[132:135], v[180:183], v[92:95]
	v_mfma_f32_16x16x32_bf16 v[88:91], v[140:143], v[180:183], v[88:91]
	v_mfma_f32_16x16x32_bf16 v[76:79], v[132:135], v[188:191], v[76:79]
	v_mfma_f32_16x16x32_bf16 v[72:75], v[140:143], v[188:191], v[72:75]
	s_setprio 0
	s_barrier
	s_add_i32 s38, 0, 0x1c000
	s_add_u32 s28, s36, 0x8000
	s_addc_u32 s29, s37, 0
	s_add_i32 s39, s70, s54
	v_add_u32_e32 v212, s38, v195
	v_lshl_add_u64 v[218:219], s[28:29], 0, v[164:165]
	s_mov_b32 m0, s39
	ds_read_b128 v[200:203], v212
	ds_read_b128 v[204:207], v212 offset:1024
	ds_read_b128 v[208:211], v212 offset:2048
	ds_read_b128 v[212:215], v212 offset:3072
	global_load_lds_dwordx4 v[218:219], off
	v_lshl_add_u64 v[218:219], s[28:29], 0, v[168:169]
	s_add_i32 m0, s39, 0x2000
	s_nop 0
	global_load_lds_dwordx4 v[218:219], off
	s_barrier
	s_waitcnt lgkmcnt(0)
	s_setprio 1
	s_waitcnt lgkmcnt(0)
	v_mfma_f32_16x16x32_bf16 v[112:115], v[200:203], v[144:147], v[112:115]
	v_mfma_f32_16x16x32_bf16 v[108:111], v[208:211], v[144:147], v[108:111]
	v_mfma_f32_16x16x32_bf16 v[100:103], v[200:203], v[152:155], v[100:103]
	v_mfma_f32_16x16x32_bf16 v[96:99], v[208:211], v[152:155], v[96:99]
	v_mfma_f32_16x16x32_bf16 v[84:87], v[200:203], v[160:163], v[84:87]
	v_mfma_f32_16x16x32_bf16 v[80:83], v[208:211], v[160:163], v[80:83]
	v_mfma_f32_16x16x32_bf16 v[68:71], v[200:203], v[184:187], v[68:71]
	v_mfma_f32_16x16x32_bf16 v[64:67], v[208:211], v[184:187], v[64:67]
	v_mfma_f32_16x16x32_bf16 v[112:115], v[204:207], v[148:151], v[112:115]
	v_mfma_f32_16x16x32_bf16 v[108:111], v[212:215], v[148:151], v[108:111]
	v_mfma_f32_16x16x32_bf16 v[100:103], v[204:207], v[156:159], v[100:103]
	v_mfma_f32_16x16x32_bf16 v[96:99], v[212:215], v[156:159], v[96:99]
	v_mfma_f32_16x16x32_bf16 v[84:87], v[204:207], v[180:183], v[84:87]
	v_mfma_f32_16x16x32_bf16 v[80:83], v[212:215], v[180:183], v[80:83]
	v_mfma_f32_16x16x32_bf16 v[68:71], v[204:207], v[188:191], v[68:71]
	v_mfma_f32_16x16x32_bf16 v[64:67], v[212:215], v[188:191], v[64:67]
	s_setprio 0
	s_mov_b32 m0, s59
	v_lshl_add_u64 v[192:193], v[192:193], 0, s[10:11]
	s_barrier
	ds_read_b128 v[144:147], v198 offset:49152
	ds_read_b128 v[148:151], v198 offset:50176
	ds_read_b128 v[152:155], v198 offset:51200
	ds_read_b128 v[156:159], v198 offset:52224
	ds_read_b128 v[160:163], v198 offset:53248
	ds_read_b128 v[180:183], v198 offset:54272
	ds_read_b128 v[184:187], v198 offset:55296
	ds_read_b128 v[188:191], v198 offset:56320
	global_load_lds_dwordx4 v[192:193], off
	v_lshl_add_u64 v[192:193], v[216:217], 0, s[10:11]
	s_mov_b32 m0, s60
	s_nop 0
	global_load_lds_dwordx4 v[192:193], off
	s_barrier
	s_waitcnt lgkmcnt(0)
	s_setprio 1
	s_waitcnt lgkmcnt(0)
	v_mfma_f32_16x16x32_bf16 v[60:63], v[128:131], v[144:147], v[60:63]
	v_mfma_f32_16x16x32_bf16 v[56:59], v[136:139], v[144:147], v[56:59]
	v_mfma_f32_16x16x32_bf16 v[44:47], v[128:131], v[152:155], v[44:47]
	v_mfma_f32_16x16x32_bf16 v[40:43], v[136:139], v[152:155], v[40:43]
	v_mfma_f32_16x16x32_bf16 v[28:31], v[128:131], v[160:163], v[28:31]
	v_mfma_f32_16x16x32_bf16 v[24:27], v[136:139], v[160:163], v[24:27]
	v_mfma_f32_16x16x32_bf16 v[12:15], v[128:131], v[184:187], v[12:15]
	v_mfma_f32_16x16x32_bf16 v[8:11], v[136:139], v[184:187], v[8:11]
	v_mfma_f32_16x16x32_bf16 v[60:63], v[132:135], v[148:151], v[60:63]
	v_mfma_f32_16x16x32_bf16 v[56:59], v[140:143], v[148:151], v[56:59]
	v_mfma_f32_16x16x32_bf16 v[44:47], v[132:135], v[156:159], v[44:47]
	v_mfma_f32_16x16x32_bf16 v[40:43], v[140:143], v[156:159], v[40:43]
	v_mfma_f32_16x16x32_bf16 v[28:31], v[132:135], v[180:183], v[28:31]
	v_mfma_f32_16x16x32_bf16 v[24:27], v[140:143], v[180:183], v[24:27]
	v_mfma_f32_16x16x32_bf16 v[12:15], v[132:135], v[188:191], v[12:15]
	v_mfma_f32_16x16x32_bf16 v[8:11], v[140:143], v[188:191], v[8:11]
	s_setprio 0
	s_barrier
	s_add_u32 s28, s36, 0xc000
	s_addc_u32 s29, s37, 0
	s_add_i32 s36, s38, s54
	v_lshl_add_u64 v[128:129], s[28:29], 0, v[164:165]
	s_mov_b32 m0, s36
	s_nop 0
	global_load_lds_dwordx4 v[128:129], off
	v_lshl_add_u64 v[128:129], s[28:29], 0, v[168:169]
	s_add_i32 m0, s36, 0x2000
	s_nop 0
	global_load_lds_dwordx4 v[128:129], off
	s_waitcnt vmcnt(6)
	s_barrier
	s_setprio 1
	v_mfma_f32_16x16x32_bf16 v[52:55], v[200:203], v[144:147], v[52:55]
	v_mfma_f32_16x16x32_bf16 v[48:51], v[208:211], v[144:147], v[48:51]
	v_mfma_f32_16x16x32_bf16 v[36:39], v[200:203], v[152:155], v[36:39]
	v_mfma_f32_16x16x32_bf16 v[32:35], v[208:211], v[152:155], v[32:35]
	v_mfma_f32_16x16x32_bf16 v[20:23], v[200:203], v[160:163], v[20:23]
	v_mfma_f32_16x16x32_bf16 v[16:19], v[208:211], v[160:163], v[16:19]
	v_mfma_f32_16x16x32_bf16 v[4:7], v[200:203], v[184:187], v[4:7]
	v_mfma_f32_16x16x32_bf16 v[0:3], v[208:211], v[184:187], v[0:3]
	v_mfma_f32_16x16x32_bf16 v[52:55], v[204:207], v[148:151], v[52:55]
	v_mfma_f32_16x16x32_bf16 v[48:51], v[212:215], v[148:151], v[48:51]
	v_mfma_f32_16x16x32_bf16 v[36:39], v[204:207], v[156:159], v[36:39]
	v_mfma_f32_16x16x32_bf16 v[32:35], v[212:215], v[156:159], v[32:35]
	v_mfma_f32_16x16x32_bf16 v[20:23], v[204:207], v[180:183], v[20:23]
	v_mfma_f32_16x16x32_bf16 v[16:19], v[212:215], v[180:183], v[16:19]
	v_mfma_f32_16x16x32_bf16 v[4:7], v[204:207], v[188:191], v[4:7]
	v_mfma_f32_16x16x32_bf16 v[0:3], v[212:215], v[188:191], v[0:3]
	s_setprio 0
	s_add_i32 s69, s69, 2
	s_add_u32 s67, s67, 0x10000
	s_addc_u32 s68, s68, 0
	s_cmp_gt_u32 s69, 29
	s_mov_b64 s[28:29], s[30:31]
	s_barrier
	s_cbranch_scc0 .LBB0_783
	s_cmp_eq_u32 s78, 0
	s_cbranch_scc0 .Lhalf_skip_x_5
	s_barrier
; __device__ __forceinline__ unsigned cvt_pk_bf16(float lo, float hi) { unsigned r; asm volatile("v_cvt_pk_bf16_f32 %0, %1, %2" : "=v"(r) : "v"(lo), "v"(hi)); return r; }
; __device__ __forceinline__ float bflo(unsigned w) { return __uint_as_float(w << 16); }
; __device__ __forceinline__ float bfhi(unsigned w) { return __uint_as_float(w & 0xffff0000u); }
;     __device__ __forceinline__ void operator()(const f32x4 (&acc)[2][2][4][2], const Unit& u, int wr, int wc, int fr, int fq) const {
;     ...
;             u32x4 hv[2][4][2];
; #pragma unroll
;             for (int ai = 0; ai < 2; ++ai)
; #pragma unroll
;                 for (int m = 0; m < 4; ++m)
; #pragma unroll
;                     for (int bj = 0; bj < 2; ++bj) hv[ai][m][bj] = *(const u32x4*)(H + (size_t)(row0 + ai * HALF + m * 16) * 2048 + col0 + bj * HALF);
; #pragma unroll
;             for (int ai = 0; ai < 2; ++ai)
; #pragma unroll
;                 for (int m = 0; m < 4; ++m)
; #pragma unroll
;                     for (int bj = 0; bj < 2; ++bj) { const size_t o = (size_t)(row0 + ai * HALF + m * 16) * 2048 + col0 + bj * HALF; const u32x4 h4 = hv[ai][m][bj];
;                         const f32x4 r0 = (f32x4){bflo(h4.x), bfhi(h4.x), bflo(h4.y), bfhi(h4.y)}, r1 = (f32x4){bflo(h4.z), bfhi(h4.z), bflo(h4.w), bfhi(h4.w)};
;                         const f32x4 v0 = r0 + acc[ai][bj][m][0] * scale, v1 = r1 + acc[ai][bj][m][1] * scale;
;                         u32x4 w; w.x = cvt_pk_bf16(v0[0], v0[1]); w.y = cvt_pk_bf16(v0[2], v0[3]); w.z = cvt_pk_bf16(v1[0], v1[1]); w.w = cvt_pk_bf16(v1[2], v1[3]);
;                         *(u32x4*)(H + o) = w; }
.Lhalf_skip_x_5:
	v_lshl_or_b32 v130, s64, 8, v196
	v_lshl_add_u32 v128, s26, 8, v194
	v_ashrrev_i32_e32 v131, 31, v130
	v_lshlrev_b64 v[180:181], 1, v[130:131]
	v_ashrrev_i32_e32 v129, 31, v128
	v_lshl_add_u64 v[130:131], s[8:9], 0, v[180:181]
	v_lshlrev_b64 v[132:133], 12, v[128:129]
	v_lshl_add_u64 v[134:135], v[130:131], 0, v[132:133]
	global_load_dwordx4 v[200:203], v[134:135], off
	global_load_dwordx4 v[204:207], v[134:135], off offset:256
	v_or_b32_e32 v134, 16, v128
	v_ashrrev_i32_e32 v135, 31, v134
	v_lshlrev_b64 v[230:231], 12, v[134:135]
	v_lshl_add_u64 v[134:135], v[130:131], 0, v[230:231]
	global_load_dwordx4 v[208:211], v[134:135], off
	global_load_dwordx4 v[212:215], v[134:135], off offset:256
	v_or_b32_e32 v136, 32, v128
	v_or_b32_e32 v128, 48, v128
	v_ashrrev_i32_e32 v137, 31, v136
	v_ashrrev_i32_e32 v129, 31, v128
	v_lshlrev_b64 v[192:193], 12, v[136:137]
	v_lshlrev_b64 v[190:191], 12, v[128:129]
	v_lshl_add_u64 v[188:189], v[132:133], 0, s[6:7]
	v_lshl_add_u64 v[186:187], v[132:133], 0, s[12:13]
	v_lshl_add_u64 v[184:185], v[132:133], 0, s[14:15]
	v_lshl_add_u64 v[182:183], v[132:133], 0, s[16:17]
	v_lshl_add_u64 v[128:129], s[8:9], 0, v[132:133]
	v_lshl_add_u64 v[132:133], v[130:131], 0, v[192:193]
	v_lshl_add_u64 v[134:135], v[130:131], 0, v[190:191]
	v_lshl_add_u64 v[136:137], v[130:131], 0, v[188:189]
	v_lshl_add_u64 v[138:139], v[130:131], 0, v[186:187]
	v_lshl_add_u64 v[232:233], v[130:131], 0, v[184:185]
	v_lshl_add_u64 v[130:131], v[130:131], 0, v[182:183]
	v_lshl_add_u64 v[234:235], v[128:129], 0, v[180:181]
	global_load_dwordx4 v[216:219], v[132:133], off
	global_load_dwordx4 v[220:223], v[132:133], off offset:256
	global_load_dwordx4 v[224:227], v[134:135], off
	global_load_dwordx4 v[160:163], v[134:135], off offset:256
	global_load_dwordx4 v[156:159], v[136:137], off
	global_load_dwordx4 v[152:155], v[136:137], off offset:256
	global_load_dwordx4 v[148:151], v[138:139], off
	global_load_dwordx4 v[144:147], v[138:139], off offset:256
	global_load_dwordx4 v[140:143], v[232:233], off
	s_nop 0
	global_load_dwordx4 v[136:139], v[232:233], off offset:256
	global_load_dwordx4 v[132:135], v[130:131], off
	s_nop 0
	global_load_dwordx4 v[128:131], v[130:131], off offset:256
	s_and_b64 vcc, exec, s[4:5]
	s_mov_b32 s64, s20
	s_mov_b32 s26, s18
	s_mov_b64 s[30:31], s[24:25]
	s_mov_b64 s[28:29], s[22:23]
	s_waitcnt vmcnt(0)
	v_lshlrev_b32_e32 v232, 16, v200
	v_and_b32_e32 v233, 0xffff0000, v200
	v_lshlrev_b32_e32 v200, 16, v201
	v_and_b32_e32 v201, 0xffff0000, v201
	v_lshlrev_b32_e32 v236, 16, v202
	v_and_b32_e32 v237, 0xffff0000, v202
	v_lshlrev_b32_e32 v202, 16, v203
	v_and_b32_e32 v203, 0xffff0000, v203
	v_lshlrev_b32_e32 v240, 16, v206
	v_and_b32_e32 v241, 0xffff0000, v206
	v_lshlrev_b32_e32 v238, 16, v204
	v_and_b32_e32 v239, 0xffff0000, v204
	v_lshlrev_b32_e32 v204, 16, v205
	v_and_b32_e32 v205, 0xffff0000, v205
	v_lshlrev_b32_e32 v206, 16, v207
	v_and_b32_e32 v207, 0xffff0000, v207
	v_pk_add_f32 v[126:127], v[126:127], v[200:201]
	v_pk_add_f32 v[124:125], v[124:125], v[232:233]
	v_pk_add_f32 v[122:123], v[122:123], v[202:203]
	v_pk_add_f32 v[202:203], v[108:109], v[240:241]
	v_cvt_pk_bf16_f32 v108, v124, v125
	v_cvt_pk_bf16_f32 v109, v126, v127
	v_lshlrev_b32_e32 v244, 16, v210
	v_and_b32_e32 v245, 0xffff0000, v210
	v_lshlrev_b32_e32 v210, 16, v211
	v_and_b32_e32 v211, 0xffff0000, v211
	v_pk_add_f32 v[120:121], v[120:121], v[236:237]
	v_pk_add_f32 v[114:115], v[114:115], v[204:205]
	v_pk_add_f32 v[112:113], v[112:113], v[238:239]
	v_pk_add_f32 v[200:201], v[110:111], v[206:207]
	v_cvt_pk_bf16_f32 v110, v120, v121
	v_cvt_pk_bf16_f32 v111, v122, v123
	global_store_dwordx4 v[234:235], v[108:111], off
	v_lshlrev_b32_e32 v242, 16, v208
	v_and_b32_e32 v243, 0xffff0000, v208
	v_cvt_pk_bf16_f32 v108, v112, v113
	v_cvt_pk_bf16_f32 v109, v114, v115
	v_lshlrev_b32_e32 v208, 16, v209
	v_and_b32_e32 v209, 0xffff0000, v209
	v_cvt_pk_bf16_f32 v110, v202, v203
	v_cvt_pk_bf16_f32 v111, v200, v201
	global_store_dwordx4 v[234:235], v[108:111], off offset:256
	v_pk_add_f32 v[118:119], v[118:119], v[208:209]
	v_pk_add_f32 v[116:117], v[116:117], v[242:243]
	v_pk_add_f32 v[108:109], v[106:107], v[210:211]
	v_pk_add_f32 v[106:107], v[104:105], v[244:245]
	v_cvt_pk_bf16_f32 v104, v116, v117
	v_cvt_pk_bf16_f32 v105, v118, v119
	v_lshlrev_b32_e32 v110, 16, v214
	v_cvt_pk_bf16_f32 v106, v106, v107
	v_cvt_pk_bf16_f32 v107, v108, v109
	v_lshl_add_u64 v[108:109], s[8:9], 0, v[230:231]
	v_lshl_add_u64 v[108:109], v[108:109], 0, v[180:181]
	global_store_dwordx4 v[108:109], v[104:107], off
	v_and_b32_e32 v111, 0xffff0000, v214
	v_lshlrev_b32_e32 v112, 16, v215
	v_lshlrev_b32_e32 v104, 16, v212
	v_and_b32_e32 v105, 0xffff0000, v212
	v_lshlrev_b32_e32 v106, 16, v213
	v_and_b32_e32 v107, 0xffff0000, v213
	v_and_b32_e32 v113, 0xffff0000, v215
	v_pk_add_f32 v[102:103], v[102:103], v[106:107]
	v_pk_add_f32 v[100:101], v[100:101], v[104:105]
	v_pk_add_f32 v[104:105], v[98:99], v[112:113]
	v_pk_add_f32 v[98:99], v[96:97], v[110:111]
	v_cvt_pk_bf16_f32 v96, v100, v101
	v_cvt_pk_bf16_f32 v97, v102, v103
	v_lshlrev_b32_e32 v100, 16, v218
	v_cvt_pk_bf16_f32 v98, v98, v99
	v_cvt_pk_bf16_f32 v99, v104, v105
	global_store_dwordx4 v[108:109], v[96:99], off offset:256
	v_and_b32_e32 v101, 0xffff0000, v218
	v_lshlrev_b32_e32 v102, 16, v219
	v_lshlrev_b32_e32 v96, 16, v216
	v_and_b32_e32 v97, 0xffff0000, v216
	v_and_b32_e32 v103, 0xffff0000, v219
	v_pk_add_f32 v[92:93], v[92:93], v[96:97]
	v_lshlrev_b32_e32 v98, 16, v217
	v_and_b32_e32 v99, 0xffff0000, v217
	v_pk_add_f32 v[96:97], v[90:91], v[102:103]
	v_pk_add_f32 v[90:91], v[88:89], v[100:101]
; __device__ __forceinline__ unsigned cvt_pk_bf16(float lo, float hi) { unsigned r; asm volatile("v_cvt_pk_bf16_f32 %0, %1, %2" : "=v"(r) : "v"(lo), "v"(hi)); return r; }
; __device__ __forceinline__ float bflo(unsigned w) { return __uint_as_float(w << 16); }
; __device__ __forceinline__ float bfhi(unsigned w) { return __uint_as_float(w & 0xffff0000u); }
;     __device__ __forceinline__ void operator()(const f32x4 (&acc)[2][2][4][2], const Unit& u, int wr, int wc, int fr, int fq) const {
;     ...
;             for (int ai = 0; ai < 2; ++ai)
; #pragma unroll
;                 for (int m = 0; m < 4; ++m)
; #pragma unroll
;                     for (int bj = 0; bj < 2; ++bj) { const size_t o = (size_t)(row0 + ai * HALF + m * 16) * 2048 + col0 + bj * HALF; const u32x4 h4 = hv[ai][m][bj];
;                         const f32x4 r0 = (f32x4){bflo(h4.x), bfhi(h4.x), bflo(h4.y), bfhi(h4.y)}, r1 = (f32x4){bflo(h4.z), bfhi(h4.z), bflo(h4.w), bfhi(h4.w)};
;                         const f32x4 v0 = r0 + acc[ai][bj][m][0] * scale, v1 = r1 + acc[ai][bj][m][1] * scale;
;                         u32x4 w; w.x = cvt_pk_bf16(v0[0], v0[1]); w.y = cvt_pk_bf16(v0[2], v0[3]); w.z = cvt_pk_bf16(v1[0], v1[1]); w.w = cvt_pk_bf16(v1[2], v1[3]);
;                         *(u32x4*)(H + o) = w; }
	v_cvt_pk_bf16_f32 v88, v92, v93
	v_lshl_add_u64 v[92:93], s[8:9], 0, v[192:193]
	v_pk_add_f32 v[94:95], v[94:95], v[98:99]
	v_lshl_add_u64 v[92:93], v[92:93], 0, v[180:181]
	v_cvt_pk_bf16_f32 v89, v94, v95
	v_cvt_pk_bf16_f32 v90, v90, v91
	v_cvt_pk_bf16_f32 v91, v96, v97
	global_store_dwordx4 v[92:93], v[88:91], off
	v_lshlrev_b32_e32 v94, 16, v222
	v_and_b32_e32 v95, 0xffff0000, v222
	v_lshlrev_b32_e32 v88, 16, v220
	v_and_b32_e32 v89, 0xffff0000, v220
	v_lshlrev_b32_e32 v90, 16, v221
	v_and_b32_e32 v91, 0xffff0000, v221
	v_lshlrev_b32_e32 v96, 16, v223
	v_and_b32_e32 v97, 0xffff0000, v223
	v_pk_add_f32 v[86:87], v[86:87], v[90:91]
	v_pk_add_f32 v[84:85], v[84:85], v[88:89]
	v_pk_add_f32 v[88:89], v[82:83], v[96:97]
	v_pk_add_f32 v[82:83], v[80:81], v[94:95]
	v_cvt_pk_bf16_f32 v80, v84, v85
	v_cvt_pk_bf16_f32 v81, v86, v87
	v_lshlrev_b32_e32 v84, 16, v226
	v_cvt_pk_bf16_f32 v82, v82, v83
	v_cvt_pk_bf16_f32 v83, v88, v89
	global_store_dwordx4 v[92:93], v[80:83], off offset:256
	v_and_b32_e32 v85, 0xffff0000, v226
	v_lshlrev_b32_e32 v86, 16, v227
	v_lshlrev_b32_e32 v80, 16, v224
	v_and_b32_e32 v81, 0xffff0000, v224
	v_and_b32_e32 v87, 0xffff0000, v227
	v_pk_add_f32 v[76:77], v[76:77], v[80:81]
	v_lshlrev_b32_e32 v82, 16, v225
	v_and_b32_e32 v83, 0xffff0000, v225
	v_pk_add_f32 v[80:81], v[74:75], v[86:87]
	v_pk_add_f32 v[74:75], v[72:73], v[84:85]
	v_cvt_pk_bf16_f32 v72, v76, v77
	v_lshl_add_u64 v[76:77], s[8:9], 0, v[190:191]
	v_pk_add_f32 v[78:79], v[78:79], v[82:83]
	v_lshl_add_u64 v[76:77], v[76:77], 0, v[180:181]
	v_cvt_pk_bf16_f32 v73, v78, v79
	v_cvt_pk_bf16_f32 v74, v74, v75
	v_cvt_pk_bf16_f32 v75, v80, v81
	global_store_dwordx4 v[76:77], v[72:75], off
	v_lshlrev_b32_e32 v78, 16, v162
	v_and_b32_e32 v79, 0xffff0000, v162
	v_lshlrev_b32_e32 v72, 16, v160
	v_and_b32_e32 v73, 0xffff0000, v160
	v_lshlrev_b32_e32 v74, 16, v161
	v_and_b32_e32 v75, 0xffff0000, v161
	v_lshlrev_b32_e32 v80, 16, v163
	v_and_b32_e32 v81, 0xffff0000, v163
	v_pk_add_f32 v[70:71], v[70:71], v[74:75]
	v_pk_add_f32 v[68:69], v[68:69], v[72:73]
	v_pk_add_f32 v[72:73], v[66:67], v[80:81]
	v_pk_add_f32 v[66:67], v[64:65], v[78:79]
	v_cvt_pk_bf16_f32 v64, v68, v69
	v_cvt_pk_bf16_f32 v65, v70, v71
	v_lshlrev_b32_e32 v68, 16, v158
	v_cvt_pk_bf16_f32 v66, v66, v67
	v_cvt_pk_bf16_f32 v67, v72, v73
	global_store_dwordx4 v[76:77], v[64:67], off offset:256
	v_and_b32_e32 v69, 0xffff0000, v158
	v_lshlrev_b32_e32 v70, 16, v159
	v_lshlrev_b32_e32 v64, 16, v156
	v_and_b32_e32 v65, 0xffff0000, v156
	v_and_b32_e32 v71, 0xffff0000, v159
	v_pk_add_f32 v[60:61], v[60:61], v[64:65]
	v_lshlrev_b32_e32 v66, 16, v157
	v_and_b32_e32 v67, 0xffff0000, v157
	v_pk_add_f32 v[64:65], v[58:59], v[70:71]
	v_pk_add_f32 v[58:59], v[56:57], v[68:69]
	v_cvt_pk_bf16_f32 v56, v60, v61
	v_lshl_add_u64 v[60:61], s[8:9], 0, v[188:189]
	v_pk_add_f32 v[62:63], v[62:63], v[66:67]
	v_lshl_add_u64 v[60:61], v[60:61], 0, v[180:181]
	v_cvt_pk_bf16_f32 v57, v62, v63
	v_cvt_pk_bf16_f32 v58, v58, v59
	v_cvt_pk_bf16_f32 v59, v64, v65
	global_store_dwordx4 v[60:61], v[56:59], off
	v_lshlrev_b32_e32 v62, 16, v154
	v_and_b32_e32 v63, 0xffff0000, v154
	v_lshlrev_b32_e32 v56, 16, v152
	v_and_b32_e32 v57, 0xffff0000, v152
	v_lshlrev_b32_e32 v58, 16, v153
	v_and_b32_e32 v59, 0xffff0000, v153
	v_lshlrev_b32_e32 v64, 16, v155
	v_and_b32_e32 v65, 0xffff0000, v155
	v_pk_add_f32 v[54:55], v[54:55], v[58:59]
	v_pk_add_f32 v[52:53], v[52:53], v[56:57]
	v_pk_add_f32 v[56:57], v[50:51], v[64:65]
	v_pk_add_f32 v[50:51], v[48:49], v[62:63]
	v_cvt_pk_bf16_f32 v48, v52, v53
	v_cvt_pk_bf16_f32 v49, v54, v55
	v_lshlrev_b32_e32 v52, 16, v150
	v_cvt_pk_bf16_f32 v50, v50, v51
	v_cvt_pk_bf16_f32 v51, v56, v57
	global_store_dwordx4 v[60:61], v[48:51], off offset:256
	v_and_b32_e32 v53, 0xffff0000, v150
	v_lshlrev_b32_e32 v54, 16, v151
	v_lshlrev_b32_e32 v48, 16, v148
	v_and_b32_e32 v49, 0xffff0000, v148
	v_and_b32_e32 v55, 0xffff0000, v151
	v_pk_add_f32 v[44:45], v[44:45], v[48:49]
; __device__ __forceinline__ unsigned cvt_pk_bf16(float lo, float hi) { unsigned r; asm volatile("v_cvt_pk_bf16_f32 %0, %1, %2" : "=v"(r) : "v"(lo), "v"(hi)); return r; }
; __device__ __forceinline__ float bflo(unsigned w) { return __uint_as_float(w << 16); }
; __device__ __forceinline__ float bfhi(unsigned w) { return __uint_as_float(w & 0xffff0000u); }
; #define PG8_WAIT_V(n) asm volatile("s_waitcnt vmcnt(" #n ")" ::: "memory")
; #define PG8_BAR __builtin_amdgcn_s_barrier()
;     __device__ __forceinline__ void operator()(const f32x4 (&acc)[2][2][4][2], const Unit& u, int wr, int wc, int fr, int fq) const {
;     ...
;             for (int ai = 0; ai < 2; ++ai)
; #pragma unroll
;                 for (int m = 0; m < 4; ++m)
; #pragma unroll
;                     for (int bj = 0; bj < 2; ++bj) { const size_t o = (size_t)(row0 + ai * HALF + m * 16) * 2048 + col0 + bj * HALF; const u32x4 h4 = hv[ai][m][bj];
;                         const f32x4 r0 = (f32x4){bflo(h4.x), bfhi(h4.x), bflo(h4.y), bfhi(h4.y)}, r1 = (f32x4){bflo(h4.z), bfhi(h4.z), bflo(h4.w), bfhi(h4.w)};
;                         const f32x4 v0 = r0 + acc[ai][bj][m][0] * scale, v1 = r1 + acc[ai][bj][m][1] * scale;
;                         u32x4 w; w.x = cvt_pk_bf16(v0[0], v0[1]); w.y = cvt_pk_bf16(v0[2], v0[3]); w.z = cvt_pk_bf16(v1[0], v1[1]); w.w = cvt_pk_bf16(v1[2], v1[3]);
;                         *(u32x4*)(H + o) = w; }
; template <class Epi, class Sched>
; __device__ __forceinline__ void gemm_phase(PG8_LAS unsigned char* lds, const Gemm g, const Sched& S, const Epi& E) {
;     ...
;     PG8_WAIT_V(0);
;     if (wr == 0) PG8_BAR;
;     PG8_BAR;
	v_lshlrev_b32_e32 v50, 16, v149
	v_and_b32_e32 v51, 0xffff0000, v149
	v_pk_add_f32 v[48:49], v[42:43], v[54:55]
	v_pk_add_f32 v[42:43], v[40:41], v[52:53]
	v_cvt_pk_bf16_f32 v40, v44, v45
	v_lshl_add_u64 v[44:45], s[8:9], 0, v[186:187]
	v_pk_add_f32 v[46:47], v[46:47], v[50:51]
	v_lshl_add_u64 v[44:45], v[44:45], 0, v[180:181]
	v_cvt_pk_bf16_f32 v41, v46, v47
	v_cvt_pk_bf16_f32 v42, v42, v43
	v_cvt_pk_bf16_f32 v43, v48, v49
	global_store_dwordx4 v[44:45], v[40:43], off
	v_lshlrev_b32_e32 v46, 16, v146
	v_and_b32_e32 v47, 0xffff0000, v146
	v_lshlrev_b32_e32 v40, 16, v144
	v_and_b32_e32 v41, 0xffff0000, v144
	v_lshlrev_b32_e32 v42, 16, v145
	v_and_b32_e32 v43, 0xffff0000, v145
	v_lshlrev_b32_e32 v48, 16, v147
	v_and_b32_e32 v49, 0xffff0000, v147
	v_pk_add_f32 v[38:39], v[38:39], v[42:43]
	v_pk_add_f32 v[36:37], v[36:37], v[40:41]
	v_pk_add_f32 v[40:41], v[34:35], v[48:49]
	v_pk_add_f32 v[34:35], v[32:33], v[46:47]
	v_cvt_pk_bf16_f32 v32, v36, v37
	v_cvt_pk_bf16_f32 v33, v38, v39
	v_lshlrev_b32_e32 v36, 16, v142
	v_cvt_pk_bf16_f32 v34, v34, v35
	v_cvt_pk_bf16_f32 v35, v40, v41
	global_store_dwordx4 v[44:45], v[32:35], off offset:256
	v_and_b32_e32 v37, 0xffff0000, v142
	v_lshlrev_b32_e32 v38, 16, v143
	v_lshlrev_b32_e32 v32, 16, v140
	v_and_b32_e32 v33, 0xffff0000, v140
	v_and_b32_e32 v39, 0xffff0000, v143
	v_pk_add_f32 v[28:29], v[28:29], v[32:33]
	v_lshlrev_b32_e32 v34, 16, v141
	v_and_b32_e32 v35, 0xffff0000, v141
	v_pk_add_f32 v[32:33], v[26:27], v[38:39]
	v_pk_add_f32 v[26:27], v[24:25], v[36:37]
	v_cvt_pk_bf16_f32 v24, v28, v29
	v_lshl_add_u64 v[28:29], s[8:9], 0, v[184:185]
	v_pk_add_f32 v[30:31], v[30:31], v[34:35]
	v_lshl_add_u64 v[28:29], v[28:29], 0, v[180:181]
	v_cvt_pk_bf16_f32 v25, v30, v31
	v_cvt_pk_bf16_f32 v26, v26, v27
	v_cvt_pk_bf16_f32 v27, v32, v33
	global_store_dwordx4 v[28:29], v[24:27], off
	v_lshlrev_b32_e32 v30, 16, v138
	v_and_b32_e32 v31, 0xffff0000, v138
	v_lshlrev_b32_e32 v24, 16, v136
	v_and_b32_e32 v25, 0xffff0000, v136
	v_lshlrev_b32_e32 v26, 16, v137
	v_and_b32_e32 v27, 0xffff0000, v137
	v_lshlrev_b32_e32 v32, 16, v139
	v_and_b32_e32 v33, 0xffff0000, v139
	v_pk_add_f32 v[22:23], v[22:23], v[26:27]
	v_pk_add_f32 v[20:21], v[20:21], v[24:25]
	v_pk_add_f32 v[24:25], v[18:19], v[32:33]
	v_pk_add_f32 v[18:19], v[16:17], v[30:31]
	v_cvt_pk_bf16_f32 v16, v20, v21
	v_cvt_pk_bf16_f32 v17, v22, v23
	v_lshlrev_b32_e32 v20, 16, v134
	v_cvt_pk_bf16_f32 v18, v18, v19
	v_cvt_pk_bf16_f32 v19, v24, v25
	global_store_dwordx4 v[28:29], v[16:19], off offset:256
	v_and_b32_e32 v21, 0xffff0000, v134
	v_lshlrev_b32_e32 v22, 16, v135
	v_lshlrev_b32_e32 v16, 16, v132
	v_and_b32_e32 v17, 0xffff0000, v132
	v_and_b32_e32 v23, 0xffff0000, v135
	v_pk_add_f32 v[12:13], v[12:13], v[16:17]
	v_lshlrev_b32_e32 v18, 16, v133
	v_and_b32_e32 v19, 0xffff0000, v133
	v_pk_add_f32 v[16:17], v[10:11], v[22:23]
	v_pk_add_f32 v[10:11], v[8:9], v[20:21]
	v_cvt_pk_bf16_f32 v8, v12, v13
	v_lshl_add_u64 v[12:13], s[8:9], 0, v[182:183]
	v_pk_add_f32 v[14:15], v[14:15], v[18:19]
	v_lshl_add_u64 v[12:13], v[12:13], 0, v[180:181]
	v_cvt_pk_bf16_f32 v9, v14, v15
	v_cvt_pk_bf16_f32 v10, v10, v11
	v_cvt_pk_bf16_f32 v11, v16, v17
	global_store_dwordx4 v[12:13], v[8:11], off
	v_lshlrev_b32_e32 v14, 16, v130
	v_and_b32_e32 v15, 0xffff0000, v130
	v_lshlrev_b32_e32 v8, 16, v128
	v_and_b32_e32 v9, 0xffff0000, v128
	v_lshlrev_b32_e32 v16, 16, v131
	v_and_b32_e32 v17, 0xffff0000, v131
	v_lshlrev_b32_e32 v10, 16, v129
	v_and_b32_e32 v11, 0xffff0000, v129
	v_pk_add_f32 v[4:5], v[4:5], v[8:9]
	v_pk_add_f32 v[8:9], v[2:3], v[16:17]
	v_pk_add_f32 v[2:3], v[0:1], v[14:15]
	v_pk_add_f32 v[6:7], v[6:7], v[10:11]
	v_cvt_pk_bf16_f32 v0, v4, v5
	s_nop 0
	v_cvt_pk_bf16_f32 v1, v6, v7
	v_cvt_pk_bf16_f32 v2, v2, v3
	v_cvt_pk_bf16_f32 v3, v8, v9
	global_store_dwordx4 v[12:13], v[0:3], off offset:256
	s_cbranch_vccz .LBB0_776
	s_waitcnt vmcnt(0)
	s_cmpk_gt_u32 s48, 0xff
	s_cbranch_scc1 .LBB0_787

; #define PG8_WAIT_V(n) asm volatile("s_waitcnt vmcnt(" #n ")" ::: "memory")
;     __host__ __device__ bool next(int i, Unit& u) const {
;         const long L = (long)i * G + c; if (L >= (long)nwg * rep) return false;
;         int wgid = (int)(L % nwg); { const int q = nwg / NXCD, r = nwg % NXCD, xcd = wgid % NXCD, off = wgid / NXCD; wgid = (xcd < r ? xcd * (q + 1) : r * (q + 1) + (xcd - r) * q) + off; }
; template <class Epi, class Sched>
; __device__ __forceinline__ void gemm_phase(PG8_LAS unsigned char* lds, const Gemm g, const Sched& S, const Epi& E) {
;     ...
;     const int tid = tix_, wid = __builtin_amdgcn_readfirstlane(tid >> 6), lane = tid & 63, wr = wid >> 2, wc = wid & 3, fr = lane & 15, fq = lane >> 4;
;     const int K = g.K, nt = K / BK;
;     unsigned voffA[2], voffB[2];
; #pragma unroll
;     for (int i = 0; i < 2; ++i) { int R, C; stage_rc(tid * 16 + i * 8192, R, C);
;         voffA[i] = (unsigned)(R * K + C) * 2u; voffB[i] = (unsigned)(tid * 16 + i * 8192); }
;     const size_t kstep = (size_t)(BK * 2);
;     const size_t hstep = (size_t)HALF * K * 2;
;     const size_t tstep = 2 * hstep;
;     const size_t kstepB = 32768, hstepB = 16384, tstepB = (size_t)nt * 32768;
;     const unsigned ldsw = (unsigned)wid * 1024u;
;     const int aoff = lds_byte(wr * 64 + fr, fq * 8), boff = lds_byte(wc * 32 + fr, fq * 8);
;     ...
;     Unit cur, nxt; int ui = 0;
;     if (!S.next(0, cur)) return;
;     f32x4 acc[2][2][4][2];
; #pragma unroll
;     for (int a = 0; a < 2; ++a)
; #pragma unroll
;         for (int b = 0; b < 2; ++b)
; #pragma unroll
;             for (int m = 0; m < 4; ++m)
; #pragma unroll
;                 for (int n = 0; n < 2; ++n) acc[a][b][m][n] = (f32x4){0.f, 0.f, 0.f, 0.f};
;     bf16x8 At[4][2], B0[2][2], B1[2][2];
;     const char* cA = (const char*)g.A + (size_t)cur.pm * tstep + (size_t)cur.br * g.strideA; const char* cB = (const char*)g.Bt + (size_t)cur.pn * tstepB + (size_t)cur.br * g.strideB;
;     S.a_ready(cur);
;     PG8_STAGE(PG8_SB(0, 0), cB, voffB); PG8_STAGE(PG8_SA(0, 0), cA, voffA); PG8_STAGE(PG8_SB(0, 1), cB + hstepB, voffB); PG8_STAGE(PG8_SA(0, 1), cA + hstep, voffA);
;     if (wr == 1) PG8_BAR;
;     PG8_WAIT_V(4); PG8_BAR;
;     PG8_STAGE(PG8_SB(1, 0), cB + kstepB, voffB); PG8_STAGE(PG8_SA(1, 0), cA + kstep, voffA); PG8_STAGE(PG8_SB(1, 1), cB + hstepB + kstepB, voffB);
;     PG8_WAIT_V(6); PG8_BAR;
.LBB0_897:
	s_or_b64 exec, exec, s[4:5]
	s_mov_b64 s[4:5], s[0:1]
	s_mov_b32 s26, s40
	s_mov_b32 s27, s2
	v_mov_b32_e32 v4, v228
	s_waitcnt lgkmcnt(0)
	s_barrier
	s_cmpk_gt_i32 s27, 0xabf
	v_readfirstlane_b32 s28, v4
	s_cbranch_scc1 .LBB0_909
	s_load_dwordx2 s[4:5], s[4:5], 0xa8
	v_lshlrev_b32_e32 v128, 4, v4
	s_mul_hi_i32 s6, s27, 0x2fa0be83
	v_add_u32_e32 v130, 0x2000, v128
	v_ashrrev_i32_e32 v0, 31, v130
	s_waitcnt lgkmcnt(0)
	s_add_u32 s29, s4, 0xc700000
	s_addc_u32 s30, s5, 0
	s_add_u32 s31, s4, 0x8680000
	s_addc_u32 s36, s5, 0
	s_lshr_b32 s7, s6, 31
	s_lshr_b32 s6, s6, 9
	s_add_i32 s6, s6, s7
	v_lshrrev_b32_e32 v0, 22, v0
	s_mulk_i32 s6, 0xac0
	v_add_u32_e32 v0, v130, v0
	s_sub_i32 s6, s27, s6
	v_ashrrev_i32_e32 v5, 10, v0
	s_sext_i32_i16 s7, s6
	v_mul_i32_i24_e32 v1, 0x400, v5
	s_bfe_u32 s7, s7, 0x3001c
	v_sub_u32_e32 v1, v130, v1
	s_add_i32 s7, s6, s7
	v_lshrrev_b32_e32 v2, 4, v1
	s_sext_i32_i16 s9, s7
	s_and_b32 s7, s7, 0xfff8
	s_ashr_i32 s8, s28, 6
	v_bitop3_b32 v1, v2, v1, 32 bitop3:0x6c
	s_sub_i32 s6, s6, s7
	s_ashr_i32 s11, s28, 8
	s_ashr_i32 s37, s27, 31
	s_lshl_b32 s38, s8, 10
	v_ashrrev_i32_e32 v2, 31, v1
	s_ashr_i32 s9, s9, 3
	s_sext_i32_i16 s7, s6
	v_lshrrev_b32_e32 v2, 26, v2
	s_cmp_lt_i32 s7, 0
	s_movk_i32 s39, 0x159
	v_add_u32_e32 v2, v1, v2
	s_cselect_b32 s7, s39, 0x158
	v_ashrrev_i32_e32 v6, 6, v2
	v_and_b32_e32 v2, 0xc0, v2
	s_mul_i32 s6, s7, s6
	v_sub_u32_e32 v1, v1, v2
	v_mov_b32_e32 v2, 1
	s_add_i32 s6, s6, s9
	v_ashrrev_i16_sdwa v1, v2, sext(v1) dst_sel:DWORD dst_unused:UNUSED_PAD src0_sel:DWORD src1_sel:BYTE_0
	s_sext_i32_i16 s7, s6
	v_lshlrev_b32_e32 v0, 5, v5
	v_bfe_i32 v7, v1, 0, 16
	v_lshlrev_b32_e32 v1, 3, v5
	s_mulk_i32 s7, 0x2fa1
	v_and_b32_e32 v0, 32, v0
	v_and_b32_e32 v1, 0xffff0, v1
	s_lshr_b32 s9, s7, 31
	s_ashr_i32 s7, s7, 22
	v_add_u32_e32 v0, v0, v7
	v_add_lshl_u32 v1, v6, v1, 12
	s_add_i32 s7, s7, s9
	v_lshl_add_u32 v132, v0, 1, v1
	v_bfe_i32 v1, v4, 27, 1
	s_lshl_b32 s9, s7, 3
	s_mulk_i32 s7, 0x158
	v_lshrrev_b32_e32 v1, 22, v1
	s_sub_i32 s6, s6, s7
	v_add_u32_e32 v1, v128, v1
	s_sext_i32_i16 s7, s6
	v_and_b32_e32 v1, 0xfffffc00, v1
	s_bfe_u32 s7, s7, 0x3001c
	v_sub_u32_e32 v1, v128, v1
	s_add_i32 s7, s6, s7
	v_lshrrev_b32_e32 v3, 4, v1
	s_sext_i32_i16 s10, s7
	s_and_b32 s7, s7, 0xfff8
	v_bitop3_b32 v1, v3, v1, 32 bitop3:0x6c
	s_sub_i32 s6, s6, s7
	v_ashrrev_i32_e32 v3, 31, v1
	s_sext_i32_i16 s6, s6
	v_lshrrev_b32_e32 v3, 26, v3
	s_lshr_b32 s10, s10, 3
	s_add_i32 s18, s9, s6
	v_ashrrev_i32_e32 v0, 31, v4
	v_add_u32_e32 v3, v1, v3
	s_ashr_i32 s19, s18, 31
	s_bfe_i64 s[12:13], s[10:11], 0x100000
	v_lshrrev_b32_e32 v0, 26, v0
	v_ashrrev_i32_e32 v9, 6, v3
	v_and_b32_e32 v3, 0xc0, v3
	s_lshl_b64 s[6:7], s[18:19], 20
	s_lshl_b64 s[12:13], s[12:13], 20
	v_add_u32_e32 v0, v4, v0
	v_sub_u32_e32 v1, v1, v3
	s_add_u32 s20, s31, s12
	v_ashrrev_i32_e32 v8, 6, v0
	v_ashrrev_i16_sdwa v1, v2, sext(v1) dst_sel:DWORD dst_unused:UNUSED_PAD src0_sel:DWORD src1_sel:BYTE_0
	s_addc_u32 s21, s36, s13
	s_add_i32 s19, s38, 0
	v_lshlrev_b32_e32 v0, 5, v8
	v_bfe_i32 v10, v1, 0, 16
	v_lshlrev_b32_e32 v1, 3, v8
	s_add_i32 m0, s19, 0x10000
	v_and_b32_e32 v0, 32, v0
	v_and_b32_e32 v1, 0xffff0, v1
	global_load_lds_dwordx4 v128, s[20:21]
	s_add_i32 m0, s19, 0x12000
	v_add_u32_e32 v0, v0, v10
	v_add_lshl_u32 v1, v9, v1, 12
	s_add_u32 s22, s29, s6
	v_lshl_add_u32 v134, v0, 1, v1
	global_load_lds_dwordx4 v130, s[20:21]
	s_addc_u32 s23, s30, s7
	s_mov_b32 m0, s19
	s_add_i32 s46, s19, 0x2000
	global_load_lds_dwordx4 v134, s[22:23]
	s_mov_b32 m0, s46
	s_add_u32 s6, s20, 0x4000
	global_load_lds_dwordx4 v132, s[22:23]
	s_addc_u32 s7, s21, 0
	s_add_i32 m0, s19, 0x14000
	v_mov_b32_e32 v129, 0
	global_load_lds_dwordx4 v128, s[6:7]
	s_add_i32 m0, s19, 0x16000
	v_mov_b32_e32 v135, v129
	global_load_lds_dwordx4 v130, s[6:7]
	s_add_u32 s6, s22, 0x80000
	s_addc_u32 s7, s23, 0
	s_add_i32 s47, s19, 0x4000
	s_mov_b32 m0, s47
	s_add_i32 s48, s19, 0x6000
	global_load_lds_dwordx4 v134, s[6:7]
	s_mov_b32 m0, s48
	v_mov_b32_e32 v133, v129
	global_load_lds_dwordx4 v132, s[6:7]
	s_mov_b32 s49, 0
	v_mov_b32_e32 v131, v129
	v_lshl_add_u64 v[2:3], s[22:23], 0, v[134:135]
	s_cmp_lg_u32 s11, 1
	v_lshl_add_u64 v[0:1], s[22:23], 0, v[132:133]
	s_cbranch_scc1 .LBB0_900
.LBB0_900:
	s_add_u32 s6, s4, 0x10700000
	s_addc_u32 s7, s5, 0
	s_lshl_b32 s4, s8, 5
	s_and_b32 s13, s4, 0x60
	s_lshl_b32 s12, s11, 13
	s_lshl_b32 s14, s13, 7
	s_add_u32 s4, s20, 0x8000
	s_addc_u32 s5, s21, 0
	s_add_i32 m0, s19, 0x18000
	v_lshl_add_u64 v[12:13], s[4:5], 0, v[128:129]
	s_waitcnt vmcnt(4)
	s_barrier
	global_load_lds_dwordx4 v[12:13], off
	v_lshl_add_u64 v[12:13], s[4:5], 0, v[130:131]
	s_add_i32 m0, s19, 0x1a000
	s_mov_b64 s[8:9], 0x80
	s_add_i32 s50, s19, 0x8000
	s_add_i32 s51, s19, 0xa000
	global_load_lds_dwordx4 v[12:13], off
	v_lshl_add_u64 v[2:3], v[2:3], 0, s[8:9]
	s_mov_b32 m0, s50
	s_add_u32 s4, s20, 0xc000
	global_load_lds_dwordx4 v[2:3], off
	v_lshl_add_u64 v[0:1], v[0:1], 0, s[8:9]
	s_mov_b32 m0, s51
	s_addc_u32 s5, s21, 0
	global_load_lds_dwordx4 v[0:1], off
	s_add_i32 m0, s19, 0x1c000
	v_lshl_add_u64 v[0:1], s[4:5], 0, v[128:129]
	global_load_lds_dwordx4 v[0:1], off
	v_lshl_add_u64 v[0:1], s[4:5], 0, v[130:131]
	s_add_i32 m0, s19, 0x1e000
	s_add_i32 s53, 0, 0x10000
	global_load_lds_dwordx4 v[0:1], off
	v_lshrrev_b32_e32 v1, 1, v4
	v_and_b32_e32 v1, 24, v1
	v_and_b32_e32 v0, 15, v4
	v_lshlrev_b32_e32 v2, 1, v1
	v_lshl_or_b32 v146, s11, 6, v0
	v_lshl_or_b32 v0, v0, 6, v2
	v_lshlrev_b32_e32 v2, 2, v4
	v_and_b32_e32 v2, 32, v2
	v_bitop3_b32 v3, v0, s12, v2 bitop3:0xde
	v_bitop3_b32 v147, v0, s14, v2 bitop3:0xde
	v_lshlrev_b32_e32 v0, 15, v8
	v_and_b32_e32 v0, 0xffff0000, v0
	v_or_b32_e32 v148, s13, v1
	v_lshl_add_u32 v0, v9, 12, v0
	v_and_b32_e32 v1, 1, v8
	v_lshl_or_b32 v0, v1, 6, v0
	v_lshl_add_u32 v136, v10, 1, v0
	v_lshlrev_b32_e32 v0, 15, v5
	v_and_b32_e32 v0, 0xffff0000, v0
	s_waitcnt vmcnt(6)
	v_lshl_add_u32 v0, v6, 12, v0
	v_and_b32_e32 v1, 1, v5
	v_lshl_or_b32 v0, v1, 6, v0
	s_add_i32 s54, 0, 0x14000
	s_sext_i32_i16 s56, s10
	s_ashr_i32 s52, s26, 31
	v_mov_b32_e32 v137, v129
	v_lshl_add_u32 v138, v7, 1, v0
	v_mov_b32_e32 v139, v129
	v_mov_b64_e32 v[140:141], 0xac0
	v_mov_b64_e32 v[142:143], 0xabf
	v_add_u32_e32 v149, s53, v147
	v_add_u32_e32 v150, 0, v3
	v_add_u32_e32 v151, s54, v147
	s_movk_i32 s55, 0x2b00
	s_barrier

;     __host__ __device__ bool next(int i, Unit& u) const { const int j = i / 3; if (!StaticOrder::next(j, u)) return false; u.br = i - 3 * j; return true; }
; #define PG8_STAGE(bufoff, gbase, voff) do { _Pragma("unroll") for (int _i = 0; _i < 2; ++_i) \
;         __builtin_amdgcn_global_load_lds((const unsigned*)((const char*)(gbase) + (voff)[_i]), (PG8_LAS unsigned*)(lds + (bufoff) + ldsw + _i * 8192), 16, 0, 0); } while (0)
; #define PG8_LDA(dst, b, h) do { _Pragma("unroll") for (int m = 0; m < 4; ++m) _Pragma("unroll") for (int k = 0; k < 2; ++k) dst[m][k] = *(const PG8_LAS bf16x8*)(lds + PG8_SA(b, h) + aoff + m * 2048 + k * 1024); } while (0)
; #define PG8_LDB(dst, b, h) do { _Pragma("unroll") for (int n = 0; n < 2; ++n) _Pragma("unroll") for (int k = 0; k < 2; ++k) dst[n][k] = *(const PG8_LAS bf16x8*)(lds + PG8_SB(b, h) + boff + n * 2048 + k * 1024); } while (0)
; #define PG8_WAIT_L(n) asm volatile("s_waitcnt lgkmcnt(" #n ")" ::: "memory")
; #define PG8_BAR __builtin_amdgcn_s_barrier()
; template <class Epi, class Sched>
; __device__ __forceinline__ void gemm_phase(PG8_LAS unsigned char* lds, const Gemm g, const Sched& S, const Epi& E) {
;     ...
;         const bool has_next = S.next(ui + 1, nxt);
;         const char* nA = has_next ? (const char*)g.A + (size_t)nxt.pm * tstep + (size_t)nxt.br * g.strideA : cA; const char* nB = has_next ? (const char*)g.Bt + (size_t)nxt.pn * tstepB + (size_t)nxt.br * g.strideB : cB;
;         for (int t = 0; t < nt; t += 2) {
;             const bool last = (t == nt - 2);
;             const char* a1 = cA + (size_t)(t + 1) * kstep;
;             const char* a2 = last ? nA : cA + (size_t)(t + 2) * kstep; const char* b2 = last ? nB : cB + (size_t)(t + 2) * kstepB;
;             const char* a3 = a2 + kstep; const char* b3 = b2 + kstepB;
;             if (last && has_next) S.a_ready(nxt);
;             PG8_LDB(B0, 0, 0); PG8_SCHED; PG8_LDA(At, 0, 0); PG8_STAGE(PG8_SA(1, 1), a1 + hstep, voffA);
;             PG8_WAIT_L(8); PG8_BAR; PG8_WAIT_L(0); PG8_MMA(0, 0, At, B0); PG8_BAR; PG8_SCHED;
;     ...
;         if (!(Epi::CHAIN && cur.br < 2))
; #pragma unroll
;         for (int a = 0; a < 2; ++a)
; #pragma unroll
;             for (int b = 0; b < 2; ++b)
; #pragma unroll
;                 for (int m = 0; m < 4; ++m)
; #pragma unroll
;                     for (int n = 0; n < 2; ++n) acc[a][b][m][n] = (f32x4){0.f, 0.f, 0.f, 0.f};
.LBB0_903:
	s_ashr_i32 s11, s10, 31
	v_cmp_lt_i64_e32 vcc, s[14:15], v[140:141]
	s_lshl_b64 s[14:15], s[10:11], 20
	s_add_u32 s14, s29, s14
	s_addc_u32 s15, s30, s15
	s_and_b64 s[16:17], vcc, exec
	s_cselect_b32 s11, s15, s23
	s_cselect_b32 s57, s14, s22
	s_ashr_i32 s13, s12, 31
	s_lshl_b64 s[16:17], s[12:13], 20
	s_add_u32 s16, s31, s16
	s_addc_u32 s17, s36, s17
	s_and_b64 s[24:25], vcc, exec
	s_cselect_b32 s13, s17, s21
	s_cselect_b32 s58, s16, s20
	s_add_u32 s59, s20, 0x10000
	s_addc_u32 s60, s21, 0
	s_add_u32 s20, s22, 0x80080
	v_mov_b32_e32 v0, 0
	s_addc_u32 s21, s23, 0
	s_mov_b32 s61, -2
	v_mov_b32_e32 v1, v0
	v_mov_b32_e32 v2, v0
	v_mov_b32_e32 v3, v0
	v_mov_b32_e32 v4, v0
	v_mov_b32_e32 v5, v0
	v_mov_b32_e32 v6, v0
	v_mov_b32_e32 v7, v0
	v_mov_b32_e32 v16, v0
	v_mov_b32_e32 v17, v0
	v_mov_b32_e32 v18, v0
	v_mov_b32_e32 v19, v0
	v_mov_b32_e32 v20, v0
	v_mov_b32_e32 v21, v0
	v_mov_b32_e32 v22, v0
	v_mov_b32_e32 v23, v0
	v_mov_b32_e32 v32, v0
	v_mov_b32_e32 v33, v0
	v_mov_b32_e32 v34, v0
	v_mov_b32_e32 v35, v0
	v_mov_b32_e32 v36, v0
	v_mov_b32_e32 v37, v0
	v_mov_b32_e32 v38, v0
	v_mov_b32_e32 v39, v0
	v_mov_b32_e32 v48, v0
	v_mov_b32_e32 v49, v0
	v_mov_b32_e32 v50, v0
	v_mov_b32_e32 v51, v0
	v_mov_b32_e32 v52, v0
	v_mov_b32_e32 v53, v0
	v_mov_b32_e32 v54, v0
	v_mov_b32_e32 v55, v0
	v_mov_b32_e32 v8, v0
	v_mov_b32_e32 v9, v0
	v_mov_b32_e32 v10, v0
	v_mov_b32_e32 v11, v0
	v_mov_b32_e32 v12, v0
	v_mov_b32_e32 v13, v0
	v_mov_b32_e32 v14, v0
	v_mov_b32_e32 v15, v0
	v_mov_b32_e32 v24, v0
	v_mov_b32_e32 v25, v0
	v_mov_b32_e32 v26, v0
	v_mov_b32_e32 v27, v0
	v_mov_b32_e32 v28, v0
	v_mov_b32_e32 v29, v0
	v_mov_b32_e32 v30, v0
	v_mov_b32_e32 v31, v0
	v_mov_b32_e32 v40, v0
	v_mov_b32_e32 v41, v0
	v_mov_b32_e32 v42, v0
	v_mov_b32_e32 v43, v0
	v_mov_b32_e32 v44, v0
	v_mov_b32_e32 v45, v0
	v_mov_b32_e32 v46, v0
	v_mov_b32_e32 v47, v0
	v_mov_b32_e32 v56, v0
	v_mov_b32_e32 v57, v0
	v_mov_b32_e32 v58, v0
	v_mov_b32_e32 v59, v0
	v_mov_b32_e32 v60, v0
	v_mov_b32_e32 v61, v0
	v_mov_b32_e32 v62, v0
	v_mov_b32_e32 v63, v0
	v_mov_b32_e32 v64, v0
	v_mov_b32_e32 v65, v0
	v_mov_b32_e32 v66, v0
	v_mov_b32_e32 v67, v0
	v_mov_b32_e32 v68, v0
	v_mov_b32_e32 v69, v0
	v_mov_b32_e32 v70, v0
	v_mov_b32_e32 v71, v0
	v_mov_b32_e32 v80, v0
	v_mov_b32_e32 v81, v0
	v_mov_b32_e32 v82, v0
	v_mov_b32_e32 v83, v0
	v_mov_b32_e32 v84, v0
	v_mov_b32_e32 v85, v0
	v_mov_b32_e32 v86, v0
	v_mov_b32_e32 v87, v0
	v_mov_b32_e32 v96, v0
	v_mov_b32_e32 v97, v0
	v_mov_b32_e32 v98, v0
	v_mov_b32_e32 v99, v0
	v_mov_b32_e32 v100, v0
	v_mov_b32_e32 v101, v0
	v_mov_b32_e32 v102, v0
	v_mov_b32_e32 v103, v0
	v_mov_b32_e32 v112, v0
	v_mov_b32_e32 v113, v0
	v_mov_b32_e32 v114, v0
	v_mov_b32_e32 v115, v0
	v_mov_b32_e32 v116, v0
	v_mov_b32_e32 v117, v0
	v_mov_b32_e32 v118, v0
	v_mov_b32_e32 v119, v0
	v_mov_b32_e32 v72, v0
	v_mov_b32_e32 v73, v0
	v_mov_b32_e32 v74, v0
	v_mov_b32_e32 v75, v0
	v_mov_b32_e32 v76, v0
	v_mov_b32_e32 v77, v0
	v_mov_b32_e32 v78, v0
	v_mov_b32_e32 v79, v0
	v_mov_b32_e32 v88, v0
	v_mov_b32_e32 v89, v0
	v_mov_b32_e32 v90, v0
	v_mov_b32_e32 v91, v0
	v_mov_b32_e32 v92, v0
	v_mov_b32_e32 v93, v0
	v_mov_b32_e32 v94, v0
	v_mov_b32_e32 v95, v0
	v_mov_b32_e32 v104, v0
	v_mov_b32_e32 v105, v0
	v_mov_b32_e32 v106, v0
	v_mov_b32_e32 v107, v0
	v_mov_b32_e32 v108, v0
	v_mov_b32_e32 v109, v0
	v_mov_b32_e32 v110, v0
	v_mov_b32_e32 v111, v0
	v_mov_b32_e32 v120, v0
	v_mov_b32_e32 v121, v0
	v_mov_b32_e32 v122, v0
	v_mov_b32_e32 v123, v0
	v_mov_b32_e32 v124, v0
	v_mov_b32_e32 v125, v0
	v_mov_b32_e32 v126, v0
	v_mov_b32_e32 v127, v0
	s_cmp_eq_u32 s78, 1
	s_cbranch_scc0 .Lhalf_skip_y_6
	s_barrier
.Lhalf_skip_y_6:
.LBB0_904:
	ds_read_b128 v[152:155], v149
	ds_read_b128 v[156:159], v149 offset:1024
	ds_read_b128 v[160:163], v149 offset:2048
	ds_read_b128 v[164:167], v149 offset:3072
	s_add_u32 s22, s20, 0xfff80080
	s_addc_u32 s23, s21, -1
	s_cmp_eq_u32 s61, 28
	s_cselect_b32 s25, s11, s23
	s_cselect_b32 s24, s57, s22
	s_cselect_b32 s23, s13, s60
	s_cselect_b32 s22, s58, s59
	v_lshl_add_u64 v[144:145], s[20:21], 0, v[136:137]
	s_add_i32 m0, s19, 0xc000
	ds_read_b128 v[168:171], v150
	ds_read_b128 v[172:175], v150 offset:1024
	ds_read_b128 v[176:179], v150 offset:2048
	ds_read_b128 v[180:183], v150 offset:3072
	ds_read_b128 v[184:187], v150 offset:4096
	ds_read_b128 v[188:191], v150 offset:5120
	ds_read_b128 v[192:195], v150 offset:6144
	ds_read_b128 v[196:199], v150 offset:7168
	global_load_lds_dwordx4 v[144:145], off
	v_lshl_add_u64 v[144:145], s[20:21], 0, v[138:139]
	s_add_i32 m0, s19, 0xe000
	s_nop 0
	global_load_lds_dwordx4 v[144:145], off
	s_waitcnt lgkmcnt(8)
	s_barrier
	s_waitcnt lgkmcnt(0)
	s_setprio 1
	s_waitcnt lgkmcnt(0)
	v_mfma_f32_16x16x32_bf16 v[124:127], v[152:155], v[168:171], v[124:127]
	v_mfma_f32_16x16x32_bf16 v[120:123], v[160:163], v[168:171], v[120:123]
	v_mfma_f32_16x16x32_bf16 v[108:111], v[152:155], v[176:179], v[108:111]
	v_mfma_f32_16x16x32_bf16 v[104:107], v[160:163], v[176:179], v[104:107]
	v_mfma_f32_16x16x32_bf16 v[92:95], v[152:155], v[184:187], v[92:95]
	v_mfma_f32_16x16x32_bf16 v[88:91], v[160:163], v[184:187], v[88:91]
	v_mfma_f32_16x16x32_bf16 v[76:79], v[152:155], v[192:195], v[76:79]
	v_mfma_f32_16x16x32_bf16 v[72:75], v[160:163], v[192:195], v[72:75]
	v_mfma_f32_16x16x32_bf16 v[124:127], v[156:159], v[172:175], v[124:127]
	v_mfma_f32_16x16x32_bf16 v[120:123], v[164:167], v[172:175], v[120:123]
	v_mfma_f32_16x16x32_bf16 v[108:111], v[156:159], v[180:183], v[108:111]
	v_mfma_f32_16x16x32_bf16 v[104:107], v[164:167], v[180:183], v[104:107]
	v_mfma_f32_16x16x32_bf16 v[92:95], v[156:159], v[188:191], v[92:95]
	v_mfma_f32_16x16x32_bf16 v[88:91], v[164:167], v[188:191], v[88:91]
	v_mfma_f32_16x16x32_bf16 v[76:79], v[156:159], v[196:199], v[76:79]
	v_mfma_f32_16x16x32_bf16 v[72:75], v[164:167], v[196:199], v[72:75]
	s_setprio 0
	s_barrier
; #define PG8_STAGE(bufoff, gbase, voff) do { _Pragma("unroll") for (int _i = 0; _i < 2; ++_i) \
;         __builtin_amdgcn_global_load_lds((const unsigned*)((const char*)(gbase) + (voff)[_i]), (PG8_LAS unsigned*)(lds + (bufoff) + ldsw + _i * 8192), 16, 0, 0); } while (0)
; #define PG8_LDA(dst, b, h) do { _Pragma("unroll") for (int m = 0; m < 4; ++m) _Pragma("unroll") for (int k = 0; k < 2; ++k) dst[m][k] = *(const PG8_LAS bf16x8*)(lds + PG8_SA(b, h) + aoff + m * 2048 + k * 1024); } while (0)
; #define PG8_LDB(dst, b, h) do { _Pragma("unroll") for (int n = 0; n < 2; ++n) _Pragma("unroll") for (int k = 0; k < 2; ++k) dst[n][k] = *(const PG8_LAS bf16x8*)(lds + PG8_SB(b, h) + boff + n * 2048 + k * 1024); } while (0)
; #define PG8_MMA(ai, bj, At, Bt) do { __builtin_amdgcn_s_setprio(1); _Pragma("unroll") for (int m = 0; m < 4; ++m) _Pragma("unroll") for (int n = 0; n < 2; ++n) _Pragma("unroll") for (int k = 0; k < 2; ++k) \
;         acc[ai][bj][m][n] = __builtin_amdgcn_mfma_f32_16x16x32_bf16(Bt[n][k], At[m][k], acc[ai][bj][m][n], 0, 0, 0); __builtin_amdgcn_s_setprio(0); } while (0)
; #define PG8_WAIT_V(n) asm volatile("s_waitcnt vmcnt(" #n ")" ::: "memory")
; #define PG8_WAIT_L(n) asm volatile("s_waitcnt lgkmcnt(" #n ")" ::: "memory")
; #define PG8_BAR __builtin_amdgcn_s_barrier()
; #define PG8_SCHED __builtin_amdgcn_sched_barrier(0)
; template <class Epi, class Sched>
; __device__ __forceinline__ void gemm_phase(PG8_LAS unsigned char* lds, const Gemm g, const Sched& S, const Epi& E) {
;     ...
;             PG8_LDB(B1, 0, 1); PG8_STAGE(PG8_SB(0, 0), b2, voffB);
;             PG8_BAR; PG8_WAIT_L(0); PG8_MMA(0, 1, At, B1); PG8_BAR;
;             PG8_LDA(At, 0, 1); PG8_STAGE(PG8_SA(0, 0), a2, voffA);
;             PG8_BAR; PG8_WAIT_L(0); PG8_MMA(1, 0, At, B0); PG8_BAR; PG8_SCHED;
;             PG8_STAGE(PG8_SB(0, 1), b2 + hstepB, voffB);
;             PG8_WAIT_V(6); PG8_BAR; PG8_MMA(1, 1, At, B1); PG8_BAR;
;             PG8_LDB(B0, 1, 0); PG8_SCHED; PG8_LDA(At, 1, 0); PG8_STAGE(PG8_SA(0, 1), a2 + hstep, voffA);
;             PG8_WAIT_L(8); PG8_BAR; PG8_WAIT_L(0); PG8_MMA(0, 0, At, B0); PG8_BAR; PG8_SCHED;
	s_add_i32 s62, s53, s38
	v_lshl_add_u64 v[144:145], s[22:23], 0, v[128:129]
	s_mov_b32 m0, s62
	ds_read_b128 v[200:203], v151
	ds_read_b128 v[204:207], v151 offset:1024
	ds_read_b128 v[208:211], v151 offset:2048
	ds_read_b128 v[212:215], v151 offset:3072
	global_load_lds_dwordx4 v[144:145], off
	v_lshl_add_u64 v[144:145], s[22:23], 0, v[130:131]
	s_add_i32 m0, s62, 0x2000
	s_nop 0
	global_load_lds_dwordx4 v[144:145], off
	s_barrier
	s_waitcnt lgkmcnt(0)
	s_setprio 1
	s_waitcnt lgkmcnt(0)
	v_mfma_f32_16x16x32_bf16 v[116:119], v[200:203], v[168:171], v[116:119]
	v_mfma_f32_16x16x32_bf16 v[112:115], v[208:211], v[168:171], v[112:115]
	v_mfma_f32_16x16x32_bf16 v[100:103], v[200:203], v[176:179], v[100:103]
	v_mfma_f32_16x16x32_bf16 v[96:99], v[208:211], v[176:179], v[96:99]
	v_mfma_f32_16x16x32_bf16 v[84:87], v[200:203], v[184:187], v[84:87]
	v_mfma_f32_16x16x32_bf16 v[80:83], v[208:211], v[184:187], v[80:83]
	v_mfma_f32_16x16x32_bf16 v[68:71], v[200:203], v[192:195], v[68:71]
	v_mfma_f32_16x16x32_bf16 v[64:67], v[208:211], v[192:195], v[64:67]
	v_mfma_f32_16x16x32_bf16 v[116:119], v[204:207], v[172:175], v[116:119]
	v_mfma_f32_16x16x32_bf16 v[112:115], v[212:215], v[172:175], v[112:115]
	v_mfma_f32_16x16x32_bf16 v[100:103], v[204:207], v[180:183], v[100:103]
	v_mfma_f32_16x16x32_bf16 v[96:99], v[212:215], v[180:183], v[96:99]
	v_mfma_f32_16x16x32_bf16 v[84:87], v[204:207], v[188:191], v[84:87]
	v_mfma_f32_16x16x32_bf16 v[80:83], v[212:215], v[188:191], v[80:83]
	v_mfma_f32_16x16x32_bf16 v[68:71], v[204:207], v[196:199], v[68:71]
	v_mfma_f32_16x16x32_bf16 v[64:67], v[212:215], v[196:199], v[64:67]
	s_setprio 0
	s_mov_b32 m0, s19
	v_lshl_add_u64 v[144:145], s[24:25], 0, v[134:135]
	s_barrier
	ds_read_b128 v[168:171], v150 offset:16384
	ds_read_b128 v[172:175], v150 offset:17408
	ds_read_b128 v[176:179], v150 offset:18432
	ds_read_b128 v[180:183], v150 offset:19456
	ds_read_b128 v[184:187], v150 offset:20480
	ds_read_b128 v[188:191], v150 offset:21504
	ds_read_b128 v[192:195], v150 offset:22528
	ds_read_b128 v[196:199], v150 offset:23552
	global_load_lds_dwordx4 v[144:145], off
	v_lshl_add_u64 v[216:217], s[24:25], 0, v[132:133]
	s_mov_b32 m0, s46
	s_nop 0
	global_load_lds_dwordx4 v[216:217], off
	s_barrier
	s_waitcnt lgkmcnt(0)
	s_setprio 1
	s_waitcnt lgkmcnt(0)
	v_mfma_f32_16x16x32_bf16 v[60:63], v[152:155], v[168:171], v[60:63]
	v_mfma_f32_16x16x32_bf16 v[56:59], v[160:163], v[168:171], v[56:59]
	v_mfma_f32_16x16x32_bf16 v[44:47], v[152:155], v[176:179], v[44:47]
	v_mfma_f32_16x16x32_bf16 v[40:43], v[160:163], v[176:179], v[40:43]
	v_mfma_f32_16x16x32_bf16 v[28:31], v[152:155], v[184:187], v[28:31]
	v_mfma_f32_16x16x32_bf16 v[24:27], v[160:163], v[184:187], v[24:27]
	v_mfma_f32_16x16x32_bf16 v[12:15], v[152:155], v[192:195], v[12:15]
	v_mfma_f32_16x16x32_bf16 v[8:11], v[160:163], v[192:195], v[8:11]
	v_mfma_f32_16x16x32_bf16 v[60:63], v[156:159], v[172:175], v[60:63]
	v_mfma_f32_16x16x32_bf16 v[56:59], v[164:167], v[172:175], v[56:59]
	v_mfma_f32_16x16x32_bf16 v[44:47], v[156:159], v[180:183], v[44:47]
	v_mfma_f32_16x16x32_bf16 v[40:43], v[164:167], v[180:183], v[40:43]
	v_mfma_f32_16x16x32_bf16 v[28:31], v[156:159], v[188:191], v[28:31]
	v_mfma_f32_16x16x32_bf16 v[24:27], v[164:167], v[188:191], v[24:27]
	v_mfma_f32_16x16x32_bf16 v[12:15], v[156:159], v[196:199], v[12:15]
	v_mfma_f32_16x16x32_bf16 v[8:11], v[164:167], v[196:199], v[8:11]
	s_setprio 0
	s_barrier
	s_add_u32 s62, s22, 0x4000
	s_addc_u32 s63, s23, 0
	s_add_i32 s64, s54, s38
	v_lshl_add_u64 v[152:153], s[62:63], 0, v[128:129]
	s_mov_b32 m0, s64
	s_nop 0
	global_load_lds_dwordx4 v[152:153], off
	v_lshl_add_u64 v[152:153], s[62:63], 0, v[130:131]
	s_add_i32 m0, s64, 0x2000
	s_nop 0
	global_load_lds_dwordx4 v[152:153], off
	s_waitcnt vmcnt(6)
	s_barrier
	s_setprio 1
	v_mfma_f32_16x16x32_bf16 v[52:55], v[200:203], v[168:171], v[52:55]
	v_mfma_f32_16x16x32_bf16 v[48:51], v[208:211], v[168:171], v[48:51]
	v_mfma_f32_16x16x32_bf16 v[36:39], v[200:203], v[176:179], v[36:39]
	v_mfma_f32_16x16x32_bf16 v[32:35], v[208:211], v[176:179], v[32:35]
	v_mfma_f32_16x16x32_bf16 v[20:23], v[200:203], v[184:187], v[20:23]
	v_mfma_f32_16x16x32_bf16 v[16:19], v[208:211], v[184:187], v[16:19]
	v_mfma_f32_16x16x32_bf16 v[4:7], v[200:203], v[192:195], v[4:7]
	v_mfma_f32_16x16x32_bf16 v[0:3], v[208:211], v[192:195], v[0:3]
	v_mfma_f32_16x16x32_bf16 v[52:55], v[204:207], v[172:175], v[52:55]
	v_mfma_f32_16x16x32_bf16 v[48:51], v[212:215], v[172:175], v[48:51]
	v_mfma_f32_16x16x32_bf16 v[36:39], v[204:207], v[180:183], v[36:39]
	v_mfma_f32_16x16x32_bf16 v[32:35], v[212:215], v[180:183], v[32:35]
	v_mfma_f32_16x16x32_bf16 v[20:23], v[204:207], v[188:191], v[20:23]
	v_mfma_f32_16x16x32_bf16 v[16:19], v[212:215], v[188:191], v[16:19]
	v_mfma_f32_16x16x32_bf16 v[4:7], v[204:207], v[196:199], v[4:7]
	v_mfma_f32_16x16x32_bf16 v[0:3], v[212:215], v[196:199], v[0:3]
	s_setprio 0
	s_add_i32 s62, 0, 0x18000
	v_add_u32_e32 v164, s62, v147
	s_barrier
	ds_read_b128 v[152:155], v164
	ds_read_b128 v[156:159], v164 offset:1024
	ds_read_b128 v[160:163], v164 offset:2048
	ds_read_b128 v[164:167], v164 offset:3072
	s_add_u32 s24, s24, 0x80000
	s_addc_u32 s25, s25, 0
	s_mov_b32 m0, s47
	v_lshl_add_u64 v[200:201], s[24:25], 0, v[134:135]
	ds_read_b128 v[168:171], v150 offset:32768
	ds_read_b128 v[172:175], v150 offset:33792
	ds_read_b128 v[176:179], v150 offset:34816
	ds_read_b128 v[180:183], v150 offset:35840
	ds_read_b128 v[184:187], v150 offset:36864
	ds_read_b128 v[188:191], v150 offset:37888
	ds_read_b128 v[192:195], v150 offset:38912
	ds_read_b128 v[196:199], v150 offset:39936
	global_load_lds_dwordx4 v[200:201], off
	v_lshl_add_u64 v[200:201], s[24:25], 0, v[132:133]
	s_mov_b32 m0, s48
	s_nop 0
	global_load_lds_dwordx4 v[200:201], off
	s_waitcnt lgkmcnt(8)
	s_barrier
; #define PG8_STAGE(bufoff, gbase, voff) do { _Pragma("unroll") for (int _i = 0; _i < 2; ++_i) \
;         __builtin_amdgcn_global_load_lds((const unsigned*)((const char*)(gbase) + (voff)[_i]), (PG8_LAS unsigned*)(lds + (bufoff) + ldsw + _i * 8192), 16, 0, 0); } while (0)
; #define PG8_LDA(dst, b, h) do { _Pragma("unroll") for (int m = 0; m < 4; ++m) _Pragma("unroll") for (int k = 0; k < 2; ++k) dst[m][k] = *(const PG8_LAS bf16x8*)(lds + PG8_SA(b, h) + aoff + m * 2048 + k * 1024); } while (0)
; #define PG8_LDB(dst, b, h) do { _Pragma("unroll") for (int n = 0; n < 2; ++n) _Pragma("unroll") for (int k = 0; k < 2; ++k) dst[n][k] = *(const PG8_LAS bf16x8*)(lds + PG8_SB(b, h) + boff + n * 2048 + k * 1024); } while (0)
; #define PG8_MMA(ai, bj, At, Bt) do { __builtin_amdgcn_s_setprio(1); _Pragma("unroll") for (int m = 0; m < 4; ++m) _Pragma("unroll") for (int n = 0; n < 2; ++n) _Pragma("unroll") for (int k = 0; k < 2; ++k) \
;         acc[ai][bj][m][n] = __builtin_amdgcn_mfma_f32_16x16x32_bf16(Bt[n][k], At[m][k], acc[ai][bj][m][n], 0, 0, 0); __builtin_amdgcn_s_setprio(0); } while (0)
; #define PG8_WAIT_V(n) asm volatile("s_waitcnt vmcnt(" #n ")" ::: "memory")
; #define PG8_WAIT_L(n) asm volatile("s_waitcnt lgkmcnt(" #n ")" ::: "memory")
; #define PG8_BAR __builtin_amdgcn_s_barrier()
; #define PG8_SCHED __builtin_amdgcn_sched_barrier(0)
; template <class Epi, class Sched>
; __device__ __forceinline__ void gemm_phase(PG8_LAS unsigned char* lds, const Gemm g, const Sched& S, const Epi& E) {
;     ...
;             PG8_WAIT_L(8); PG8_BAR; PG8_WAIT_L(0); PG8_MMA(0, 0, At, B0); PG8_BAR; PG8_SCHED;
;             PG8_LDB(B1, 1, 1); PG8_STAGE(PG8_SB(1, 0), b3, voffB);
;             PG8_BAR; PG8_WAIT_L(0); PG8_MMA(0, 1, At, B1); PG8_BAR;
;             PG8_LDA(At, 1, 1); PG8_STAGE(PG8_SA(1, 0), a3, voffA);
;             PG8_BAR; PG8_WAIT_L(0); PG8_MMA(1, 0, At, B0); PG8_BAR; PG8_SCHED;
;             PG8_STAGE(PG8_SB(1, 1), b3 + hstepB, voffB);
;             PG8_WAIT_V(6); PG8_BAR; PG8_MMA(1, 1, At, B1); PG8_BAR;
;         }
	s_waitcnt lgkmcnt(0)
	s_setprio 1
	s_waitcnt lgkmcnt(0)
	v_mfma_f32_16x16x32_bf16 v[124:127], v[152:155], v[168:171], v[124:127]
	v_mfma_f32_16x16x32_bf16 v[120:123], v[160:163], v[168:171], v[120:123]
	v_mfma_f32_16x16x32_bf16 v[108:111], v[152:155], v[176:179], v[108:111]
	v_mfma_f32_16x16x32_bf16 v[104:107], v[160:163], v[176:179], v[104:107]
	v_mfma_f32_16x16x32_bf16 v[92:95], v[152:155], v[184:187], v[92:95]
	v_mfma_f32_16x16x32_bf16 v[88:91], v[160:163], v[184:187], v[88:91]
	v_mfma_f32_16x16x32_bf16 v[76:79], v[152:155], v[192:195], v[76:79]
	v_mfma_f32_16x16x32_bf16 v[72:75], v[160:163], v[192:195], v[72:75]
	v_mfma_f32_16x16x32_bf16 v[124:127], v[156:159], v[172:175], v[124:127]
	v_mfma_f32_16x16x32_bf16 v[120:123], v[164:167], v[172:175], v[120:123]
	v_mfma_f32_16x16x32_bf16 v[108:111], v[156:159], v[180:183], v[108:111]
	v_mfma_f32_16x16x32_bf16 v[104:107], v[164:167], v[180:183], v[104:107]
	v_mfma_f32_16x16x32_bf16 v[92:95], v[156:159], v[188:191], v[92:95]
	v_mfma_f32_16x16x32_bf16 v[88:91], v[164:167], v[188:191], v[88:91]
	v_mfma_f32_16x16x32_bf16 v[76:79], v[156:159], v[196:199], v[76:79]
	v_mfma_f32_16x16x32_bf16 v[72:75], v[164:167], v[196:199], v[72:75]
	s_setprio 0
	s_barrier
	s_add_i32 s63, 0, 0x1c000
	s_add_u32 s24, s22, 0x8000
	s_addc_u32 s25, s23, 0
	s_add_i32 s62, s62, s38
	v_add_u32_e32 v212, s63, v147
	v_lshl_add_u64 v[218:219], s[24:25], 0, v[128:129]
	s_mov_b32 m0, s62
	ds_read_b128 v[200:203], v212
	ds_read_b128 v[204:207], v212 offset:1024
	ds_read_b128 v[208:211], v212 offset:2048
	ds_read_b128 v[212:215], v212 offset:3072
	global_load_lds_dwordx4 v[218:219], off
	v_lshl_add_u64 v[218:219], s[24:25], 0, v[130:131]
	s_add_i32 m0, s62, 0x2000
	s_nop 0
	global_load_lds_dwordx4 v[218:219], off
	s_barrier
	s_waitcnt lgkmcnt(0)
	s_setprio 1
	s_waitcnt lgkmcnt(0)
	v_mfma_f32_16x16x32_bf16 v[116:119], v[200:203], v[168:171], v[116:119]
	v_mfma_f32_16x16x32_bf16 v[112:115], v[208:211], v[168:171], v[112:115]
	v_mfma_f32_16x16x32_bf16 v[100:103], v[200:203], v[176:179], v[100:103]
	v_mfma_f32_16x16x32_bf16 v[96:99], v[208:211], v[176:179], v[96:99]
	v_mfma_f32_16x16x32_bf16 v[84:87], v[200:203], v[184:187], v[84:87]
	v_mfma_f32_16x16x32_bf16 v[80:83], v[208:211], v[184:187], v[80:83]
	v_mfma_f32_16x16x32_bf16 v[68:71], v[200:203], v[192:195], v[68:71]
	v_mfma_f32_16x16x32_bf16 v[64:67], v[208:211], v[192:195], v[64:67]
	v_mfma_f32_16x16x32_bf16 v[116:119], v[204:207], v[172:175], v[116:119]
	v_mfma_f32_16x16x32_bf16 v[112:115], v[212:215], v[172:175], v[112:115]
	v_mfma_f32_16x16x32_bf16 v[100:103], v[204:207], v[180:183], v[100:103]
	v_mfma_f32_16x16x32_bf16 v[96:99], v[212:215], v[180:183], v[96:99]
	v_mfma_f32_16x16x32_bf16 v[84:87], v[204:207], v[188:191], v[84:87]
	v_mfma_f32_16x16x32_bf16 v[80:83], v[212:215], v[188:191], v[80:83]
	v_mfma_f32_16x16x32_bf16 v[68:71], v[204:207], v[196:199], v[68:71]
	v_mfma_f32_16x16x32_bf16 v[64:67], v[212:215], v[196:199], v[64:67]
	s_setprio 0
	s_mov_b32 m0, s50
	v_lshl_add_u64 v[144:145], v[144:145], 0, s[8:9]
	s_barrier
	ds_read_b128 v[168:171], v150 offset:49152
	ds_read_b128 v[172:175], v150 offset:50176
	ds_read_b128 v[176:179], v150 offset:51200
	ds_read_b128 v[180:183], v150 offset:52224
	ds_read_b128 v[184:187], v150 offset:53248
	ds_read_b128 v[188:191], v150 offset:54272
	ds_read_b128 v[192:195], v150 offset:55296
	ds_read_b128 v[196:199], v150 offset:56320
	global_load_lds_dwordx4 v[144:145], off
	v_lshl_add_u64 v[144:145], v[216:217], 0, s[8:9]
	s_mov_b32 m0, s51
	s_nop 0
	global_load_lds_dwordx4 v[144:145], off
	s_barrier
	s_waitcnt lgkmcnt(0)
	s_setprio 1
	s_waitcnt lgkmcnt(0)
	v_mfma_f32_16x16x32_bf16 v[60:63], v[152:155], v[168:171], v[60:63]
	v_mfma_f32_16x16x32_bf16 v[56:59], v[160:163], v[168:171], v[56:59]
	v_mfma_f32_16x16x32_bf16 v[44:47], v[152:155], v[176:179], v[44:47]
	v_mfma_f32_16x16x32_bf16 v[40:43], v[160:163], v[176:179], v[40:43]
	v_mfma_f32_16x16x32_bf16 v[28:31], v[152:155], v[184:187], v[28:31]
	v_mfma_f32_16x16x32_bf16 v[24:27], v[160:163], v[184:187], v[24:27]
	v_mfma_f32_16x16x32_bf16 v[12:15], v[152:155], v[192:195], v[12:15]
	v_mfma_f32_16x16x32_bf16 v[8:11], v[160:163], v[192:195], v[8:11]
	v_mfma_f32_16x16x32_bf16 v[60:63], v[156:159], v[172:175], v[60:63]
	v_mfma_f32_16x16x32_bf16 v[56:59], v[164:167], v[172:175], v[56:59]
	v_mfma_f32_16x16x32_bf16 v[44:47], v[156:159], v[180:183], v[44:47]
	v_mfma_f32_16x16x32_bf16 v[40:43], v[164:167], v[180:183], v[40:43]
	v_mfma_f32_16x16x32_bf16 v[28:31], v[156:159], v[188:191], v[28:31]
	v_mfma_f32_16x16x32_bf16 v[24:27], v[164:167], v[188:191], v[24:27]
	v_mfma_f32_16x16x32_bf16 v[12:15], v[156:159], v[196:199], v[12:15]
	v_mfma_f32_16x16x32_bf16 v[8:11], v[164:167], v[196:199], v[8:11]
	s_setprio 0
	s_barrier
	s_add_u32 s22, s22, 0xc000
	s_addc_u32 s23, s23, 0
	s_add_i32 s24, s63, s38
	v_lshl_add_u64 v[144:145], s[22:23], 0, v[128:129]
	s_mov_b32 m0, s24
	s_nop 0
	global_load_lds_dwordx4 v[144:145], off
	v_lshl_add_u64 v[144:145], s[22:23], 0, v[130:131]
	s_add_i32 m0, s24, 0x2000
	s_nop 0
	global_load_lds_dwordx4 v[144:145], off
	s_waitcnt vmcnt(6)
	s_barrier
	s_setprio 1
	v_mfma_f32_16x16x32_bf16 v[52:55], v[200:203], v[168:171], v[52:55]
	v_mfma_f32_16x16x32_bf16 v[48:51], v[208:211], v[168:171], v[48:51]
	v_mfma_f32_16x16x32_bf16 v[36:39], v[200:203], v[176:179], v[36:39]
	v_mfma_f32_16x16x32_bf16 v[32:35], v[208:211], v[176:179], v[32:35]
	v_mfma_f32_16x16x32_bf16 v[20:23], v[200:203], v[184:187], v[20:23]
	v_mfma_f32_16x16x32_bf16 v[16:19], v[208:211], v[184:187], v[16:19]
	v_mfma_f32_16x16x32_bf16 v[4:7], v[200:203], v[192:195], v[4:7]
	v_mfma_f32_16x16x32_bf16 v[0:3], v[208:211], v[192:195], v[0:3]
	v_mfma_f32_16x16x32_bf16 v[52:55], v[204:207], v[172:175], v[52:55]
	v_mfma_f32_16x16x32_bf16 v[48:51], v[212:215], v[172:175], v[48:51]
	v_mfma_f32_16x16x32_bf16 v[36:39], v[204:207], v[180:183], v[36:39]
	v_mfma_f32_16x16x32_bf16 v[32:35], v[212:215], v[180:183], v[32:35]
	v_mfma_f32_16x16x32_bf16 v[20:23], v[204:207], v[188:191], v[20:23]
	v_mfma_f32_16x16x32_bf16 v[16:19], v[212:215], v[188:191], v[16:19]
	v_mfma_f32_16x16x32_bf16 v[4:7], v[204:207], v[196:199], v[4:7]
	v_mfma_f32_16x16x32_bf16 v[0:3], v[212:215], v[196:199], v[0:3]
	s_setprio 0
	s_add_i32 s61, s61, 2
	s_add_u32 s59, s59, 0x10000
	s_addc_u32 s60, s60, 0
	s_add_u32 s20, s20, 0x100
	s_addc_u32 s21, s21, 0
	s_cmp_gt_u32 s61, 29
	s_barrier
	s_cbranch_scc0 .LBB0_904
	s_cmp_eq_u32 s78, 0
	s_cbranch_scc0 .Lhalf_skip_x_6
	s_barrier
; __device__ __forceinline__ unsigned cvt_pk_bf16(float lo, float hi) { unsigned r; asm volatile("v_cvt_pk_bf16_f32 %0, %1, %2" : "=v"(r) : "v"(lo), "v"(hi)); return r; }
; __device__ __forceinline__ float fast_sigmoid(float x) { return __builtin_amdgcn_rcpf(1.0f + __expf(-x)); }
;     __device__ __forceinline__ void operator()(const f32x4 (&acc)[2][2][4][2], const Unit& u, int wr, int wc, int fr, int fq) const {
;         const int row0 = u.pm * BM + wr * 64 + fr; const int col0 = u.pn * HALF + wc * 32 + 8 * fq;
; #pragma unroll
;         for (int ai = 0; ai < 2; ++ai)
; #pragma unroll
;             for (int m = 0; m < 4; ++m) { bf16_t* rowp = O + (size_t)(row0 + ai * HALF + m * 16) * ldc + col0;
;                 f32x4 a0 = acc[ai][0][m][0], a1 = acc[ai][0][m][1], b0 = acc[ai][1][m][0], b1 = acc[ai][1][m][1]; f32x4 v0, v1;
; #pragma unroll
;                 for (int j = 0; j < 4; ++j) { v0[j] = a0[j] * fast_sigmoid(a0[j]) * b0[j]; v1[j] = a1[j] * fast_sigmoid(a1[j]) * b1[j]; }
;                 u32x4 w; w.x = cvt_pk_bf16(v0[0], v0[1]); w.y = cvt_pk_bf16(v0[2], v0[3]); w.z = cvt_pk_bf16(v1[0], v1[1]); w.w = cvt_pk_bf16(v1[2], v1[3]);
;                 __builtin_nontemporal_store(w, (u32x4*)rowp); }
.Lhalf_skip_x_6:
	v_mul_f32_e32 v144, 0xbfb8aa3b, v124
	v_exp_f32_e32 v153, v144
	v_mul_f32_e32 v144, 0xbfb8aa3b, v120
	v_exp_f32_e32 v156, v144
	v_lshl_or_b32 v154, s56, 7, v148
	v_add_f32_e32 v153, 1.0, v153
	v_rcp_f32_e32 v153, v153
	v_add_f32_e32 v156, 1.0, v156
	v_rcp_f32_e32 v158, v156
	v_lshl_add_u32 v152, s18, 8, v146
	v_mul_f32_e32 v124, v124, v153
	v_mul_f32_e32 v116, v124, v116
	v_mul_f32_e32 v124, 0xbfb8aa3b, v125
	v_exp_f32_e32 v124, v124
	v_mul_f32_e32 v153, 0xbfb8aa3b, v121
	v_exp_f32_e32 v153, v153
	v_mul_f32_e32 v120, v120, v158
	v_mul_f32_e32 v120, v120, v112
	v_add_f32_e32 v112, 1.0, v124
	v_rcp_f32_e32 v112, v112
	v_add_f32_e32 v124, 1.0, v153
	v_mul_f32_e32 v153, 0xbfb8aa3b, v126
	v_rcp_f32_e32 v124, v124
	v_exp_f32_e32 v153, v153
	v_mul_f32_e32 v112, v125, v112
	v_mul_f32_e32 v117, v112, v117
	v_mul_f32_e32 v112, v121, v124
	v_add_f32_e32 v121, 1.0, v153
	v_rcp_f32_e32 v121, v121
	v_mul_f32_e32 v124, 0xbfb8aa3b, v122
	v_exp_f32_e32 v124, v124
	v_mul_f32_e32 v125, v112, v113
	v_mul_f32_e32 v112, v126, v121
	v_mul_f32_e32 v113, 0xbfb8aa3b, v127
	v_mul_f32_e32 v121, v112, v118
	v_exp_f32_e32 v113, v113
	v_mul_f32_e32 v118, 0xbfb8aa3b, v123
	v_exp_f32_e32 v118, v118
	v_add_f32_e32 v112, 1.0, v124
	v_rcp_f32_e32 v112, v112
	v_add_f32_e32 v113, 1.0, v113
	v_rcp_f32_e32 v113, v113
	v_add_f32_e32 v118, 1.0, v118
	v_rcp_f32_e32 v118, v118
	v_mul_f32_e32 v112, v122, v112
	v_mul_f32_e32 v122, v112, v114
	v_mul_f32_e32 v112, v127, v113
	v_ashrrev_i32_e32 v155, 31, v154
	v_mov_b64_e32 v[144:145], s[6:7]
	v_mul_f32_e32 v124, v112, v119
	v_mul_f32_e32 v112, v123, v118
	v_mad_i64_i32 v[156:157], s[20:21], v152, s55, v[144:145]
	v_mul_f32_e32 v123, v112, v115
	v_lshlrev_b64 v[112:113], 1, v[154:155]
	v_lshl_add_u64 v[118:119], v[156:157], 0, v[112:113]
	v_cvt_pk_bf16_f32 v114, v116, v117
	v_cvt_pk_bf16_f32 v115, v121, v124
	v_cvt_pk_bf16_f32 v116, v120, v125
	v_cvt_pk_bf16_f32 v117, v122, v123
	global_store_dwordx4 v[118:119], v[114:117], off nt
	s_and_b64 vcc, exec, s[4:5]
	s_mov_b32 s56, s12
	v_mul_f32_e32 v114, 0xbfb8aa3b, v108
	v_exp_f32_e32 v114, v114
	v_mul_f32_e32 v115, 0xbfb8aa3b, v104
	v_exp_f32_e32 v115, v115
	v_or_b32_e32 v116, 16, v152
	v_add_f32_e32 v114, 1.0, v114
	v_rcp_f32_e32 v117, v114
	v_add_f32_e32 v114, 1.0, v115
	v_rcp_f32_e32 v118, v114
	v_mad_i64_i32 v[114:115], s[20:21], v116, s55, v[144:145]
	v_mul_f32_e32 v108, v108, v117
	v_mul_f32_e32 v108, v108, v100
	v_mul_f32_e32 v100, v104, v118
	v_mul_f32_e32 v104, 0xbfb8aa3b, v109
	v_exp_f32_e32 v104, v104
	v_mul_f32_e32 v116, 0xbfb8aa3b, v105
	v_mul_f32_e32 v117, v100, v96
	v_exp_f32_e32 v116, v116
	v_add_f32_e32 v96, 1.0, v104
	v_rcp_f32_e32 v96, v96
	v_mul_f32_e32 v104, 0xbfb8aa3b, v110
	v_exp_f32_e32 v104, v104
	v_add_f32_e32 v100, 1.0, v116
	v_mul_f32_e32 v96, v109, v96
	v_rcp_f32_e32 v100, v100
	v_mul_f32_e32 v96, v96, v101
	v_add_f32_e32 v101, 1.0, v104
	v_rcp_f32_e32 v101, v101
	v_mul_f32_e32 v100, v105, v100
	v_mul_f32_e32 v104, 0xbfb8aa3b, v106
	v_mul_f32_e32 v105, v100, v97
	v_mul_f32_e32 v97, v110, v101
	v_exp_f32_e32 v104, v104
	v_mul_f32_e32 v97, v97, v102
	v_mul_f32_e32 v101, 0xbfb8aa3b, v111
	v_mul_f32_e32 v102, 0xbfb8aa3b, v107
	v_exp_f32_e32 v101, v101
	v_exp_f32_e32 v102, v102
	v_add_f32_e32 v100, 1.0, v104
	v_rcp_f32_e32 v100, v100
	v_add_f32_e32 v101, 1.0, v101
	v_add_f32_e32 v102, 1.0, v102
	v_rcp_f32_e32 v101, v101
	v_rcp_f32_e32 v102, v102
	v_mul_f32_e32 v100, v106, v100
	v_mul_f32_e32 v104, v100, v98
	v_mul_f32_e32 v98, v111, v101
	v_mul_f32_e32 v100, v107, v102
	v_mul_f32_e32 v98, v98, v103
	v_mul_f32_e32 v99, v100, v99
	v_lshl_add_u64 v[100:101], v[114:115], 0, v[112:113]
	v_cvt_pk_bf16_f32 v96, v108, v96
	v_cvt_pk_bf16_f32 v97, v97, v98
	v_cvt_pk_bf16_f32 v98, v117, v105
	v_cvt_pk_bf16_f32 v99, v104, v99
	global_store_dwordx4 v[100:101], v[96:99], off nt
	s_mov_b32 s18, s10
	s_mov_b64 s[22:23], s[14:15]
	v_mul_f32_e32 v96, 0xbfb8aa3b, v92
	v_exp_f32_e32 v96, v96
	v_mul_f32_e32 v97, 0xbfb8aa3b, v88
	v_exp_f32_e32 v97, v97
	v_or_b32_e32 v98, 32, v152
	v_add_f32_e32 v96, 1.0, v96
	v_rcp_f32_e32 v99, v96
	v_add_f32_e32 v96, 1.0, v97
	v_rcp_f32_e32 v100, v96
	v_mad_i64_i32 v[96:97], s[20:21], v98, s55, v[144:145]
	v_mul_f32_e32 v92, v92, v99
	v_mul_f32_e32 v92, v92, v84
	v_mul_f32_e32 v84, v88, v100
	v_mul_f32_e32 v88, 0xbfb8aa3b, v93
	v_exp_f32_e32 v88, v88
	v_mul_f32_e32 v98, 0xbfb8aa3b, v89
	v_mul_f32_e32 v99, v84, v80
	v_exp_f32_e32 v98, v98
	v_add_f32_e32 v80, 1.0, v88
	v_rcp_f32_e32 v80, v80
	v_mul_f32_e32 v88, 0xbfb8aa3b, v94
	v_exp_f32_e32 v88, v88
	v_add_f32_e32 v84, 1.0, v98
	v_mul_f32_e32 v80, v93, v80
	v_rcp_f32_e32 v84, v84
	v_mul_f32_e32 v80, v80, v85
	v_add_f32_e32 v85, 1.0, v88
	v_rcp_f32_e32 v85, v85
	v_mul_f32_e32 v84, v89, v84
	v_mul_f32_e32 v88, 0xbfb8aa3b, v90
	v_mul_f32_e32 v89, v84, v81
	v_mul_f32_e32 v81, v94, v85
	v_exp_f32_e32 v88, v88
	v_mul_f32_e32 v81, v81, v86
	v_mul_f32_e32 v85, 0xbfb8aa3b, v95
	v_mul_f32_e32 v86, 0xbfb8aa3b, v91
	v_exp_f32_e32 v85, v85
	v_exp_f32_e32 v86, v86
	v_add_f32_e32 v84, 1.0, v88
	v_rcp_f32_e32 v84, v84
	v_add_f32_e32 v85, 1.0, v85
	v_add_f32_e32 v86, 1.0, v86
	v_rcp_f32_e32 v85, v85
	v_rcp_f32_e32 v86, v86
	v_mul_f32_e32 v84, v90, v84
	v_mul_f32_e32 v88, v84, v82
	v_mul_f32_e32 v82, v95, v85
	v_mul_f32_e32 v84, v91, v86
	v_mul_f32_e32 v82, v82, v87
	v_mul_f32_e32 v83, v84, v83
	v_lshl_add_u64 v[84:85], v[96:97], 0, v[112:113]
	v_cvt_pk_bf16_f32 v80, v92, v80
	v_cvt_pk_bf16_f32 v81, v81, v82
	v_cvt_pk_bf16_f32 v82, v99, v89
	v_cvt_pk_bf16_f32 v83, v88, v83
	global_store_dwordx4 v[84:85], v[80:83], off nt
	s_nop 1
	v_mul_f32_e32 v80, 0xbfb8aa3b, v76
	v_exp_f32_e32 v80, v80
; __device__ __forceinline__ unsigned cvt_pk_bf16(float lo, float hi) { unsigned r; asm volatile("v_cvt_pk_bf16_f32 %0, %1, %2" : "=v"(r) : "v"(lo), "v"(hi)); return r; }
; __device__ __forceinline__ float fast_sigmoid(float x) { return __builtin_amdgcn_rcpf(1.0f + __expf(-x)); }
;     __device__ __forceinline__ void operator()(const f32x4 (&acc)[2][2][4][2], const Unit& u, int wr, int wc, int fr, int fq) const {
;         const int row0 = u.pm * BM + wr * 64 + fr; const int col0 = u.pn * HALF + wc * 32 + 8 * fq;
; #pragma unroll
;         for (int ai = 0; ai < 2; ++ai)
; #pragma unroll
;             for (int m = 0; m < 4; ++m) { bf16_t* rowp = O + (size_t)(row0 + ai * HALF + m * 16) * ldc + col0;
;                 f32x4 a0 = acc[ai][0][m][0], a1 = acc[ai][0][m][1], b0 = acc[ai][1][m][0], b1 = acc[ai][1][m][1]; f32x4 v0, v1;
; #pragma unroll
;                 for (int j = 0; j < 4; ++j) { v0[j] = a0[j] * fast_sigmoid(a0[j]) * b0[j]; v1[j] = a1[j] * fast_sigmoid(a1[j]) * b1[j]; }
;                 u32x4 w; w.x = cvt_pk_bf16(v0[0], v0[1]); w.y = cvt_pk_bf16(v0[2], v0[3]); w.z = cvt_pk_bf16(v1[0], v1[1]); w.w = cvt_pk_bf16(v1[2], v1[3]);
;                 __builtin_nontemporal_store(w, (u32x4*)rowp); }
	v_mul_f32_e32 v81, 0xbfb8aa3b, v72
	v_exp_f32_e32 v81, v81
	v_or_b32_e32 v82, 48, v152
	v_add_f32_e32 v80, 1.0, v80
	v_rcp_f32_e32 v83, v80
	v_add_f32_e32 v80, 1.0, v81
	v_rcp_f32_e32 v84, v80
	v_mad_i64_i32 v[80:81], s[20:21], v82, s55, v[144:145]
	v_mul_f32_e32 v76, v76, v83
	v_mul_f32_e32 v76, v76, v68
	v_mul_f32_e32 v68, v72, v84
	v_mul_f32_e32 v72, 0xbfb8aa3b, v77
	v_exp_f32_e32 v72, v72
	v_mul_f32_e32 v82, 0xbfb8aa3b, v73
	v_mul_f32_e32 v83, v68, v64
	v_exp_f32_e32 v82, v82
	v_add_f32_e32 v64, 1.0, v72
	v_rcp_f32_e32 v64, v64
	v_mul_f32_e32 v72, 0xbfb8aa3b, v78
	v_exp_f32_e32 v72, v72
	v_add_f32_e32 v68, 1.0, v82
	v_mul_f32_e32 v64, v77, v64
	v_rcp_f32_e32 v68, v68
	v_mul_f32_e32 v64, v64, v69
	v_add_f32_e32 v69, 1.0, v72
	v_rcp_f32_e32 v69, v69
	v_mul_f32_e32 v68, v73, v68
	v_mul_f32_e32 v72, 0xbfb8aa3b, v74
	v_mul_f32_e32 v73, v68, v65
	v_mul_f32_e32 v65, v78, v69
	v_exp_f32_e32 v72, v72
	v_mul_f32_e32 v65, v65, v70
	v_mul_f32_e32 v69, 0xbfb8aa3b, v79
	v_mul_f32_e32 v70, 0xbfb8aa3b, v75
	v_exp_f32_e32 v69, v69
	v_exp_f32_e32 v70, v70
	v_add_f32_e32 v68, 1.0, v72
	v_rcp_f32_e32 v68, v68
	v_add_f32_e32 v69, 1.0, v69
	v_add_f32_e32 v70, 1.0, v70
	v_rcp_f32_e32 v69, v69
	v_rcp_f32_e32 v70, v70
	v_mul_f32_e32 v68, v74, v68
	v_mul_f32_e32 v72, v68, v66
	v_mul_f32_e32 v66, v79, v69
	v_mul_f32_e32 v68, v75, v70
	v_mul_f32_e32 v66, v66, v71
	v_mul_f32_e32 v67, v68, v67
	v_lshl_add_u64 v[68:69], v[80:81], 0, v[112:113]
	v_cvt_pk_bf16_f32 v64, v76, v64
	v_cvt_pk_bf16_f32 v65, v65, v66
	v_cvt_pk_bf16_f32 v66, v83, v73
	v_cvt_pk_bf16_f32 v67, v72, v67
	global_store_dwordx4 v[68:69], v[64:67], off nt
	s_nop 1
	v_mul_f32_e32 v64, 0xbfb8aa3b, v60
	v_exp_f32_e32 v64, v64
	v_mul_f32_e32 v65, 0xbfb8aa3b, v56
	v_exp_f32_e32 v65, v65
	v_add_u32_e32 v66, 0x80, v152
	v_add_f32_e32 v64, 1.0, v64
	v_rcp_f32_e32 v67, v64
	v_add_f32_e32 v64, 1.0, v65
	v_rcp_f32_e32 v68, v64
	v_mad_i64_i32 v[64:65], s[20:21], v66, s55, v[144:145]
	v_mul_f32_e32 v60, v60, v67
	v_mul_f32_e32 v60, v60, v52
	v_mul_f32_e32 v52, v56, v68
	v_mul_f32_e32 v56, 0xbfb8aa3b, v61
	v_exp_f32_e32 v56, v56
	v_mul_f32_e32 v66, 0xbfb8aa3b, v57
	v_mul_f32_e32 v67, v52, v48
	v_exp_f32_e32 v66, v66
	v_add_f32_e32 v48, 1.0, v56
	v_rcp_f32_e32 v48, v48
	v_mul_f32_e32 v56, 0xbfb8aa3b, v62
	v_exp_f32_e32 v56, v56
	v_add_f32_e32 v52, 1.0, v66
	v_mul_f32_e32 v48, v61, v48
	v_rcp_f32_e32 v52, v52
	v_mul_f32_e32 v48, v48, v53
	v_add_f32_e32 v53, 1.0, v56
	v_rcp_f32_e32 v53, v53
	v_mul_f32_e32 v52, v57, v52
	v_mul_f32_e32 v56, 0xbfb8aa3b, v58
	v_mul_f32_e32 v57, v52, v49
	v_mul_f32_e32 v49, v62, v53
	v_exp_f32_e32 v56, v56
	v_mul_f32_e32 v49, v49, v54
	v_mul_f32_e32 v53, 0xbfb8aa3b, v63
	v_mul_f32_e32 v54, 0xbfb8aa3b, v59
	v_exp_f32_e32 v53, v53
	v_exp_f32_e32 v54, v54
	v_add_f32_e32 v52, 1.0, v56
	v_rcp_f32_e32 v52, v52
	v_add_f32_e32 v53, 1.0, v53
	v_add_f32_e32 v54, 1.0, v54
	v_rcp_f32_e32 v53, v53
	v_rcp_f32_e32 v54, v54
	v_mul_f32_e32 v52, v58, v52
	v_mul_f32_e32 v56, v52, v50
	v_mul_f32_e32 v50, v63, v53
	v_mul_f32_e32 v52, v59, v54
	v_mul_f32_e32 v50, v50, v55
	v_mul_f32_e32 v51, v52, v51
	v_lshl_add_u64 v[52:53], v[64:65], 0, v[112:113]
	v_cvt_pk_bf16_f32 v48, v60, v48
	v_cvt_pk_bf16_f32 v49, v49, v50
	v_cvt_pk_bf16_f32 v50, v67, v57
	v_cvt_pk_bf16_f32 v51, v56, v51
	global_store_dwordx4 v[52:53], v[48:51], off nt
	s_nop 1
	v_mul_f32_e32 v48, 0xbfb8aa3b, v44
	v_exp_f32_e32 v48, v48
	v_mul_f32_e32 v49, 0xbfb8aa3b, v40
	v_exp_f32_e32 v49, v49
	v_add_u32_e32 v50, 0x90, v152
	v_add_f32_e32 v48, 1.0, v48
	v_rcp_f32_e32 v51, v48
	v_add_f32_e32 v48, 1.0, v49
	v_rcp_f32_e32 v52, v48
	v_mad_i64_i32 v[48:49], s[20:21], v50, s55, v[144:145]
	v_mul_f32_e32 v44, v44, v51
	v_mul_f32_e32 v44, v44, v36
	v_mul_f32_e32 v36, v40, v52
	v_mul_f32_e32 v40, 0xbfb8aa3b, v45
	v_exp_f32_e32 v40, v40
	v_mul_f32_e32 v50, 0xbfb8aa3b, v41
	v_mul_f32_e32 v51, v36, v32
	v_exp_f32_e32 v50, v50
	v_add_f32_e32 v32, 1.0, v40
	v_rcp_f32_e32 v32, v32
	v_mul_f32_e32 v40, 0xbfb8aa3b, v46
	v_exp_f32_e32 v40, v40
	v_add_f32_e32 v36, 1.0, v50
	v_mul_f32_e32 v32, v45, v32
	v_rcp_f32_e32 v36, v36
	v_mul_f32_e32 v32, v32, v37
	v_add_f32_e32 v37, 1.0, v40
	v_rcp_f32_e32 v37, v37
	v_mul_f32_e32 v36, v41, v36
	v_mul_f32_e32 v40, 0xbfb8aa3b, v42
; __device__ __forceinline__ unsigned cvt_pk_bf16(float lo, float hi) { unsigned r; asm volatile("v_cvt_pk_bf16_f32 %0, %1, %2" : "=v"(r) : "v"(lo), "v"(hi)); return r; }
; __device__ __forceinline__ float fast_sigmoid(float x) { return __builtin_amdgcn_rcpf(1.0f + __expf(-x)); }
;     __device__ __forceinline__ void operator()(const f32x4 (&acc)[2][2][4][2], const Unit& u, int wr, int wc, int fr, int fq) const {
;         const int row0 = u.pm * BM + wr * 64 + fr; const int col0 = u.pn * HALF + wc * 32 + 8 * fq;
; #pragma unroll
;         for (int ai = 0; ai < 2; ++ai)
; #pragma unroll
;             for (int m = 0; m < 4; ++m) { bf16_t* rowp = O + (size_t)(row0 + ai * HALF + m * 16) * ldc + col0;
;                 f32x4 a0 = acc[ai][0][m][0], a1 = acc[ai][0][m][1], b0 = acc[ai][1][m][0], b1 = acc[ai][1][m][1]; f32x4 v0, v1;
; #pragma unroll
;                 for (int j = 0; j < 4; ++j) { v0[j] = a0[j] * fast_sigmoid(a0[j]) * b0[j]; v1[j] = a1[j] * fast_sigmoid(a1[j]) * b1[j]; }
;                 u32x4 w; w.x = cvt_pk_bf16(v0[0], v0[1]); w.y = cvt_pk_bf16(v0[2], v0[3]); w.z = cvt_pk_bf16(v1[0], v1[1]); w.w = cvt_pk_bf16(v1[2], v1[3]);
;                 __builtin_nontemporal_store(w, (u32x4*)rowp); }
; template <class Epi, class Sched>
; __device__ __forceinline__ void gemm_phase(PG8_LAS unsigned char* lds, const Gemm g, const Sched& S, const Epi& E) {
;     ...
;         if (!has_next) break;
	v_mul_f32_e32 v41, v36, v33
	v_mul_f32_e32 v33, v46, v37
	v_exp_f32_e32 v40, v40
	v_mul_f32_e32 v33, v33, v38
	v_mul_f32_e32 v37, 0xbfb8aa3b, v47
	v_mul_f32_e32 v38, 0xbfb8aa3b, v43
	v_exp_f32_e32 v37, v37
	v_exp_f32_e32 v38, v38
	v_add_f32_e32 v36, 1.0, v40
	v_rcp_f32_e32 v36, v36
	v_add_f32_e32 v37, 1.0, v37
	v_add_f32_e32 v38, 1.0, v38
	v_rcp_f32_e32 v37, v37
	v_rcp_f32_e32 v38, v38
	v_mul_f32_e32 v36, v42, v36
	v_mul_f32_e32 v40, v36, v34
	v_mul_f32_e32 v34, v47, v37
	v_mul_f32_e32 v36, v43, v38
	v_mul_f32_e32 v34, v34, v39
	v_mul_f32_e32 v35, v36, v35
	v_lshl_add_u64 v[36:37], v[48:49], 0, v[112:113]
	v_cvt_pk_bf16_f32 v32, v44, v32
	v_cvt_pk_bf16_f32 v33, v33, v34
	v_cvt_pk_bf16_f32 v34, v51, v41
	v_cvt_pk_bf16_f32 v35, v40, v35
	global_store_dwordx4 v[36:37], v[32:35], off nt
	s_nop 1
	v_mul_f32_e32 v32, 0xbfb8aa3b, v28
	v_exp_f32_e32 v32, v32
	v_mul_f32_e32 v33, 0xbfb8aa3b, v24
	v_exp_f32_e32 v33, v33
	v_add_u32_e32 v34, 0xa0, v152
	v_add_f32_e32 v32, 1.0, v32
	v_rcp_f32_e32 v35, v32
	v_add_f32_e32 v32, 1.0, v33
	v_rcp_f32_e32 v36, v32
	v_mad_i64_i32 v[32:33], s[20:21], v34, s55, v[144:145]
	v_mul_f32_e32 v28, v28, v35
	v_mul_f32_e32 v28, v28, v20
	v_mul_f32_e32 v20, v24, v36
	v_mul_f32_e32 v24, 0xbfb8aa3b, v29
	v_exp_f32_e32 v24, v24
	v_mul_f32_e32 v34, 0xbfb8aa3b, v25
	v_mul_f32_e32 v35, v20, v16
	v_exp_f32_e32 v34, v34
	v_add_f32_e32 v16, 1.0, v24
	v_rcp_f32_e32 v16, v16
	v_mul_f32_e32 v24, 0xbfb8aa3b, v30
	v_exp_f32_e32 v24, v24
	v_add_f32_e32 v20, 1.0, v34
	v_mul_f32_e32 v16, v29, v16
	v_rcp_f32_e32 v20, v20
	v_mul_f32_e32 v16, v16, v21
	v_add_f32_e32 v21, 1.0, v24
	v_rcp_f32_e32 v21, v21
	v_mul_f32_e32 v20, v25, v20
	v_mul_f32_e32 v24, 0xbfb8aa3b, v26
	v_mul_f32_e32 v25, v20, v17
	v_mul_f32_e32 v17, v30, v21
	v_exp_f32_e32 v24, v24
	v_mul_f32_e32 v17, v17, v22
	v_mul_f32_e32 v21, 0xbfb8aa3b, v31
	v_mul_f32_e32 v22, 0xbfb8aa3b, v27
	v_exp_f32_e32 v21, v21
	v_exp_f32_e32 v22, v22
	v_add_f32_e32 v20, 1.0, v24
	v_rcp_f32_e32 v20, v20
	v_add_f32_e32 v21, 1.0, v21
	v_add_f32_e32 v22, 1.0, v22
	v_rcp_f32_e32 v21, v21
	v_rcp_f32_e32 v22, v22
	v_mul_f32_e32 v20, v26, v20
	v_mul_f32_e32 v24, v20, v18
	v_mul_f32_e32 v18, v31, v21
	v_mul_f32_e32 v20, v27, v22
	v_mul_f32_e32 v18, v18, v23
	v_mul_f32_e32 v19, v20, v19
	v_lshl_add_u64 v[20:21], v[32:33], 0, v[112:113]
	v_cvt_pk_bf16_f32 v16, v28, v16
	v_cvt_pk_bf16_f32 v17, v17, v18
	v_cvt_pk_bf16_f32 v18, v35, v25
	v_cvt_pk_bf16_f32 v19, v24, v19
	global_store_dwordx4 v[20:21], v[16:19], off nt
	s_nop 1
	v_mul_f32_e32 v16, 0xbfb8aa3b, v12
	v_exp_f32_e32 v16, v16
	v_mul_f32_e32 v17, 0xbfb8aa3b, v8
	v_exp_f32_e32 v17, v17
	v_add_u32_e32 v18, 0xb0, v152
	v_add_f32_e32 v16, 1.0, v16
	v_rcp_f32_e32 v19, v16
	v_add_f32_e32 v16, 1.0, v17
	v_rcp_f32_e32 v20, v16
	v_mad_i64_i32 v[16:17], s[20:21], v18, s55, v[144:145]
	v_mul_f32_e32 v12, v12, v19
	v_mul_f32_e32 v12, v12, v4
	v_mul_f32_e32 v4, v8, v20
	v_mul_f32_e32 v8, 0xbfb8aa3b, v13
	v_exp_f32_e32 v8, v8
	v_mul_f32_e32 v18, 0xbfb8aa3b, v9
	v_mul_f32_e32 v19, v4, v0
	v_exp_f32_e32 v18, v18
	v_add_f32_e32 v0, 1.0, v8
	v_rcp_f32_e32 v0, v0
	v_mul_f32_e32 v8, 0xbfb8aa3b, v14
	v_exp_f32_e32 v8, v8
	v_add_f32_e32 v4, 1.0, v18
	v_mul_f32_e32 v0, v13, v0
	v_rcp_f32_e32 v4, v4
	v_mul_f32_e32 v0, v0, v5
	v_add_f32_e32 v5, 1.0, v8
	v_rcp_f32_e32 v5, v5
	v_mul_f32_e32 v4, v9, v4
	v_mul_f32_e32 v8, 0xbfb8aa3b, v10
	v_mul_f32_e32 v9, v4, v1
	v_mul_f32_e32 v1, v14, v5
	v_exp_f32_e32 v8, v8
	v_mul_f32_e32 v1, v1, v6
	v_mul_f32_e32 v5, 0xbfb8aa3b, v15
	v_mul_f32_e32 v6, 0xbfb8aa3b, v11
	v_exp_f32_e32 v5, v5
	v_exp_f32_e32 v6, v6
	v_add_f32_e32 v4, 1.0, v8
	v_rcp_f32_e32 v4, v4
	v_add_f32_e32 v5, 1.0, v5
	v_add_f32_e32 v6, 1.0, v6
	v_rcp_f32_e32 v5, v5
	v_rcp_f32_e32 v6, v6
	v_mul_f32_e32 v4, v10, v4
	v_mul_f32_e32 v8, v4, v2
	v_mul_f32_e32 v2, v15, v5
	v_mul_f32_e32 v4, v11, v6
	v_mul_f32_e32 v2, v2, v7
	v_mul_f32_e32 v3, v4, v3
	v_lshl_add_u64 v[4:5], v[16:17], 0, v[112:113]
	s_mov_b64 s[20:21], s[16:17]
	v_cvt_pk_bf16_f32 v0, v12, v0
	v_cvt_pk_bf16_f32 v1, v1, v2
	v_cvt_pk_bf16_f32 v2, v19, v9
	v_cvt_pk_bf16_f32 v3, v8, v3
	global_store_dwordx4 v[4:5], v[0:3], off nt
	s_cbranch_vccz .LBB0_901
	s_waitcnt vmcnt(0)
	s_cmpk_gt_u32 s28, 0xff
	s_cbranch_scc1 .LBB0_908

;     __host__ __device__ bool next(int i, Unit& u) const { const int j = i / 3; if (!StaticOrder::next(j, u)) return false; u.br = i - 3 * j; return true; }
; #define PG8_STAGE(bufoff, gbase, voff) do { _Pragma("unroll") for (int _i = 0; _i < 2; ++_i) \
;         __builtin_amdgcn_global_load_lds((const unsigned*)((const char*)(gbase) + (voff)[_i]), (PG8_LAS unsigned*)(lds + (bufoff) + ldsw + _i * 8192), 16, 0, 0); } while (0)
; template <class Epi, class Sched>
; __device__ __forceinline__ void gemm_phase(PG8_LAS unsigned char* lds, const Gemm g, const Sched& S, const Epi& E) {
;     ...
;     const int tid = tix_, wid = __builtin_amdgcn_readfirstlane(tid >> 6), lane = tid & 63, wr = wid >> 2, wc = wid & 3, fr = lane & 15, fq = lane >> 4;
;     const int K = g.K, nt = K / BK;
;     unsigned voffA[2], voffB[2];
; #pragma unroll
;     for (int i = 0; i < 2; ++i) { int R, C; stage_rc(tid * 16 + i * 8192, R, C);
;         voffA[i] = (unsigned)(R * K + C) * 2u; voffB[i] = (unsigned)(tid * 16 + i * 8192); }
;     const size_t kstep = (size_t)(BK * 2);
;     const size_t hstep = (size_t)HALF * K * 2;
;     const size_t tstep = 2 * hstep;
;     const size_t kstepB = 32768, hstepB = 16384, tstepB = (size_t)nt * 32768;
;     const unsigned ldsw = (unsigned)wid * 1024u;
;     const int aoff = lds_byte(wr * 64 + fr, fq * 8), boff = lds_byte(wc * 32 + fr, fq * 8);
;     ...
;     Unit cur, nxt; int ui = 0;
;     if (!S.next(0, cur)) return;
;     f32x4 acc[2][2][4][2];
; #pragma unroll
;     for (int a = 0; a < 2; ++a)
; #pragma unroll
;         for (int b = 0; b < 2; ++b)
; #pragma unroll
;             for (int m = 0; m < 4; ++m)
; #pragma unroll
;                 for (int n = 0; n < 2; ++n) acc[a][b][m][n] = (f32x4){0.f, 0.f, 0.f, 0.f};
;     bf16x8 At[4][2], B0[2][2], B1[2][2];
;     const char* cA = (const char*)g.A + (size_t)cur.pm * tstep + (size_t)cur.br * g.strideA; const char* cB = (const char*)g.Bt + (size_t)cur.pn * tstepB + (size_t)cur.br * g.strideB;
;     S.a_ready(cur);
;     PG8_STAGE(PG8_SB(0, 0), cB, voffB); PG8_STAGE(PG8_SA(0, 0), cA, voffA); PG8_STAGE(PG8_SB(0, 1), cB + hstepB, voffB); PG8_STAGE(PG8_SA(0, 1), cA + hstep, voffA);
;     if (wr == 1) PG8_BAR;
;     PG8_WAIT_V(4); PG8_BAR;
;     PG8_STAGE(PG8_SB(1, 0), cB + kstepB, voffB); PG8_STAGE(PG8_SA(1, 0), cA + kstep, voffA); PG8_STAGE(PG8_SB(1, 1), cB + hstepB + kstepB, voffB);
;     PG8_WAIT_V(6); PG8_BAR;
.LBB0_966:
	v_ashrrev_i32_e32 v0, 31, v4
	v_lshrrev_b32_e32 v0, 26, v0
	v_add_u32_e32 v0, v4, v0
	v_ashrrev_i32_e32 v5, 6, v0
	v_bfe_i32 v0, v4, 27, 1
	v_lshlrev_b32_e32 v164, 4, v4
	v_lshrrev_b32_e32 v0, 22, v0
	v_add_u32_e32 v0, v164, v0
	v_and_b32_e32 v0, 0xfffffc00, v0
	v_sub_u32_e32 v0, v164, v0
	v_lshrrev_b32_e32 v1, 4, v0
	v_bitop3_b32 v0, v1, v0, 32 bitop3:0x6c
	v_ashrrev_i32_e32 v2, 31, v0
	v_lshrrev_b32_e32 v2, 26, v2
	s_waitcnt lgkmcnt(0)
	s_add_u32 s38, s4, 0x10700000
	v_add_u32_e32 v2, v0, v2
	s_addc_u32 s39, s5, 0
	v_lshlrev_b32_e32 v1, 3, v5
	v_ashrrev_i32_e32 v7, 6, v2
	v_and_b32_e32 v2, 0xc0, v2
	s_add_u32 s46, s4, 0xb180000
	v_and_b32_e32 v1, 0x1fffff0, v1
	v_sub_u32_e32 v0, v0, v2
	v_mov_b32_e32 v2, 1
	s_addc_u32 s47, s5, 0
	v_add_u32_e32 v1, v7, v1
	v_lshlrev_b32_e32 v3, 5, v5
	v_ashrrev_i16_sdwa v0, v2, sext(v0) dst_sel:DWORD dst_unused:UNUSED_PAD src0_sel:DWORD src1_sel:BYTE_0
	s_movk_i32 s6, 0x1580
	s_add_i32 s9, s9, s10
	v_and_b32_e32 v6, 32, v3
	v_bfe_i32 v8, v0, 0, 16
	v_mul_lo_u32 v0, v1, s6
	s_sext_i32_i16 s10, s9
	v_or_b32_e32 v0, v0, v6
	v_add_u32_e32 v168, 0x2000, v164
	s_bfe_u32 s10, s10, 0x5001a
	v_add_lshl_u32 v166, v0, v8, 1
	v_ashrrev_i32_e32 v0, 31, v168
	s_add_i32 s10, s9, s10
	v_lshrrev_b32_e32 v0, 22, v0
	s_sext_i32_i16 s11, s10
	s_and_b32 s10, s10, 0xffe0
	v_add_u32_e32 v0, v168, v0
	s_sub_i32 s10, s9, s10
	v_ashrrev_i32_e32 v9, 10, v0
	s_bfe_i32 s9, s10, 0x80000
	v_mul_i32_i24_e32 v0, 0x400, v9
	s_bfe_u32 s9, s9, 0x2000d
	v_sub_u32_e32 v0, v168, v0
	s_add_i32 s12, s10, s9
	v_lshrrev_b32_e32 v1, 4, v0
	s_bfe_i32 s9, s12, 0x80000
	s_and_b32 s12, s12, 0xfc
	v_bitop3_b32 v0, v1, v0, 32 bitop3:0x6c
	s_ashr_i32 s11, s11, 5
	s_sext_i32_i16 s13, s9
	s_sub_i32 s10, s10, s12
	s_ashr_i32 s7, s36, 6
	v_ashrrev_i32_e32 v3, 31, v0
	s_lshl_b32 s11, s11, 2
	s_sext_i32_i8 s10, s10
	s_ashr_i32 s12, s13, 2
	v_lshrrev_b32_e32 v3, 26, v3
	s_ashr_i32 s8, s36, 8
	s_lshl_b32 s48, s7, 10
	s_lshr_b32 s9, s13, 2
	s_add_i32 s61, s11, s10
	s_mul_hi_i32 s13, s12, 0x2b0000
	s_mul_i32 s12, s12, 0x2b0000
	v_add_u32_e32 v3, v0, v3
	s_add_u32 s24, s46, s12
	v_lshlrev_b32_e32 v1, 3, v9
	v_ashrrev_i32_e32 v10, 6, v3
	v_and_b32_e32 v3, 0xc0, v3
	s_addc_u32 s25, s47, s13
	s_add_i32 s49, s48, 0
	v_and_b32_e32 v1, 0x1fffff0, v1
	v_sub_u32_e32 v0, v0, v3
	s_add_i32 m0, s49, 0x10000
	v_add_u32_e32 v1, v10, v1
	v_lshlrev_b32_e32 v11, 5, v9
	v_ashrrev_i16_sdwa v0, v2, sext(v0) dst_sel:DWORD dst_unused:UNUSED_PAD src0_sel:DWORD src1_sel:BYTE_0
	s_mul_i32 s11, s61, 0x2b0000
	global_load_lds_dwordx4 v164, s[24:25]
	s_add_i32 m0, s49, 0x12000
	v_and_b32_e32 v11, 32, v11
	v_bfe_i32 v12, v0, 0, 16
	v_mul_lo_u32 v0, v1, s6
	s_mul_hi_i32 s10, s61, 0x2b0000
	s_add_u32 s22, s38, s11
	v_or_b32_e32 v0, v0, v11
	global_load_lds_dwordx4 v168, s[24:25]
	s_addc_u32 s23, s39, s10
	s_mov_b32 m0, s49
	s_add_i32 s50, s49, 0x2000
	v_add_lshl_u32 v170, v0, v12, 1
	global_load_lds_dwordx4 v166, s[22:23]
	s_mov_b32 m0, s50
	s_add_u32 s10, s24, 0x4000
	global_load_lds_dwordx4 v170, s[22:23]
	s_addc_u32 s11, s25, 0
	s_add_i32 m0, s49, 0x14000
	v_mov_b32_e32 v165, 0
	global_load_lds_dwordx4 v164, s[10:11]
	s_add_i32 m0, s49, 0x16000
	v_mov_b32_e32 v167, v165
	global_load_lds_dwordx4 v168, s[10:11]
	s_add_u32 s10, s22, 0x158000
	s_addc_u32 s11, s23, 0
	s_add_i32 s51, s49, 0x4000
	s_mov_b32 m0, s51
	s_add_i32 s52, s49, 0x6000
	global_load_lds_dwordx4 v166, s[10:11]
	s_mov_b32 m0, s52
	v_mov_b32_e32 v171, v165
	global_load_lds_dwordx4 v170, s[10:11]
	s_mov_b32 s53, 0
	v_mov_b32_e32 v169, v165
	v_lshl_add_u64 v[2:3], s[22:23], 0, v[166:167]
	s_cmp_lg_u32 s8, 1
	v_lshl_add_u64 v[0:1], s[22:23], 0, v[170:171]
	s_cbranch_scc1 .LBB0_968
.LBB0_968:
	s_add_u32 s10, s4, 0x2dd24000
	s_addc_u32 s11, s5, 0
	s_lshl_b32 s4, s7, 5
	s_and_b32 s7, s4, 0x60
	s_lshl_b32 s14, s8, 13
	s_lshl_b32 s15, s7, 7
	s_add_u32 s4, s24, 0x8000
	s_addc_u32 s5, s25, 0
	s_add_i32 m0, s49, 0x18000
	v_lshl_add_u64 v[14:15], s[4:5], 0, v[164:165]
	s_waitcnt vmcnt(4)
	s_barrier
	global_load_lds_dwordx4 v[14:15], off
	v_lshl_add_u64 v[14:15], s[4:5], 0, v[168:169]
	s_add_i32 m0, s49, 0x1a000
	s_mov_b64 s[12:13], 0x80
	s_add_i32 s54, s49, 0x8000
	s_add_i32 s55, s49, 0xa000
	global_load_lds_dwordx4 v[14:15], off
	v_lshl_add_u64 v[2:3], v[2:3], 0, s[12:13]
	s_mov_b32 m0, s54
	s_add_u32 s4, s24, 0xc000
	global_load_lds_dwordx4 v[2:3], off
	v_lshl_add_u64 v[0:1], v[0:1], 0, s[12:13]
	s_mov_b32 m0, s55
	s_addc_u32 s5, s25, 0
	global_load_lds_dwordx4 v[0:1], off
	s_add_i32 m0, s49, 0x1c000
	v_lshl_add_u64 v[0:1], s[4:5], 0, v[164:165]
	global_load_lds_dwordx4 v[0:1], off
	v_lshl_add_u64 v[0:1], s[4:5], 0, v[168:169]
	s_add_i32 m0, s49, 0x1e000
	s_add_i32 s57, 0, 0x10000
	global_load_lds_dwordx4 v[0:1], off
	v_lshrrev_b32_e32 v1, 1, v4
	v_and_b32_e32 v1, 24, v1
	v_and_b32_e32 v0, 15, v4
	v_lshlrev_b32_e32 v2, 1, v1
	v_lshl_or_b32 v194, s8, 6, v0
	v_lshl_or_b32 v0, v0, 6, v2
	v_lshlrev_b32_e32 v2, 2, v4
	v_and_b32_e32 v2, 32, v2
	v_bitop3_b32 v3, v0, s14, v2 bitop3:0xde
	v_bitop3_b32 v195, v0, s15, v2 bitop3:0xde
	v_or_b32_e32 v196, s7, v1
	v_lshrrev_b32_e32 v1, 1, v5
	v_mul_lo_u32 v0, v7, s6
	s_mov_b32 s7, 0x15800
	v_mad_u64_u32 v[0:1], s[4:5], v1, s7, v[0:1]
	v_or_b32_e32 v0, v0, v6
	v_add_lshl_u32 v0, v0, v8, 1
	v_mov_b32_e32 v1, v165
	s_mov_b64 s[4:5], 0x158080
	v_lshl_add_u64 v[172:173], v[0:1], 0, s[4:5]
	v_lshrrev_b32_e32 v1, 1, v9
	v_mul_lo_u32 v0, v10, s6
	v_mad_u64_u32 v[0:1], s[6:7], v1, s7, v[0:1]
	s_waitcnt vmcnt(6)
	v_or_b32_e32 v0, v0, v11
	v_add_lshl_u32 v0, v0, v12, 1
	v_mov_b32_e32 v1, v165
	s_add_i32 s58, 0, 0x14000
	s_sext_i32_i8 s62, s9
	s_ashr_i32 s56, s30, 31
	v_lshl_add_u64 v[174:175], v[0:1], 0, s[4:5]
	v_mov_b64_e32 v[176:177], 0x200
	v_mov_b64_e32 v[178:179], 0x1ff
	v_add_u32_e32 v197, s57, v195
	v_add_u32_e32 v198, 0, v3
	v_add_u32_e32 v199, s58, v195
	s_mov_b64 s[14:15], 0x80000
	s_mov_b64 s[16:17], 0x90000
	s_mov_b64 s[18:19], 0xa0000
	s_mov_b64 s[20:21], 0xb0000
	s_barrier

;     __host__ __device__ bool next(int i, Unit& u) const { const int j = i / 3; if (!StaticOrder::next(j, u)) return false; u.br = i - 3 * j; return true; }
; #define PG8_STAGE(bufoff, gbase, voff) do { _Pragma("unroll") for (int _i = 0; _i < 2; ++_i) \
;         __builtin_amdgcn_global_load_lds((const unsigned*)((const char*)(gbase) + (voff)[_i]), (PG8_LAS unsigned*)(lds + (bufoff) + ldsw + _i * 8192), 16, 0, 0); } while (0)
; #define PG8_LDA(dst, b, h) do { _Pragma("unroll") for (int m = 0; m < 4; ++m) _Pragma("unroll") for (int k = 0; k < 2; ++k) dst[m][k] = *(const PG8_LAS bf16x8*)(lds + PG8_SA(b, h) + aoff + m * 2048 + k * 1024); } while (0)
; #define PG8_LDB(dst, b, h) do { _Pragma("unroll") for (int n = 0; n < 2; ++n) _Pragma("unroll") for (int k = 0; k < 2; ++k) dst[n][k] = *(const PG8_LAS bf16x8*)(lds + PG8_SB(b, h) + boff + n * 2048 + k * 1024); } while (0)
; #define PG8_WAIT_L(n) asm volatile("s_waitcnt lgkmcnt(" #n ")" ::: "memory")
; #define PG8_BAR __builtin_amdgcn_s_barrier()
; template <class Epi, class Sched>
; __device__ __forceinline__ void gemm_phase(PG8_LAS unsigned char* lds, const Gemm g, const Sched& S, const Epi& E) {
;     ...
;         const bool has_next = S.next(ui + 1, nxt);
;         const char* nA = has_next ? (const char*)g.A + (size_t)nxt.pm * tstep + (size_t)nxt.br * g.strideA : cA; const char* nB = has_next ? (const char*)g.Bt + (size_t)nxt.pn * tstepB + (size_t)nxt.br * g.strideB : cB;
;         for (int t = 0; t < nt; t += 2) {
;             const bool last = (t == nt - 2);
;             const char* a1 = cA + (size_t)(t + 1) * kstep;
;             const char* a2 = last ? nA : cA + (size_t)(t + 2) * kstep; const char* b2 = last ? nB : cB + (size_t)(t + 2) * kstepB;
;             const char* a3 = a2 + kstep; const char* b3 = b2 + kstepB;
;             if (last && has_next) S.a_ready(nxt);
;             PG8_LDB(B0, 0, 0); PG8_SCHED; PG8_LDA(At, 0, 0); PG8_STAGE(PG8_SA(1, 1), a1 + hstep, voffA);
;             PG8_WAIT_L(8); PG8_BAR; PG8_WAIT_L(0); PG8_MMA(0, 0, At, B0); PG8_BAR; PG8_SCHED;
;     ...
;         if (!(Epi::CHAIN && cur.br < 2))
; #pragma unroll
;         for (int a = 0; a < 2; ++a)
; #pragma unroll
;             for (int b = 0; b < 2; ++b)
; #pragma unroll
;                 for (int m = 0; m < 4; ++m)
; #pragma unroll
;                     for (int n = 0; n < 2; ++n) acc[a][b][m][n] = (f32x4){0.f, 0.f, 0.f, 0.f};
.LBB0_979:
	s_add_u32 s63, s24, 0x10000
	v_mov_b32_e32 v0, 0
	s_addc_u32 s64, s25, 0
	s_mov_b32 s65, -2
	v_mov_b32_e32 v1, v0
	v_mov_b32_e32 v2, v0
	v_mov_b32_e32 v3, v0
	v_mov_b32_e32 v4, v0
	v_mov_b32_e32 v5, v0
	v_mov_b32_e32 v6, v0
	v_mov_b32_e32 v7, v0
	v_mov_b32_e32 v16, v0
	v_mov_b32_e32 v17, v0
	v_mov_b32_e32 v18, v0
	v_mov_b32_e32 v19, v0
	v_mov_b32_e32 v20, v0
	v_mov_b32_e32 v21, v0
	v_mov_b32_e32 v22, v0
	v_mov_b32_e32 v23, v0
	v_mov_b32_e32 v32, v0
	v_mov_b32_e32 v33, v0
	v_mov_b32_e32 v34, v0
	v_mov_b32_e32 v35, v0
	v_mov_b32_e32 v36, v0
	v_mov_b32_e32 v37, v0
	v_mov_b32_e32 v38, v0
	v_mov_b32_e32 v39, v0
	v_mov_b32_e32 v48, v0
	v_mov_b32_e32 v49, v0
	v_mov_b32_e32 v50, v0
	v_mov_b32_e32 v51, v0
	v_mov_b32_e32 v52, v0
	v_mov_b32_e32 v53, v0
	v_mov_b32_e32 v54, v0
	v_mov_b32_e32 v55, v0
	v_mov_b32_e32 v8, v0
	v_mov_b32_e32 v9, v0
	v_mov_b32_e32 v10, v0
	v_mov_b32_e32 v11, v0
	v_mov_b32_e32 v12, v0
	v_mov_b32_e32 v13, v0
	v_mov_b32_e32 v14, v0
	v_mov_b32_e32 v15, v0
	v_mov_b32_e32 v24, v0
	v_mov_b32_e32 v25, v0
	v_mov_b32_e32 v26, v0
	v_mov_b32_e32 v27, v0
	v_mov_b32_e32 v28, v0
	v_mov_b32_e32 v29, v0
	v_mov_b32_e32 v30, v0
	v_mov_b32_e32 v31, v0
	v_mov_b32_e32 v40, v0
	v_mov_b32_e32 v41, v0
	v_mov_b32_e32 v42, v0
	v_mov_b32_e32 v43, v0
	v_mov_b32_e32 v44, v0
	v_mov_b32_e32 v45, v0
	v_mov_b32_e32 v46, v0
	v_mov_b32_e32 v47, v0
	v_mov_b32_e32 v56, v0
	v_mov_b32_e32 v57, v0
	v_mov_b32_e32 v58, v0
	v_mov_b32_e32 v59, v0
	v_mov_b32_e32 v60, v0
	v_mov_b32_e32 v61, v0
	v_mov_b32_e32 v62, v0
	v_mov_b32_e32 v63, v0
	v_mov_b32_e32 v64, v0
	v_mov_b32_e32 v65, v0
	v_mov_b32_e32 v66, v0
	v_mov_b32_e32 v67, v0
	v_mov_b32_e32 v68, v0
	v_mov_b32_e32 v69, v0
	v_mov_b32_e32 v70, v0
	v_mov_b32_e32 v71, v0
	v_mov_b32_e32 v80, v0
	v_mov_b32_e32 v81, v0
	v_mov_b32_e32 v82, v0
	v_mov_b32_e32 v83, v0
	v_mov_b32_e32 v84, v0
	v_mov_b32_e32 v85, v0
	v_mov_b32_e32 v86, v0
	v_mov_b32_e32 v87, v0
	v_mov_b32_e32 v96, v0
	v_mov_b32_e32 v97, v0
	v_mov_b32_e32 v98, v0
	v_mov_b32_e32 v99, v0
	v_mov_b32_e32 v100, v0
	v_mov_b32_e32 v101, v0
	v_mov_b32_e32 v102, v0
	v_mov_b32_e32 v103, v0
	v_mov_b32_e32 v108, v0
	v_mov_b32_e32 v109, v0
	v_mov_b32_e32 v110, v0
	v_mov_b32_e32 v111, v0
	v_mov_b32_e32 v112, v0
	v_mov_b32_e32 v113, v0
	v_mov_b32_e32 v114, v0
	v_mov_b32_e32 v115, v0
	v_mov_b32_e32 v72, v0
	v_mov_b32_e32 v73, v0
	v_mov_b32_e32 v74, v0
	v_mov_b32_e32 v75, v0
	v_mov_b32_e32 v76, v0
	v_mov_b32_e32 v77, v0
	v_mov_b32_e32 v78, v0
	v_mov_b32_e32 v79, v0
	v_mov_b32_e32 v88, v0
	v_mov_b32_e32 v89, v0
	v_mov_b32_e32 v90, v0
	v_mov_b32_e32 v91, v0
	v_mov_b32_e32 v92, v0
	v_mov_b32_e32 v93, v0
	v_mov_b32_e32 v94, v0
	v_mov_b32_e32 v95, v0
	v_mov_b32_e32 v104, v0
	v_mov_b32_e32 v105, v0
	v_mov_b32_e32 v106, v0
	v_mov_b32_e32 v107, v0
	v_mov_b32_e32 v116, v0
	v_mov_b32_e32 v117, v0
	v_mov_b32_e32 v118, v0
	v_mov_b32_e32 v119, v0
	v_mov_b32_e32 v120, v0
	v_mov_b32_e32 v121, v0
	v_mov_b32_e32 v122, v0
	v_mov_b32_e32 v123, v0
	v_mov_b32_e32 v124, v0
	v_mov_b32_e32 v125, v0
	v_mov_b32_e32 v126, v0
	v_mov_b32_e32 v127, v0
	s_cmp_eq_u32 s78, 1
	s_cbranch_scc0 .Lhalf_skip_y_7
	s_barrier
.Lhalf_skip_y_7:
.LBB0_980:
	ds_read_b128 v[128:131], v197
	ds_read_b128 v[132:135], v197 offset:1024
	ds_read_b128 v[136:139], v197 offset:2048
	ds_read_b128 v[140:143], v197 offset:3072
	s_add_u32 s24, s22, 0x100
	s_addc_u32 s25, s23, 0
	s_cmpk_eq_i32 s65, 0x52
	s_cselect_b32 s29, s7, s25
	s_cselect_b32 s28, s6, s24
	s_cselect_b32 s27, s9, s64
	s_cselect_b32 s26, s8, s63
	v_lshl_add_u64 v[192:193], s[22:23], 0, v[172:173]
	s_add_i32 m0, s49, 0xc000
	ds_read_b128 v[144:147], v198
	ds_read_b128 v[148:151], v198 offset:1024
	ds_read_b128 v[152:155], v198 offset:2048
	ds_read_b128 v[156:159], v198 offset:3072
	ds_read_b128 v[160:163], v198 offset:4096
	ds_read_b128 v[180:183], v198 offset:5120
	ds_read_b128 v[184:187], v198 offset:6144
	ds_read_b128 v[188:191], v198 offset:7168
	global_load_lds_dwordx4 v[192:193], off
	v_lshl_add_u64 v[192:193], s[22:23], 0, v[174:175]
	s_add_i32 m0, s49, 0xe000
	s_nop 0
	global_load_lds_dwordx4 v[192:193], off
	s_waitcnt lgkmcnt(8)
	s_barrier
	s_waitcnt lgkmcnt(0)
	s_setprio 1
	s_waitcnt lgkmcnt(0)
	v_mfma_f32_16x16x32_bf16 v[124:127], v[128:131], v[144:147], v[124:127]
	v_mfma_f32_16x16x32_bf16 v[120:123], v[136:139], v[144:147], v[120:123]
	v_mfma_f32_16x16x32_bf16 v[116:119], v[128:131], v[152:155], v[116:119]
	v_mfma_f32_16x16x32_bf16 v[104:107], v[136:139], v[152:155], v[104:107]
	v_mfma_f32_16x16x32_bf16 v[92:95], v[128:131], v[160:163], v[92:95]
	v_mfma_f32_16x16x32_bf16 v[88:91], v[136:139], v[160:163], v[88:91]
	v_mfma_f32_16x16x32_bf16 v[76:79], v[128:131], v[184:187], v[76:79]
	v_mfma_f32_16x16x32_bf16 v[72:75], v[136:139], v[184:187], v[72:75]
	v_mfma_f32_16x16x32_bf16 v[124:127], v[132:135], v[148:151], v[124:127]
	v_mfma_f32_16x16x32_bf16 v[120:123], v[140:143], v[148:151], v[120:123]
	v_mfma_f32_16x16x32_bf16 v[116:119], v[132:135], v[156:159], v[116:119]
	v_mfma_f32_16x16x32_bf16 v[104:107], v[140:143], v[156:159], v[104:107]
	v_mfma_f32_16x16x32_bf16 v[92:95], v[132:135], v[180:183], v[92:95]
	v_mfma_f32_16x16x32_bf16 v[88:91], v[140:143], v[180:183], v[88:91]
	v_mfma_f32_16x16x32_bf16 v[76:79], v[132:135], v[188:191], v[76:79]
	v_mfma_f32_16x16x32_bf16 v[72:75], v[140:143], v[188:191], v[72:75]
	s_setprio 0
	s_barrier
	s_add_i32 s22, s57, s48
	v_lshl_add_u64 v[192:193], s[26:27], 0, v[164:165]
	s_mov_b32 m0, s22
	ds_read_b128 v[200:203], v199
	ds_read_b128 v[204:207], v199 offset:1024
	ds_read_b128 v[208:211], v199 offset:2048
	ds_read_b128 v[212:215], v199 offset:3072
	global_load_lds_dwordx4 v[192:193], off
	v_lshl_add_u64 v[192:193], s[26:27], 0, v[168:169]
	s_add_i32 m0, s22, 0x2000
	s_nop 0
	global_load_lds_dwordx4 v[192:193], off
	s_barrier
; #define PG8_STAGE(bufoff, gbase, voff) do { _Pragma("unroll") for (int _i = 0; _i < 2; ++_i) \
;         __builtin_amdgcn_global_load_lds((const unsigned*)((const char*)(gbase) + (voff)[_i]), (PG8_LAS unsigned*)(lds + (bufoff) + ldsw + _i * 8192), 16, 0, 0); } while (0)
; #define PG8_LDA(dst, b, h) do { _Pragma("unroll") for (int m = 0; m < 4; ++m) _Pragma("unroll") for (int k = 0; k < 2; ++k) dst[m][k] = *(const PG8_LAS bf16x8*)(lds + PG8_SA(b, h) + aoff + m * 2048 + k * 1024); } while (0)
; #define PG8_LDB(dst, b, h) do { _Pragma("unroll") for (int n = 0; n < 2; ++n) _Pragma("unroll") for (int k = 0; k < 2; ++k) dst[n][k] = *(const PG8_LAS bf16x8*)(lds + PG8_SB(b, h) + boff + n * 2048 + k * 1024); } while (0)
; #define PG8_MMA(ai, bj, At, Bt) do { __builtin_amdgcn_s_setprio(1); _Pragma("unroll") for (int m = 0; m < 4; ++m) _Pragma("unroll") for (int n = 0; n < 2; ++n) _Pragma("unroll") for (int k = 0; k < 2; ++k) \
;         acc[ai][bj][m][n] = __builtin_amdgcn_mfma_f32_16x16x32_bf16(Bt[n][k], At[m][k], acc[ai][bj][m][n], 0, 0, 0); __builtin_amdgcn_s_setprio(0); } while (0)
; #define PG8_WAIT_V(n) asm volatile("s_waitcnt vmcnt(" #n ")" ::: "memory")
; #define PG8_WAIT_L(n) asm volatile("s_waitcnt lgkmcnt(" #n ")" ::: "memory")
; #define PG8_BAR __builtin_amdgcn_s_barrier()
; #define PG8_SCHED __builtin_amdgcn_sched_barrier(0)
; template <class Epi, class Sched>
; __device__ __forceinline__ void gemm_phase(PG8_LAS unsigned char* lds, const Gemm g, const Sched& S, const Epi& E) {
;     ...
;             PG8_BAR; PG8_WAIT_L(0); PG8_MMA(0, 1, At, B1); PG8_BAR;
;             PG8_LDA(At, 0, 1); PG8_STAGE(PG8_SA(0, 0), a2, voffA);
;             PG8_BAR; PG8_WAIT_L(0); PG8_MMA(1, 0, At, B0); PG8_BAR; PG8_SCHED;
;             PG8_STAGE(PG8_SB(0, 1), b2 + hstepB, voffB);
;             PG8_WAIT_V(6); PG8_BAR; PG8_MMA(1, 1, At, B1); PG8_BAR;
;             PG8_LDB(B0, 1, 0); PG8_SCHED; PG8_LDA(At, 1, 0); PG8_STAGE(PG8_SA(0, 1), a2 + hstep, voffA);
;             PG8_WAIT_L(8); PG8_BAR; PG8_WAIT_L(0); PG8_MMA(0, 0, At, B0); PG8_BAR; PG8_SCHED;
	s_waitcnt lgkmcnt(0)
	s_setprio 1
	s_waitcnt lgkmcnt(0)
	v_mfma_f32_16x16x32_bf16 v[112:115], v[200:203], v[144:147], v[112:115]
	v_mfma_f32_16x16x32_bf16 v[108:111], v[208:211], v[144:147], v[108:111]
	v_mfma_f32_16x16x32_bf16 v[100:103], v[200:203], v[152:155], v[100:103]
	v_mfma_f32_16x16x32_bf16 v[96:99], v[208:211], v[152:155], v[96:99]
	v_mfma_f32_16x16x32_bf16 v[84:87], v[200:203], v[160:163], v[84:87]
	v_mfma_f32_16x16x32_bf16 v[80:83], v[208:211], v[160:163], v[80:83]
	v_mfma_f32_16x16x32_bf16 v[68:71], v[200:203], v[184:187], v[68:71]
	v_mfma_f32_16x16x32_bf16 v[64:67], v[208:211], v[184:187], v[64:67]
	v_mfma_f32_16x16x32_bf16 v[112:115], v[204:207], v[148:151], v[112:115]
	v_mfma_f32_16x16x32_bf16 v[108:111], v[212:215], v[148:151], v[108:111]
	v_mfma_f32_16x16x32_bf16 v[100:103], v[204:207], v[156:159], v[100:103]
	v_mfma_f32_16x16x32_bf16 v[96:99], v[212:215], v[156:159], v[96:99]
	v_mfma_f32_16x16x32_bf16 v[84:87], v[204:207], v[180:183], v[84:87]
	v_mfma_f32_16x16x32_bf16 v[80:83], v[212:215], v[180:183], v[80:83]
	v_mfma_f32_16x16x32_bf16 v[68:71], v[204:207], v[188:191], v[68:71]
	v_mfma_f32_16x16x32_bf16 v[64:67], v[212:215], v[188:191], v[64:67]
	s_setprio 0
	s_mov_b32 m0, s49
	v_lshl_add_u64 v[192:193], s[28:29], 0, v[166:167]
	s_barrier
	ds_read_b128 v[144:147], v198 offset:16384
	ds_read_b128 v[148:151], v198 offset:17408
	ds_read_b128 v[152:155], v198 offset:18432
	ds_read_b128 v[156:159], v198 offset:19456
	ds_read_b128 v[160:163], v198 offset:20480
	ds_read_b128 v[180:183], v198 offset:21504
	ds_read_b128 v[184:187], v198 offset:22528
	ds_read_b128 v[188:191], v198 offset:23552
	global_load_lds_dwordx4 v[192:193], off
	v_lshl_add_u64 v[216:217], s[28:29], 0, v[170:171]
	s_mov_b32 m0, s50
	s_nop 0
	global_load_lds_dwordx4 v[216:217], off
	s_barrier
	s_waitcnt lgkmcnt(0)
	s_setprio 1
	s_waitcnt lgkmcnt(0)
	v_mfma_f32_16x16x32_bf16 v[60:63], v[128:131], v[144:147], v[60:63]
	v_mfma_f32_16x16x32_bf16 v[56:59], v[136:139], v[144:147], v[56:59]
	v_mfma_f32_16x16x32_bf16 v[44:47], v[128:131], v[152:155], v[44:47]
	v_mfma_f32_16x16x32_bf16 v[40:43], v[136:139], v[152:155], v[40:43]
	v_mfma_f32_16x16x32_bf16 v[28:31], v[128:131], v[160:163], v[28:31]
	v_mfma_f32_16x16x32_bf16 v[24:27], v[136:139], v[160:163], v[24:27]
	v_mfma_f32_16x16x32_bf16 v[12:15], v[128:131], v[184:187], v[12:15]
	v_mfma_f32_16x16x32_bf16 v[8:11], v[136:139], v[184:187], v[8:11]
	v_mfma_f32_16x16x32_bf16 v[60:63], v[132:135], v[148:151], v[60:63]
	v_mfma_f32_16x16x32_bf16 v[56:59], v[140:143], v[148:151], v[56:59]
	v_mfma_f32_16x16x32_bf16 v[44:47], v[132:135], v[156:159], v[44:47]
	v_mfma_f32_16x16x32_bf16 v[40:43], v[140:143], v[156:159], v[40:43]
	v_mfma_f32_16x16x32_bf16 v[28:31], v[132:135], v[180:183], v[28:31]
	v_mfma_f32_16x16x32_bf16 v[24:27], v[140:143], v[180:183], v[24:27]
	v_mfma_f32_16x16x32_bf16 v[12:15], v[132:135], v[188:191], v[12:15]
	v_mfma_f32_16x16x32_bf16 v[8:11], v[140:143], v[188:191], v[8:11]
	s_setprio 0
	s_barrier
	s_add_u32 s22, s26, 0x4000
	s_addc_u32 s23, s27, 0
	s_add_i32 s66, s58, s48
	v_lshl_add_u64 v[128:129], s[22:23], 0, v[164:165]
	s_mov_b32 m0, s66
	s_nop 0
	global_load_lds_dwordx4 v[128:129], off
	v_lshl_add_u64 v[128:129], s[22:23], 0, v[168:169]
	s_add_i32 m0, s66, 0x2000
	s_nop 0
	global_load_lds_dwordx4 v[128:129], off
	s_waitcnt vmcnt(6)
	s_barrier
	s_setprio 1
	v_mfma_f32_16x16x32_bf16 v[52:55], v[200:203], v[144:147], v[52:55]
	v_mfma_f32_16x16x32_bf16 v[48:51], v[208:211], v[144:147], v[48:51]
	v_mfma_f32_16x16x32_bf16 v[36:39], v[200:203], v[152:155], v[36:39]
	v_mfma_f32_16x16x32_bf16 v[32:35], v[208:211], v[152:155], v[32:35]
	v_mfma_f32_16x16x32_bf16 v[20:23], v[200:203], v[160:163], v[20:23]
	v_mfma_f32_16x16x32_bf16 v[16:19], v[208:211], v[160:163], v[16:19]
	v_mfma_f32_16x16x32_bf16 v[4:7], v[200:203], v[184:187], v[4:7]
	v_mfma_f32_16x16x32_bf16 v[0:3], v[208:211], v[184:187], v[0:3]
	v_mfma_f32_16x16x32_bf16 v[52:55], v[204:207], v[148:151], v[52:55]
	v_mfma_f32_16x16x32_bf16 v[48:51], v[212:215], v[148:151], v[48:51]
	v_mfma_f32_16x16x32_bf16 v[36:39], v[204:207], v[156:159], v[36:39]
	v_mfma_f32_16x16x32_bf16 v[32:35], v[212:215], v[156:159], v[32:35]
	v_mfma_f32_16x16x32_bf16 v[20:23], v[204:207], v[180:183], v[20:23]
	v_mfma_f32_16x16x32_bf16 v[16:19], v[212:215], v[180:183], v[16:19]
	v_mfma_f32_16x16x32_bf16 v[4:7], v[204:207], v[188:191], v[4:7]
	v_mfma_f32_16x16x32_bf16 v[0:3], v[212:215], v[188:191], v[0:3]
	s_setprio 0
	s_add_i32 s66, 0, 0x18000
	v_add_u32_e32 v140, s66, v195
	s_barrier
	ds_read_b128 v[128:131], v140
	ds_read_b128 v[132:135], v140 offset:1024
	ds_read_b128 v[136:139], v140 offset:2048
	ds_read_b128 v[140:143], v140 offset:3072
	s_add_u32 s22, s28, 0x158000
	s_addc_u32 s23, s29, 0
	s_mov_b32 m0, s51
	v_lshl_add_u64 v[200:201], s[22:23], 0, v[166:167]
	ds_read_b128 v[144:147], v198 offset:32768
	ds_read_b128 v[148:151], v198 offset:33792
	ds_read_b128 v[152:155], v198 offset:34816
	ds_read_b128 v[156:159], v198 offset:35840
	ds_read_b128 v[160:163], v198 offset:36864
	ds_read_b128 v[180:183], v198 offset:37888
	ds_read_b128 v[184:187], v198 offset:38912
	ds_read_b128 v[188:191], v198 offset:39936
	global_load_lds_dwordx4 v[200:201], off
	v_lshl_add_u64 v[200:201], s[22:23], 0, v[170:171]
	s_mov_b32 m0, s52
	s_nop 0
	global_load_lds_dwordx4 v[200:201], off
	s_waitcnt lgkmcnt(8)
	s_barrier
; #define PG8_STAGE(bufoff, gbase, voff) do { _Pragma("unroll") for (int _i = 0; _i < 2; ++_i) \
;         __builtin_amdgcn_global_load_lds((const unsigned*)((const char*)(gbase) + (voff)[_i]), (PG8_LAS unsigned*)(lds + (bufoff) + ldsw + _i * 8192), 16, 0, 0); } while (0)
; #define PG8_LDA(dst, b, h) do { _Pragma("unroll") for (int m = 0; m < 4; ++m) _Pragma("unroll") for (int k = 0; k < 2; ++k) dst[m][k] = *(const PG8_LAS bf16x8*)(lds + PG8_SA(b, h) + aoff + m * 2048 + k * 1024); } while (0)
; #define PG8_LDB(dst, b, h) do { _Pragma("unroll") for (int n = 0; n < 2; ++n) _Pragma("unroll") for (int k = 0; k < 2; ++k) dst[n][k] = *(const PG8_LAS bf16x8*)(lds + PG8_SB(b, h) + boff + n * 2048 + k * 1024); } while (0)
; #define PG8_MMA(ai, bj, At, Bt) do { __builtin_amdgcn_s_setprio(1); _Pragma("unroll") for (int m = 0; m < 4; ++m) _Pragma("unroll") for (int n = 0; n < 2; ++n) _Pragma("unroll") for (int k = 0; k < 2; ++k) \
;         acc[ai][bj][m][n] = __builtin_amdgcn_mfma_f32_16x16x32_bf16(Bt[n][k], At[m][k], acc[ai][bj][m][n], 0, 0, 0); __builtin_amdgcn_s_setprio(0); } while (0)
; #define PG8_WAIT_V(n) asm volatile("s_waitcnt vmcnt(" #n ")" ::: "memory")
; #define PG8_WAIT_L(n) asm volatile("s_waitcnt lgkmcnt(" #n ")" ::: "memory")
; #define PG8_BAR __builtin_amdgcn_s_barrier()
; #define PG8_SCHED __builtin_amdgcn_sched_barrier(0)
; template <class Epi, class Sched>
; __device__ __forceinline__ void gemm_phase(PG8_LAS unsigned char* lds, const Gemm g, const Sched& S, const Epi& E) {
;     ...
;             PG8_WAIT_L(8); PG8_BAR; PG8_WAIT_L(0); PG8_MMA(0, 0, At, B0); PG8_BAR; PG8_SCHED;
;             PG8_LDB(B1, 1, 1); PG8_STAGE(PG8_SB(1, 0), b3, voffB);
;             PG8_BAR; PG8_WAIT_L(0); PG8_MMA(0, 1, At, B1); PG8_BAR;
;             PG8_LDA(At, 1, 1); PG8_STAGE(PG8_SA(1, 0), a3, voffA);
;             PG8_BAR; PG8_WAIT_L(0); PG8_MMA(1, 0, At, B0); PG8_BAR; PG8_SCHED;
;             PG8_STAGE(PG8_SB(1, 1), b3 + hstepB, voffB);
;             PG8_WAIT_V(6); PG8_BAR; PG8_MMA(1, 1, At, B1); PG8_BAR;
;     ...
;     if (wr == 0) PG8_BAR;
	s_waitcnt lgkmcnt(0)
	s_setprio 1
	s_waitcnt lgkmcnt(0)
	v_mfma_f32_16x16x32_bf16 v[124:127], v[128:131], v[144:147], v[124:127]
	v_mfma_f32_16x16x32_bf16 v[120:123], v[136:139], v[144:147], v[120:123]
	v_mfma_f32_16x16x32_bf16 v[116:119], v[128:131], v[152:155], v[116:119]
	v_mfma_f32_16x16x32_bf16 v[104:107], v[136:139], v[152:155], v[104:107]
	v_mfma_f32_16x16x32_bf16 v[92:95], v[128:131], v[160:163], v[92:95]
	v_mfma_f32_16x16x32_bf16 v[88:91], v[136:139], v[160:163], v[88:91]
	v_mfma_f32_16x16x32_bf16 v[76:79], v[128:131], v[184:187], v[76:79]
	v_mfma_f32_16x16x32_bf16 v[72:75], v[136:139], v[184:187], v[72:75]
	v_mfma_f32_16x16x32_bf16 v[124:127], v[132:135], v[148:151], v[124:127]
	v_mfma_f32_16x16x32_bf16 v[120:123], v[140:143], v[148:151], v[120:123]
	v_mfma_f32_16x16x32_bf16 v[116:119], v[132:135], v[156:159], v[116:119]
	v_mfma_f32_16x16x32_bf16 v[104:107], v[140:143], v[156:159], v[104:107]
	v_mfma_f32_16x16x32_bf16 v[92:95], v[132:135], v[180:183], v[92:95]
	v_mfma_f32_16x16x32_bf16 v[88:91], v[140:143], v[180:183], v[88:91]
	v_mfma_f32_16x16x32_bf16 v[76:79], v[132:135], v[188:191], v[76:79]
	v_mfma_f32_16x16x32_bf16 v[72:75], v[140:143], v[188:191], v[72:75]
	s_setprio 0
	s_barrier
	s_add_i32 s28, 0, 0x1c000
	s_add_u32 s22, s26, 0x8000
	s_addc_u32 s23, s27, 0
	s_add_i32 s29, s66, s48
	v_add_u32_e32 v212, s28, v195
	v_lshl_add_u64 v[218:219], s[22:23], 0, v[164:165]
	s_mov_b32 m0, s29
	ds_read_b128 v[200:203], v212
	ds_read_b128 v[204:207], v212 offset:1024
	ds_read_b128 v[208:211], v212 offset:2048
	ds_read_b128 v[212:215], v212 offset:3072
	global_load_lds_dwordx4 v[218:219], off
	v_lshl_add_u64 v[218:219], s[22:23], 0, v[168:169]
	s_add_i32 m0, s29, 0x2000
	s_nop 0
	global_load_lds_dwordx4 v[218:219], off
	s_barrier
	s_waitcnt lgkmcnt(0)
	s_setprio 1
	s_waitcnt lgkmcnt(0)
	v_mfma_f32_16x16x32_bf16 v[112:115], v[200:203], v[144:147], v[112:115]
	v_mfma_f32_16x16x32_bf16 v[108:111], v[208:211], v[144:147], v[108:111]
	v_mfma_f32_16x16x32_bf16 v[100:103], v[200:203], v[152:155], v[100:103]
	v_mfma_f32_16x16x32_bf16 v[96:99], v[208:211], v[152:155], v[96:99]
	v_mfma_f32_16x16x32_bf16 v[84:87], v[200:203], v[160:163], v[84:87]
	v_mfma_f32_16x16x32_bf16 v[80:83], v[208:211], v[160:163], v[80:83]
	v_mfma_f32_16x16x32_bf16 v[68:71], v[200:203], v[184:187], v[68:71]
	v_mfma_f32_16x16x32_bf16 v[64:67], v[208:211], v[184:187], v[64:67]
	v_mfma_f32_16x16x32_bf16 v[112:115], v[204:207], v[148:151], v[112:115]
	v_mfma_f32_16x16x32_bf16 v[108:111], v[212:215], v[148:151], v[108:111]
	v_mfma_f32_16x16x32_bf16 v[100:103], v[204:207], v[156:159], v[100:103]
	v_mfma_f32_16x16x32_bf16 v[96:99], v[212:215], v[156:159], v[96:99]
	v_mfma_f32_16x16x32_bf16 v[84:87], v[204:207], v[180:183], v[84:87]
	v_mfma_f32_16x16x32_bf16 v[80:83], v[212:215], v[180:183], v[80:83]
	v_mfma_f32_16x16x32_bf16 v[68:71], v[204:207], v[188:191], v[68:71]
	v_mfma_f32_16x16x32_bf16 v[64:67], v[212:215], v[188:191], v[64:67]
	s_setprio 0
	s_mov_b32 m0, s54
	v_lshl_add_u64 v[192:193], v[192:193], 0, s[12:13]
	s_barrier
	ds_read_b128 v[144:147], v198 offset:49152
	ds_read_b128 v[148:151], v198 offset:50176
	ds_read_b128 v[152:155], v198 offset:51200
	ds_read_b128 v[156:159], v198 offset:52224
	ds_read_b128 v[160:163], v198 offset:53248
	ds_read_b128 v[180:183], v198 offset:54272
	ds_read_b128 v[184:187], v198 offset:55296
	ds_read_b128 v[188:191], v198 offset:56320
	global_load_lds_dwordx4 v[192:193], off
	v_lshl_add_u64 v[192:193], v[216:217], 0, s[12:13]
	s_mov_b32 m0, s55
	s_nop 0
	global_load_lds_dwordx4 v[192:193], off
	s_barrier
	s_waitcnt lgkmcnt(0)
	s_setprio 1
	s_waitcnt lgkmcnt(0)
	v_mfma_f32_16x16x32_bf16 v[60:63], v[128:131], v[144:147], v[60:63]
	v_mfma_f32_16x16x32_bf16 v[56:59], v[136:139], v[144:147], v[56:59]
	v_mfma_f32_16x16x32_bf16 v[44:47], v[128:131], v[152:155], v[44:47]
	v_mfma_f32_16x16x32_bf16 v[40:43], v[136:139], v[152:155], v[40:43]
	v_mfma_f32_16x16x32_bf16 v[28:31], v[128:131], v[160:163], v[28:31]
	v_mfma_f32_16x16x32_bf16 v[24:27], v[136:139], v[160:163], v[24:27]
	v_mfma_f32_16x16x32_bf16 v[12:15], v[128:131], v[184:187], v[12:15]
	v_mfma_f32_16x16x32_bf16 v[8:11], v[136:139], v[184:187], v[8:11]
	v_mfma_f32_16x16x32_bf16 v[60:63], v[132:135], v[148:151], v[60:63]
	v_mfma_f32_16x16x32_bf16 v[56:59], v[140:143], v[148:151], v[56:59]
	v_mfma_f32_16x16x32_bf16 v[44:47], v[132:135], v[156:159], v[44:47]
	v_mfma_f32_16x16x32_bf16 v[40:43], v[140:143], v[156:159], v[40:43]
	v_mfma_f32_16x16x32_bf16 v[28:31], v[132:135], v[180:183], v[28:31]
	v_mfma_f32_16x16x32_bf16 v[24:27], v[140:143], v[180:183], v[24:27]
	v_mfma_f32_16x16x32_bf16 v[12:15], v[132:135], v[188:191], v[12:15]
	v_mfma_f32_16x16x32_bf16 v[8:11], v[140:143], v[188:191], v[8:11]
	s_setprio 0
	s_barrier
	s_add_u32 s22, s26, 0xc000
	s_addc_u32 s23, s27, 0
	s_add_i32 s26, s28, s48
	v_lshl_add_u64 v[128:129], s[22:23], 0, v[164:165]
	s_mov_b32 m0, s26
	s_nop 0
	global_load_lds_dwordx4 v[128:129], off
	v_lshl_add_u64 v[128:129], s[22:23], 0, v[168:169]
	s_add_i32 m0, s26, 0x2000
	s_nop 0
	global_load_lds_dwordx4 v[128:129], off
	s_waitcnt vmcnt(6)
	s_barrier
	s_setprio 1
	v_mfma_f32_16x16x32_bf16 v[52:55], v[200:203], v[144:147], v[52:55]
	v_mfma_f32_16x16x32_bf16 v[48:51], v[208:211], v[144:147], v[48:51]
	v_mfma_f32_16x16x32_bf16 v[36:39], v[200:203], v[152:155], v[36:39]
	v_mfma_f32_16x16x32_bf16 v[32:35], v[208:211], v[152:155], v[32:35]
	v_mfma_f32_16x16x32_bf16 v[20:23], v[200:203], v[160:163], v[20:23]
	v_mfma_f32_16x16x32_bf16 v[16:19], v[208:211], v[160:163], v[16:19]
	v_mfma_f32_16x16x32_bf16 v[4:7], v[200:203], v[184:187], v[4:7]
	v_mfma_f32_16x16x32_bf16 v[0:3], v[208:211], v[184:187], v[0:3]
	v_mfma_f32_16x16x32_bf16 v[52:55], v[204:207], v[148:151], v[52:55]
	v_mfma_f32_16x16x32_bf16 v[48:51], v[212:215], v[148:151], v[48:51]
	v_mfma_f32_16x16x32_bf16 v[36:39], v[204:207], v[156:159], v[36:39]
	v_mfma_f32_16x16x32_bf16 v[32:35], v[212:215], v[156:159], v[32:35]
	v_mfma_f32_16x16x32_bf16 v[20:23], v[204:207], v[180:183], v[20:23]
	v_mfma_f32_16x16x32_bf16 v[16:19], v[212:215], v[180:183], v[16:19]
	v_mfma_f32_16x16x32_bf16 v[4:7], v[204:207], v[188:191], v[4:7]
	v_mfma_f32_16x16x32_bf16 v[0:3], v[212:215], v[188:191], v[0:3]
	s_setprio 0
	s_add_i32 s65, s65, 2
	s_add_u32 s63, s63, 0x10000
	s_addc_u32 s64, s64, 0
	s_cmpk_gt_u32 s65, 0x53
	s_mov_b64 s[22:23], s[24:25]
	s_barrier
	s_cbranch_scc0 .LBB0_980
	s_cmp_eq_u32 s78, 0
	s_cbranch_scc0 .Lhalf_skip_x_7
	s_barrier
; __device__ __forceinline__ unsigned cvt_pk_bf16(float lo, float hi) { unsigned r; asm volatile("v_cvt_pk_bf16_f32 %0, %1, %2" : "=v"(r) : "v"(lo), "v"(hi)); return r; }
; __device__ __forceinline__ float bflo(unsigned w) { return __uint_as_float(w << 16); }
; __device__ __forceinline__ float bfhi(unsigned w) { return __uint_as_float(w & 0xffff0000u); }
;     __device__ __forceinline__ void operator()(const f32x4 (&acc)[2][2][4][2], const Unit& u, int wr, int wc, int fr, int fq) const {
;     ...
;             u32x4 hv[2][4][2];
; #pragma unroll
;             for (int ai = 0; ai < 2; ++ai)
; #pragma unroll
;                 for (int m = 0; m < 4; ++m)
; #pragma unroll
;                     for (int bj = 0; bj < 2; ++bj) hv[ai][m][bj] = *(const u32x4*)(H + (size_t)(row0 + ai * HALF + m * 16) * 2048 + col0 + bj * HALF);
; #pragma unroll
;             for (int ai = 0; ai < 2; ++ai)
; #pragma unroll
;                 for (int m = 0; m < 4; ++m)
; #pragma unroll
;                     for (int bj = 0; bj < 2; ++bj) { const size_t o = (size_t)(row0 + ai * HALF + m * 16) * 2048 + col0 + bj * HALF; const u32x4 h4 = hv[ai][m][bj];
;                         const f32x4 r0 = (f32x4){bflo(h4.x), bfhi(h4.x), bflo(h4.y), bfhi(h4.y)}, r1 = (f32x4){bflo(h4.z), bfhi(h4.z), bflo(h4.w), bfhi(h4.w)};
;                         const f32x4 v0 = r0 + acc[ai][bj][m][0] * scale, v1 = r1 + acc[ai][bj][m][1] * scale;
;                         u32x4 w; w.x = cvt_pk_bf16(v0[0], v0[1]); w.y = cvt_pk_bf16(v0[2], v0[3]); w.z = cvt_pk_bf16(v1[0], v1[1]); w.w = cvt_pk_bf16(v1[2], v1[3]);
;                         *(u32x4*)(H + o) = w; }
.Lhalf_skip_x_7:
	v_lshl_or_b32 v130, s62, 8, v196
	v_lshl_add_u32 v128, s61, 8, v194
	v_ashrrev_i32_e32 v131, 31, v130
	v_lshlrev_b64 v[180:181], 1, v[130:131]
	v_ashrrev_i32_e32 v129, 31, v128
	v_lshl_add_u64 v[130:131], s[10:11], 0, v[180:181]
	v_lshlrev_b64 v[132:133], 12, v[128:129]
	v_lshl_add_u64 v[134:135], v[130:131], 0, v[132:133]
	global_load_dwordx4 v[200:203], v[134:135], off
	global_load_dwordx4 v[204:207], v[134:135], off offset:256
	v_or_b32_e32 v134, 16, v128
	v_ashrrev_i32_e32 v135, 31, v134
	v_lshlrev_b64 v[230:231], 12, v[134:135]
	v_lshl_add_u64 v[134:135], v[130:131], 0, v[230:231]
	global_load_dwordx4 v[208:211], v[134:135], off
	global_load_dwordx4 v[212:215], v[134:135], off offset:256
	v_or_b32_e32 v136, 32, v128
	v_or_b32_e32 v128, 48, v128
	v_ashrrev_i32_e32 v137, 31, v136
	v_ashrrev_i32_e32 v129, 31, v128
	v_lshlrev_b64 v[192:193], 12, v[136:137]
	v_lshlrev_b64 v[190:191], 12, v[128:129]
	v_lshl_add_u64 v[188:189], v[132:133], 0, s[14:15]
	v_lshl_add_u64 v[186:187], v[132:133], 0, s[16:17]
	v_lshl_add_u64 v[184:185], v[132:133], 0, s[18:19]
	v_lshl_add_u64 v[182:183], v[132:133], 0, s[20:21]
	v_lshl_add_u64 v[128:129], s[10:11], 0, v[132:133]
	v_lshl_add_u64 v[132:133], v[130:131], 0, v[192:193]
	v_lshl_add_u64 v[134:135], v[130:131], 0, v[190:191]
	v_lshl_add_u64 v[136:137], v[130:131], 0, v[188:189]
	v_lshl_add_u64 v[138:139], v[130:131], 0, v[186:187]
	v_lshl_add_u64 v[232:233], v[130:131], 0, v[184:185]
	v_lshl_add_u64 v[130:131], v[130:131], 0, v[182:183]
	v_lshl_add_u64 v[234:235], v[128:129], 0, v[180:181]
	global_load_dwordx4 v[216:219], v[132:133], off
	global_load_dwordx4 v[220:223], v[132:133], off offset:256
	global_load_dwordx4 v[224:227], v[134:135], off
	global_load_dwordx4 v[160:163], v[134:135], off offset:256
	global_load_dwordx4 v[156:159], v[136:137], off
	global_load_dwordx4 v[152:155], v[136:137], off offset:256
	global_load_dwordx4 v[148:151], v[138:139], off
	global_load_dwordx4 v[144:147], v[138:139], off offset:256
	global_load_dwordx4 v[140:143], v[232:233], off
	s_nop 0
	global_load_dwordx4 v[136:139], v[232:233], off offset:256
	global_load_dwordx4 v[132:135], v[130:131], off
	s_nop 0
	global_load_dwordx4 v[128:131], v[130:131], off offset:256
	s_and_b64 vcc, exec, s[4:5]
	s_mov_b32 s62, s60
	s_mov_b32 s61, s59
	s_mov_b64 s[24:25], s[8:9]
	s_mov_b64 s[22:23], s[6:7]
	s_waitcnt vmcnt(0)
	v_lshlrev_b32_e32 v232, 16, v200
	v_and_b32_e32 v233, 0xffff0000, v200
	v_lshlrev_b32_e32 v200, 16, v201
	v_and_b32_e32 v201, 0xffff0000, v201
	v_lshlrev_b32_e32 v236, 16, v202
	v_and_b32_e32 v237, 0xffff0000, v202
	v_lshlrev_b32_e32 v202, 16, v203
	v_and_b32_e32 v203, 0xffff0000, v203
	v_lshlrev_b32_e32 v240, 16, v206
	v_and_b32_e32 v241, 0xffff0000, v206
	v_lshlrev_b32_e32 v238, 16, v204
	v_and_b32_e32 v239, 0xffff0000, v204
	v_lshlrev_b32_e32 v204, 16, v205
	v_and_b32_e32 v205, 0xffff0000, v205
	v_lshlrev_b32_e32 v206, 16, v207
	v_and_b32_e32 v207, 0xffff0000, v207
	v_pk_fma_f32 v[126:127], v[126:127], 0.5, v[200:201] op_sel_hi:[1,0,1]
	v_pk_fma_f32 v[124:125], v[124:125], 0.5, v[232:233] op_sel_hi:[1,0,1]
	v_pk_fma_f32 v[122:123], v[122:123], 0.5, v[202:203] op_sel_hi:[1,0,1]
	v_pk_fma_f32 v[202:203], v[108:109], 0.5, v[240:241] op_sel_hi:[1,0,1]
	v_cvt_pk_bf16_f32 v108, v124, v125
	v_cvt_pk_bf16_f32 v109, v126, v127
	v_lshlrev_b32_e32 v244, 16, v210
	v_and_b32_e32 v245, 0xffff0000, v210
	v_lshlrev_b32_e32 v210, 16, v211
	v_and_b32_e32 v211, 0xffff0000, v211
	v_pk_fma_f32 v[120:121], v[120:121], 0.5, v[236:237] op_sel_hi:[1,0,1]
	v_pk_fma_f32 v[114:115], v[114:115], 0.5, v[204:205] op_sel_hi:[1,0,1]
	v_pk_fma_f32 v[112:113], v[112:113], 0.5, v[238:239] op_sel_hi:[1,0,1]
	v_pk_fma_f32 v[200:201], v[110:111], 0.5, v[206:207] op_sel_hi:[1,0,1]
	v_cvt_pk_bf16_f32 v110, v120, v121
	v_cvt_pk_bf16_f32 v111, v122, v123
	global_store_dwordx4 v[234:235], v[108:111], off
	v_lshlrev_b32_e32 v242, 16, v208
	v_and_b32_e32 v243, 0xffff0000, v208
	v_cvt_pk_bf16_f32 v108, v112, v113
	v_cvt_pk_bf16_f32 v109, v114, v115
	v_lshlrev_b32_e32 v208, 16, v209
	v_and_b32_e32 v209, 0xffff0000, v209
	v_cvt_pk_bf16_f32 v110, v202, v203
	v_cvt_pk_bf16_f32 v111, v200, v201
	global_store_dwordx4 v[234:235], v[108:111], off offset:256
	v_pk_fma_f32 v[118:119], v[118:119], 0.5, v[208:209] op_sel_hi:[1,0,1]
	v_pk_fma_f32 v[116:117], v[116:117], 0.5, v[242:243] op_sel_hi:[1,0,1]
	v_pk_fma_f32 v[108:109], v[106:107], 0.5, v[210:211] op_sel_hi:[1,0,1]
	v_pk_fma_f32 v[106:107], v[104:105], 0.5, v[244:245] op_sel_hi:[1,0,1]
	v_cvt_pk_bf16_f32 v104, v116, v117
	v_cvt_pk_bf16_f32 v105, v118, v119
	v_lshlrev_b32_e32 v110, 16, v214
	v_cvt_pk_bf16_f32 v106, v106, v107
	v_cvt_pk_bf16_f32 v107, v108, v109
	v_lshl_add_u64 v[108:109], s[10:11], 0, v[230:231]
	v_lshl_add_u64 v[108:109], v[108:109], 0, v[180:181]
	global_store_dwordx4 v[108:109], v[104:107], off
	v_and_b32_e32 v111, 0xffff0000, v214
	v_lshlrev_b32_e32 v112, 16, v215
	v_lshlrev_b32_e32 v104, 16, v212
	v_and_b32_e32 v105, 0xffff0000, v212
	v_lshlrev_b32_e32 v106, 16, v213
	v_and_b32_e32 v107, 0xffff0000, v213
	v_and_b32_e32 v113, 0xffff0000, v215
	v_pk_fma_f32 v[102:103], v[102:103], 0.5, v[106:107] op_sel_hi:[1,0,1]
	v_pk_fma_f32 v[100:101], v[100:101], 0.5, v[104:105] op_sel_hi:[1,0,1]
	v_pk_fma_f32 v[104:105], v[98:99], 0.5, v[112:113] op_sel_hi:[1,0,1]
	v_pk_fma_f32 v[98:99], v[96:97], 0.5, v[110:111] op_sel_hi:[1,0,1]
	v_cvt_pk_bf16_f32 v96, v100, v101
	v_cvt_pk_bf16_f32 v97, v102, v103
	v_lshlrev_b32_e32 v100, 16, v218
	v_cvt_pk_bf16_f32 v98, v98, v99
	v_cvt_pk_bf16_f32 v99, v104, v105
	global_store_dwordx4 v[108:109], v[96:99], off offset:256
	v_and_b32_e32 v101, 0xffff0000, v218
; __device__ __forceinline__ unsigned cvt_pk_bf16(float lo, float hi) { unsigned r; asm volatile("v_cvt_pk_bf16_f32 %0, %1, %2" : "=v"(r) : "v"(lo), "v"(hi)); return r; }
; __device__ __forceinline__ float bflo(unsigned w) { return __uint_as_float(w << 16); }
; __device__ __forceinline__ float bfhi(unsigned w) { return __uint_as_float(w & 0xffff0000u); }
;     __device__ __forceinline__ void operator()(const f32x4 (&acc)[2][2][4][2], const Unit& u, int wr, int wc, int fr, int fq) const {
;     ...
;             for (int ai = 0; ai < 2; ++ai)
; #pragma unroll
;                 for (int m = 0; m < 4; ++m)
; #pragma unroll
;                     for (int bj = 0; bj < 2; ++bj) { const size_t o = (size_t)(row0 + ai * HALF + m * 16) * 2048 + col0 + bj * HALF; const u32x4 h4 = hv[ai][m][bj];
;                         const f32x4 r0 = (f32x4){bflo(h4.x), bfhi(h4.x), bflo(h4.y), bfhi(h4.y)}, r1 = (f32x4){bflo(h4.z), bfhi(h4.z), bflo(h4.w), bfhi(h4.w)};
;                         const f32x4 v0 = r0 + acc[ai][bj][m][0] * scale, v1 = r1 + acc[ai][bj][m][1] * scale;
;                         u32x4 w; w.x = cvt_pk_bf16(v0[0], v0[1]); w.y = cvt_pk_bf16(v0[2], v0[3]); w.z = cvt_pk_bf16(v1[0], v1[1]); w.w = cvt_pk_bf16(v1[2], v1[3]);
;                         *(u32x4*)(H + o) = w; }
	v_lshlrev_b32_e32 v102, 16, v219
	v_lshlrev_b32_e32 v96, 16, v216
	v_and_b32_e32 v97, 0xffff0000, v216
	v_and_b32_e32 v103, 0xffff0000, v219
	v_pk_fma_f32 v[92:93], v[92:93], 0.5, v[96:97] op_sel_hi:[1,0,1]
	v_lshlrev_b32_e32 v98, 16, v217
	v_and_b32_e32 v99, 0xffff0000, v217
	v_pk_fma_f32 v[96:97], v[90:91], 0.5, v[102:103] op_sel_hi:[1,0,1]
	v_pk_fma_f32 v[90:91], v[88:89], 0.5, v[100:101] op_sel_hi:[1,0,1]
	v_cvt_pk_bf16_f32 v88, v92, v93
	v_lshl_add_u64 v[92:93], s[10:11], 0, v[192:193]
	v_pk_fma_f32 v[94:95], v[94:95], 0.5, v[98:99] op_sel_hi:[1,0,1]
	v_lshl_add_u64 v[92:93], v[92:93], 0, v[180:181]
	v_cvt_pk_bf16_f32 v89, v94, v95
	v_cvt_pk_bf16_f32 v90, v90, v91
	v_cvt_pk_bf16_f32 v91, v96, v97
	global_store_dwordx4 v[92:93], v[88:91], off
	v_lshlrev_b32_e32 v94, 16, v222
	v_and_b32_e32 v95, 0xffff0000, v222
	v_lshlrev_b32_e32 v88, 16, v220
	v_and_b32_e32 v89, 0xffff0000, v220
	v_lshlrev_b32_e32 v90, 16, v221
	v_and_b32_e32 v91, 0xffff0000, v221
	v_lshlrev_b32_e32 v96, 16, v223
	v_and_b32_e32 v97, 0xffff0000, v223
	v_pk_fma_f32 v[86:87], v[86:87], 0.5, v[90:91] op_sel_hi:[1,0,1]
	v_pk_fma_f32 v[84:85], v[84:85], 0.5, v[88:89] op_sel_hi:[1,0,1]
	v_pk_fma_f32 v[88:89], v[82:83], 0.5, v[96:97] op_sel_hi:[1,0,1]
	v_pk_fma_f32 v[82:83], v[80:81], 0.5, v[94:95] op_sel_hi:[1,0,1]
	v_cvt_pk_bf16_f32 v80, v84, v85
	v_cvt_pk_bf16_f32 v81, v86, v87
	v_lshlrev_b32_e32 v84, 16, v226
	v_cvt_pk_bf16_f32 v82, v82, v83
	v_cvt_pk_bf16_f32 v83, v88, v89
	global_store_dwordx4 v[92:93], v[80:83], off offset:256
	v_and_b32_e32 v85, 0xffff0000, v226
	v_lshlrev_b32_e32 v86, 16, v227
	v_lshlrev_b32_e32 v80, 16, v224
	v_and_b32_e32 v81, 0xffff0000, v224
	v_and_b32_e32 v87, 0xffff0000, v227
	v_pk_fma_f32 v[76:77], v[76:77], 0.5, v[80:81] op_sel_hi:[1,0,1]
	v_lshlrev_b32_e32 v82, 16, v225
	v_and_b32_e32 v83, 0xffff0000, v225
	v_pk_fma_f32 v[80:81], v[74:75], 0.5, v[86:87] op_sel_hi:[1,0,1]
	v_pk_fma_f32 v[74:75], v[72:73], 0.5, v[84:85] op_sel_hi:[1,0,1]
	v_cvt_pk_bf16_f32 v72, v76, v77
	v_lshl_add_u64 v[76:77], s[10:11], 0, v[190:191]
	v_pk_fma_f32 v[78:79], v[78:79], 0.5, v[82:83] op_sel_hi:[1,0,1]
	v_lshl_add_u64 v[76:77], v[76:77], 0, v[180:181]
	v_cvt_pk_bf16_f32 v73, v78, v79
	v_cvt_pk_bf16_f32 v74, v74, v75
	v_cvt_pk_bf16_f32 v75, v80, v81
	global_store_dwordx4 v[76:77], v[72:75], off
	v_lshlrev_b32_e32 v78, 16, v162
	v_and_b32_e32 v79, 0xffff0000, v162
	v_lshlrev_b32_e32 v72, 16, v160
	v_and_b32_e32 v73, 0xffff0000, v160
	v_lshlrev_b32_e32 v74, 16, v161
	v_and_b32_e32 v75, 0xffff0000, v161
	v_lshlrev_b32_e32 v80, 16, v163
	v_and_b32_e32 v81, 0xffff0000, v163
	v_pk_fma_f32 v[70:71], v[70:71], 0.5, v[74:75] op_sel_hi:[1,0,1]
	v_pk_fma_f32 v[68:69], v[68:69], 0.5, v[72:73] op_sel_hi:[1,0,1]
	v_pk_fma_f32 v[72:73], v[66:67], 0.5, v[80:81] op_sel_hi:[1,0,1]
	v_pk_fma_f32 v[66:67], v[64:65], 0.5, v[78:79] op_sel_hi:[1,0,1]
	v_cvt_pk_bf16_f32 v64, v68, v69
	v_cvt_pk_bf16_f32 v65, v70, v71
	v_lshlrev_b32_e32 v68, 16, v158
	v_cvt_pk_bf16_f32 v66, v66, v67
	v_cvt_pk_bf16_f32 v67, v72, v73
	global_store_dwordx4 v[76:77], v[64:67], off offset:256
	v_and_b32_e32 v69, 0xffff0000, v158
	v_lshlrev_b32_e32 v70, 16, v159
	v_lshlrev_b32_e32 v64, 16, v156
	v_and_b32_e32 v65, 0xffff0000, v156
	v_and_b32_e32 v71, 0xffff0000, v159
	v_pk_fma_f32 v[60:61], v[60:61], 0.5, v[64:65] op_sel_hi:[1,0,1]
	v_lshlrev_b32_e32 v66, 16, v157
	v_and_b32_e32 v67, 0xffff0000, v157
	v_pk_fma_f32 v[64:65], v[58:59], 0.5, v[70:71] op_sel_hi:[1,0,1]
	v_pk_fma_f32 v[58:59], v[56:57], 0.5, v[68:69] op_sel_hi:[1,0,1]
	v_cvt_pk_bf16_f32 v56, v60, v61
	v_lshl_add_u64 v[60:61], s[10:11], 0, v[188:189]
	v_pk_fma_f32 v[62:63], v[62:63], 0.5, v[66:67] op_sel_hi:[1,0,1]
	v_lshl_add_u64 v[60:61], v[60:61], 0, v[180:181]
	v_cvt_pk_bf16_f32 v57, v62, v63
	v_cvt_pk_bf16_f32 v58, v58, v59
	v_cvt_pk_bf16_f32 v59, v64, v65
	global_store_dwordx4 v[60:61], v[56:59], off
	v_lshlrev_b32_e32 v62, 16, v154
	v_and_b32_e32 v63, 0xffff0000, v154
	v_lshlrev_b32_e32 v56, 16, v152
	v_and_b32_e32 v57, 0xffff0000, v152
	v_lshlrev_b32_e32 v58, 16, v153
	v_and_b32_e32 v59, 0xffff0000, v153
	v_lshlrev_b32_e32 v64, 16, v155
	v_and_b32_e32 v65, 0xffff0000, v155
	v_pk_fma_f32 v[54:55], v[54:55], 0.5, v[58:59] op_sel_hi:[1,0,1]
	v_pk_fma_f32 v[52:53], v[52:53], 0.5, v[56:57] op_sel_hi:[1,0,1]
	v_pk_fma_f32 v[56:57], v[50:51], 0.5, v[64:65] op_sel_hi:[1,0,1]
	v_pk_fma_f32 v[50:51], v[48:49], 0.5, v[62:63] op_sel_hi:[1,0,1]
	v_cvt_pk_bf16_f32 v48, v52, v53
	v_cvt_pk_bf16_f32 v49, v54, v55
	v_lshlrev_b32_e32 v52, 16, v150
	v_cvt_pk_bf16_f32 v50, v50, v51
	v_cvt_pk_bf16_f32 v51, v56, v57
	global_store_dwordx4 v[60:61], v[48:51], off offset:256
	v_and_b32_e32 v53, 0xffff0000, v150
; __device__ __forceinline__ unsigned cvt_pk_bf16(float lo, float hi) { unsigned r; asm volatile("v_cvt_pk_bf16_f32 %0, %1, %2" : "=v"(r) : "v"(lo), "v"(hi)); return r; }
; __device__ __forceinline__ float bflo(unsigned w) { return __uint_as_float(w << 16); }
; __device__ __forceinline__ float bfhi(unsigned w) { return __uint_as_float(w & 0xffff0000u); }
; #define PG8_WAIT_V(n) asm volatile("s_waitcnt vmcnt(" #n ")" ::: "memory")
; #define PG8_BAR __builtin_amdgcn_s_barrier()
;     __device__ __forceinline__ void operator()(const f32x4 (&acc)[2][2][4][2], const Unit& u, int wr, int wc, int fr, int fq) const {
;     ...
;             for (int ai = 0; ai < 2; ++ai)
; #pragma unroll
;                 for (int m = 0; m < 4; ++m)
; #pragma unroll
;                     for (int bj = 0; bj < 2; ++bj) { const size_t o = (size_t)(row0 + ai * HALF + m * 16) * 2048 + col0 + bj * HALF; const u32x4 h4 = hv[ai][m][bj];
;                         const f32x4 r0 = (f32x4){bflo(h4.x), bfhi(h4.x), bflo(h4.y), bfhi(h4.y)}, r1 = (f32x4){bflo(h4.z), bfhi(h4.z), bflo(h4.w), bfhi(h4.w)};
;                         const f32x4 v0 = r0 + acc[ai][bj][m][0] * scale, v1 = r1 + acc[ai][bj][m][1] * scale;
;                         u32x4 w; w.x = cvt_pk_bf16(v0[0], v0[1]); w.y = cvt_pk_bf16(v0[2], v0[3]); w.z = cvt_pk_bf16(v1[0], v1[1]); w.w = cvt_pk_bf16(v1[2], v1[3]);
;                         *(u32x4*)(H + o) = w; }
; template <class Epi, class Sched>
; __device__ __forceinline__ void gemm_phase(PG8_LAS unsigned char* lds, const Gemm g, const Sched& S, const Epi& E) {
;     ...
;     PG8_WAIT_V(0);
;     if (wr == 0) PG8_BAR;
;     PG8_BAR;
	v_lshlrev_b32_e32 v54, 16, v151
	v_lshlrev_b32_e32 v48, 16, v148
	v_and_b32_e32 v49, 0xffff0000, v148
	v_and_b32_e32 v55, 0xffff0000, v151
	v_pk_fma_f32 v[44:45], v[44:45], 0.5, v[48:49] op_sel_hi:[1,0,1]
	v_lshlrev_b32_e32 v50, 16, v149
	v_and_b32_e32 v51, 0xffff0000, v149
	v_pk_fma_f32 v[48:49], v[42:43], 0.5, v[54:55] op_sel_hi:[1,0,1]
	v_pk_fma_f32 v[42:43], v[40:41], 0.5, v[52:53] op_sel_hi:[1,0,1]
	v_cvt_pk_bf16_f32 v40, v44, v45
	v_lshl_add_u64 v[44:45], s[10:11], 0, v[186:187]
	v_pk_fma_f32 v[46:47], v[46:47], 0.5, v[50:51] op_sel_hi:[1,0,1]
	v_lshl_add_u64 v[44:45], v[44:45], 0, v[180:181]
	v_cvt_pk_bf16_f32 v41, v46, v47
	v_cvt_pk_bf16_f32 v42, v42, v43
	v_cvt_pk_bf16_f32 v43, v48, v49
	global_store_dwordx4 v[44:45], v[40:43], off
	v_lshlrev_b32_e32 v46, 16, v146
	v_and_b32_e32 v47, 0xffff0000, v146
	v_lshlrev_b32_e32 v40, 16, v144
	v_and_b32_e32 v41, 0xffff0000, v144
	v_lshlrev_b32_e32 v42, 16, v145
	v_and_b32_e32 v43, 0xffff0000, v145
	v_lshlrev_b32_e32 v48, 16, v147
	v_and_b32_e32 v49, 0xffff0000, v147
	v_pk_fma_f32 v[38:39], v[38:39], 0.5, v[42:43] op_sel_hi:[1,0,1]
	v_pk_fma_f32 v[36:37], v[36:37], 0.5, v[40:41] op_sel_hi:[1,0,1]
	v_pk_fma_f32 v[40:41], v[34:35], 0.5, v[48:49] op_sel_hi:[1,0,1]
	v_pk_fma_f32 v[34:35], v[32:33], 0.5, v[46:47] op_sel_hi:[1,0,1]
	v_cvt_pk_bf16_f32 v32, v36, v37
	v_cvt_pk_bf16_f32 v33, v38, v39
	v_lshlrev_b32_e32 v36, 16, v142
	v_cvt_pk_bf16_f32 v34, v34, v35
	v_cvt_pk_bf16_f32 v35, v40, v41
	global_store_dwordx4 v[44:45], v[32:35], off offset:256
	v_and_b32_e32 v37, 0xffff0000, v142
	v_lshlrev_b32_e32 v38, 16, v143
	v_lshlrev_b32_e32 v32, 16, v140
	v_and_b32_e32 v33, 0xffff0000, v140
	v_and_b32_e32 v39, 0xffff0000, v143
	v_pk_fma_f32 v[28:29], v[28:29], 0.5, v[32:33] op_sel_hi:[1,0,1]
	v_lshlrev_b32_e32 v34, 16, v141
	v_and_b32_e32 v35, 0xffff0000, v141
	v_pk_fma_f32 v[32:33], v[26:27], 0.5, v[38:39] op_sel_hi:[1,0,1]
	v_pk_fma_f32 v[26:27], v[24:25], 0.5, v[36:37] op_sel_hi:[1,0,1]
	v_cvt_pk_bf16_f32 v24, v28, v29
	v_lshl_add_u64 v[28:29], s[10:11], 0, v[184:185]
	v_pk_fma_f32 v[30:31], v[30:31], 0.5, v[34:35] op_sel_hi:[1,0,1]
	v_lshl_add_u64 v[28:29], v[28:29], 0, v[180:181]
	v_cvt_pk_bf16_f32 v25, v30, v31
	v_cvt_pk_bf16_f32 v26, v26, v27
	v_cvt_pk_bf16_f32 v27, v32, v33
	global_store_dwordx4 v[28:29], v[24:27], off
	v_lshlrev_b32_e32 v30, 16, v138
	v_and_b32_e32 v31, 0xffff0000, v138
	v_lshlrev_b32_e32 v24, 16, v136
	v_and_b32_e32 v25, 0xffff0000, v136
	v_lshlrev_b32_e32 v26, 16, v137
	v_and_b32_e32 v27, 0xffff0000, v137
	v_lshlrev_b32_e32 v32, 16, v139
	v_and_b32_e32 v33, 0xffff0000, v139
	v_pk_fma_f32 v[22:23], v[22:23], 0.5, v[26:27] op_sel_hi:[1,0,1]
	v_pk_fma_f32 v[20:21], v[20:21], 0.5, v[24:25] op_sel_hi:[1,0,1]
	v_pk_fma_f32 v[24:25], v[18:19], 0.5, v[32:33] op_sel_hi:[1,0,1]
	v_pk_fma_f32 v[18:19], v[16:17], 0.5, v[30:31] op_sel_hi:[1,0,1]
	v_cvt_pk_bf16_f32 v16, v20, v21
	v_cvt_pk_bf16_f32 v17, v22, v23
	v_lshlrev_b32_e32 v20, 16, v134
	v_cvt_pk_bf16_f32 v18, v18, v19
	v_cvt_pk_bf16_f32 v19, v24, v25
	global_store_dwordx4 v[28:29], v[16:19], off offset:256
	v_and_b32_e32 v21, 0xffff0000, v134
	v_lshlrev_b32_e32 v22, 16, v135
	v_lshlrev_b32_e32 v16, 16, v132
	v_and_b32_e32 v17, 0xffff0000, v132
	v_and_b32_e32 v23, 0xffff0000, v135
	v_pk_fma_f32 v[12:13], v[12:13], 0.5, v[16:17] op_sel_hi:[1,0,1]
	v_lshlrev_b32_e32 v18, 16, v133
	v_and_b32_e32 v19, 0xffff0000, v133
	v_pk_fma_f32 v[16:17], v[10:11], 0.5, v[22:23] op_sel_hi:[1,0,1]
	v_pk_fma_f32 v[10:11], v[8:9], 0.5, v[20:21] op_sel_hi:[1,0,1]
	v_cvt_pk_bf16_f32 v8, v12, v13
	v_lshl_add_u64 v[12:13], s[10:11], 0, v[182:183]
	v_pk_fma_f32 v[14:15], v[14:15], 0.5, v[18:19] op_sel_hi:[1,0,1]
	v_lshl_add_u64 v[12:13], v[12:13], 0, v[180:181]
	v_cvt_pk_bf16_f32 v9, v14, v15
	v_cvt_pk_bf16_f32 v10, v10, v11
	v_cvt_pk_bf16_f32 v11, v16, v17
	global_store_dwordx4 v[12:13], v[8:11], off
	v_lshlrev_b32_e32 v14, 16, v130
	v_and_b32_e32 v15, 0xffff0000, v130
	v_lshlrev_b32_e32 v8, 16, v128
	v_and_b32_e32 v9, 0xffff0000, v128
	v_lshlrev_b32_e32 v16, 16, v131
	v_and_b32_e32 v17, 0xffff0000, v131
	v_lshlrev_b32_e32 v10, 16, v129
	v_and_b32_e32 v11, 0xffff0000, v129
	v_pk_fma_f32 v[4:5], v[4:5], 0.5, v[8:9] op_sel_hi:[1,0,1]
	v_pk_fma_f32 v[8:9], v[2:3], 0.5, v[16:17] op_sel_hi:[1,0,1]
	v_pk_fma_f32 v[2:3], v[0:1], 0.5, v[14:15] op_sel_hi:[1,0,1]
	v_pk_fma_f32 v[6:7], v[6:7], 0.5, v[10:11] op_sel_hi:[1,0,1]
	v_cvt_pk_bf16_f32 v0, v4, v5
	s_nop 0
	v_cvt_pk_bf16_f32 v1, v6, v7
	v_cvt_pk_bf16_f32 v2, v2, v3
	v_cvt_pk_bf16_f32 v3, v8, v9
	global_store_dwordx4 v[12:13], v[0:3], off offset:256
	s_cbranch_vccz .LBB0_969
	s_waitcnt vmcnt(0)
	s_cmpk_gt_u32 s36, 0xff
	s_cbranch_scc1 .LBB0_984

;     __host__ __device__ bool next(int i, Unit& u) const { const int j = i / 3; if (!StaticOrder::next(j, u)) return false; u.br = i - 3 * j; return true; }
; #define PG8_STAGE(bufoff, gbase, voff) do { _Pragma("unroll") for (int _i = 0; _i < 2; ++_i) \
;         __builtin_amdgcn_global_load_lds((const unsigned*)((const char*)(gbase) + (voff)[_i]), (PG8_LAS unsigned*)(lds + (bufoff) + ldsw + _i * 8192), 16, 0, 0); } while (0)
; #define PG8_WAIT_V(n) asm volatile("s_waitcnt vmcnt(" #n ")" ::: "memory")
; #define PG8_BAR __builtin_amdgcn_s_barrier()
; template <class Epi, class Sched>
; __device__ __forceinline__ void gemm_phase(PG8_LAS unsigned char* lds, const Gemm g, const Sched& S, const Epi& E) {
;     ...
;     for (int i = 0; i < 2; ++i) { int R, C; stage_rc(tid * 16 + i * 8192, R, C);
;         voffA[i] = (unsigned)(R * K + C) * 2u; voffB[i] = (unsigned)(tid * 16 + i * 8192); }
;     const size_t kstep = (size_t)(BK * 2);
;     const size_t hstep = (size_t)HALF * K * 2;
;     const size_t tstep = 2 * hstep;
;     const size_t kstepB = 32768, hstepB = 16384, tstepB = (size_t)nt * 32768;
;     const unsigned ldsw = (unsigned)wid * 1024u;
;     const int aoff = lds_byte(wr * 64 + fr, fq * 8), boff = lds_byte(wc * 32 + fr, fq * 8);
;     ...
;     Unit cur, nxt; int ui = 0;
;     if (!S.next(0, cur)) return;
;     f32x4 acc[2][2][4][2];
; #pragma unroll
;     for (int a = 0; a < 2; ++a)
; #pragma unroll
;         for (int b = 0; b < 2; ++b)
; #pragma unroll
;             for (int m = 0; m < 4; ++m)
; #pragma unroll
;                 for (int n = 0; n < 2; ++n) acc[a][b][m][n] = (f32x4){0.f, 0.f, 0.f, 0.f};
;     bf16x8 At[4][2], B0[2][2], B1[2][2];
;     const char* cA = (const char*)g.A + (size_t)cur.pm * tstep + (size_t)cur.br * g.strideA; const char* cB = (const char*)g.Bt + (size_t)cur.pn * tstepB + (size_t)cur.br * g.strideB;
;     S.a_ready(cur);
;     PG8_STAGE(PG8_SB(0, 0), cB, voffB); PG8_STAGE(PG8_SA(0, 0), cA, voffA); PG8_STAGE(PG8_SB(0, 1), cB + hstepB, voffB); PG8_STAGE(PG8_SA(0, 1), cA + hstep, voffA);
;     if (wr == 1) PG8_BAR;
;     PG8_WAIT_V(4); PG8_BAR;
;     PG8_STAGE(PG8_SB(1, 0), cB + kstepB, voffB); PG8_STAGE(PG8_SA(1, 0), cA + kstep, voffA); PG8_STAGE(PG8_SB(1, 1), cB + hstepB + kstepB, voffB);
;     PG8_WAIT_V(6); PG8_BAR;
.LBB0_1146:
	s_or_b64 exec, exec, s[4:5]
	s_mov_b64 s[4:5], s[0:1]
	s_mov_b32 s28, s40
	s_mov_b32 s29, s2
	v_mov_b32_e32 v4, v228
	s_waitcnt lgkmcnt(0)
	s_barrier
	s_cmpk_gt_i32 s29, 0xabf
	v_readfirstlane_b32 s30, v4
	s_cbranch_scc1 .LBB0_1158
	s_load_dwordx2 s[6:7], s[4:5], 0xa8
	v_lshlrev_b32_e32 v128, 4, v4
	s_mul_hi_i32 s4, s29, 0x2fa0be83
	v_add_u32_e32 v130, 0x2000, v128
	v_ashrrev_i32_e32 v0, 31, v130
	s_waitcnt lgkmcnt(0)
	s_add_u32 s31, s6, 0xc700000
	s_addc_u32 s36, s7, 0
	s_lshr_b32 s8, s4, 31
	s_lshr_b32 s4, s4, 9
	s_add_i32 s4, s4, s8
	v_lshrrev_b32_e32 v0, 22, v0
	s_mulk_i32 s4, 0xac0
	v_add_u32_e32 v0, v130, v0
	s_sub_i32 s4, s29, s4
	v_ashrrev_i32_e32 v5, 10, v0
	s_sext_i32_i16 s8, s4
	v_mul_i32_i24_e32 v1, 0x400, v5
	s_bfe_u32 s8, s8, 0x3001c
	v_sub_u32_e32 v1, v130, v1
	s_add_i32 s8, s4, s8
	v_lshrrev_b32_e32 v2, 4, v1
	s_sext_i32_i16 s9, s8
	s_and_b32 s8, s8, 0xfff8
	s_ashr_i32 s10, s30, 6
	v_bitop3_b32 v1, v2, v1, 32 bitop3:0x6c
	s_sub_i32 s4, s4, s8
	s_ashr_i32 s5, s30, 8
	s_ashr_i32 s37, s29, 31
	s_lshl_b32 s38, s10, 10
	v_ashrrev_i32_e32 v2, 31, v1
	s_ashr_i32 s9, s9, 3
	s_sext_i32_i16 s8, s4
	v_lshrrev_b32_e32 v2, 26, v2
	s_cmp_lt_i32 s8, 0
	s_movk_i32 s39, 0x159
	v_add_u32_e32 v2, v1, v2
	s_cselect_b32 s8, s39, 0x158
	v_ashrrev_i32_e32 v6, 6, v2
	v_and_b32_e32 v2, 0xc0, v2
	s_mul_i32 s4, s8, s4
	v_sub_u32_e32 v1, v1, v2
	v_mov_b32_e32 v2, 1
	s_add_i32 s4, s4, s9
	v_ashrrev_i16_sdwa v1, v2, sext(v1) dst_sel:DWORD dst_unused:UNUSED_PAD src0_sel:DWORD src1_sel:BYTE_0
	s_sext_i32_i16 s8, s4
	v_lshlrev_b32_e32 v0, 5, v5
	v_bfe_i32 v7, v1, 0, 16
	v_lshlrev_b32_e32 v1, 3, v5
	s_mulk_i32 s8, 0x2fa1
	v_and_b32_e32 v0, 32, v0
	v_and_b32_e32 v1, 0xffff0, v1
	s_lshr_b32 s9, s8, 31
	s_ashr_i32 s8, s8, 22
	v_add_u32_e32 v0, v0, v7
	v_add_lshl_u32 v1, v6, v1, 12
	s_add_i32 s8, s8, s9
	v_lshl_add_u32 v132, v0, 1, v1
	v_bfe_i32 v1, v4, 27, 1
	s_lshl_b32 s9, s8, 3
	s_mulk_i32 s8, 0x158
	v_lshrrev_b32_e32 v1, 22, v1
	s_sub_i32 s8, s4, s8
	v_add_u32_e32 v1, v128, v1
	s_sext_i32_i16 s4, s8
	v_and_b32_e32 v1, 0xfffffc00, v1
	s_bfe_u32 s4, s4, 0x3001c
	v_sub_u32_e32 v1, v128, v1
	s_add_i32 s11, s8, s4
	v_lshrrev_b32_e32 v3, 4, v1
	s_sext_i32_i16 s4, s11
	s_and_b32 s11, s11, 0xfff8
	v_bitop3_b32 v1, v3, v1, 32 bitop3:0x6c
	s_sub_i32 s8, s8, s11
	v_ashrrev_i32_e32 v3, 31, v1
	s_sext_i32_i16 s8, s8
	v_lshrrev_b32_e32 v3, 26, v3
	s_lshr_b32 s4, s4, 3
	s_add_i32 s20, s9, s8
	v_ashrrev_i32_e32 v0, 31, v4
	v_add_u32_e32 v3, v1, v3
	s_ashr_i32 s21, s20, 31
	s_bfe_i64 s[12:13], s[4:5], 0x100000
	v_lshrrev_b32_e32 v0, 26, v0
	s_waitcnt vmcnt(9)
	v_ashrrev_i32_e32 v9, 6, v3
	v_and_b32_e32 v3, 0xc0, v3
	s_lshl_b64 s[8:9], s[20:21], 20
	s_lshl_b64 s[12:13], s[12:13], 20
	v_add_u32_e32 v0, v4, v0
	v_sub_u32_e32 v1, v1, v3
	s_add_u32 s22, s6, s12
	v_ashrrev_i32_e32 v8, 6, v0
	v_ashrrev_i16_sdwa v1, v2, sext(v1) dst_sel:DWORD dst_unused:UNUSED_PAD src0_sel:DWORD src1_sel:BYTE_0
	s_addc_u32 s23, s7, s13
	s_add_i32 s21, s38, 0
	v_lshlrev_b32_e32 v0, 5, v8
	v_bfe_i32 v10, v1, 0, 16
	v_lshlrev_b32_e32 v1, 3, v8
	s_add_i32 m0, s21, 0x10000
	v_and_b32_e32 v0, 32, v0
	v_and_b32_e32 v1, 0xffff0, v1
	global_load_lds_dwordx4 v128, s[22:23]
	s_add_i32 m0, s21, 0x12000
	v_add_u32_e32 v0, v0, v10
	v_add_lshl_u32 v1, v9, v1, 12
	s_add_u32 s24, s31, s8
	v_lshl_add_u32 v134, v0, 1, v1
	global_load_lds_dwordx4 v130, s[22:23]
	s_addc_u32 s25, s36, s9
	s_mov_b32 m0, s21
	s_add_i32 s46, s21, 0x2000
	global_load_lds_dwordx4 v134, s[24:25]
	s_mov_b32 m0, s46
	s_add_u32 s8, s22, 0x4000
	global_load_lds_dwordx4 v132, s[24:25]
	s_addc_u32 s9, s23, 0
	s_add_i32 m0, s21, 0x14000
	v_mov_b32_e32 v129, 0
	global_load_lds_dwordx4 v128, s[8:9]
	s_add_i32 m0, s21, 0x16000
	v_mov_b32_e32 v135, v129
	global_load_lds_dwordx4 v130, s[8:9]
	s_add_u32 s8, s24, 0x80000
	s_addc_u32 s9, s25, 0
	s_add_i32 s47, s21, 0x4000
	s_mov_b32 m0, s47
	s_add_i32 s48, s21, 0x6000
	global_load_lds_dwordx4 v134, s[8:9]
	s_mov_b32 m0, s48
	v_mov_b32_e32 v133, v129
	global_load_lds_dwordx4 v132, s[8:9]
	s_mov_b32 s49, 0
	v_mov_b32_e32 v131, v129
	v_lshl_add_u64 v[2:3], s[24:25], 0, v[134:135]
	s_cmp_lg_u32 s5, 1
	v_lshl_add_u64 v[0:1], s[24:25], 0, v[132:133]
	s_cbranch_scc1 .LBB0_1149
.LBB0_1149:
	s_add_u32 s8, s6, 0x10700000
	s_addc_u32 s9, s7, 0
	s_lshl_b32 s10, s10, 5
	s_and_b32 s15, s10, 0x60
	s_lshl_b32 s14, s5, 13
	s_lshl_b32 s16, s15, 7
	s_add_u32 s10, s22, 0x8000
	s_addc_u32 s11, s23, 0
	s_add_i32 m0, s21, 0x18000
	s_waitcnt vmcnt(0)
	v_lshl_add_u64 v[12:13], s[10:11], 0, v[128:129]
	s_waitcnt vmcnt(4)
	s_barrier
	global_load_lds_dwordx4 v[12:13], off
	v_lshl_add_u64 v[12:13], s[10:11], 0, v[130:131]
	s_add_i32 m0, s21, 0x1a000
	s_mov_b64 s[10:11], 0x80
	s_add_i32 s50, s21, 0x8000
	s_add_i32 s51, s21, 0xa000
	global_load_lds_dwordx4 v[12:13], off
	v_lshl_add_u64 v[2:3], v[2:3], 0, s[10:11]
	s_mov_b32 m0, s50
	s_add_u32 s12, s22, 0xc000
	global_load_lds_dwordx4 v[2:3], off
	v_lshl_add_u64 v[0:1], v[0:1], 0, s[10:11]
	s_mov_b32 m0, s51
	s_addc_u32 s13, s23, 0
	global_load_lds_dwordx4 v[0:1], off
	s_add_i32 m0, s21, 0x1c000
	v_lshl_add_u64 v[0:1], s[12:13], 0, v[128:129]
	global_load_lds_dwordx4 v[0:1], off
	v_lshl_add_u64 v[0:1], s[12:13], 0, v[130:131]
	s_add_i32 m0, s21, 0x1e000
	s_add_i32 s53, 0, 0x10000
	global_load_lds_dwordx4 v[0:1], off
	v_lshrrev_b32_e32 v1, 1, v4
	v_and_b32_e32 v1, 24, v1
	v_and_b32_e32 v0, 15, v4
	v_lshlrev_b32_e32 v2, 1, v1
	v_lshl_or_b32 v146, s5, 6, v0
	v_lshl_or_b32 v0, v0, 6, v2
	v_lshlrev_b32_e32 v2, 2, v4
	v_and_b32_e32 v2, 32, v2
	v_bitop3_b32 v3, v0, s14, v2 bitop3:0xde
	v_bitop3_b32 v147, v0, s16, v2 bitop3:0xde
	v_lshlrev_b32_e32 v0, 15, v8
	v_and_b32_e32 v0, 0xffff0000, v0
	v_or_b32_e32 v148, s15, v1
	v_lshl_add_u32 v0, v9, 12, v0
	v_and_b32_e32 v1, 1, v8
	v_lshl_or_b32 v0, v1, 6, v0
	v_lshl_add_u32 v136, v10, 1, v0
	v_lshlrev_b32_e32 v0, 15, v5
	v_and_b32_e32 v0, 0xffff0000, v0
	s_waitcnt vmcnt(6)
	v_lshl_add_u32 v0, v6, 12, v0
	v_and_b32_e32 v1, 1, v5
	v_lshl_or_b32 v0, v1, 6, v0
	s_add_i32 s54, 0, 0x14000
	s_sext_i32_i16 s56, s4
	s_ashr_i32 s52, s28, 31
	v_mov_b32_e32 v137, v129
	v_lshl_add_u32 v138, v7, 1, v0
	v_mov_b32_e32 v139, v129
	v_mov_b64_e32 v[140:141], 0xac0
	v_mov_b64_e32 v[142:143], 0xabf
	v_add_u32_e32 v149, s53, v147
	v_add_u32_e32 v150, 0, v3
	v_add_u32_e32 v151, s54, v147
	s_movk_i32 s55, 0x2b00
	s_barrier

;     __host__ __device__ bool next(int i, Unit& u) const { const int j = i / 3; if (!StaticOrder::next(j, u)) return false; u.br = i - 3 * j; return true; }
; #define PG8_STAGE(bufoff, gbase, voff) do { _Pragma("unroll") for (int _i = 0; _i < 2; ++_i) \
;         __builtin_amdgcn_global_load_lds((const unsigned*)((const char*)(gbase) + (voff)[_i]), (PG8_LAS unsigned*)(lds + (bufoff) + ldsw + _i * 8192), 16, 0, 0); } while (0)
; #define PG8_WAIT_V(n) asm volatile("s_waitcnt vmcnt(" #n ")" ::: "memory")
; #define PG8_BAR __builtin_amdgcn_s_barrier()
; template <class Epi, class Sched>
; __device__ __forceinline__ void gemm_phase(PG8_LAS unsigned char* lds, const Gemm g, const Sched& S, const Epi& E) {
;     ...
;     for (int i = 0; i < 2; ++i) { int R, C; stage_rc(tid * 16 + i * 8192, R, C);
;         voffA[i] = (unsigned)(R * K + C) * 2u; voffB[i] = (unsigned)(tid * 16 + i * 8192); }
;     const size_t kstep = (size_t)(BK * 2);
;     const size_t hstep = (size_t)HALF * K * 2;
;     const size_t tstep = 2 * hstep;
;     const size_t kstepB = 32768, hstepB = 16384, tstepB = (size_t)nt * 32768;
;     const unsigned ldsw = (unsigned)wid * 1024u;
;     const int aoff = lds_byte(wr * 64 + fr, fq * 8), boff = lds_byte(wc * 32 + fr, fq * 8);
;     ...
;     Unit cur, nxt; int ui = 0;
;     if (!S.next(0, cur)) return;
;     f32x4 acc[2][2][4][2];
; #pragma unroll
;     for (int a = 0; a < 2; ++a)
; #pragma unroll
;         for (int b = 0; b < 2; ++b)
; #pragma unroll
;             for (int m = 0; m < 4; ++m)
; #pragma unroll
;                 for (int n = 0; n < 2; ++n) acc[a][b][m][n] = (f32x4){0.f, 0.f, 0.f, 0.f};
;     bf16x8 At[4][2], B0[2][2], B1[2][2];
;     const char* cA = (const char*)g.A + (size_t)cur.pm * tstep + (size_t)cur.br * g.strideA; const char* cB = (const char*)g.Bt + (size_t)cur.pn * tstepB + (size_t)cur.br * g.strideB;
;     S.a_ready(cur);
;     PG8_STAGE(PG8_SB(0, 0), cB, voffB); PG8_STAGE(PG8_SA(0, 0), cA, voffA); PG8_STAGE(PG8_SB(0, 1), cB + hstepB, voffB); PG8_STAGE(PG8_SA(0, 1), cA + hstep, voffA);
;     if (wr == 1) PG8_BAR;
;     PG8_WAIT_V(4); PG8_BAR;
;     PG8_STAGE(PG8_SB(1, 0), cB + kstepB, voffB); PG8_STAGE(PG8_SA(1, 0), cA + kstep, voffA); PG8_STAGE(PG8_SB(1, 1), cB + hstepB + kstepB, voffB);
;     PG8_WAIT_V(6); PG8_BAR;
.LBB0_1215:
	v_ashrrev_i32_e32 v0, 31, v4
	v_lshrrev_b32_e32 v0, 26, v0
	v_add_u32_e32 v0, v4, v0
	v_ashrrev_i32_e32 v5, 6, v0
	v_bfe_i32 v0, v4, 27, 1
	v_lshlrev_b32_e32 v164, 4, v4
	v_lshrrev_b32_e32 v0, 22, v0
	v_add_u32_e32 v0, v164, v0
	v_and_b32_e32 v0, 0xfffffc00, v0
	v_sub_u32_e32 v0, v164, v0
	v_lshrrev_b32_e32 v1, 4, v0
	v_bitop3_b32 v0, v1, v0, 32 bitop3:0x6c
	v_ashrrev_i32_e32 v2, 31, v0
	v_lshrrev_b32_e32 v2, 26, v2
	s_waitcnt lgkmcnt(0)
	s_add_u32 s38, s4, 0x10700000
	v_add_u32_e32 v2, v0, v2
	s_addc_u32 s39, s5, 0
	v_lshlrev_b32_e32 v1, 3, v5
	v_ashrrev_i32_e32 v7, 6, v2
	v_and_b32_e32 v2, 0xc0, v2
	s_add_u32 s46, s4, 0x2b00000
	v_and_b32_e32 v1, 0x1fffff0, v1
	v_sub_u32_e32 v0, v0, v2
	v_mov_b32_e32 v2, 1
	s_addc_u32 s47, s5, 0
	v_add_u32_e32 v1, v7, v1
	v_lshlrev_b32_e32 v3, 5, v5
	v_ashrrev_i16_sdwa v0, v2, sext(v0) dst_sel:DWORD dst_unused:UNUSED_PAD src0_sel:DWORD src1_sel:BYTE_0
	s_movk_i32 s6, 0x1580
	s_add_i32 s9, s9, s10
	v_and_b32_e32 v6, 32, v3
	v_bfe_i32 v8, v0, 0, 16
	v_mul_lo_u32 v0, v1, s6
	s_sext_i32_i16 s10, s9
	v_or_b32_e32 v0, v0, v6
	v_add_u32_e32 v168, 0x2000, v164
	s_bfe_u32 s10, s10, 0x5001a
	v_add_lshl_u32 v166, v0, v8, 1
	v_ashrrev_i32_e32 v0, 31, v168
	s_add_i32 s10, s9, s10
	v_lshrrev_b32_e32 v0, 22, v0
	s_sext_i32_i16 s11, s10
	s_and_b32 s10, s10, 0xffe0
	v_add_u32_e32 v0, v168, v0
	s_sub_i32 s10, s9, s10
	v_ashrrev_i32_e32 v9, 10, v0
	s_bfe_i32 s9, s10, 0x80000
	v_mul_i32_i24_e32 v0, 0x400, v9
	s_bfe_u32 s9, s9, 0x2000d
	v_sub_u32_e32 v0, v168, v0
	s_add_i32 s12, s10, s9
	v_lshrrev_b32_e32 v1, 4, v0
	s_bfe_i32 s9, s12, 0x80000
	s_and_b32 s12, s12, 0xfc
	v_bitop3_b32 v0, v1, v0, 32 bitop3:0x6c
	s_ashr_i32 s11, s11, 5
	s_sext_i32_i16 s13, s9
	s_sub_i32 s10, s10, s12
	s_ashr_i32 s7, s36, 6
	v_ashrrev_i32_e32 v3, 31, v0
	s_lshl_b32 s11, s11, 2
	s_sext_i32_i8 s10, s10
	s_ashr_i32 s12, s13, 2
	v_lshrrev_b32_e32 v3, 26, v3
	s_ashr_i32 s8, s36, 8
	s_lshl_b32 s48, s7, 10
	s_lshr_b32 s9, s13, 2
	s_add_i32 s61, s11, s10
	s_mul_hi_i32 s13, s12, 0x2b0000
	s_mul_i32 s12, s12, 0x2b0000
	v_add_u32_e32 v3, v0, v3
	s_add_u32 s24, s46, s12
	v_lshlrev_b32_e32 v1, 3, v9
	v_ashrrev_i32_e32 v10, 6, v3
	v_and_b32_e32 v3, 0xc0, v3
	s_addc_u32 s25, s47, s13
	s_add_i32 s49, s48, 0
	v_and_b32_e32 v1, 0x1fffff0, v1
	v_sub_u32_e32 v0, v0, v3
	s_add_i32 m0, s49, 0x10000
	v_add_u32_e32 v1, v10, v1
	v_lshlrev_b32_e32 v11, 5, v9
	v_ashrrev_i16_sdwa v0, v2, sext(v0) dst_sel:DWORD dst_unused:UNUSED_PAD src0_sel:DWORD src1_sel:BYTE_0
	s_mul_i32 s11, s61, 0x2b0000
	global_load_lds_dwordx4 v164, s[24:25]
	s_add_i32 m0, s49, 0x12000
	v_and_b32_e32 v11, 32, v11
	v_bfe_i32 v12, v0, 0, 16
	v_mul_lo_u32 v0, v1, s6
	s_mul_hi_i32 s10, s61, 0x2b0000
	s_add_u32 s22, s38, s11
	v_or_b32_e32 v0, v0, v11
	global_load_lds_dwordx4 v168, s[24:25]
	s_addc_u32 s23, s39, s10
	s_mov_b32 m0, s49
	s_add_i32 s50, s49, 0x2000
	v_add_lshl_u32 v170, v0, v12, 1
	global_load_lds_dwordx4 v166, s[22:23]
	s_mov_b32 m0, s50
	s_add_u32 s10, s24, 0x4000
	global_load_lds_dwordx4 v170, s[22:23]
	s_addc_u32 s11, s25, 0
	s_add_i32 m0, s49, 0x14000
	v_mov_b32_e32 v165, 0
	global_load_lds_dwordx4 v164, s[10:11]
	s_add_i32 m0, s49, 0x16000
	v_mov_b32_e32 v167, v165
	global_load_lds_dwordx4 v168, s[10:11]
	s_add_u32 s10, s22, 0x158000
	s_addc_u32 s11, s23, 0
	s_add_i32 s51, s49, 0x4000
	s_mov_b32 m0, s51
	s_add_i32 s52, s49, 0x6000
	global_load_lds_dwordx4 v166, s[10:11]
	s_mov_b32 m0, s52
	v_mov_b32_e32 v171, v165
	global_load_lds_dwordx4 v170, s[10:11]
	s_mov_b32 s53, 0
	v_mov_b32_e32 v169, v165
	v_lshl_add_u64 v[2:3], s[22:23], 0, v[166:167]
	s_cmp_lg_u32 s8, 1
	v_lshl_add_u64 v[0:1], s[22:23], 0, v[170:171]
	s_cbranch_scc1 .LBB0_1217
.LBB0_1217:
	s_add_u32 s10, s4, 0x2dd24000
	s_addc_u32 s11, s5, 0
	s_lshl_b32 s4, s7, 5
	s_and_b32 s7, s4, 0x60
	s_lshl_b32 s14, s8, 13
	s_lshl_b32 s15, s7, 7
	s_add_u32 s4, s24, 0x8000
	s_addc_u32 s5, s25, 0
	s_add_i32 m0, s49, 0x18000
	v_lshl_add_u64 v[14:15], s[4:5], 0, v[164:165]
	s_waitcnt vmcnt(4)
	s_barrier
	global_load_lds_dwordx4 v[14:15], off
	v_lshl_add_u64 v[14:15], s[4:5], 0, v[168:169]
	s_add_i32 m0, s49, 0x1a000
	s_mov_b64 s[12:13], 0x80
	s_add_i32 s54, s49, 0x8000
	s_add_i32 s55, s49, 0xa000
	global_load_lds_dwordx4 v[14:15], off
	v_lshl_add_u64 v[2:3], v[2:3], 0, s[12:13]
	s_mov_b32 m0, s54
	s_add_u32 s4, s24, 0xc000
	global_load_lds_dwordx4 v[2:3], off
	v_lshl_add_u64 v[0:1], v[0:1], 0, s[12:13]
	s_mov_b32 m0, s55
	s_addc_u32 s5, s25, 0
	global_load_lds_dwordx4 v[0:1], off
	s_add_i32 m0, s49, 0x1c000
	v_lshl_add_u64 v[0:1], s[4:5], 0, v[164:165]
	global_load_lds_dwordx4 v[0:1], off
	v_lshl_add_u64 v[0:1], s[4:5], 0, v[168:169]
	s_add_i32 m0, s49, 0x1e000
	s_add_i32 s57, 0, 0x10000
	global_load_lds_dwordx4 v[0:1], off
	v_lshrrev_b32_e32 v1, 1, v4
	v_and_b32_e32 v1, 24, v1
	v_and_b32_e32 v0, 15, v4
	v_lshlrev_b32_e32 v2, 1, v1
	v_lshl_or_b32 v194, s8, 6, v0
	v_lshl_or_b32 v0, v0, 6, v2
	v_lshlrev_b32_e32 v2, 2, v4
	v_and_b32_e32 v2, 32, v2
	v_bitop3_b32 v3, v0, s14, v2 bitop3:0xde
	v_bitop3_b32 v195, v0, s15, v2 bitop3:0xde
	v_or_b32_e32 v196, s7, v1
	v_lshrrev_b32_e32 v1, 1, v5
	v_mul_lo_u32 v0, v7, s6
	s_mov_b32 s7, 0x15800
	v_mad_u64_u32 v[0:1], s[4:5], v1, s7, v[0:1]
	v_or_b32_e32 v0, v0, v6
	v_add_lshl_u32 v0, v0, v8, 1
	v_mov_b32_e32 v1, v165
	s_mov_b64 s[4:5], 0x158080
	v_lshl_add_u64 v[172:173], v[0:1], 0, s[4:5]
	v_lshrrev_b32_e32 v1, 1, v9
	v_mul_lo_u32 v0, v10, s6
	v_mad_u64_u32 v[0:1], s[6:7], v1, s7, v[0:1]
	s_waitcnt vmcnt(6)
	v_or_b32_e32 v0, v0, v11
	v_add_lshl_u32 v0, v0, v12, 1
	v_mov_b32_e32 v1, v165
	s_add_i32 s58, 0, 0x14000
	s_sext_i32_i8 s62, s9
	s_ashr_i32 s56, s31, 31
	v_lshl_add_u64 v[174:175], v[0:1], 0, s[4:5]
	v_mov_b64_e32 v[176:177], 0x200
	v_mov_b64_e32 v[178:179], 0x1ff
	v_add_u32_e32 v197, s57, v195
	v_add_u32_e32 v198, 0, v3
	v_add_u32_e32 v199, s58, v195
	s_mov_b64 s[14:15], 0x80000
	s_mov_b64 s[16:17], 0x90000
	s_mov_b64 s[18:19], 0xa0000
	s_mov_b64 s[20:21], 0xb0000
	s_barrier

;     __host__ __device__ bool next(int i, Unit& u) const { const int j = i / 3; if (!StaticOrder::next(j, u)) return false; u.br = i - 3 * j; return true; }
; #define PG8_STAGE(bufoff, gbase, voff) do { _Pragma("unroll") for (int _i = 0; _i < 2; ++_i) \
;         __builtin_amdgcn_global_load_lds((const unsigned*)((const char*)(gbase) + (voff)[_i]), (PG8_LAS unsigned*)(lds + (bufoff) + ldsw + _i * 8192), 16, 0, 0); } while (0)
; #define PG8_WAIT_V(n) asm volatile("s_waitcnt vmcnt(" #n ")" ::: "memory")
; #define PG8_BAR __builtin_amdgcn_s_barrier()
; template <class Epi, class Sched>
; __device__ __forceinline__ void gemm_phase(PG8_LAS unsigned char* lds, const Gemm g, const Sched& S, const Epi& E) {
;     ...
;     for (int i = 0; i < 2; ++i) { int R, C; stage_rc(tid * 16 + i * 8192, R, C);
;         voffA[i] = (unsigned)(R * K + C) * 2u; voffB[i] = (unsigned)(tid * 16 + i * 8192); }
;     const size_t kstep = (size_t)(BK * 2);
;     const size_t hstep = (size_t)HALF * K * 2;
;     const size_t tstep = 2 * hstep;
;     const size_t kstepB = 32768, hstepB = 16384, tstepB = (size_t)nt * 32768;
;     const unsigned ldsw = (unsigned)wid * 1024u;
;     const int aoff = lds_byte(wr * 64 + fr, fq * 8), boff = lds_byte(wc * 32 + fr, fq * 8);
;     ...
;     Unit cur, nxt; int ui = 0;
;     if (!S.next(0, cur)) return;
;     f32x4 acc[2][2][4][2];
; #pragma unroll
;     for (int a = 0; a < 2; ++a)
; #pragma unroll
;         for (int b = 0; b < 2; ++b)
; #pragma unroll
;             for (int m = 0; m < 4; ++m)
; #pragma unroll
;                 for (int n = 0; n < 2; ++n) acc[a][b][m][n] = (f32x4){0.f, 0.f, 0.f, 0.f};
;     bf16x8 At[4][2], B0[2][2], B1[2][2];
;     const char* cA = (const char*)g.A + (size_t)cur.pm * tstep + (size_t)cur.br * g.strideA; const char* cB = (const char*)g.Bt + (size_t)cur.pn * tstepB + (size_t)cur.br * g.strideB;
;     S.a_ready(cur);
;     PG8_STAGE(PG8_SB(0, 0), cB, voffB); PG8_STAGE(PG8_SA(0, 0), cA, voffA); PG8_STAGE(PG8_SB(0, 1), cB + hstepB, voffB); PG8_STAGE(PG8_SA(0, 1), cA + hstep, voffA);
;     if (wr == 1) PG8_BAR;
;     PG8_WAIT_V(4); PG8_BAR;
;     PG8_STAGE(PG8_SB(1, 0), cB + kstepB, voffB); PG8_STAGE(PG8_SA(1, 0), cA + kstep, voffA); PG8_STAGE(PG8_SB(1, 1), cB + hstepB + kstepB, voffB);
;     PG8_WAIT_V(6); PG8_BAR;
.LBB0_1345:
	s_andn2_b64 vcc, exec, s[4:5]
	s_cbranch_vccnz .LBB0_1453
	v_ashrrev_i32_e32 v0, 31, v4
	v_lshrrev_b32_e32 v0, 26, v0
	v_add_u32_e32 v0, v4, v0
	v_ashrrev_i32_e32 v5, 6, v0
	v_bfe_i32 v0, v4, 27, 1
	v_lshlrev_b32_e32 v128, 4, v4
	v_lshrrev_b32_e32 v0, 22, v0
	v_add_u32_e32 v0, v128, v0
	v_and_b32_e32 v0, 0xfffffc00, v0
	v_sub_u32_e32 v0, v128, v0
	v_lshrrev_b32_e32 v1, 4, v0
	v_bitop3_b32 v0, v1, v0, 32 bitop3:0x6c
	v_ashrrev_i32_e32 v2, 31, v0
	v_lshrrev_b32_e32 v2, 26, v2
	v_add_u32_e32 v2, v0, v2
	v_ashrrev_i32_e32 v6, 6, v2
	v_and_b32_e32 v2, 0xc0, v2
	v_sub_u32_e32 v0, v0, v2
	v_mov_b32_e32 v2, 1
	v_lshlrev_b32_e32 v1, 3, v5
	v_lshlrev_b32_e32 v3, 5, v5
	v_ashrrev_i16_sdwa v0, v2, sext(v0) dst_sel:DWORD dst_unused:UNUSED_PAD src0_sel:DWORD src1_sel:BYTE_0
	v_and_b32_e32 v1, 0xffff0, v1
	v_and_b32_e32 v3, 32, v3
	v_bfe_i32 v7, v0, 0, 16
	v_add_u32_e32 v0, v3, v7
	v_add_lshl_u32 v1, v6, v1, 12
	v_add_u32_e32 v132, 0x2000, v128
	v_lshl_add_u32 v130, v0, 1, v1
	v_ashrrev_i32_e32 v0, 31, v132
	v_lshrrev_b32_e32 v0, 22, v0
	v_add_u32_e32 v0, v132, v0
	v_ashrrev_i32_e32 v8, 10, v0
	v_mul_i32_i24_e32 v0, 0x400, v8
	s_waitcnt lgkmcnt(0)
	s_add_u32 s21, s10, 0xc700000
	v_sub_u32_e32 v0, v132, v0
	s_addc_u32 s23, s11, 0
	v_lshrrev_b32_e32 v1, 4, v0
	s_add_u32 s25, s10, 0x4080000
	v_bitop3_b32 v0, v1, v0, 32 bitop3:0x6c
	s_addc_u32 s27, s11, 0
	v_ashrrev_i32_e32 v3, 31, v0
	s_ashr_i32 s5, s19, 6
	s_ashr_i32 s47, s46, 31
	s_ashr_i32 s9, s8, 31
	s_ashr_i32 s4, s19, 8
	v_lshrrev_b32_e32 v3, 26, v3
	s_lshl_b32 s53, s5, 10
	s_lshl_b64 s[12:13], s[46:47], 20
	s_lshl_b64 s[6:7], s[8:9], 20
	v_add_u32_e32 v3, v0, v3
	s_add_u32 s6, s25, s6
	v_ashrrev_i32_e32 v9, 6, v3
	v_and_b32_e32 v3, 0xc0, v3
	s_addc_u32 s7, s27, s7
	s_add_i32 s54, s53, 0
	v_sub_u32_e32 v0, v0, v3
	s_add_i32 m0, s54, 0x10000
	v_lshlrev_b32_e32 v1, 3, v8
	v_lshlrev_b32_e32 v10, 5, v8
	v_ashrrev_i16_sdwa v0, v2, sext(v0) dst_sel:DWORD dst_unused:UNUSED_PAD src0_sel:DWORD src1_sel:BYTE_0
	global_load_lds_dwordx4 v128, s[6:7]
	s_add_i32 m0, s54, 0x12000
	v_and_b32_e32 v1, 0xffff0, v1
	v_and_b32_e32 v11, 32, v10
	v_bfe_i32 v10, v0, 0, 16
	s_add_u32 s48, s21, s12
	v_add_u32_e32 v0, v11, v10
	v_add_lshl_u32 v1, v9, v1, 12
	global_load_lds_dwordx4 v132, s[6:7]
	s_addc_u32 s49, s23, s13
	s_mov_b32 m0, s54
	s_add_i32 s55, s54, 0x2000
	v_lshl_add_u32 v134, v0, 1, v1
	global_load_lds_dwordx4 v130, s[48:49]
	s_mov_b32 m0, s55
	s_add_u32 s12, s6, 0x4000
	global_load_lds_dwordx4 v134, s[48:49]
	s_addc_u32 s13, s7, 0
	s_add_i32 m0, s54, 0x14000
	v_mov_b32_e32 v129, 0
	global_load_lds_dwordx4 v128, s[12:13]
	s_add_i32 m0, s54, 0x16000
	v_mov_b32_e32 v131, v129
	global_load_lds_dwordx4 v132, s[12:13]
	s_add_u32 s12, s48, 0x80000
	s_addc_u32 s13, s49, 0
	s_add_i32 s56, s54, 0x4000
	s_mov_b32 m0, s56
	s_add_i32 s57, s54, 0x6000
	global_load_lds_dwordx4 v130, s[12:13]
	s_mov_b32 m0, s57
	v_mov_b32_e32 v135, v129
	global_load_lds_dwordx4 v134, s[12:13]
	s_mov_b32 s58, 0
	v_mov_b32_e32 v133, v129
	v_lshl_add_u64 v[2:3], s[48:49], 0, v[130:131]
	s_cmp_lg_u32 s4, 1
	v_lshl_add_u64 v[0:1], s[48:49], 0, v[134:135]
	s_cbranch_scc1 .LBB0_1348
.LBB0_1348:
	s_lshl_b32 s5, s5, 5
	s_and_b32 s5, s5, 0x60
	s_lshl_b32 s9, s4, 13
	s_lshl_b32 s14, s5, 7
	s_add_u32 s12, s6, 0x8000
	s_addc_u32 s13, s7, 0
	s_add_i32 m0, s54, 0x18000
	v_lshl_add_u64 v[12:13], s[12:13], 0, v[128:129]
	s_waitcnt vmcnt(4)
	s_barrier
	global_load_lds_dwordx4 v[12:13], off
	v_lshl_add_u64 v[12:13], s[12:13], 0, v[132:133]
	s_add_i32 m0, s54, 0x1a000
	s_mov_b64 s[12:13], 0x80
	s_add_i32 s59, s54, 0x8000
	s_add_i32 s60, s54, 0xa000
	global_load_lds_dwordx4 v[12:13], off
	v_lshl_add_u64 v[2:3], v[2:3], 0, s[12:13]
	s_mov_b32 m0, s59
	s_add_u32 s28, s6, 0xc000
	global_load_lds_dwordx4 v[2:3], off
	v_lshl_add_u64 v[0:1], v[0:1], 0, s[12:13]
	s_mov_b32 m0, s60
	s_addc_u32 s29, s7, 0
	global_load_lds_dwordx4 v[0:1], off
	s_add_i32 m0, s54, 0x1c000
	v_lshl_add_u64 v[0:1], s[28:29], 0, v[128:129]
	global_load_lds_dwordx4 v[0:1], off
	v_lshl_add_u64 v[0:1], s[28:29], 0, v[132:133]
	s_add_i32 m0, s54, 0x1e000
	s_add_i32 s63, 0, 0x10000
	global_load_lds_dwordx4 v[0:1], off
	v_lshrrev_b32_e32 v1, 1, v4
	v_and_b32_e32 v1, 24, v1
	v_and_b32_e32 v0, 15, v4
	v_lshlrev_b32_e32 v2, 1, v1
	v_lshl_or_b32 v144, s4, 6, v0
	v_lshl_or_b32 v0, v0, 6, v2
	v_lshlrev_b32_e32 v2, 2, v4
	v_and_b32_e32 v2, 32, v2
	v_bitop3_b32 v3, v0, s9, v2 bitop3:0xde
	v_bitop3_b32 v145, v0, s14, v2 bitop3:0xde
	v_lshlrev_b32_e32 v0, 15, v5
	v_and_b32_e32 v0, 0xffff0000, v0
	v_or_b32_e32 v146, s5, v1
	v_lshl_add_u32 v0, v6, 12, v0
	v_and_b32_e32 v1, 1, v5
	v_lshl_or_b32 v0, v1, 6, v0
	v_lshl_add_u32 v136, v7, 1, v0
	v_lshlrev_b32_e32 v0, 15, v8
	v_and_b32_e32 v0, 0xffff0000, v0
	s_waitcnt vmcnt(6)
	v_lshl_add_u32 v0, v9, 12, v0
	v_and_b32_e32 v1, 1, v8
	v_lshl_or_b32 v0, v1, 6, v0
	s_add_i32 s64, 0, 0x14000
	s_ashr_i32 s61, s52, 31
	v_mov_b32_e32 v137, v129
	v_lshl_add_u32 v138, v10, 1, v0
	v_mov_b32_e32 v139, v129
	v_mov_b64_e32 v[140:141], 0xa80
	v_mov_b64_e32 v[142:143], 0xa7f
	s_movk_i32 s62, 0x151
	v_add_u32_e32 v147, s63, v145
	v_add_u32_e32 v148, 0, v3
	v_add_u32_e32 v149, s64, v145
	s_mov_b32 s14, 0x3e6d3388
	s_mov_b32 s16, 0x3f07dc22
	s_mov_b32 s18, 0xbf3a00e3
	s_mov_b32 s20, 0x3f35f0e3
	s_mov_b32 s22, 0xbe11a98e
	s_mov_b32 s24, 0x3e027906
	s_mov_b32 s26, 0xbf38aa3b
	s_movk_i32 s65, 0x1800
	s_mov_b32 s66, 0x1b300000
	s_barrier
	s_branch .LBB0_1351

; #define PG8_WAIT_V(n) asm volatile("s_waitcnt vmcnt(" #n ")" ::: "memory")
; #define PG8_BAR __builtin_amdgcn_s_barrier()
; template <class Epi, class Sched>
; __device__ __forceinline__ void gemm_phase(PG8_LAS unsigned char* lds, const Gemm g, const Sched& S, const Epi& E) {
;     ...
;     PG8_WAIT_V(0);
;     if (wr == 0) PG8_BAR;
;     PG8_BAR;
.LBB0_1450:
	s_waitcnt vmcnt(0)
	s_cmpk_gt_u32 s19, 0xff
	s_cbranch_scc1 .LBB0_1452
.LBB0_1452:
	s_barrier

;     __host__ __device__ bool next(int i, Unit& u) const { const int j = i / 3; if (!StaticOrder::next(j, u)) return false; u.br = i - 3 * j; return true; }
; #define PG8_STAGE(bufoff, gbase, voff) do { _Pragma("unroll") for (int _i = 0; _i < 2; ++_i) \
;         __builtin_amdgcn_global_load_lds((const unsigned*)((const char*)(gbase) + (voff)[_i]), (PG8_LAS unsigned*)(lds + (bufoff) + ldsw + _i * 8192), 16, 0, 0); } while (0)
; #define PG8_WAIT_V(n) asm volatile("s_waitcnt vmcnt(" #n ")" ::: "memory")
; #define PG8_BAR __builtin_amdgcn_s_barrier()
; template <class Epi, class Sched>
; __device__ __forceinline__ void gemm_phase(PG8_LAS unsigned char* lds, const Gemm g, const Sched& S, const Epi& E) {
;     ...
;     for (int i = 0; i < 2; ++i) { int R, C; stage_rc(tid * 16 + i * 8192, R, C);
;         voffA[i] = (unsigned)(R * K + C) * 2u; voffB[i] = (unsigned)(tid * 16 + i * 8192); }
;     const size_t kstep = (size_t)(BK * 2);
;     const size_t hstep = (size_t)HALF * K * 2;
;     const size_t tstep = 2 * hstep;
;     const size_t kstepB = 32768, hstepB = 16384, tstepB = (size_t)nt * 32768;
;     const unsigned ldsw = (unsigned)wid * 1024u;
;     const int aoff = lds_byte(wr * 64 + fr, fq * 8), boff = lds_byte(wc * 32 + fr, fq * 8);
;     ...
;     Unit cur, nxt; int ui = 0;
;     if (!S.next(0, cur)) return;
;     f32x4 acc[2][2][4][2];
; #pragma unroll
;     for (int a = 0; a < 2; ++a)
; #pragma unroll
;         for (int b = 0; b < 2; ++b)
; #pragma unroll
;             for (int m = 0; m < 4; ++m)
; #pragma unroll
;                 for (int n = 0; n < 2; ++n) acc[a][b][m][n] = (f32x4){0.f, 0.f, 0.f, 0.f};
;     bf16x8 At[4][2], B0[2][2], B1[2][2];
;     const char* cA = (const char*)g.A + (size_t)cur.pm * tstep + (size_t)cur.br * g.strideA; const char* cB = (const char*)g.Bt + (size_t)cur.pn * tstepB + (size_t)cur.br * g.strideB;
;     S.a_ready(cur);
;     PG8_STAGE(PG8_SB(0, 0), cB, voffB); PG8_STAGE(PG8_SA(0, 0), cA, voffA); PG8_STAGE(PG8_SB(0, 1), cB + hstepB, voffB); PG8_STAGE(PG8_SA(0, 1), cA + hstep, voffA);
;     if (wr == 1) PG8_BAR;
;     PG8_WAIT_V(4); PG8_BAR;
;     PG8_STAGE(PG8_SB(1, 0), cB + kstepB, voffB); PG8_STAGE(PG8_SA(1, 0), cA + kstep, voffA); PG8_STAGE(PG8_SB(1, 1), cB + hstepB + kstepB, voffB);
;     PG8_WAIT_V(6); PG8_BAR;
.LBB0_1459:
	s_andn2_b64 vcc, exec, s[6:7]
	s_cbranch_vccnz .LBB0_1539
	v_ashrrev_i32_e32 v0, 31, v4
	v_lshrrev_b32_e32 v0, 26, v0
	v_add_u32_e32 v0, v4, v0
	v_ashrrev_i32_e32 v5, 6, v0
	v_bfe_i32 v0, v4, 27, 1
	v_lshlrev_b32_e32 v128, 4, v4
	v_lshrrev_b32_e32 v0, 22, v0
	v_add_u32_e32 v0, v128, v0
	v_and_b32_e32 v0, 0xfffffc00, v0
	v_sub_u32_e32 v0, v128, v0
	v_lshrrev_b32_e32 v1, 4, v0
	v_bitop3_b32 v0, v1, v0, 32 bitop3:0x6c
	v_ashrrev_i32_e32 v2, 31, v0
	v_lshrrev_b32_e32 v2, 26, v2
	v_add_u32_e32 v2, v0, v2
	v_ashrrev_i32_e32 v6, 6, v2
	v_and_b32_e32 v2, 0xc0, v2
	v_sub_u32_e32 v0, v0, v2
	v_mov_b32_e32 v146, 1
	v_lshlrev_b32_e32 v1, 3, v5
	v_lshlrev_b32_e32 v3, 5, v5
	v_ashrrev_i16_sdwa v0, v146, sext(v0) dst_sel:DWORD dst_unused:UNUSED_PAD src0_sel:DWORD src1_sel:BYTE_0
	v_and_b32_e32 v1, 0xffff0, v1
	v_and_b32_e32 v3, 32, v3
	v_bfe_i32 v7, v0, 0, 16
	v_add_u32_e32 v0, v3, v7
	v_add_lshl_u32 v1, v6, v1, 12
	v_add_u32_e32 v132, 0x2000, v128
	v_lshl_add_u32 v130, v0, 1, v1
	v_ashrrev_i32_e32 v0, 31, v132
	v_lshrrev_b32_e32 v0, 22, v0
	v_add_u32_e32 v0, v132, v0
	v_ashrrev_i32_e32 v8, 10, v0
	s_waitcnt lgkmcnt(0)
	s_add_u32 s37, s10, 0x6a80000
	v_mul_i32_i24_e32 v0, 0x400, v8
	s_addc_u32 s38, s11, 0
	v_sub_u32_e32 v0, v132, v0
	s_ashr_i32 s7, s36, 6
	s_ashr_i32 s6, s36, 8
	v_lshrrev_b32_e32 v1, 4, v0
	s_lshl_b32 s39, s7, 10
	v_bitop3_b32 v0, v1, v0, 32 bitop3:0x6c
	s_add_u32 s46, s10, 0x2d300000
	v_ashrrev_i32_e32 v2, 31, v0
	s_addc_u32 s47, s11, 0
	s_ashr_i32 s23, s22, 31
	s_ashr_i32 s5, s4, 31
	v_lshrrev_b32_e32 v2, 26, v2
	s_lshl_b64 s[8:9], s[22:23], 20
	s_lshl_b64 s[12:13], s[4:5], 20
	v_add_u32_e32 v2, v0, v2
	s_add_u32 s24, s37, s12
	v_ashrrev_i32_e32 v9, 6, v2
	v_and_b32_e32 v2, 0xc0, v2
	s_addc_u32 s25, s38, s13
	s_add_i32 s48, s39, 0
	v_sub_u32_e32 v0, v0, v2
	s_add_i32 m0, s48, 0x10000
	v_lshlrev_b32_e32 v1, 3, v8
	v_lshlrev_b32_e32 v3, 5, v8
	v_ashrrev_i16_sdwa v0, v146, sext(v0) dst_sel:DWORD dst_unused:UNUSED_PAD src0_sel:DWORD src1_sel:BYTE_0
	global_load_lds_dwordx4 v128, s[24:25]
	s_add_i32 m0, s48, 0x12000
	v_and_b32_e32 v1, 0xffff0, v1
	v_and_b32_e32 v3, 32, v3
	v_bfe_i32 v10, v0, 0, 16
	s_add_u32 s26, s46, s8
	v_add_u32_e32 v0, v3, v10
	v_add_lshl_u32 v1, v9, v1, 12
	global_load_lds_dwordx4 v132, s[24:25]
	s_addc_u32 s27, s47, s9
	s_mov_b32 m0, s48
	s_add_i32 s49, s48, 0x2000
	v_lshl_add_u32 v134, v0, 1, v1
	global_load_lds_dwordx4 v130, s[26:27]
	s_mov_b32 m0, s49
	s_add_u32 s8, s24, 0x4000
	global_load_lds_dwordx4 v134, s[26:27]
	s_addc_u32 s9, s25, 0
	s_add_i32 m0, s48, 0x14000
	v_mov_b32_e32 v137, 0
	global_load_lds_dwordx4 v128, s[8:9]
	s_add_i32 m0, s48, 0x16000
	v_mov_b32_e32 v131, v137
	global_load_lds_dwordx4 v132, s[8:9]
	s_add_u32 s8, s26, 0x80000
	s_addc_u32 s9, s27, 0
	s_add_i32 s50, s48, 0x4000
	s_mov_b32 m0, s50
	s_add_i32 s51, s48, 0x6000
	global_load_lds_dwordx4 v130, s[8:9]
	s_mov_b32 m0, s51
	v_mov_b32_e32 v135, v137
	global_load_lds_dwordx4 v134, s[8:9]
	s_mov_b32 s53, 0
	v_mov_b32_e32 v129, v137
	v_mov_b32_e32 v133, v137
	v_lshl_add_u64 v[2:3], s[26:27], 0, v[130:131]
	s_cmp_lg_u32 s6, 1
	v_lshl_add_u64 v[0:1], s[26:27], 0, v[134:135]
	s_cbranch_scc1 .LBB0_1462
.LBB0_1462:
	s_lshl_b32 s54, s6, 6
	s_lshl_b32 s5, s6, 13
	s_lshl_b32 s6, s7, 5
	s_and_b32 s14, s6, 0x60
	s_lshl_b32 s15, s14, 7
	s_add_u32 s6, s10, 0x2d700000
	s_addc_u32 s7, s11, 0
	s_add_u32 s8, s10, 0x2db00000
	s_addc_u32 s9, s11, 0
	s_add_u32 s10, s24, 0x8000
	s_addc_u32 s11, s25, 0
	s_add_i32 m0, s48, 0x18000
	v_lshl_add_u64 v[12:13], s[10:11], 0, v[128:129]
	s_waitcnt vmcnt(4)
	s_barrier
	global_load_lds_dwordx4 v[12:13], off
	v_lshl_add_u64 v[12:13], s[10:11], 0, v[132:133]
	s_add_i32 m0, s48, 0x1a000
	s_mov_b64 s[10:11], 0x80
	s_add_i32 s55, s48, 0x8000
	s_add_i32 s56, s48, 0xa000
	global_load_lds_dwordx4 v[12:13], off
	v_lshl_add_u64 v[2:3], v[2:3], 0, s[10:11]
	s_mov_b32 m0, s55
	s_add_u32 s12, s24, 0xc000
	global_load_lds_dwordx4 v[2:3], off
	v_lshl_add_u64 v[0:1], v[0:1], 0, s[10:11]
	s_mov_b32 m0, s56
	s_addc_u32 s13, s25, 0
	global_load_lds_dwordx4 v[0:1], off
	s_add_i32 m0, s48, 0x1c000
	v_lshl_add_u64 v[0:1], s[12:13], 0, v[128:129]
	global_load_lds_dwordx4 v[0:1], off
	v_lshl_add_u64 v[0:1], s[12:13], 0, v[132:133]
	s_add_i32 m0, s48, 0x1e000
	v_and_b32_e32 v147, 15, v4
	global_load_lds_dwordx4 v[0:1], off
	v_lshrrev_b32_e32 v0, 1, v4
	v_and_b32_e32 v0, 24, v0
	v_lshlrev_b32_e32 v1, 1, v0
	v_lshlrev_b32_e32 v2, 2, v4
	v_or_b32_e32 v149, s14, v0
	v_lshlrev_b32_e32 v0, 15, v5
	v_lshl_or_b32 v1, v147, 6, v1
	v_and_b32_e32 v2, 32, v2
	v_and_b32_e32 v0, 0xffff0000, v0
	v_bitop3_b32 v3, v1, s5, v2 bitop3:0xde
	v_bitop3_b32 v148, v1, s15, v2 bitop3:0xde
	v_lshl_add_u32 v0, v6, 12, v0
	v_and_b32_e32 v1, 1, v5
	v_lshl_or_b32 v0, v1, 6, v0
	v_lshl_add_u32 v138, v7, 1, v0
	v_lshlrev_b32_e32 v0, 15, v8
	v_and_b32_e32 v0, 0xffff0000, v0
	s_waitcnt vmcnt(6)
	v_lshl_add_u32 v0, v9, 12, v0
	v_and_b32_e32 v1, 1, v8
	v_lshl_or_b32 v0, v1, 6, v0
	s_add_i32 s59, 0, 0x10000
	s_add_i32 s60, 0, 0x14000
	s_ashr_i32 s57, s52, 31
	v_mov_b32_e32 v139, v137
	v_lshl_add_u32 v140, v10, 1, v0
	v_mov_b32_e32 v141, v137
	s_movk_i32 s58, 0xf8
	v_add_u32_e32 v150, s59, v148
	v_add_u32_e32 v151, 0, v3
	v_add_u32_e32 v152, s60, v148
	s_movk_i32 s61, 0xdf
	s_movk_i32 s62, 0xef
	s_movk_i32 s63, 0xff
	v_mov_b32_e32 v153, 0xcf
	s_barrier
	s_branch .LBB0_1464

; #define PG8_WAIT_V(n) asm volatile("s_waitcnt vmcnt(" #n ")" ::: "memory")
; #define PG8_BAR __builtin_amdgcn_s_barrier()
; template <class Epi, class Sched>
; __device__ __forceinline__ void gemm_phase(PG8_LAS unsigned char* lds, const Gemm g, const Sched& S, const Epi& E) {
;     ...
;     PG8_WAIT_V(0);
;     if (wr == 0) PG8_BAR;
;     PG8_BAR;
.LBB0_1536:
	s_waitcnt vmcnt(0)
	s_cmpk_gt_u32 s36, 0xff
	s_cbranch_scc1 .LBB0_1538
.LBB0_1538:
	s_barrier

;     __host__ __device__ bool next(int i, Unit& u) const { const int j = i / 3; if (!StaticOrder::next(j, u)) return false; u.br = i - 3 * j; return true; }
; #define PG8_STAGE(bufoff, gbase, voff) do { _Pragma("unroll") for (int _i = 0; _i < 2; ++_i) \
;         __builtin_amdgcn_global_load_lds((const unsigned*)((const char*)(gbase) + (voff)[_i]), (PG8_LAS unsigned*)(lds + (bufoff) + ldsw + _i * 8192), 16, 0, 0); } while (0)
; #define PG8_BAR __builtin_amdgcn_s_barrier()
; template <class Epi, class Sched>
; __device__ __forceinline__ void gemm_phase(PG8_LAS unsigned char* lds, const Gemm g, const Sched& S, const Epi& E) {
;     ...
;     for (int i = 0; i < 2; ++i) { int R, C; stage_rc(tid * 16 + i * 8192, R, C);
;         voffA[i] = (unsigned)(R * K + C) * 2u; voffB[i] = (unsigned)(tid * 16 + i * 8192); }
;     const size_t kstep = (size_t)(BK * 2);
;     const size_t hstep = (size_t)HALF * K * 2;
;     const size_t tstep = 2 * hstep;
;     const size_t kstepB = 32768, hstepB = 16384, tstepB = (size_t)nt * 32768;
;     const unsigned ldsw = (unsigned)wid * 1024u;
;     const int aoff = lds_byte(wr * 64 + fr, fq * 8), boff = lds_byte(wc * 32 + fr, fq * 8);
;     ...
;     Unit cur, nxt; int ui = 0;
;     if (!S.next(0, cur)) return;
;     f32x4 acc[2][2][4][2];
; #pragma unroll
;     for (int a = 0; a < 2; ++a)
; #pragma unroll
;         for (int b = 0; b < 2; ++b)
; #pragma unroll
;             for (int m = 0; m < 4; ++m)
; #pragma unroll
;                 for (int n = 0; n < 2; ++n) acc[a][b][m][n] = (f32x4){0.f, 0.f, 0.f, 0.f};
;     bf16x8 At[4][2], B0[2][2], B1[2][2];
;     const char* cA = (const char*)g.A + (size_t)cur.pm * tstep + (size_t)cur.br * g.strideA; const char* cB = (const char*)g.Bt + (size_t)cur.pn * tstepB + (size_t)cur.br * g.strideB;
;     S.a_ready(cur);
;     PG8_STAGE(PG8_SB(0, 0), cB, voffB); PG8_STAGE(PG8_SA(0, 0), cA, voffA); PG8_STAGE(PG8_SB(0, 1), cB + hstepB, voffB); PG8_STAGE(PG8_SA(0, 1), cA + hstep, voffA);
;     if (wr == 1) PG8_BAR;
.LBB0_1674:
	s_andn2_b64 vcc, exec, s[10:11]
	s_cbranch_vccnz .LBB0_1790
	v_ashrrev_i32_e32 v0, 31, v1
	v_lshrrev_b32_e32 v0, 26, v0
	v_add_u32_e32 v0, v1, v0
	v_ashrrev_i32_e32 v6, 6, v0
	v_bfe_i32 v0, v1, 27, 1
	v_lshlrev_b32_e32 v196, 4, v1
	v_lshrrev_b32_e32 v0, 22, v0
	v_add_u32_e32 v0, v196, v0
	v_and_b32_e32 v0, 0xfffffc00, v0
	v_sub_u32_e32 v0, v196, v0
	v_lshrrev_b32_e32 v2, 4, v0
	v_bitop3_b32 v0, v2, v0, 32 bitop3:0x6c
	v_ashrrev_i32_e32 v3, 31, v0
	v_lshrrev_b32_e32 v3, 26, v3
	v_add_u32_e32 v3, v0, v3
	v_ashrrev_i32_e32 v7, 6, v3
	v_and_b32_e32 v3, 0xc0, v3
	v_sub_u32_e32 v0, v0, v3
	v_mov_b32_e32 v3, 1
	v_lshlrev_b32_e32 v2, 3, v6
	v_lshlrev_b32_e32 v4, 5, v6
	v_ashrrev_i16_sdwa v0, v3, sext(v0) dst_sel:DWORD dst_unused:UNUSED_PAD src0_sel:DWORD src1_sel:BYTE_0
	v_and_b32_e32 v2, 0x1ffff0, v2
	v_and_b32_e32 v4, 32, v4
	v_bfe_i32 v8, v0, 0, 16
	v_add_u32_e32 v0, v4, v8
	v_add_lshl_u32 v2, v7, v2, 11
	v_add_u32_e32 v200, 0x2000, v196
	v_lshl_add_u32 v198, v0, 1, v2
	v_ashrrev_i32_e32 v0, 31, v200
	v_lshrrev_b32_e32 v0, 22, v0
	v_add_u32_e32 v0, v200, v0
	v_ashrrev_i32_e32 v9, 10, v0
	v_mul_i32_i24_e32 v0, 0x400, v9
	s_waitcnt lgkmcnt(0)
	s_add_u32 s38, s4, 0x27300000
	v_sub_u32_e32 v0, v200, v0
	s_addc_u32 s39, s5, 0
	v_lshrrev_b32_e32 v2, 4, v0
	s_add_u32 s46, s4, 0x7280000
	v_bitop3_b32 v0, v2, v0, 32 bitop3:0x6c
	s_addc_u32 s47, s5, 0
	v_ashrrev_i32_e32 v4, 31, v0
	s_ashr_i32 s12, s37, 6
	s_ashr_i32 s7, s6, 31
	s_ashr_i32 s9, s8, 31
	s_ashr_i32 s14, s37, 8
	v_lshrrev_b32_e32 v4, 26, v4
	s_lshl_b32 s48, s12, 10
	s_lshl_b64 s[10:11], s[6:7], 19
	s_lshl_b64 s[16:17], s[8:9], 19
	v_add_u32_e32 v4, v0, v4
	s_add_u32 s24, s46, s16
	v_ashrrev_i32_e32 v10, 6, v4
	v_and_b32_e32 v4, 0xc0, v4
	s_addc_u32 s25, s47, s17
	s_add_i32 s49, s48, 0
	v_sub_u32_e32 v0, v0, v4
	s_add_i32 m0, s49, 0x10000
	v_lshlrev_b32_e32 v2, 3, v9
	v_lshlrev_b32_e32 v5, 5, v9
	v_ashrrev_i16_sdwa v0, v3, sext(v0) dst_sel:DWORD dst_unused:UNUSED_PAD src0_sel:DWORD src1_sel:BYTE_0
	global_load_lds_dwordx4 v196, s[24:25]
	s_add_i32 m0, s49, 0x12000
	v_and_b32_e32 v2, 0x1ffff0, v2
	v_and_b32_e32 v5, 32, v5
	v_bfe_i32 v11, v0, 0, 16
	s_add_u32 s26, s38, s10
	v_add_u32_e32 v0, v5, v11
	v_add_lshl_u32 v2, v10, v2, 11
	global_load_lds_dwordx4 v200, s[24:25]
	s_addc_u32 s27, s39, s11
	s_mov_b32 m0, s49
	s_add_i32 s50, s49, 0x2000
	v_lshl_add_u32 v202, v0, 1, v2
	global_load_lds_dwordx4 v198, s[26:27]
	s_mov_b32 m0, s50
	s_add_u32 s10, s24, 0x4000
	global_load_lds_dwordx4 v202, s[26:27]
	s_addc_u32 s11, s25, 0
	s_add_i32 m0, s49, 0x14000
	v_mov_b32_e32 v0, 0
	global_load_lds_dwordx4 v196, s[10:11]
	s_add_i32 m0, s49, 0x16000
	v_mov_b32_e32 v199, v0
	global_load_lds_dwordx4 v200, s[10:11]
	s_add_u32 s10, s26, 0x40000
	s_addc_u32 s11, s27, 0
	s_add_i32 s51, s49, 0x4000
	s_mov_b32 m0, s51
	s_add_i32 s52, s49, 0x6000
	global_load_lds_dwordx4 v198, s[10:11]
	s_mov_b32 m0, s52
	v_mov_b32_e32 v203, v0
	global_load_lds_dwordx4 v202, s[10:11]
	v_mov_b32_e32 v197, v0
	v_mov_b32_e32 v201, v0
	v_lshl_add_u64 v[4:5], s[26:27], 0, v[198:199]
	s_cmp_lg_u32 s14, 1
	v_lshl_add_u64 v[2:3], s[26:27], 0, v[202:203]
	s_cbranch_scc1 .LBB0_1677
; #define PG8_STAGE(bufoff, gbase, voff) do { _Pragma("unroll") for (int _i = 0; _i < 2; ++_i) \
;         __builtin_amdgcn_global_load_lds((const unsigned*)((const char*)(gbase) + (voff)[_i]), (PG8_LAS unsigned*)(lds + (bufoff) + ldsw + _i * 8192), 16, 0, 0); } while (0)
; #define PG8_WAIT_V(n) asm volatile("s_waitcnt vmcnt(" #n ")" ::: "memory")
; #define PG8_BAR __builtin_amdgcn_s_barrier()
; template <class Epi, class Sched>
; __device__ __forceinline__ void gemm_phase(PG8_LAS unsigned char* lds, const Gemm g, const Sched& S, const Epi& E) {
;     ...
;     f32x4 acc[2][2][4][2];
; #pragma unroll
;     for (int a = 0; a < 2; ++a)
; #pragma unroll
;         for (int b = 0; b < 2; ++b)
; #pragma unroll
;             for (int m = 0; m < 4; ++m)
; #pragma unroll
;                 for (int n = 0; n < 2; ++n) acc[a][b][m][n] = (f32x4){0.f, 0.f, 0.f, 0.f};
;     bf16x8 At[4][2], B0[2][2], B1[2][2];
;     const char* cA = (const char*)g.A + (size_t)cur.pm * tstep + (size_t)cur.br * g.strideA; const char* cB = (const char*)g.Bt + (size_t)cur.pn * tstepB + (size_t)cur.br * g.strideB;
;     S.a_ready(cur);
;     PG8_STAGE(PG8_SB(0, 0), cB, voffB); PG8_STAGE(PG8_SA(0, 0), cA, voffA); PG8_STAGE(PG8_SB(0, 1), cB + hstepB, voffB); PG8_STAGE(PG8_SA(0, 1), cA + hstep, voffA);
;     if (wr == 1) PG8_BAR;
;     PG8_WAIT_V(4); PG8_BAR;
;     PG8_STAGE(PG8_SB(1, 0), cB + kstepB, voffB); PG8_STAGE(PG8_SA(1, 0), cA + kstep, voffA); PG8_STAGE(PG8_SB(1, 1), cB + hstepB + kstepB, voffB);
;     PG8_WAIT_V(6); PG8_BAR;
.LBB0_1677:
	s_add_u32 s10, s4, 0xc700000
	s_addc_u32 s11, s5, 0
	s_add_u32 s53, s4, 0x1b300000
	s_addc_u32 s54, s5, 0
	s_lshl_b32 s4, s12, 5
	s_and_b32 s9, s4, 0x60
	s_lshl_b32 s7, s14, 13
	s_lshl_b32 s15, s9, 7
	s_add_u32 s4, s24, 0x8000
	s_addc_u32 s5, s25, 0
	s_add_i32 m0, s49, 0x18000
	v_lshl_add_u64 v[12:13], s[4:5], 0, v[196:197]
	s_waitcnt vmcnt(4)
	s_barrier
	global_load_lds_dwordx4 v[12:13], off
	v_lshl_add_u64 v[12:13], s[4:5], 0, v[200:201]
	s_add_i32 m0, s49, 0x1a000
	s_mov_b64 s[12:13], 0x80
	s_add_i32 s55, s49, 0x8000
	s_add_i32 s56, s49, 0xa000
	global_load_lds_dwordx4 v[12:13], off
	v_lshl_add_u64 v[4:5], v[4:5], 0, s[12:13]
	s_mov_b32 m0, s55
	s_add_u32 s4, s24, 0xc000
	global_load_lds_dwordx4 v[4:5], off
	v_lshl_add_u64 v[2:3], v[2:3], 0, s[12:13]
	s_mov_b32 m0, s56
	s_addc_u32 s5, s25, 0
	global_load_lds_dwordx4 v[2:3], off
	s_add_i32 m0, s49, 0x1c000
	v_lshl_add_u64 v[2:3], s[4:5], 0, v[196:197]
	global_load_lds_dwordx4 v[2:3], off
	v_lshl_add_u64 v[2:3], s[4:5], 0, v[200:201]
	s_add_i32 m0, s49, 0x1e000
	v_mov_b32_e32 v205, v0
	global_load_lds_dwordx4 v[2:3], off
	v_lshrrev_b32_e32 v3, 1, v1
	v_and_b32_e32 v3, 24, v3
	v_and_b32_e32 v2, 15, v1
	v_lshlrev_b32_e32 v4, 1, v3
	v_lshlrev_b32_e32 v1, 2, v1
	v_lshl_or_b32 v230, s14, 6, v2
	v_lshl_or_b32 v2, v2, 6, v4
	v_and_b32_e32 v1, 32, v1
	v_bitop3_b32 v4, v2, s7, v1 bitop3:0xde
	v_bitop3_b32 v231, v2, s15, v1 bitop3:0xde
	v_lshlrev_b32_e32 v1, 14, v6
	v_and_b32_e32 v1, 0xffff8000, v1
	v_lshl_add_u32 v1, v7, 11, v1
	v_and_b32_e32 v2, 1, v6
	v_lshl_or_b32 v1, v2, 6, v1
	v_lshl_add_u32 v204, v8, 1, v1
	v_lshlrev_b32_e32 v1, 14, v9
	v_and_b32_e32 v1, 0xffff8000, v1
	v_lshl_add_u32 v1, v10, 11, v1
	v_and_b32_e32 v2, 1, v9
	s_waitcnt vmcnt(6)
	v_or_b32_e32 v232, s9, v3
	v_lshl_or_b32 v1, v2, 6, v1
	v_mov_b32_e32 v2, v0
	v_mov_b32_e32 v3, v0
	v_lshl_add_u32 v206, v11, 1, v1
	v_mov_b32_e32 v1, v0
	v_add_u32_e32 v233, 0, v4
	v_mov_b64_e32 v[38:39], v[2:3]
	v_mov_b64_e32 v[42:43], v[2:3]
	v_mov_b64_e32 v[46:47], v[2:3]
	v_mov_b64_e32 v[50:51], v[2:3]
	v_mov_b64_e32 v[54:55], v[2:3]
	v_mov_b64_e32 v[58:59], v[2:3]
	v_mov_b64_e32 v[62:63], v[2:3]
	v_mov_b64_e32 v[66:67], v[2:3]
	v_mov_b64_e32 v[70:71], v[2:3]
	v_mov_b64_e32 v[74:75], v[2:3]
	v_mov_b64_e32 v[78:79], v[2:3]
	v_mov_b64_e32 v[82:83], v[2:3]
	v_mov_b64_e32 v[86:87], v[2:3]
	v_mov_b64_e32 v[90:91], v[2:3]
	v_mov_b64_e32 v[94:95], v[2:3]
	v_mov_b64_e32 v[98:99], v[2:3]
	v_mov_b64_e32 v[102:103], v[2:3]
	v_mov_b64_e32 v[106:107], v[2:3]
	v_mov_b64_e32 v[110:111], v[2:3]
	v_mov_b64_e32 v[114:115], v[2:3]
	v_mov_b64_e32 v[118:119], v[2:3]
	v_mov_b64_e32 v[122:123], v[2:3]
	v_mov_b64_e32 v[126:127], v[2:3]
	v_mov_b64_e32 v[130:131], v[2:3]
	v_mov_b64_e32 v[14:15], v[2:3]
	v_mov_b64_e32 v[18:19], v[2:3]
	v_mov_b64_e32 v[22:23], v[2:3]
	v_mov_b64_e32 v[26:27], v[2:3]
	v_mov_b64_e32 v[30:31], v[2:3]
	v_mov_b64_e32 v[34:35], v[2:3]
	v_mov_b64_e32 v[10:11], v[2:3]
	v_mov_b64_e32 v[6:7], v[2:3]
	v_mov_b32_e32 v207, v0
	s_mov_b32 s9, 0
	v_mov_b64_e32 v[208:209], 0x200
	v_mov_b64_e32 v[210:211], 0x1ff
	s_add_i32 s57, 0, 0x10000
	s_add_i32 s58, 0, 0x14000
	s_movk_i32 s59, 0x3000
	v_mov_b64_e32 v[36:37], v[0:1]
	v_mov_b64_e32 v[40:41], v[0:1]
	v_mov_b64_e32 v[44:45], v[0:1]
	v_mov_b64_e32 v[48:49], v[0:1]
	v_mov_b64_e32 v[52:53], v[0:1]
	v_mov_b64_e32 v[56:57], v[0:1]
	v_mov_b64_e32 v[60:61], v[0:1]
	v_mov_b64_e32 v[64:65], v[0:1]
	v_mov_b64_e32 v[68:69], v[0:1]
	v_mov_b64_e32 v[72:73], v[0:1]
	v_mov_b64_e32 v[76:77], v[0:1]
	v_mov_b64_e32 v[80:81], v[0:1]
	v_mov_b64_e32 v[84:85], v[0:1]
	v_mov_b64_e32 v[88:89], v[0:1]
	v_mov_b64_e32 v[92:93], v[0:1]
	v_mov_b64_e32 v[96:97], v[0:1]
	v_mov_b64_e32 v[100:101], v[0:1]
	v_mov_b64_e32 v[104:105], v[0:1]
	v_mov_b64_e32 v[108:109], v[0:1]
	v_mov_b64_e32 v[112:113], v[0:1]
	v_mov_b64_e32 v[116:117], v[0:1]
	v_mov_b64_e32 v[120:121], v[0:1]
	v_mov_b64_e32 v[124:125], v[0:1]
	v_mov_b64_e32 v[128:129], v[0:1]
	v_mov_b64_e32 v[12:13], v[0:1]
	v_mov_b64_e32 v[16:17], v[0:1]
	v_mov_b64_e32 v[20:21], v[0:1]
	v_mov_b64_e32 v[24:25], v[0:1]
	v_mov_b64_e32 v[28:29], v[0:1]
	v_mov_b64_e32 v[32:33], v[0:1]
	v_mov_b64_e32 v[8:9], v[0:1]
	v_mov_b64_e32 v[4:5], v[0:1]
	s_mov_b32 s60, 0
	s_barrier
	s_branch .LBB0_1680

; #define PG8_WAIT_V(n) asm volatile("s_waitcnt vmcnt(" #n ")" ::: "memory")
; #define PG8_BAR __builtin_amdgcn_s_barrier()
; template <class Epi, class Sched>
; __device__ __forceinline__ void gemm_phase(PG8_LAS unsigned char* lds, const Gemm g, const Sched& S, const Epi& E) {
;     ...
;     PG8_WAIT_V(0);
;     if (wr == 0) PG8_BAR;
;     PG8_BAR;
.LBB0_1787:
	s_waitcnt vmcnt(0)
	s_cmpk_gt_u32 s37, 0xff
	s_cbranch_scc1 .LBB0_1789
.LBB0_1789:
	s_barrier

;     __host__ __device__ bool next(int i, Unit& u) const { const int j = i / 3; if (!StaticOrder::next(j, u)) return false; u.br = i - 3 * j; return true; }
; #define PG8_STAGE(bufoff, gbase, voff) do { _Pragma("unroll") for (int _i = 0; _i < 2; ++_i) \
;         __builtin_amdgcn_global_load_lds((const unsigned*)((const char*)(gbase) + (voff)[_i]), (PG8_LAS unsigned*)(lds + (bufoff) + ldsw + _i * 8192), 16, 0, 0); } while (0)
; #define PG8_WAIT_V(n) asm volatile("s_waitcnt vmcnt(" #n ")" ::: "memory")
; #define PG8_BAR __builtin_amdgcn_s_barrier()
; template <class Epi, class Sched>
; __device__ __forceinline__ void gemm_phase(PG8_LAS unsigned char* lds, const Gemm g, const Sched& S, const Epi& E) {
;     ...
;     for (int i = 0; i < 2; ++i) { int R, C; stage_rc(tid * 16 + i * 8192, R, C);
;         voffA[i] = (unsigned)(R * K + C) * 2u; voffB[i] = (unsigned)(tid * 16 + i * 8192); }
;     const size_t kstep = (size_t)(BK * 2);
;     const size_t hstep = (size_t)HALF * K * 2;
;     const size_t tstep = 2 * hstep;
;     const size_t kstepB = 32768, hstepB = 16384, tstepB = (size_t)nt * 32768;
;     const unsigned ldsw = (unsigned)wid * 1024u;
;     const int aoff = lds_byte(wr * 64 + fr, fq * 8), boff = lds_byte(wc * 32 + fr, fq * 8);
;     ...
;     Unit cur, nxt; int ui = 0;
;     if (!S.next(0, cur)) return;
;     f32x4 acc[2][2][4][2];
; #pragma unroll
;     for (int a = 0; a < 2; ++a)
; #pragma unroll
;         for (int b = 0; b < 2; ++b)
; #pragma unroll
;             for (int m = 0; m < 4; ++m)
; #pragma unroll
;                 for (int n = 0; n < 2; ++n) acc[a][b][m][n] = (f32x4){0.f, 0.f, 0.f, 0.f};
;     bf16x8 At[4][2], B0[2][2], B1[2][2];
;     const char* cA = (const char*)g.A + (size_t)cur.pm * tstep + (size_t)cur.br * g.strideA; const char* cB = (const char*)g.Bt + (size_t)cur.pn * tstepB + (size_t)cur.br * g.strideB;
;     S.a_ready(cur);
;     PG8_STAGE(PG8_SB(0, 0), cB, voffB); PG8_STAGE(PG8_SA(0, 0), cA, voffA); PG8_STAGE(PG8_SB(0, 1), cB + hstepB, voffB); PG8_STAGE(PG8_SA(0, 1), cA + hstep, voffA);
;     if (wr == 1) PG8_BAR;
;     PG8_WAIT_V(4); PG8_BAR;
;     PG8_STAGE(PG8_SB(1, 0), cB + kstepB, voffB); PG8_STAGE(PG8_SA(1, 0), cA + kstep, voffA); PG8_STAGE(PG8_SB(1, 1), cB + hstepB + kstepB, voffB);
;     PG8_WAIT_V(6); PG8_BAR;
.LBB0_1847:
	v_ashrrev_i32_e32 v0, 31, v4
	v_lshrrev_b32_e32 v0, 26, v0
	v_add_u32_e32 v0, v4, v0
	v_ashrrev_i32_e32 v5, 6, v0
	v_bfe_i32 v0, v4, 27, 1
	v_lshlrev_b32_e32 v164, 4, v4
	v_lshrrev_b32_e32 v0, 22, v0
	v_add_u32_e32 v0, v164, v0
	v_and_b32_e32 v0, 0xfffffc00, v0
	v_sub_u32_e32 v0, v164, v0
	s_waitcnt lgkmcnt(0)
	s_add_u32 s50, s4, 0xc700000
	v_lshrrev_b32_e32 v1, 4, v0
	s_addc_u32 s51, s5, 0
	v_bitop3_b32 v0, v1, v0, 32 bitop3:0x6c
	s_add_u32 s52, s4, 0x7e80000
	v_ashrrev_i32_e32 v2, 31, v0
	s_addc_u32 s53, s5, 0
	v_lshrrev_b32_e32 v2, 26, v2
	s_add_i32 s6, s8, s6
	v_add_u32_e32 v2, v0, v2
	s_sext_i32_i16 s7, s6
	v_lshlrev_b32_e32 v1, 3, v5
	v_ashrrev_i32_e32 v6, 6, v2
	v_and_b32_e32 v2, 0xc0, v2
	s_bfe_u32 s7, s7, 0x5001a
	v_and_b32_e32 v1, 0xffff0, v1
	v_lshlrev_b32_e32 v3, 5, v5
	v_sub_u32_e32 v0, v0, v2
	v_mov_b32_e32 v2, 1
	s_add_i32 s7, s6, s7
	v_add_u32_e32 v1, v6, v1
	v_and_b32_e32 v7, 32, v3
	v_ashrrev_i16_sdwa v0, v2, sext(v0) dst_sel:DWORD dst_unused:UNUSED_PAD src0_sel:DWORD src1_sel:BYTE_0
	s_sext_i32_i16 s8, s7
	s_and_b32 s7, s7, 0xffe0
	v_bfe_i32 v8, v0, 0, 16
	v_lshl_or_b32 v0, v1, 11, v7
	v_add_u32_e32 v168, 0x2000, v164
	s_sub_i32 s6, s6, s7
	v_add_lshl_u32 v166, v0, v8, 1
	v_ashrrev_i32_e32 v0, 31, v168
	s_bfe_i32 s7, s6, 0x80000
	v_lshrrev_b32_e32 v0, 22, v0
	s_bfe_u32 s7, s7, 0x2000d
	v_add_u32_e32 v0, v168, v0
	s_add_i32 s7, s6, s7
	v_ashrrev_i32_e32 v9, 10, v0
	s_bfe_i32 s9, s7, 0x80000
	s_and_b32 s7, s7, 0xfc
	v_mul_i32_i24_e32 v0, 0x400, v9
	s_ashr_i32 s8, s8, 5
	s_sub_i32 s6, s6, s7
	v_sub_u32_e32 v0, v168, v0
	s_lshl_b32 s8, s8, 2
	s_sext_i32_i16 s9, s9
	s_sext_i32_i8 s6, s6
	v_lshrrev_b32_e32 v1, 4, v0
	s_ashr_i32 s13, s48, 8
	s_lshr_b32 s12, s9, 2
	s_add_i32 s26, s8, s6
	s_ashr_i32 s10, s48, 6
	v_bitop3_b32 v0, v1, v0, 32 bitop3:0x6c
	s_ashr_i32 s27, s26, 31
	s_bfe_i64 s[8:9], s[12:13], 0x100000
	v_ashrrev_i32_e32 v3, 31, v0
	s_lshl_b32 s54, s10, 10
	s_lshl_b64 s[6:7], s[26:27], 20
	s_lshl_b64 s[8:9], s[8:9], 20
	v_lshrrev_b32_e32 v3, 26, v3
	s_add_u32 s30, s52, s8
	v_add_u32_e32 v3, v0, v3
	s_addc_u32 s31, s53, s9
	s_add_i32 s27, s54, 0
	v_lshlrev_b32_e32 v1, 3, v9
	v_ashrrev_i32_e32 v10, 6, v3
	v_and_b32_e32 v3, 0xc0, v3
	s_add_i32 m0, s27, 0x10000
	v_and_b32_e32 v1, 0xffff0, v1
	v_lshlrev_b32_e32 v11, 5, v9
	v_sub_u32_e32 v0, v0, v3
	global_load_lds_dwordx4 v164, s[30:31]
	s_add_i32 m0, s27, 0x12000
	v_add_u32_e32 v1, v10, v1
	v_and_b32_e32 v11, 32, v11
	v_ashrrev_i16_sdwa v0, v2, sext(v0) dst_sel:DWORD dst_unused:UNUSED_PAD src0_sel:DWORD src1_sel:BYTE_0
	s_add_u32 s28, s50, s6
	v_bfe_i32 v12, v0, 0, 16
	v_lshl_or_b32 v0, v1, 11, v11
	global_load_lds_dwordx4 v168, s[30:31]
	s_addc_u32 s29, s51, s7
	s_mov_b32 m0, s27
	s_add_i32 s55, s27, 0x2000
	v_add_lshl_u32 v170, v0, v12, 1
	global_load_lds_dwordx4 v166, s[28:29]
	s_mov_b32 m0, s55
	s_add_u32 s6, s30, 0x4000
	global_load_lds_dwordx4 v170, s[28:29]
	s_addc_u32 s7, s31, 0
	s_add_i32 m0, s27, 0x14000
	v_mov_b32_e32 v165, 0
	global_load_lds_dwordx4 v164, s[6:7]
	s_add_i32 m0, s27, 0x16000
	v_mov_b32_e32 v167, v165
	global_load_lds_dwordx4 v168, s[6:7]
	s_add_u32 s6, s28, 0x80000
	s_addc_u32 s7, s29, 0
	s_add_i32 s56, s27, 0x4000
	s_mov_b32 m0, s56
	s_add_i32 s57, s27, 0x6000
	global_load_lds_dwordx4 v166, s[6:7]
	s_mov_b32 m0, s57
	v_mov_b32_e32 v171, v165
	global_load_lds_dwordx4 v170, s[6:7]
	s_mov_b32 s58, 0
	v_mov_b32_e32 v169, v165
	v_lshl_add_u64 v[2:3], s[28:29], 0, v[166:167]
	v_lshl_add_u64 v[0:1], s[28:29], 0, v[170:171]
	s_cmp_lg_u32 s13, 1
	s_mov_b64 s[6:7], 0x80000
	s_cbranch_scc1 .LBB0_1849
.LBB0_1849:
	s_add_u32 s8, s4, 0x2dd24000
	s_addc_u32 s9, s5, 0
	s_lshl_b32 s4, s10, 5
	s_and_b32 s15, s4, 0x60
	s_lshl_b32 s14, s13, 13
	s_lshl_b32 s16, s15, 7
	s_add_u32 s4, s30, 0x8000
	s_addc_u32 s5, s31, 0
	s_add_i32 m0, s27, 0x18000
	v_lshl_add_u64 v[14:15], s[4:5], 0, v[164:165]
	s_waitcnt vmcnt(4)
	s_barrier
	global_load_lds_dwordx4 v[14:15], off
	v_lshl_add_u64 v[14:15], s[4:5], 0, v[168:169]
	s_add_i32 m0, s27, 0x1a000
	s_mov_b64 s[10:11], 0x80
	s_add_i32 s59, s27, 0x8000
	s_add_i32 s60, s27, 0xa000
	global_load_lds_dwordx4 v[14:15], off
	v_lshl_add_u64 v[2:3], v[2:3], 0, s[10:11]
	s_mov_b32 m0, s59
	s_add_u32 s4, s30, 0xc000
	global_load_lds_dwordx4 v[2:3], off
	v_lshl_add_u64 v[0:1], v[0:1], 0, s[10:11]
	s_mov_b32 m0, s60
	s_addc_u32 s5, s31, 0
	global_load_lds_dwordx4 v[0:1], off
	s_add_i32 m0, s27, 0x1c000
	v_lshl_add_u64 v[0:1], s[4:5], 0, v[164:165]
	global_load_lds_dwordx4 v[0:1], off
	v_lshl_add_u64 v[0:1], s[4:5], 0, v[168:169]
	s_add_i32 m0, s27, 0x1e000
	s_mov_b64 s[4:5], 0x80080
	global_load_lds_dwordx4 v[0:1], off
	v_lshrrev_b32_e32 v1, 1, v4
	v_and_b32_e32 v1, 24, v1
	v_and_b32_e32 v0, 15, v4
	v_lshlrev_b32_e32 v2, 1, v1
	v_lshl_or_b32 v194, s13, 6, v0
	v_lshl_or_b32 v0, v0, 6, v2
	v_lshlrev_b32_e32 v2, 2, v4
	v_and_b32_e32 v2, 32, v2
	v_bitop3_b32 v3, v0, s14, v2 bitop3:0xde
	v_bitop3_b32 v195, v0, s16, v2 bitop3:0xde
	v_lshlrev_b32_e32 v0, 14, v5
	v_and_b32_e32 v0, 0x7fff8000, v0
	v_lshl_add_u32 v0, v6, 11, v0
	v_or_b32_e32 v0, v0, v7
	v_or_b32_e32 v196, s15, v1
	v_add_lshl_u32 v0, v0, v8, 1
	v_mov_b32_e32 v1, v165
	v_lshl_add_u64 v[172:173], v[0:1], 0, s[4:5]
	v_lshlrev_b32_e32 v0, 14, v9
	v_and_b32_e32 v0, 0x7fff8000, v0
	v_lshl_add_u32 v0, v10, 11, v0
	s_waitcnt vmcnt(6)
	v_or_b32_e32 v0, v0, v11
	v_add_lshl_u32 v0, v0, v12, 1
	s_add_i32 s62, 0, 0x10000
	s_add_i32 s63, 0, 0x14000
	s_sext_i32_i8 s64, s12
	s_ashr_i32 s61, s46, 31
	v_lshl_add_u64 v[174:175], v[0:1], 0, s[4:5]
	v_mov_b64_e32 v[176:177], 0x200
	v_mov_b64_e32 v[178:179], 0x1ff
	v_add_u32_e32 v197, s62, v195
	v_add_u32_e32 v198, 0, v3
	v_add_u32_e32 v199, s63, v195
	s_mov_b64 s[12:13], 0x90000
	s_mov_b64 s[14:15], 0xa0000
	s_mov_b64 s[16:17], 0xb0000
	s_barrier

;     __host__ __device__ bool next(int i, Unit& u) const { const int j = i / 3; if (!StaticOrder::next(j, u)) return false; u.br = i - 3 * j; return true; }
; #define PG8_STAGE(bufoff, gbase, voff) do { _Pragma("unroll") for (int _i = 0; _i < 2; ++_i) \
;         __builtin_amdgcn_global_load_lds((const unsigned*)((const char*)(gbase) + (voff)[_i]), (PG8_LAS unsigned*)(lds + (bufoff) + ldsw + _i * 8192), 16, 0, 0); } while (0)
; #define PG8_WAIT_V(n) asm volatile("s_waitcnt vmcnt(" #n ")" ::: "memory")
; #define PG8_BAR __builtin_amdgcn_s_barrier()
; template <class Epi, class Sched>
; __device__ __forceinline__ void gemm_phase(PG8_LAS unsigned char* lds, const Gemm g, const Sched& S, const Epi& E) {
;     ...
;     for (int i = 0; i < 2; ++i) { int R, C; stage_rc(tid * 16 + i * 8192, R, C);
;         voffA[i] = (unsigned)(R * K + C) * 2u; voffB[i] = (unsigned)(tid * 16 + i * 8192); }
;     const size_t kstep = (size_t)(BK * 2);
;     const size_t hstep = (size_t)HALF * K * 2;
;     const size_t tstep = 2 * hstep;
;     const size_t kstepB = 32768, hstepB = 16384, tstepB = (size_t)nt * 32768;
;     const unsigned ldsw = (unsigned)wid * 1024u;
;     const int aoff = lds_byte(wr * 64 + fr, fq * 8), boff = lds_byte(wc * 32 + fr, fq * 8);
;     ...
;     Unit cur, nxt; int ui = 0;
;     if (!S.next(0, cur)) return;
;     f32x4 acc[2][2][4][2];
; #pragma unroll
;     for (int a = 0; a < 2; ++a)
; #pragma unroll
;         for (int b = 0; b < 2; ++b)
; #pragma unroll
;             for (int m = 0; m < 4; ++m)
; #pragma unroll
;                 for (int n = 0; n < 2; ++n) acc[a][b][m][n] = (f32x4){0.f, 0.f, 0.f, 0.f};
;     bf16x8 At[4][2], B0[2][2], B1[2][2];
;     const char* cA = (const char*)g.A + (size_t)cur.pm * tstep + (size_t)cur.br * g.strideA; const char* cB = (const char*)g.Bt + (size_t)cur.pn * tstepB + (size_t)cur.br * g.strideB;
;     S.a_ready(cur);
;     PG8_STAGE(PG8_SB(0, 0), cB, voffB); PG8_STAGE(PG8_SA(0, 0), cA, voffA); PG8_STAGE(PG8_SB(0, 1), cB + hstepB, voffB); PG8_STAGE(PG8_SA(0, 1), cA + hstep, voffA);
;     if (wr == 1) PG8_BAR;
;     PG8_WAIT_V(4); PG8_BAR;
;     PG8_STAGE(PG8_SB(1, 0), cB + kstepB, voffB); PG8_STAGE(PG8_SA(1, 0), cA + kstep, voffA); PG8_STAGE(PG8_SB(1, 1), cB + hstepB + kstepB, voffB);
;     PG8_WAIT_V(6); PG8_BAR;
.LBB0_1971:
	s_or_b64 exec, exec, s[4:5]
	s_mov_b64 s[4:5], s[0:1]
	s_mov_b32 s26, s40
	s_mov_b32 s27, s2
	v_mov_b32_e32 v4, v228
	s_waitcnt lgkmcnt(0)
	s_barrier
	s_cmpk_gt_i32 s27, 0xabf
	v_readfirstlane_b32 s28, v4
	s_cbranch_scc1 .LBB0_1983
	s_load_dwordx2 s[4:5], s[4:5], 0xa8
	v_lshlrev_b32_e32 v128, 4, v4
	s_mul_hi_i32 s6, s27, 0x2fa0be83
	v_add_u32_e32 v130, 0x2000, v128
	v_ashrrev_i32_e32 v0, 31, v130
	s_waitcnt lgkmcnt(0)
	s_add_u32 s29, s4, 0xc700000
	s_addc_u32 s30, s5, 0
	s_add_u32 s31, s4, 0x8680000
	s_addc_u32 s36, s5, 0
	s_lshr_b32 s7, s6, 31
	s_lshr_b32 s6, s6, 9
	s_add_i32 s6, s6, s7
	v_lshrrev_b32_e32 v0, 22, v0
	s_mulk_i32 s6, 0xac0
	v_add_u32_e32 v0, v130, v0
	s_sub_i32 s6, s27, s6
	v_ashrrev_i32_e32 v5, 10, v0
	s_sext_i32_i16 s7, s6
	v_mul_i32_i24_e32 v1, 0x400, v5
	s_bfe_u32 s7, s7, 0x3001c
	v_sub_u32_e32 v1, v130, v1
	s_add_i32 s7, s6, s7
	v_lshrrev_b32_e32 v2, 4, v1
	s_sext_i32_i16 s9, s7
	s_and_b32 s7, s7, 0xfff8
	s_ashr_i32 s8, s28, 6
	v_bitop3_b32 v1, v2, v1, 32 bitop3:0x6c
	s_sub_i32 s6, s6, s7
	s_ashr_i32 s11, s28, 8
	s_ashr_i32 s37, s27, 31
	s_lshl_b32 s38, s8, 10
	v_ashrrev_i32_e32 v2, 31, v1
	s_ashr_i32 s9, s9, 3
	s_sext_i32_i16 s7, s6
	v_lshrrev_b32_e32 v2, 26, v2
	s_cmp_lt_i32 s7, 0
	s_movk_i32 s39, 0x159
	v_add_u32_e32 v2, v1, v2
	s_cselect_b32 s7, s39, 0x158
	v_ashrrev_i32_e32 v6, 6, v2
	v_and_b32_e32 v2, 0xc0, v2
	s_mul_i32 s6, s7, s6
	v_sub_u32_e32 v1, v1, v2
	v_mov_b32_e32 v2, 1
	s_add_i32 s6, s6, s9
	v_ashrrev_i16_sdwa v1, v2, sext(v1) dst_sel:DWORD dst_unused:UNUSED_PAD src0_sel:DWORD src1_sel:BYTE_0
	s_sext_i32_i16 s7, s6
	v_lshlrev_b32_e32 v0, 5, v5
	v_bfe_i32 v7, v1, 0, 16
	v_lshlrev_b32_e32 v1, 3, v5
	s_mulk_i32 s7, 0x2fa1
	v_and_b32_e32 v0, 32, v0
	v_and_b32_e32 v1, 0xffff0, v1
	s_lshr_b32 s9, s7, 31
	s_ashr_i32 s7, s7, 22
	v_add_u32_e32 v0, v0, v7
	v_add_lshl_u32 v1, v6, v1, 12
	s_add_i32 s7, s7, s9
	v_lshl_add_u32 v132, v0, 1, v1
	v_bfe_i32 v1, v4, 27, 1
	s_lshl_b32 s9, s7, 3
	s_mulk_i32 s7, 0x158
	v_lshrrev_b32_e32 v1, 22, v1
	s_sub_i32 s6, s6, s7
	v_add_u32_e32 v1, v128, v1
	s_sext_i32_i16 s7, s6
	v_and_b32_e32 v1, 0xfffffc00, v1
	s_bfe_u32 s7, s7, 0x3001c
	v_sub_u32_e32 v1, v128, v1
	s_add_i32 s7, s6, s7
	v_lshrrev_b32_e32 v3, 4, v1
	s_sext_i32_i16 s10, s7
	s_and_b32 s7, s7, 0xfff8
	v_bitop3_b32 v1, v3, v1, 32 bitop3:0x6c
	s_sub_i32 s6, s6, s7
	v_ashrrev_i32_e32 v3, 31, v1
	s_sext_i32_i16 s6, s6
	v_lshrrev_b32_e32 v3, 26, v3
	s_lshr_b32 s10, s10, 3
	s_add_i32 s18, s9, s6
	v_ashrrev_i32_e32 v0, 31, v4
	v_add_u32_e32 v3, v1, v3
	s_ashr_i32 s19, s18, 31
	s_bfe_i64 s[12:13], s[10:11], 0x100000
	v_lshrrev_b32_e32 v0, 26, v0
	v_ashrrev_i32_e32 v9, 6, v3
	v_and_b32_e32 v3, 0xc0, v3
	s_lshl_b64 s[6:7], s[18:19], 20
	s_lshl_b64 s[12:13], s[12:13], 20
	v_add_u32_e32 v0, v4, v0
	v_sub_u32_e32 v1, v1, v3
	s_add_u32 s20, s31, s12
	v_ashrrev_i32_e32 v8, 6, v0
	v_ashrrev_i16_sdwa v1, v2, sext(v1) dst_sel:DWORD dst_unused:UNUSED_PAD src0_sel:DWORD src1_sel:BYTE_0
	s_addc_u32 s21, s36, s13
	s_add_i32 s19, s38, 0
	v_lshlrev_b32_e32 v0, 5, v8
	v_bfe_i32 v10, v1, 0, 16
	v_lshlrev_b32_e32 v1, 3, v8
	s_add_i32 m0, s19, 0x10000
	v_and_b32_e32 v0, 32, v0
	v_and_b32_e32 v1, 0xffff0, v1
	global_load_lds_dwordx4 v128, s[20:21]
	s_add_i32 m0, s19, 0x12000
	v_add_u32_e32 v0, v0, v10
	v_add_lshl_u32 v1, v9, v1, 12
	s_add_u32 s22, s29, s6
	v_lshl_add_u32 v134, v0, 1, v1
	global_load_lds_dwordx4 v130, s[20:21]
	s_addc_u32 s23, s30, s7
	s_mov_b32 m0, s19
	s_add_i32 s46, s19, 0x2000
	global_load_lds_dwordx4 v134, s[22:23]
	s_mov_b32 m0, s46
	s_add_u32 s6, s20, 0x4000
	global_load_lds_dwordx4 v132, s[22:23]
	s_addc_u32 s7, s21, 0
	s_add_i32 m0, s19, 0x14000
	v_mov_b32_e32 v129, 0
	global_load_lds_dwordx4 v128, s[6:7]
	s_add_i32 m0, s19, 0x16000
	v_mov_b32_e32 v135, v129
	global_load_lds_dwordx4 v130, s[6:7]
	s_add_u32 s6, s22, 0x80000
	s_addc_u32 s7, s23, 0
	s_add_i32 s47, s19, 0x4000
	s_mov_b32 m0, s47
	s_add_i32 s48, s19, 0x6000
	global_load_lds_dwordx4 v134, s[6:7]
	s_mov_b32 m0, s48
	v_mov_b32_e32 v133, v129
	global_load_lds_dwordx4 v132, s[6:7]
	s_mov_b32 s49, 0
	v_mov_b32_e32 v131, v129
	v_lshl_add_u64 v[2:3], s[22:23], 0, v[134:135]
	s_cmp_lg_u32 s11, 1
	v_lshl_add_u64 v[0:1], s[22:23], 0, v[132:133]
	s_cbranch_scc1 .LBB0_1974
.LBB0_1974:
	s_add_u32 s6, s4, 0x10700000
	s_addc_u32 s7, s5, 0
	s_lshl_b32 s4, s8, 5
	s_and_b32 s13, s4, 0x60
	s_lshl_b32 s12, s11, 13
	s_lshl_b32 s14, s13, 7
	s_add_u32 s4, s20, 0x8000
	s_addc_u32 s5, s21, 0
	s_add_i32 m0, s19, 0x18000
	v_lshl_add_u64 v[12:13], s[4:5], 0, v[128:129]
	s_waitcnt vmcnt(4)
	s_barrier
	global_load_lds_dwordx4 v[12:13], off
	v_lshl_add_u64 v[12:13], s[4:5], 0, v[130:131]
	s_add_i32 m0, s19, 0x1a000
	s_mov_b64 s[8:9], 0x80
	s_add_i32 s50, s19, 0x8000
	s_add_i32 s51, s19, 0xa000
	global_load_lds_dwordx4 v[12:13], off
	v_lshl_add_u64 v[2:3], v[2:3], 0, s[8:9]
	s_mov_b32 m0, s50
	s_add_u32 s4, s20, 0xc000
	global_load_lds_dwordx4 v[2:3], off
	v_lshl_add_u64 v[0:1], v[0:1], 0, s[8:9]
	s_mov_b32 m0, s51
	s_addc_u32 s5, s21, 0
	global_load_lds_dwordx4 v[0:1], off
	s_add_i32 m0, s19, 0x1c000
	v_lshl_add_u64 v[0:1], s[4:5], 0, v[128:129]
	global_load_lds_dwordx4 v[0:1], off
	v_lshl_add_u64 v[0:1], s[4:5], 0, v[130:131]
	s_add_i32 m0, s19, 0x1e000
	s_add_i32 s53, 0, 0x10000
	global_load_lds_dwordx4 v[0:1], off
	v_lshrrev_b32_e32 v1, 1, v4
	v_and_b32_e32 v1, 24, v1
	v_and_b32_e32 v0, 15, v4
	v_lshlrev_b32_e32 v2, 1, v1
	v_lshl_or_b32 v146, s11, 6, v0
	v_lshl_or_b32 v0, v0, 6, v2
	v_lshlrev_b32_e32 v2, 2, v4
	v_and_b32_e32 v2, 32, v2
	v_bitop3_b32 v3, v0, s12, v2 bitop3:0xde
	v_bitop3_b32 v147, v0, s14, v2 bitop3:0xde
	v_lshlrev_b32_e32 v0, 15, v8
	v_and_b32_e32 v0, 0xffff0000, v0
	v_or_b32_e32 v148, s13, v1
	v_lshl_add_u32 v0, v9, 12, v0
	v_and_b32_e32 v1, 1, v8
	v_lshl_or_b32 v0, v1, 6, v0
	v_lshl_add_u32 v136, v10, 1, v0
	v_lshlrev_b32_e32 v0, 15, v5
	v_and_b32_e32 v0, 0xffff0000, v0
	s_waitcnt vmcnt(6)
	v_lshl_add_u32 v0, v6, 12, v0
	v_and_b32_e32 v1, 1, v5
	v_lshl_or_b32 v0, v1, 6, v0
	s_add_i32 s54, 0, 0x14000
	s_sext_i32_i16 s56, s10
	s_ashr_i32 s52, s26, 31
	v_mov_b32_e32 v137, v129
	v_lshl_add_u32 v138, v7, 1, v0
	v_mov_b32_e32 v139, v129
	v_mov_b64_e32 v[140:141], 0xac0
	v_mov_b64_e32 v[142:143], 0xabf
	v_add_u32_e32 v149, s53, v147
	v_add_u32_e32 v150, 0, v3
	v_add_u32_e32 v151, s54, v147
	s_movk_i32 s55, 0x2b00
	s_barrier

;     __host__ __device__ bool next(int i, Unit& u) const { const int j = i / 3; if (!StaticOrder::next(j, u)) return false; u.br = i - 3 * j; return true; }
; #define PG8_STAGE(bufoff, gbase, voff) do { _Pragma("unroll") for (int _i = 0; _i < 2; ++_i) \
;         __builtin_amdgcn_global_load_lds((const unsigned*)((const char*)(gbase) + (voff)[_i]), (PG8_LAS unsigned*)(lds + (bufoff) + ldsw + _i * 8192), 16, 0, 0); } while (0)
; #define PG8_WAIT_V(n) asm volatile("s_waitcnt vmcnt(" #n ")" ::: "memory")
; #define PG8_BAR __builtin_amdgcn_s_barrier()
; template <class Epi, class Sched>
; __device__ __forceinline__ void gemm_phase(PG8_LAS unsigned char* lds, const Gemm g, const Sched& S, const Epi& E) {
;     ...
;     for (int i = 0; i < 2; ++i) { int R, C; stage_rc(tid * 16 + i * 8192, R, C);
;         voffA[i] = (unsigned)(R * K + C) * 2u; voffB[i] = (unsigned)(tid * 16 + i * 8192); }
;     const size_t kstep = (size_t)(BK * 2);
;     const size_t hstep = (size_t)HALF * K * 2;
;     const size_t tstep = 2 * hstep;
;     const size_t kstepB = 32768, hstepB = 16384, tstepB = (size_t)nt * 32768;
;     const unsigned ldsw = (unsigned)wid * 1024u;
;     const int aoff = lds_byte(wr * 64 + fr, fq * 8), boff = lds_byte(wc * 32 + fr, fq * 8);
;     ...
;     Unit cur, nxt; int ui = 0;
;     if (!S.next(0, cur)) return;
;     f32x4 acc[2][2][4][2];
; #pragma unroll
;     for (int a = 0; a < 2; ++a)
; #pragma unroll
;         for (int b = 0; b < 2; ++b)
; #pragma unroll
;             for (int m = 0; m < 4; ++m)
; #pragma unroll
;                 for (int n = 0; n < 2; ++n) acc[a][b][m][n] = (f32x4){0.f, 0.f, 0.f, 0.f};
;     bf16x8 At[4][2], B0[2][2], B1[2][2];
;     const char* cA = (const char*)g.A + (size_t)cur.pm * tstep + (size_t)cur.br * g.strideA; const char* cB = (const char*)g.Bt + (size_t)cur.pn * tstepB + (size_t)cur.br * g.strideB;
;     S.a_ready(cur);
;     PG8_STAGE(PG8_SB(0, 0), cB, voffB); PG8_STAGE(PG8_SA(0, 0), cA, voffA); PG8_STAGE(PG8_SB(0, 1), cB + hstepB, voffB); PG8_STAGE(PG8_SA(0, 1), cA + hstep, voffA);
;     if (wr == 1) PG8_BAR;
;     PG8_WAIT_V(4); PG8_BAR;
;     PG8_STAGE(PG8_SB(1, 0), cB + kstepB, voffB); PG8_STAGE(PG8_SA(1, 0), cA + kstep, voffA); PG8_STAGE(PG8_SB(1, 1), cB + hstepB + kstepB, voffB);
;     PG8_WAIT_V(6); PG8_BAR;
.LBB0_2040:
	v_ashrrev_i32_e32 v0, 31, v4
	v_lshrrev_b32_e32 v0, 26, v0
	v_add_u32_e32 v0, v4, v0
	v_ashrrev_i32_e32 v5, 6, v0
	v_bfe_i32 v0, v4, 27, 1
	v_lshlrev_b32_e32 v164, 4, v4
	v_lshrrev_b32_e32 v0, 22, v0
	v_add_u32_e32 v0, v164, v0
	v_and_b32_e32 v0, 0xfffffc00, v0
	v_sub_u32_e32 v0, v164, v0
	v_lshrrev_b32_e32 v1, 4, v0
	v_bitop3_b32 v0, v1, v0, 32 bitop3:0x6c
	v_ashrrev_i32_e32 v2, 31, v0
	v_lshrrev_b32_e32 v2, 26, v2
	s_waitcnt lgkmcnt(0)
	s_add_u32 s38, s4, 0x10700000
	v_add_u32_e32 v2, v0, v2
	s_addc_u32 s39, s5, 0
	v_lshlrev_b32_e32 v1, 3, v5
	v_ashrrev_i32_e32 v7, 6, v2
	v_and_b32_e32 v2, 0xc0, v2
	s_add_u32 s46, s4, 0xb180000
	v_and_b32_e32 v1, 0x1fffff0, v1
	v_sub_u32_e32 v0, v0, v2
	v_mov_b32_e32 v2, 1
	s_addc_u32 s47, s5, 0
	v_add_u32_e32 v1, v7, v1
	v_lshlrev_b32_e32 v3, 5, v5
	v_ashrrev_i16_sdwa v0, v2, sext(v0) dst_sel:DWORD dst_unused:UNUSED_PAD src0_sel:DWORD src1_sel:BYTE_0
	s_movk_i32 s6, 0x1580
	s_add_i32 s9, s9, s10
	v_and_b32_e32 v6, 32, v3
	v_bfe_i32 v8, v0, 0, 16
	v_mul_lo_u32 v0, v1, s6
	s_sext_i32_i16 s10, s9
	v_or_b32_e32 v0, v0, v6
	v_add_u32_e32 v168, 0x2000, v164
	s_bfe_u32 s10, s10, 0x5001a
	v_add_lshl_u32 v166, v0, v8, 1
	v_ashrrev_i32_e32 v0, 31, v168
	s_add_i32 s10, s9, s10
	v_lshrrev_b32_e32 v0, 22, v0
	s_sext_i32_i16 s11, s10
	s_and_b32 s10, s10, 0xffe0
	v_add_u32_e32 v0, v168, v0
	s_sub_i32 s10, s9, s10
	v_ashrrev_i32_e32 v9, 10, v0
	s_bfe_i32 s9, s10, 0x80000
	v_mul_i32_i24_e32 v0, 0x400, v9
	s_bfe_u32 s9, s9, 0x2000d
	v_sub_u32_e32 v0, v168, v0
	s_add_i32 s12, s10, s9
	v_lshrrev_b32_e32 v1, 4, v0
	s_bfe_i32 s9, s12, 0x80000
	s_and_b32 s12, s12, 0xfc
	v_bitop3_b32 v0, v1, v0, 32 bitop3:0x6c
	s_ashr_i32 s11, s11, 5
	s_sext_i32_i16 s13, s9
	s_sub_i32 s10, s10, s12
	s_ashr_i32 s7, s36, 6
	v_ashrrev_i32_e32 v3, 31, v0
	s_lshl_b32 s11, s11, 2
	s_sext_i32_i8 s10, s10
	s_ashr_i32 s12, s13, 2
	v_lshrrev_b32_e32 v3, 26, v3
	s_ashr_i32 s8, s36, 8
	s_lshl_b32 s48, s7, 10
	s_lshr_b32 s9, s13, 2
	s_add_i32 s61, s11, s10
	s_mul_hi_i32 s13, s12, 0x2b0000
	s_mul_i32 s12, s12, 0x2b0000
	v_add_u32_e32 v3, v0, v3
	s_add_u32 s24, s46, s12
	v_lshlrev_b32_e32 v1, 3, v9
	v_ashrrev_i32_e32 v10, 6, v3
	v_and_b32_e32 v3, 0xc0, v3
	s_addc_u32 s25, s47, s13
	s_add_i32 s49, s48, 0
	v_and_b32_e32 v1, 0x1fffff0, v1
	v_sub_u32_e32 v0, v0, v3
	s_add_i32 m0, s49, 0x10000
	v_add_u32_e32 v1, v10, v1
	v_lshlrev_b32_e32 v11, 5, v9
	v_ashrrev_i16_sdwa v0, v2, sext(v0) dst_sel:DWORD dst_unused:UNUSED_PAD src0_sel:DWORD src1_sel:BYTE_0
	s_mul_i32 s11, s61, 0x2b0000
	global_load_lds_dwordx4 v164, s[24:25]
	s_add_i32 m0, s49, 0x12000
	v_and_b32_e32 v11, 32, v11
	v_bfe_i32 v12, v0, 0, 16
	v_mul_lo_u32 v0, v1, s6
	s_mul_hi_i32 s10, s61, 0x2b0000
	s_add_u32 s22, s38, s11
	v_or_b32_e32 v0, v0, v11
	global_load_lds_dwordx4 v168, s[24:25]
	s_addc_u32 s23, s39, s10
	s_mov_b32 m0, s49
	s_add_i32 s50, s49, 0x2000
	v_add_lshl_u32 v170, v0, v12, 1
	global_load_lds_dwordx4 v166, s[22:23]
	s_mov_b32 m0, s50
	s_add_u32 s10, s24, 0x4000
	global_load_lds_dwordx4 v170, s[22:23]
	s_addc_u32 s11, s25, 0
	s_add_i32 m0, s49, 0x14000
	v_mov_b32_e32 v165, 0
	global_load_lds_dwordx4 v164, s[10:11]
	s_add_i32 m0, s49, 0x16000
	v_mov_b32_e32 v167, v165
	global_load_lds_dwordx4 v168, s[10:11]
	s_add_u32 s10, s22, 0x158000
	s_addc_u32 s11, s23, 0
	s_add_i32 s51, s49, 0x4000
	s_mov_b32 m0, s51
	s_add_i32 s52, s49, 0x6000
	global_load_lds_dwordx4 v166, s[10:11]
	s_mov_b32 m0, s52
	v_mov_b32_e32 v171, v165
	global_load_lds_dwordx4 v170, s[10:11]
	s_mov_b32 s53, 0
	v_mov_b32_e32 v169, v165
	v_lshl_add_u64 v[2:3], s[22:23], 0, v[166:167]
	s_cmp_lg_u32 s8, 1
	v_lshl_add_u64 v[0:1], s[22:23], 0, v[170:171]
	s_cbranch_scc1 .LBB0_2042
.LBB0_2042:
	s_add_u32 s10, s4, 0x2dd24000
	s_addc_u32 s11, s5, 0
	s_lshl_b32 s4, s7, 5
	s_and_b32 s7, s4, 0x60
	s_lshl_b32 s14, s8, 13
	s_lshl_b32 s15, s7, 7
	s_add_u32 s4, s24, 0x8000
	s_addc_u32 s5, s25, 0
	s_add_i32 m0, s49, 0x18000
	v_lshl_add_u64 v[14:15], s[4:5], 0, v[164:165]
	s_waitcnt vmcnt(4)
	s_barrier
	global_load_lds_dwordx4 v[14:15], off
	v_lshl_add_u64 v[14:15], s[4:5], 0, v[168:169]
	s_add_i32 m0, s49, 0x1a000
	s_mov_b64 s[12:13], 0x80
	s_add_i32 s54, s49, 0x8000
	s_add_i32 s55, s49, 0xa000
	global_load_lds_dwordx4 v[14:15], off
	v_lshl_add_u64 v[2:3], v[2:3], 0, s[12:13]
	s_mov_b32 m0, s54
	s_add_u32 s4, s24, 0xc000
	global_load_lds_dwordx4 v[2:3], off
	v_lshl_add_u64 v[0:1], v[0:1], 0, s[12:13]
	s_mov_b32 m0, s55
	s_addc_u32 s5, s25, 0
	global_load_lds_dwordx4 v[0:1], off
	s_add_i32 m0, s49, 0x1c000
	v_lshl_add_u64 v[0:1], s[4:5], 0, v[164:165]
	global_load_lds_dwordx4 v[0:1], off
	v_lshl_add_u64 v[0:1], s[4:5], 0, v[168:169]
	s_add_i32 m0, s49, 0x1e000
	s_add_i32 s57, 0, 0x10000
	global_load_lds_dwordx4 v[0:1], off
	v_lshrrev_b32_e32 v1, 1, v4
	v_and_b32_e32 v1, 24, v1
	v_and_b32_e32 v0, 15, v4
	v_lshlrev_b32_e32 v2, 1, v1
	v_lshl_or_b32 v194, s8, 6, v0
	v_lshl_or_b32 v0, v0, 6, v2
	v_lshlrev_b32_e32 v2, 2, v4
	v_and_b32_e32 v2, 32, v2
	v_bitop3_b32 v3, v0, s14, v2 bitop3:0xde
	v_bitop3_b32 v195, v0, s15, v2 bitop3:0xde
	v_or_b32_e32 v196, s7, v1
	v_lshrrev_b32_e32 v1, 1, v5
	v_mul_lo_u32 v0, v7, s6
	s_mov_b32 s7, 0x15800
	v_mad_u64_u32 v[0:1], s[4:5], v1, s7, v[0:1]
	v_or_b32_e32 v0, v0, v6
	v_add_lshl_u32 v0, v0, v8, 1
	v_mov_b32_e32 v1, v165
	s_mov_b64 s[4:5], 0x158080
	v_lshl_add_u64 v[172:173], v[0:1], 0, s[4:5]
	v_lshrrev_b32_e32 v1, 1, v9
	v_mul_lo_u32 v0, v10, s6
	v_mad_u64_u32 v[0:1], s[6:7], v1, s7, v[0:1]
	s_waitcnt vmcnt(6)
	v_or_b32_e32 v0, v0, v11
	v_add_lshl_u32 v0, v0, v12, 1
	v_mov_b32_e32 v1, v165
	s_add_i32 s58, 0, 0x14000
	s_sext_i32_i8 s62, s9
	s_ashr_i32 s56, s30, 31
	v_lshl_add_u64 v[174:175], v[0:1], 0, s[4:5]
	v_mov_b64_e32 v[176:177], 0x200
	v_mov_b64_e32 v[178:179], 0x1ff
	v_add_u32_e32 v197, s57, v195
	v_add_u32_e32 v198, 0, v3
	v_add_u32_e32 v199, s58, v195
	s_mov_b64 s[14:15], 0x80000
	s_mov_b64 s[16:17], 0x90000
	s_mov_b64 s[18:19], 0xa0000
	s_mov_b64 s[20:21], 0xb0000
	s_barrier

; __global__ void __launch_bounds__(512, 2) mega_fwd(Params p, int ph_lo, int ph_hi) {
	.amdhsa_kernel _Z8mega_fwd6Paramsii
		.amdhsa_group_segment_fixed_size 0
		.amdhsa_private_segment_fixed_size 0
		.amdhsa_kernarg_size 440
		.amdhsa_user_sgpr_count 2
		.amdhsa_user_sgpr_dispatch_ptr 0
		.amdhsa_user_sgpr_queue_ptr 0
		.amdhsa_user_sgpr_kernarg_segment_ptr 1
		.amdhsa_user_sgpr_dispatch_id 0
		.amdhsa_user_sgpr_kernarg_preload_length 0
		.amdhsa_user_sgpr_kernarg_preload_offset 0
		.amdhsa_user_sgpr_private_segment_size 0
		.amdhsa_uses_dynamic_stack 0
		.amdhsa_enable_private_segment 0
		.amdhsa_system_sgpr_workgroup_id_x 1
		.amdhsa_system_sgpr_workgroup_id_y 0
		.amdhsa_system_sgpr_workgroup_id_z 0
		.amdhsa_system_sgpr_workgroup_info 0
		.amdhsa_system_vgpr_workitem_id 2
		.amdhsa_next_free_vgpr 249
		.amdhsa_next_free_sgpr 79
		.amdhsa_accum_offset 252
		.amdhsa_reserve_vcc 1
		.amdhsa_float_round_mode_32 0
		.amdhsa_float_round_mode_16_64 0
		.amdhsa_float_denorm_mode_32 3
		.amdhsa_float_denorm_mode_16_64 3
		.amdhsa_dx10_clamp 1
		.amdhsa_ieee_mode 1
		.amdhsa_fp16_overflow 0
		.amdhsa_tg_split 0
		.amdhsa_exception_fp_ieee_invalid_op 0
		.amdhsa_exception_fp_denorm_src 0
		.amdhsa_exception_fp_ieee_div_zero 0
		.amdhsa_exception_fp_ieee_overflow 0
		.amdhsa_exception_fp_ieee_underflow 0
		.amdhsa_exception_fp_ieee_inexact 0
		.amdhsa_exception_int_div_zero 0
	.end_amdhsa_kernel

; __global__ void __launch_bounds__(512, 2) mega_fwd(Params p, int ph_lo, int ph_hi) {
amdhsa.kernels:
  - .agpr_count:     0
    .args:
      - .offset:         0
        .size:           176
        .value_kind:     by_value
      - .offset:         176
        .size:           4
        .value_kind:     by_value
      - .offset:         180
        .size:           4
        .value_kind:     by_value
      - .offset:         184
        .size:           4
        .value_kind:     hidden_block_count_x
      - .offset:         188
        .size:           4
        .value_kind:     hidden_block_count_y
      - .offset:         192
        .size:           4
        .value_kind:     hidden_block_count_z
      - .offset:         196
        .size:           2
        .value_kind:     hidden_group_size_x
      - .offset:         198
        .size:           2
        .value_kind:     hidden_group_size_y
      - .offset:         200
        .size:           2
        .value_kind:     hidden_group_size_z
      - .offset:         202
        .size:           2
        .value_kind:     hidden_remainder_x
      - .offset:         204
        .size:           2
        .value_kind:     hidden_remainder_y
      - .offset:         206
        .size:           2
        .value_kind:     hidden_remainder_z
      - .offset:         224
        .size:           8
        .value_kind:     hidden_global_offset_x
      - .offset:         232
        .size:           8
        .value_kind:     hidden_global_offset_y
      - .offset:         240
        .size:           8
        .value_kind:     hidden_global_offset_z
      - .offset:         248
        .size:           2
        .value_kind:     hidden_grid_dims
      - .offset:         272
        .size:           8
        .value_kind:     hidden_multigrid_sync_arg
      - .offset:         304
        .size:           4
        .value_kind:     hidden_dynamic_lds_size
    .group_segment_fixed_size: 0
    .kernarg_segment_align: 8
    .kernarg_segment_size: 440
    .language:       OpenCL C
    .language_version:
      - 2
      - 0
    .max_flat_workgroup_size: 512
    .name:           _Z8mega_fwd6Paramsii
    .private_segment_fixed_size: 0
    .sgpr_count:     85
    .sgpr_spill_count: 0
    .symbol:         _Z8mega_fwd6Paramsii.kd
    .uniform_work_group_size: 1
    .uses_dynamic_stack: false
    .vgpr_count:     249
    .vgpr_spill_count: 0
    .wavefront_size: 64
